# peeled first K-iteration on all 11 GEMM sites + NSA tile LDS hoist + WINROWS dead-store removal
# baseline (speedup 1.0000x reference)
; #define PG8_STAGE(bufoff, gbase, voff) do { _Pragma("unroll") for (int _i = 0; _i < 2; ++_i) \
;         __builtin_amdgcn_global_load_lds((const unsigned*)((const char*)(gbase) + (voff)[_i]), (PG8_LAS unsigned*)(lds + (bufoff) + ldsw + _i * 8192), 16, 0, 0); } while (0)
; #define PG8_WAIT_V(n) asm volatile("s_waitcnt vmcnt(" #n ")" ::: "memory")
; #define PG8_BAR __builtin_amdgcn_s_barrier()
; template <class Epi, class Sched, bool ALIGN_EPI = false, bool SP2 = false>
; __device__ __forceinline__ void gemm_phase(PG8_LAS unsigned char* lds, const Gemm g, const Sched& S, const Epi& E) {
;     ...
;     for (int i = 0; i < 2; ++i) { int R, C; stage_rc(tid * 16 + i * 8192, R, C); const int Rb = Epi::PERM ? ((R & ~31) + perm32(R & 31)) : R;
;         voffA[i] = (unsigned)(R * LD + C) * 2u; voffB[i] = (unsigned)(Rb * LD + C) * 2u; }
;     const size_t kstep = (size_t)(BK * 2);
;     const size_t hstep = (size_t)HALF * LD * 2;
;     const size_t tstep = 2 * hstep;
;     const unsigned ldsw = (unsigned)wid * 1024u;
;     const int aoff = lds_byte(wr * 64 + fr, fq * 8), boff = lds_byte(wc * 32 + fr, fq * 8);
;     ...
;     if constexpr (SP2) {
;         PG8_STAGE(PG8_SB(0, 0), cB, voffB); PG8_STAGE(PG8_SB(0, 1), cB + hstep, voffB); PG8_STAGE(PG8_SA(0, 0), cA, voffA); PG8_STAGE(PG8_SA(0, 1), cA + hstep, voffA);
;         if (wr == 1) PG8_BAR;
;         PG8_WAIT_V(2); PG8_BAR;
;         PG8_STAGE(PG8_SB(1, 0), cB + kstep, voffB); PG8_STAGE(PG8_SA(1, 0), cA + kstep, voffA); PG8_STAGE(PG8_SB(1, 1), cB + hstep + kstep, voffB);
;         PG8_WAIT_V(6); PG8_BAR;
.LBB0_194:
	s_lshl_b32 s3, s3, 5
	s_mov_b64 s[10:11], 0x80
	s_and_b32 s3, s3, 0x60
	s_add_i32 m0, s28, 0x18000
	v_lshl_add_u64 v[8:9], v[8:9], 0, s[10:11]
	s_ashr_i32 s40, s78, 31
	s_lshl_b32 s15, s1, 13
	s_lshl_b32 s24, s3, 7
	s_waitcnt vmcnt(2)
	s_barrier
	global_load_lds_dwordx4 v[8:9], off
	v_lshl_add_u64 v[4:5], v[4:5], 0, s[10:11]
	s_add_i32 m0, s28, 0x1a000
	s_add_i32 s41, s28, 0x8000
	s_add_i32 s50, s28, 0xa000
	global_load_lds_dwordx4 v[4:5], off
	v_lshl_add_u64 v[2:3], v[2:3], 0, s[10:11]
	s_mov_b32 m0, s41
	s_add_u32 s18, s22, 0x160080
	global_load_lds_dwordx4 v[2:3], off
	v_lshl_add_u64 v[2:3], v[6:7], 0, s[10:11]
	s_mov_b32 m0, s50
	s_addc_u32 s19, s23, 0
	global_load_lds_dwordx4 v[2:3], off
	s_add_i32 m0, s28, 0x1c000
	v_lshl_add_u64 v[2:3], s[18:19], 0, v[134:135]
	global_load_lds_dwordx4 v[2:3], off
	v_lshl_add_u64 v[2:3], s[18:19], 0, v[130:131]
	s_add_i32 m0, s28, 0x1e000
	s_cmpk_lt_u32 s0, 0x100
	global_load_lds_dwordx4 v[2:3], off
	v_lshrrev_b32_e32 v3, 1, v11
	v_and_b32_e32 v3, 24, v3
	v_and_b32_e32 v2, 15, v11
	v_lshlrev_b32_e32 v4, 1, v3
	v_lshl_or_b32 v152, s1, 6, v2
	v_lshl_or_b32 v2, v2, 6, v4
	v_lshlrev_b32_e32 v4, 2, v11
	v_and_b32_e32 v4, 32, v4
	v_bitop3_b32 v5, v2, s15, v4 bitop3:0xde
	v_bitop3_b32 v153, v2, s24, v4 bitop3:0xde
	v_or_b32_e32 v154, s3, v3
	v_lshrrev_b32_e32 v3, 1, v16
	v_mul_lo_u32 v2, v15, s2
	v_mad_u64_u32 v[2:3], s[0:1], v3, s16, v[2:3]
	v_or_b32_e32 v2, v2, v17
	s_mov_b64 s[18:19], 0x160080
	v_add_lshl_u32 v2, v2, v18, 1
	v_mov_b32_e32 v3, v135
	v_lshl_add_u64 v[138:139], v[2:3], 0, s[18:19]
	v_lshrrev_b32_e32 v3, 1, v10
	v_mul_lo_u32 v2, v12, s2
	v_mad_u64_u32 v[2:3], s[0:1], v3, s16, v[2:3]
	s_waitcnt vmcnt(6)
	v_or_b32_e32 v2, v2, v13
	s_sext_i32_i8 s56, s14
	s_cselect_b64 s[14:15], -1, 0
	v_add_lshl_u32 v2, v2, v14, 1
	v_mov_b32_e32 v3, v135
	s_add_i32 s51, 0, 0x10000
	s_add_i32 s52, 0, 0x14000
	v_lshl_add_u64 v[140:141], v[2:3], 0, s[18:19]
	v_mov_b64_e32 v[142:143], 0x200
	v_mov_b64_e32 v[144:145], 0x1ff
	v_add_u32_e32 v155, s51, v153
	v_add_u32_e32 v156, s52, v153
	v_add_u32_e32 v157, 0, v5
	s_mov_b32 s16, 0x3f9837f0
	s_barrier
	s_mov_b32 s98, 0
	s_branch .LBB0_197

; #define PG8_STAGE(bufoff, gbase, voff) do { _Pragma("unroll") for (int _i = 0; _i < 2; ++_i) \
;         __builtin_amdgcn_global_load_lds((const unsigned*)((const char*)(gbase) + (voff)[_i]), (PG8_LAS unsigned*)(lds + (bufoff) + ldsw + _i * 8192), 16, 0, 0); } while (0)
; #define PG8_LDA(dst, b, h) do { _Pragma("unroll") for (int m = 0; m < 4; ++m) _Pragma("unroll") for (int k = 0; k < 2; ++k) dst[m][k] = *(const PG8_LAS bf16x8*)(lds + PG8_SA(b, h) + aoff + m * 2048 + k * 1024); } while (0)
; #define PG8_LDB(dst, b, h) do { _Pragma("unroll") for (int n = 0; n < 2; ++n) _Pragma("unroll") for (int k = 0; k < 2; ++k) dst[n][k] = *(const PG8_LAS bf16x8*)(lds + PG8_SB(b, h) + boff + n * 2048 + k * 1024); } while (0)
; #define PG8_MMA(ai, bj, At, Bt) do { __builtin_amdgcn_s_setprio(1); _Pragma("unroll") for (int m = 0; m < 4; ++m) _Pragma("unroll") for (int n = 0; n < 2; ++n) _Pragma("unroll") for (int k = 0; k < 2; ++k) \
;         acc[ai][bj][m][n] = __builtin_amdgcn_mfma_f32_16x16x32_bf16(Bt[n][k], At[m][k], acc[ai][bj][m][n], 0, 0, 0); __builtin_amdgcn_s_setprio(0); } while (0)
; #define PG8_WAIT_V(n) asm volatile("s_waitcnt vmcnt(" #n ")" ::: "memory")
; #define PG8_WAIT_L(n) asm volatile("s_waitcnt lgkmcnt(" #n ")" ::: "memory")
; #define PG8_BAR __builtin_amdgcn_s_barrier()
; #define PG8_SCHED __builtin_amdgcn_sched_barrier(0)
; template <class Epi, class Sched, bool ALIGN_EPI = false, bool SP2 = false>
; __device__ __forceinline__ void gemm_phase(PG8_LAS unsigned char* lds, const Gemm g, const Sched& S, const Epi& E) {
;     ...
;             PG8_LDB(B0, 0, 0); PG8_LDB(B1, 0, 1); PG8_SCHED; PG8_LDA(At, 0, 0); PG8_STAGE(PG8_SA(1, 1), a1 + hstep, voffA);
;             PG8_WAIT_V(8); PG8_WAIT_L(0); PG8_BAR; PG8_MMA(0, 0, At, B0); PG8_MMA(0, 1, At, B1); PG8_BAR; PG8_SCHED;
;     ...
; #pragma unroll
;         for (int a = 0; a < 2; ++a)
; #pragma unroll
;             for (int b = 0; b < 2; ++b)
; #pragma unroll
;                 for (int m = 0; m < 4; ++m)
; #pragma unroll
;                     for (int n = 0; n < 2; ++n) acc[a][b][m][n] = (f32x4){0.f, 0.f, 0.f, 0.f};
.LBB0_207:
	s_add_u32 s57, s22, 0x100
	v_mov_b32_e32 v2, 0
	s_addc_u32 s58, s23, 0
	s_mov_b32 s59, -2
	s_cmp_lg_u32 s98, 0
	s_cbranch_scc1 .Lpeel_3
	v_mov_b32_e32 v3, v2
	v_mov_b32_e32 v4, v2
	v_mov_b32_e32 v5, v2
	v_mov_b32_e32 v6, v2
	v_mov_b32_e32 v7, v2
	v_mov_b32_e32 v8, v2
	v_mov_b32_e32 v9, v2
	v_mov_b32_e32 v14, v2
	v_mov_b32_e32 v15, v2
	v_mov_b32_e32 v16, v2
	v_mov_b32_e32 v17, v2
	v_mov_b32_e32 v22, v2
	v_mov_b32_e32 v23, v2
	v_mov_b32_e32 v24, v2
	v_mov_b32_e32 v25, v2
	v_mov_b32_e32 v30, v2
	v_mov_b32_e32 v31, v2
	v_mov_b32_e32 v32, v2
	v_mov_b32_e32 v33, v2
	v_mov_b32_e32 v38, v2
	v_mov_b32_e32 v39, v2
	v_mov_b32_e32 v40, v2
	v_mov_b32_e32 v41, v2
	v_mov_b32_e32 v46, v2
	v_mov_b32_e32 v47, v2
	v_mov_b32_e32 v48, v2
	v_mov_b32_e32 v49, v2
	v_mov_b32_e32 v54, v2
	v_mov_b32_e32 v55, v2
	v_mov_b32_e32 v56, v2
	v_mov_b32_e32 v57, v2
	v_mov_b32_e32 v10, v2
	v_mov_b32_e32 v11, v2
	v_mov_b32_e32 v12, v2
	v_mov_b32_e32 v13, v2
	v_mov_b32_e32 v18, v2
	v_mov_b32_e32 v19, v2
	v_mov_b32_e32 v20, v2
	v_mov_b32_e32 v21, v2
	v_mov_b32_e32 v26, v2
	v_mov_b32_e32 v27, v2
	v_mov_b32_e32 v28, v2
	v_mov_b32_e32 v29, v2
	v_mov_b32_e32 v34, v2
	v_mov_b32_e32 v35, v2
	v_mov_b32_e32 v36, v2
	v_mov_b32_e32 v37, v2
	v_mov_b32_e32 v42, v2
	v_mov_b32_e32 v43, v2
	v_mov_b32_e32 v44, v2
	v_mov_b32_e32 v45, v2
	v_mov_b32_e32 v50, v2
	v_mov_b32_e32 v51, v2
	v_mov_b32_e32 v52, v2
	v_mov_b32_e32 v53, v2
	v_mov_b32_e32 v58, v2
	v_mov_b32_e32 v59, v2
	v_mov_b32_e32 v60, v2
	v_mov_b32_e32 v61, v2
	v_mov_b32_e32 v62, v2
	v_mov_b32_e32 v63, v2
	v_mov_b32_e32 v64, v2
	v_mov_b32_e32 v65, v2
	v_mov_b32_e32 v66, v2
	v_mov_b32_e32 v67, v2
	v_mov_b32_e32 v68, v2
	v_mov_b32_e32 v69, v2
	v_mov_b32_e32 v70, v2
	v_mov_b32_e32 v71, v2
	v_mov_b32_e32 v72, v2
	v_mov_b32_e32 v73, v2
	v_mov_b32_e32 v78, v2
	v_mov_b32_e32 v79, v2
	v_mov_b32_e32 v80, v2
	v_mov_b32_e32 v81, v2
	v_mov_b32_e32 v86, v2
	v_mov_b32_e32 v87, v2
	v_mov_b32_e32 v88, v2
	v_mov_b32_e32 v89, v2
	v_mov_b32_e32 v94, v2
	v_mov_b32_e32 v95, v2
	v_mov_b32_e32 v96, v2
	v_mov_b32_e32 v97, v2
	v_mov_b32_e32 v102, v2
	v_mov_b32_e32 v103, v2
	v_mov_b32_e32 v104, v2
	v_mov_b32_e32 v105, v2
	v_mov_b32_e32 v110, v2
	v_mov_b32_e32 v111, v2
	v_mov_b32_e32 v112, v2
	v_mov_b32_e32 v113, v2
	v_mov_b32_e32 v118, v2
	v_mov_b32_e32 v119, v2
	v_mov_b32_e32 v120, v2
	v_mov_b32_e32 v121, v2
	v_mov_b32_e32 v74, v2
	v_mov_b32_e32 v75, v2
	v_mov_b32_e32 v76, v2
	v_mov_b32_e32 v77, v2
	v_mov_b32_e32 v82, v2
	v_mov_b32_e32 v83, v2
	v_mov_b32_e32 v84, v2
	v_mov_b32_e32 v85, v2
	v_mov_b32_e32 v90, v2
	v_mov_b32_e32 v91, v2
	v_mov_b32_e32 v92, v2
	v_mov_b32_e32 v93, v2
	v_mov_b32_e32 v98, v2
	v_mov_b32_e32 v99, v2
	v_mov_b32_e32 v100, v2
	v_mov_b32_e32 v101, v2
	v_mov_b32_e32 v106, v2
	v_mov_b32_e32 v107, v2
	v_mov_b32_e32 v108, v2
	v_mov_b32_e32 v109, v2
	v_mov_b32_e32 v114, v2
	v_mov_b32_e32 v115, v2
	v_mov_b32_e32 v116, v2
	v_mov_b32_e32 v117, v2
	v_mov_b32_e32 v122, v2
	v_mov_b32_e32 v123, v2
	v_mov_b32_e32 v124, v2
	v_mov_b32_e32 v125, v2
	v_mov_b32_e32 v126, v2
	v_mov_b32_e32 v127, v2
	v_mov_b32_e32 v128, v2
	v_mov_b32_e32 v129, v2
.LBB0_208:
	ds_read_b128 v[146:149], v155
	ds_read_b128 v[158:161], v155 offset:1024
	ds_read_b128 v[162:165], v155 offset:2048
	ds_read_b128 v[166:169], v155 offset:3072
	ds_read_b128 v[170:173], v156
	ds_read_b128 v[174:177], v156 offset:1024
	ds_read_b128 v[178:181], v156 offset:2048
	ds_read_b128 v[182:185], v156 offset:3072
	s_add_u32 s22, s20, 0x100
	s_addc_u32 s23, s21, 0
	s_cmpk_eq_i32 s59, 0x54
	s_cselect_b32 s27, s3, s23
	s_cselect_b32 s26, s2, s22
	s_cselect_b32 s25, s19, s58
	s_cselect_b32 s24, s18, s57
	v_lshl_add_u64 v[150:151], s[20:21], 0, v[138:139]
	s_add_i32 m0, s28, 0xc000
	ds_read_b128 v[186:189], v157
	ds_read_b128 v[190:193], v157 offset:1024
	ds_read_b128 v[194:197], v157 offset:2048
	ds_read_b128 v[198:201], v157 offset:3072
	ds_read_b128 v[202:205], v157 offset:4096
	ds_read_b128 v[206:209], v157 offset:5120
	ds_read_b128 v[210:213], v157 offset:6144
	ds_read_b128 v[214:217], v157 offset:7168
	global_load_lds_dwordx4 v[150:151], off
	v_lshl_add_u64 v[150:151], s[20:21], 0, v[140:141]
	s_add_i32 m0, s28, 0xe000
	s_nop 0
	global_load_lds_dwordx4 v[150:151], off
	s_waitcnt vmcnt(8)
	s_waitcnt lgkmcnt(0)
	s_barrier
	s_setprio 1
	s_waitcnt lgkmcnt(0)
	v_mfma_f32_16x16x32_bf16 v[126:129], v[146:149], v[186:189], v[126:129]
	v_mfma_f32_16x16x32_bf16 v[122:125], v[162:165], v[186:189], v[122:125]
	v_mfma_f32_16x16x32_bf16 v[114:117], v[146:149], v[194:197], v[114:117]
	v_mfma_f32_16x16x32_bf16 v[106:109], v[162:165], v[194:197], v[106:109]
	v_mfma_f32_16x16x32_bf16 v[98:101], v[146:149], v[202:205], v[98:101]
	v_mfma_f32_16x16x32_bf16 v[90:93], v[162:165], v[202:205], v[90:93]
	v_mfma_f32_16x16x32_bf16 v[82:85], v[146:149], v[210:213], v[82:85]
	v_mfma_f32_16x16x32_bf16 v[74:77], v[162:165], v[210:213], v[74:77]
	v_mfma_f32_16x16x32_bf16 v[126:129], v[158:161], v[190:193], v[126:129]
	v_mfma_f32_16x16x32_bf16 v[122:125], v[166:169], v[190:193], v[122:125]
	v_mfma_f32_16x16x32_bf16 v[114:117], v[158:161], v[198:201], v[114:117]
	v_mfma_f32_16x16x32_bf16 v[106:109], v[166:169], v[198:201], v[106:109]
	v_mfma_f32_16x16x32_bf16 v[98:101], v[158:161], v[206:209], v[98:101]
	v_mfma_f32_16x16x32_bf16 v[90:93], v[166:169], v[206:209], v[90:93]
	v_mfma_f32_16x16x32_bf16 v[82:85], v[158:161], v[214:217], v[82:85]
	v_mfma_f32_16x16x32_bf16 v[74:77], v[166:169], v[214:217], v[74:77]
	s_setprio 0
	s_setprio 1
	v_mfma_f32_16x16x32_bf16 v[118:121], v[170:173], v[186:189], v[118:121]
	v_mfma_f32_16x16x32_bf16 v[110:113], v[178:181], v[186:189], v[110:113]
	v_mfma_f32_16x16x32_bf16 v[102:105], v[170:173], v[194:197], v[102:105]
	v_mfma_f32_16x16x32_bf16 v[94:97], v[178:181], v[194:197], v[94:97]
	v_mfma_f32_16x16x32_bf16 v[86:89], v[170:173], v[202:205], v[86:89]
	v_mfma_f32_16x16x32_bf16 v[78:81], v[178:181], v[202:205], v[78:81]
	v_mfma_f32_16x16x32_bf16 v[70:73], v[170:173], v[210:213], v[70:73]
	v_mfma_f32_16x16x32_bf16 v[66:69], v[178:181], v[210:213], v[66:69]
	v_mfma_f32_16x16x32_bf16 v[118:121], v[174:177], v[190:193], v[118:121]
	v_mfma_f32_16x16x32_bf16 v[110:113], v[182:185], v[190:193], v[110:113]
	v_mfma_f32_16x16x32_bf16 v[102:105], v[174:177], v[198:201], v[102:105]
	v_mfma_f32_16x16x32_bf16 v[94:97], v[182:185], v[198:201], v[94:97]
	v_mfma_f32_16x16x32_bf16 v[86:89], v[174:177], v[206:209], v[86:89]
	v_mfma_f32_16x16x32_bf16 v[78:81], v[182:185], v[206:209], v[78:81]
	v_mfma_f32_16x16x32_bf16 v[70:73], v[174:177], v[214:217], v[70:73]
	v_mfma_f32_16x16x32_bf16 v[66:69], v[182:185], v[214:217], v[66:69]
	s_setprio 0
	s_barrier
; #define PG8_STAGE(bufoff, gbase, voff) do { _Pragma("unroll") for (int _i = 0; _i < 2; ++_i) \
;         __builtin_amdgcn_global_load_lds((const unsigned*)((const char*)(gbase) + (voff)[_i]), (PG8_LAS unsigned*)(lds + (bufoff) + ldsw + _i * 8192), 16, 0, 0); } while (0)
; #define PG8_LDA(dst, b, h) do { _Pragma("unroll") for (int m = 0; m < 4; ++m) _Pragma("unroll") for (int k = 0; k < 2; ++k) dst[m][k] = *(const PG8_LAS bf16x8*)(lds + PG8_SA(b, h) + aoff + m * 2048 + k * 1024); } while (0)
; #define PG8_LDB(dst, b, h) do { _Pragma("unroll") for (int n = 0; n < 2; ++n) _Pragma("unroll") for (int k = 0; k < 2; ++k) dst[n][k] = *(const PG8_LAS bf16x8*)(lds + PG8_SB(b, h) + boff + n * 2048 + k * 1024); } while (0)
; #define PG8_MMA(ai, bj, At, Bt) do { __builtin_amdgcn_s_setprio(1); _Pragma("unroll") for (int m = 0; m < 4; ++m) _Pragma("unroll") for (int n = 0; n < 2; ++n) _Pragma("unroll") for (int k = 0; k < 2; ++k) \
;         acc[ai][bj][m][n] = __builtin_amdgcn_mfma_f32_16x16x32_bf16(Bt[n][k], At[m][k], acc[ai][bj][m][n], 0, 0, 0); __builtin_amdgcn_s_setprio(0); } while (0)
; #define PG8_WAIT_V(n) asm volatile("s_waitcnt vmcnt(" #n ")" ::: "memory")
; #define PG8_WAIT_L(n) asm volatile("s_waitcnt lgkmcnt(" #n ")" ::: "memory")
; #define PG8_BAR __builtin_amdgcn_s_barrier()
; #define PG8_SCHED __builtin_amdgcn_sched_barrier(0)
; template <class Epi, class Sched, bool ALIGN_EPI = false, bool SP2 = false>
; __device__ __forceinline__ void gemm_phase(PG8_LAS unsigned char* lds, const Gemm g, const Sched& S, const Epi& E) {
;     ...
;             PG8_LDA(At, 0, 1); PG8_STAGE(PG8_SB(0, 0), b2, voffB); PG8_STAGE(PG8_SB(0, 1), b2 + hstep, voffB); PG8_STAGE(PG8_SA(0, 0), a2, voffA);
;             PG8_WAIT_V(8); PG8_WAIT_L(0); PG8_BAR; PG8_MMA(1, 0, At, B0); PG8_MMA(1, 1, At, B1); PG8_BAR; PG8_SCHED;
;             PG8_LDB(B0, 1, 0); PG8_LDB(B1, 1, 1); PG8_SCHED; PG8_LDA(At, 1, 0); PG8_STAGE(PG8_SA(0, 1), a2 + hstep, voffA);
;             PG8_WAIT_V(8); PG8_WAIT_L(0); PG8_BAR; PG8_MMA(0, 0, At, B0); PG8_MMA(0, 1, At, B1); PG8_BAR; PG8_SCHED;
;             PG8_LDA(At, 1, 1); PG8_STAGE(PG8_SB(1, 0), b3, voffB); PG8_STAGE(PG8_SB(1, 1), b3 + hstep, voffB); PG8_STAGE(PG8_SA(1, 0), a3, voffA);
	s_add_i32 s20, s51, s13
	v_lshl_add_u64 v[150:151], s[24:25], 0, v[134:135]
	s_mov_b32 m0, s20
	ds_read_b128 v[186:189], v157 offset:16384
	ds_read_b128 v[190:193], v157 offset:17408
	ds_read_b128 v[194:197], v157 offset:18432
	ds_read_b128 v[198:201], v157 offset:19456
	ds_read_b128 v[202:205], v157 offset:20480
	ds_read_b128 v[206:209], v157 offset:21504
	ds_read_b128 v[210:213], v157 offset:22528
	ds_read_b128 v[214:217], v157 offset:23552
	global_load_lds_dwordx4 v[150:151], off
	s_add_i32 m0, s20, 0x2000
	s_add_u32 s20, s24, 0x160000
	v_lshl_add_u64 v[218:219], s[24:25], 0, v[130:131]
	s_addc_u32 s21, s25, 0
	s_add_i32 s60, s52, s13
	global_load_lds_dwordx4 v[218:219], off
	v_lshl_add_u64 v[220:221], s[20:21], 0, v[134:135]
	s_mov_b32 m0, s60
	v_lshl_add_u64 v[222:223], s[26:27], 0, v[132:133]
	global_load_lds_dwordx4 v[220:221], off
	v_lshl_add_u64 v[220:221], s[20:21], 0, v[130:131]
	s_add_i32 m0, s60, 0x2000
	s_nop 0
	global_load_lds_dwordx4 v[220:221], off
	v_lshl_add_u64 v[220:221], s[26:27], 0, v[136:137]
	s_mov_b32 m0, s28
	s_nop 0
	global_load_lds_dwordx4 v[220:221], off
	s_mov_b32 m0, s29
	s_nop 0
	global_load_lds_dwordx4 v[222:223], off
	s_waitcnt vmcnt(8)
	s_waitcnt lgkmcnt(0)
	s_barrier
	s_setprio 1
	s_waitcnt lgkmcnt(0)
	v_mfma_f32_16x16x32_bf16 v[62:65], v[146:149], v[186:189], v[62:65]
	v_mfma_f32_16x16x32_bf16 v[58:61], v[162:165], v[186:189], v[58:61]
	v_mfma_f32_16x16x32_bf16 v[50:53], v[146:149], v[194:197], v[50:53]
	v_mfma_f32_16x16x32_bf16 v[42:45], v[162:165], v[194:197], v[42:45]
	v_mfma_f32_16x16x32_bf16 v[34:37], v[146:149], v[202:205], v[34:37]
	v_mfma_f32_16x16x32_bf16 v[26:29], v[162:165], v[202:205], v[26:29]
	v_mfma_f32_16x16x32_bf16 v[18:21], v[146:149], v[210:213], v[18:21]
	v_mfma_f32_16x16x32_bf16 v[10:13], v[162:165], v[210:213], v[10:13]
	v_mfma_f32_16x16x32_bf16 v[62:65], v[158:161], v[190:193], v[62:65]
	v_mfma_f32_16x16x32_bf16 v[58:61], v[166:169], v[190:193], v[58:61]
	v_mfma_f32_16x16x32_bf16 v[50:53], v[158:161], v[198:201], v[50:53]
	v_mfma_f32_16x16x32_bf16 v[42:45], v[166:169], v[198:201], v[42:45]
	v_mfma_f32_16x16x32_bf16 v[34:37], v[158:161], v[206:209], v[34:37]
	v_mfma_f32_16x16x32_bf16 v[26:29], v[166:169], v[206:209], v[26:29]
	v_mfma_f32_16x16x32_bf16 v[18:21], v[158:161], v[214:217], v[18:21]
	v_mfma_f32_16x16x32_bf16 v[10:13], v[166:169], v[214:217], v[10:13]
	s_setprio 0
	s_setprio 1
	v_mfma_f32_16x16x32_bf16 v[54:57], v[170:173], v[186:189], v[54:57]
	v_mfma_f32_16x16x32_bf16 v[46:49], v[178:181], v[186:189], v[46:49]
	v_mfma_f32_16x16x32_bf16 v[38:41], v[170:173], v[194:197], v[38:41]
	v_mfma_f32_16x16x32_bf16 v[30:33], v[178:181], v[194:197], v[30:33]
	v_mfma_f32_16x16x32_bf16 v[22:25], v[170:173], v[202:205], v[22:25]
	v_mfma_f32_16x16x32_bf16 v[14:17], v[178:181], v[202:205], v[14:17]
	v_mfma_f32_16x16x32_bf16 v[6:9], v[170:173], v[210:213], v[6:9]
	v_mfma_f32_16x16x32_bf16 v[2:5], v[178:181], v[210:213], v[2:5]
	v_mfma_f32_16x16x32_bf16 v[54:57], v[174:177], v[190:193], v[54:57]
	v_mfma_f32_16x16x32_bf16 v[46:49], v[182:185], v[190:193], v[46:49]
	v_mfma_f32_16x16x32_bf16 v[38:41], v[174:177], v[198:201], v[38:41]
	v_mfma_f32_16x16x32_bf16 v[30:33], v[182:185], v[198:201], v[30:33]
	v_mfma_f32_16x16x32_bf16 v[22:25], v[174:177], v[206:209], v[22:25]
	v_mfma_f32_16x16x32_bf16 v[14:17], v[182:185], v[206:209], v[14:17]
	v_mfma_f32_16x16x32_bf16 v[6:9], v[174:177], v[214:217], v[6:9]
	v_mfma_f32_16x16x32_bf16 v[2:5], v[182:185], v[214:217], v[2:5]
	s_setprio 0
	s_barrier
	s_add_i32 s60, 0, 0x18000
	s_add_i32 s61, 0, 0x1c000
	v_add_u32_e32 v166, s60, v153
	v_add_u32_e32 v182, s61, v153
	ds_read_b128 v[146:149], v166
	ds_read_b128 v[158:161], v166 offset:1024
	ds_read_b128 v[162:165], v166 offset:2048
	ds_read_b128 v[166:169], v166 offset:3072
	ds_read_b128 v[170:173], v182
	ds_read_b128 v[174:177], v182 offset:1024
	ds_read_b128 v[178:181], v182 offset:2048
	ds_read_b128 v[182:185], v182 offset:3072
	s_add_u32 s20, s26, 0x160000
	s_addc_u32 s21, s27, 0
	s_mov_b32 m0, s33
	v_lshl_add_u64 v[224:225], s[20:21], 0, v[136:137]
	ds_read_b128 v[186:189], v157 offset:32768
	ds_read_b128 v[190:193], v157 offset:33792
	ds_read_b128 v[194:197], v157 offset:34816
	ds_read_b128 v[198:201], v157 offset:35840
	ds_read_b128 v[202:205], v157 offset:36864
	ds_read_b128 v[206:209], v157 offset:37888
	ds_read_b128 v[210:213], v157 offset:38912
	ds_read_b128 v[214:217], v157 offset:39936
	global_load_lds_dwordx4 v[224:225], off
	v_lshl_add_u64 v[224:225], s[20:21], 0, v[132:133]
	s_mov_b32 m0, s34
	s_nop 0
	global_load_lds_dwordx4 v[224:225], off
	s_waitcnt vmcnt(8)
	s_waitcnt lgkmcnt(0)
	s_barrier
; #define PG8_STAGE(bufoff, gbase, voff) do { _Pragma("unroll") for (int _i = 0; _i < 2; ++_i) \
;         __builtin_amdgcn_global_load_lds((const unsigned*)((const char*)(gbase) + (voff)[_i]), (PG8_LAS unsigned*)(lds + (bufoff) + ldsw + _i * 8192), 16, 0, 0); } while (0)
; #define PG8_LDA(dst, b, h) do { _Pragma("unroll") for (int m = 0; m < 4; ++m) _Pragma("unroll") for (int k = 0; k < 2; ++k) dst[m][k] = *(const PG8_LAS bf16x8*)(lds + PG8_SA(b, h) + aoff + m * 2048 + k * 1024); } while (0)
; #define PG8_LDB(dst, b, h) do { _Pragma("unroll") for (int n = 0; n < 2; ++n) _Pragma("unroll") for (int k = 0; k < 2; ++k) dst[n][k] = *(const PG8_LAS bf16x8*)(lds + PG8_SB(b, h) + boff + n * 2048 + k * 1024); } while (0)
; #define PG8_MMA(ai, bj, At, Bt) do { __builtin_amdgcn_s_setprio(1); _Pragma("unroll") for (int m = 0; m < 4; ++m) _Pragma("unroll") for (int n = 0; n < 2; ++n) _Pragma("unroll") for (int k = 0; k < 2; ++k) \
;         acc[ai][bj][m][n] = __builtin_amdgcn_mfma_f32_16x16x32_bf16(Bt[n][k], At[m][k], acc[ai][bj][m][n], 0, 0, 0); __builtin_amdgcn_s_setprio(0); } while (0)
; #define PG8_WAIT_V(n) asm volatile("s_waitcnt vmcnt(" #n ")" ::: "memory")
; #define PG8_WAIT_L(n) asm volatile("s_waitcnt lgkmcnt(" #n ")" ::: "memory")
; #define PG8_BAR __builtin_amdgcn_s_barrier()
; #define PG8_SCHED __builtin_amdgcn_sched_barrier(0)
; template <class Epi, class Sched, bool ALIGN_EPI = false, bool SP2 = false>
; __device__ __forceinline__ void gemm_phase(PG8_LAS unsigned char* lds, const Gemm g, const Sched& S, const Epi& E) {
;     ...
;             PG8_LDB(B0, 1, 0); PG8_LDB(B1, 1, 1); PG8_SCHED; PG8_LDA(At, 1, 0); PG8_STAGE(PG8_SA(0, 1), a2 + hstep, voffA);
;             PG8_WAIT_V(8); PG8_WAIT_L(0); PG8_BAR; PG8_MMA(0, 0, At, B0); PG8_MMA(0, 1, At, B1); PG8_BAR; PG8_SCHED;
;             PG8_LDA(At, 1, 1); PG8_STAGE(PG8_SB(1, 0), b3, voffB); PG8_STAGE(PG8_SB(1, 1), b3 + hstep, voffB); PG8_STAGE(PG8_SA(1, 0), a3, voffA);
;             PG8_WAIT_V(8); PG8_WAIT_L(0); PG8_BAR; PG8_MMA(1, 0, At, B0); PG8_MMA(1, 1, At, B1); PG8_BAR; PG8_SCHED;
	s_setprio 1
	s_waitcnt lgkmcnt(0)
	v_mfma_f32_16x16x32_bf16 v[126:129], v[146:149], v[186:189], v[126:129]
	v_mfma_f32_16x16x32_bf16 v[122:125], v[162:165], v[186:189], v[122:125]
	v_mfma_f32_16x16x32_bf16 v[114:117], v[146:149], v[194:197], v[114:117]
	v_mfma_f32_16x16x32_bf16 v[106:109], v[162:165], v[194:197], v[106:109]
	v_mfma_f32_16x16x32_bf16 v[98:101], v[146:149], v[202:205], v[98:101]
	v_mfma_f32_16x16x32_bf16 v[90:93], v[162:165], v[202:205], v[90:93]
	v_mfma_f32_16x16x32_bf16 v[82:85], v[146:149], v[210:213], v[82:85]
	v_mfma_f32_16x16x32_bf16 v[74:77], v[162:165], v[210:213], v[74:77]
	v_mfma_f32_16x16x32_bf16 v[126:129], v[158:161], v[190:193], v[126:129]
	v_mfma_f32_16x16x32_bf16 v[122:125], v[166:169], v[190:193], v[122:125]
	v_mfma_f32_16x16x32_bf16 v[114:117], v[158:161], v[198:201], v[114:117]
	v_mfma_f32_16x16x32_bf16 v[106:109], v[166:169], v[198:201], v[106:109]
	v_mfma_f32_16x16x32_bf16 v[98:101], v[158:161], v[206:209], v[98:101]
	v_mfma_f32_16x16x32_bf16 v[90:93], v[166:169], v[206:209], v[90:93]
	v_mfma_f32_16x16x32_bf16 v[82:85], v[158:161], v[214:217], v[82:85]
	v_mfma_f32_16x16x32_bf16 v[74:77], v[166:169], v[214:217], v[74:77]
	s_setprio 0
	s_setprio 1
	v_mfma_f32_16x16x32_bf16 v[118:121], v[170:173], v[186:189], v[118:121]
	v_mfma_f32_16x16x32_bf16 v[110:113], v[178:181], v[186:189], v[110:113]
	v_mfma_f32_16x16x32_bf16 v[102:105], v[170:173], v[194:197], v[102:105]
	v_mfma_f32_16x16x32_bf16 v[94:97], v[178:181], v[194:197], v[94:97]
	v_mfma_f32_16x16x32_bf16 v[86:89], v[170:173], v[202:205], v[86:89]
	v_mfma_f32_16x16x32_bf16 v[78:81], v[178:181], v[202:205], v[78:81]
	v_mfma_f32_16x16x32_bf16 v[70:73], v[170:173], v[210:213], v[70:73]
	v_mfma_f32_16x16x32_bf16 v[66:69], v[178:181], v[210:213], v[66:69]
	v_mfma_f32_16x16x32_bf16 v[118:121], v[174:177], v[190:193], v[118:121]
	v_mfma_f32_16x16x32_bf16 v[110:113], v[182:185], v[190:193], v[110:113]
	v_mfma_f32_16x16x32_bf16 v[102:105], v[174:177], v[198:201], v[102:105]
	v_mfma_f32_16x16x32_bf16 v[94:97], v[182:185], v[198:201], v[94:97]
	v_mfma_f32_16x16x32_bf16 v[86:89], v[174:177], v[206:209], v[86:89]
	v_mfma_f32_16x16x32_bf16 v[78:81], v[182:185], v[206:209], v[78:81]
	v_mfma_f32_16x16x32_bf16 v[70:73], v[174:177], v[214:217], v[70:73]
	v_mfma_f32_16x16x32_bf16 v[66:69], v[182:185], v[214:217], v[66:69]
	s_setprio 0
	s_barrier
	s_add_i32 s20, s60, s13
	v_lshl_add_u64 v[150:151], v[150:151], 0, s[10:11]
	s_mov_b32 m0, s20
	ds_read_b128 v[186:189], v157 offset:49152
	ds_read_b128 v[190:193], v157 offset:50176
	ds_read_b128 v[194:197], v157 offset:51200
	ds_read_b128 v[198:201], v157 offset:52224
	ds_read_b128 v[202:205], v157 offset:53248
	ds_read_b128 v[206:209], v157 offset:54272
	ds_read_b128 v[210:213], v157 offset:55296
	ds_read_b128 v[214:217], v157 offset:56320
	global_load_lds_dwordx4 v[150:151], off
	s_add_i32 m0, s20, 0x2000
	s_add_u32 s20, s24, 0x160080
	v_lshl_add_u64 v[150:151], v[218:219], 0, s[10:11]
	s_addc_u32 s21, s25, 0
	s_add_i32 s24, s61, s13
	global_load_lds_dwordx4 v[150:151], off
	v_lshl_add_u64 v[150:151], s[20:21], 0, v[134:135]
	s_mov_b32 m0, s24
	s_nop 0
	global_load_lds_dwordx4 v[150:151], off
	v_lshl_add_u64 v[150:151], s[20:21], 0, v[130:131]
	s_add_i32 m0, s24, 0x2000
	s_nop 0
	global_load_lds_dwordx4 v[150:151], off
	v_lshl_add_u64 v[150:151], v[220:221], 0, s[10:11]
	s_mov_b32 m0, s41
	s_nop 0
	global_load_lds_dwordx4 v[150:151], off
	v_lshl_add_u64 v[150:151], v[222:223], 0, s[10:11]
	s_mov_b32 m0, s50
	s_nop 0
	global_load_lds_dwordx4 v[150:151], off
	s_waitcnt vmcnt(8)
	s_waitcnt lgkmcnt(0)
	s_barrier
	s_setprio 1
	s_waitcnt lgkmcnt(0)
	v_mfma_f32_16x16x32_bf16 v[62:65], v[146:149], v[186:189], v[62:65]
	v_mfma_f32_16x16x32_bf16 v[58:61], v[162:165], v[186:189], v[58:61]
	v_mfma_f32_16x16x32_bf16 v[50:53], v[146:149], v[194:197], v[50:53]
	v_mfma_f32_16x16x32_bf16 v[42:45], v[162:165], v[194:197], v[42:45]
	v_mfma_f32_16x16x32_bf16 v[34:37], v[146:149], v[202:205], v[34:37]
	v_mfma_f32_16x16x32_bf16 v[26:29], v[162:165], v[202:205], v[26:29]
	v_mfma_f32_16x16x32_bf16 v[18:21], v[146:149], v[210:213], v[18:21]
	v_mfma_f32_16x16x32_bf16 v[10:13], v[162:165], v[210:213], v[10:13]
	v_mfma_f32_16x16x32_bf16 v[62:65], v[158:161], v[190:193], v[62:65]
	v_mfma_f32_16x16x32_bf16 v[58:61], v[166:169], v[190:193], v[58:61]
	v_mfma_f32_16x16x32_bf16 v[50:53], v[158:161], v[198:201], v[50:53]
	v_mfma_f32_16x16x32_bf16 v[42:45], v[166:169], v[198:201], v[42:45]
	v_mfma_f32_16x16x32_bf16 v[34:37], v[158:161], v[206:209], v[34:37]
	v_mfma_f32_16x16x32_bf16 v[26:29], v[166:169], v[206:209], v[26:29]
	v_mfma_f32_16x16x32_bf16 v[18:21], v[158:161], v[214:217], v[18:21]
	v_mfma_f32_16x16x32_bf16 v[10:13], v[166:169], v[214:217], v[10:13]
	s_setprio 0
	s_setprio 1
	v_mfma_f32_16x16x32_bf16 v[54:57], v[170:173], v[186:189], v[54:57]
	v_mfma_f32_16x16x32_bf16 v[46:49], v[178:181], v[186:189], v[46:49]
	v_mfma_f32_16x16x32_bf16 v[38:41], v[170:173], v[194:197], v[38:41]
	v_mfma_f32_16x16x32_bf16 v[30:33], v[178:181], v[194:197], v[30:33]
	v_mfma_f32_16x16x32_bf16 v[22:25], v[170:173], v[202:205], v[22:25]
	v_mfma_f32_16x16x32_bf16 v[14:17], v[178:181], v[202:205], v[14:17]
	v_mfma_f32_16x16x32_bf16 v[6:9], v[170:173], v[210:213], v[6:9]
	v_mfma_f32_16x16x32_bf16 v[2:5], v[178:181], v[210:213], v[2:5]
	v_mfma_f32_16x16x32_bf16 v[54:57], v[174:177], v[190:193], v[54:57]
	v_mfma_f32_16x16x32_bf16 v[46:49], v[182:185], v[190:193], v[46:49]
	v_mfma_f32_16x16x32_bf16 v[38:41], v[174:177], v[198:201], v[38:41]
	v_mfma_f32_16x16x32_bf16 v[30:33], v[182:185], v[198:201], v[30:33]
	v_mfma_f32_16x16x32_bf16 v[22:25], v[174:177], v[206:209], v[22:25]
	v_mfma_f32_16x16x32_bf16 v[14:17], v[182:185], v[206:209], v[14:17]
	v_mfma_f32_16x16x32_bf16 v[6:9], v[174:177], v[214:217], v[6:9]
	v_mfma_f32_16x16x32_bf16 v[2:5], v[182:185], v[214:217], v[2:5]
	s_setprio 0
	s_barrier
	s_add_i32 s59, s59, 2
	s_add_u32 s57, s57, 0x100
	s_addc_u32 s58, s58, 0
	s_cmpk_gt_u32 s59, 0x55
	s_mov_b64 s[20:21], s[22:23]
	s_cbranch_scc0 .LBB0_208
	s_branch .Lpeel_after_3
; #define PG8_STAGE(bufoff, gbase, voff) do { _Pragma("unroll") for (int _i = 0; _i < 2; ++_i) \
;         __builtin_amdgcn_global_load_lds((const unsigned*)((const char*)(gbase) + (voff)[_i]), (PG8_LAS unsigned*)(lds + (bufoff) + ldsw + _i * 8192), 16, 0, 0); } while (0)
; #define PG8_LDA(dst, b, h) do { _Pragma("unroll") for (int m = 0; m < 4; ++m) _Pragma("unroll") for (int k = 0; k < 2; ++k) dst[m][k] = *(const PG8_LAS bf16x8*)(lds + PG8_SA(b, h) + aoff + m * 2048 + k * 1024); } while (0)
; #define PG8_LDB(dst, b, h) do { _Pragma("unroll") for (int n = 0; n < 2; ++n) _Pragma("unroll") for (int k = 0; k < 2; ++k) dst[n][k] = *(const PG8_LAS bf16x8*)(lds + PG8_SB(b, h) + boff + n * 2048 + k * 1024); } while (0)
; #define PG8_MMA(ai, bj, At, Bt) do { __builtin_amdgcn_s_setprio(1); _Pragma("unroll") for (int m = 0; m < 4; ++m) _Pragma("unroll") for (int n = 0; n < 2; ++n) _Pragma("unroll") for (int k = 0; k < 2; ++k) \
;         acc[ai][bj][m][n] = __builtin_amdgcn_mfma_f32_16x16x32_bf16(Bt[n][k], At[m][k], acc[ai][bj][m][n], 0, 0, 0); __builtin_amdgcn_s_setprio(0); } while (0)
; #define PG8_WAIT_V(n) asm volatile("s_waitcnt vmcnt(" #n ")" ::: "memory")
; #define PG8_WAIT_L(n) asm volatile("s_waitcnt lgkmcnt(" #n ")" ::: "memory")
; #define PG8_BAR __builtin_amdgcn_s_barrier()
; #define PG8_SCHED __builtin_amdgcn_sched_barrier(0)
; template <class Epi, class Sched, bool ALIGN_EPI = false, bool SP2 = false>
; __device__ __forceinline__ void gemm_phase(PG8_LAS unsigned char* lds, const Gemm g, const Sched& S, const Epi& E) {
;     ...
;             PG8_LDB(B0, 0, 0); PG8_LDB(B1, 0, 1); PG8_SCHED; PG8_LDA(At, 0, 0); PG8_STAGE(PG8_SA(1, 1), a1 + hstep, voffA);
;             PG8_WAIT_V(8); PG8_WAIT_L(0); PG8_BAR; PG8_MMA(0, 0, At, B0); PG8_MMA(0, 1, At, B1); PG8_BAR; PG8_SCHED;
;             PG8_LDA(At, 0, 1); PG8_STAGE(PG8_SB(0, 0), b2, voffB); PG8_STAGE(PG8_SB(0, 1), b2 + hstep, voffB); PG8_STAGE(PG8_SA(0, 0), a2, voffA);
;             PG8_WAIT_V(8); PG8_WAIT_L(0); PG8_BAR; PG8_MMA(1, 0, At, B0); PG8_MMA(1, 1, At, B1); PG8_BAR; PG8_SCHED;
.Lpeel_3:
	ds_read_b128 v[146:149], v155
	ds_read_b128 v[158:161], v155 offset:1024
	ds_read_b128 v[162:165], v155 offset:2048
	ds_read_b128 v[166:169], v155 offset:3072
	ds_read_b128 v[170:173], v156
	ds_read_b128 v[174:177], v156 offset:1024
	ds_read_b128 v[178:181], v156 offset:2048
	ds_read_b128 v[182:185], v156 offset:3072
	s_add_u32 s22, s20, 0x100
	s_addc_u32 s23, s21, 0
	s_cmpk_eq_i32 s59, 0x54
	s_cselect_b32 s27, s3, s23
	s_cselect_b32 s26, s2, s22
	s_cselect_b32 s25, s19, s58
	s_cselect_b32 s24, s18, s57
	v_lshl_add_u64 v[150:151], s[20:21], 0, v[138:139]
	s_add_i32 m0, s28, 0xc000
	ds_read_b128 v[186:189], v157
	ds_read_b128 v[190:193], v157 offset:1024
	ds_read_b128 v[194:197], v157 offset:2048
	ds_read_b128 v[198:201], v157 offset:3072
	ds_read_b128 v[202:205], v157 offset:4096
	ds_read_b128 v[206:209], v157 offset:5120
	ds_read_b128 v[210:213], v157 offset:6144
	ds_read_b128 v[214:217], v157 offset:7168
	global_load_lds_dwordx4 v[150:151], off
	v_lshl_add_u64 v[150:151], s[20:21], 0, v[140:141]
	s_add_i32 m0, s28, 0xe000
	s_nop 0
	global_load_lds_dwordx4 v[150:151], off
	s_waitcnt vmcnt(56)
	s_waitcnt lgkmcnt(0)
	s_barrier
	s_setprio 1
	s_waitcnt lgkmcnt(0)
	v_mfma_f32_16x16x32_bf16 v[126:129], v[146:149], v[186:189], 0
	v_mfma_f32_16x16x32_bf16 v[122:125], v[162:165], v[186:189], 0
	v_mfma_f32_16x16x32_bf16 v[114:117], v[146:149], v[194:197], 0
	v_mfma_f32_16x16x32_bf16 v[106:109], v[162:165], v[194:197], 0
	v_mfma_f32_16x16x32_bf16 v[98:101], v[146:149], v[202:205], 0
	v_mfma_f32_16x16x32_bf16 v[90:93], v[162:165], v[202:205], 0
	v_mfma_f32_16x16x32_bf16 v[82:85], v[146:149], v[210:213], 0
	v_mfma_f32_16x16x32_bf16 v[74:77], v[162:165], v[210:213], 0
	v_mfma_f32_16x16x32_bf16 v[126:129], v[158:161], v[190:193], v[126:129]
	v_mfma_f32_16x16x32_bf16 v[122:125], v[166:169], v[190:193], v[122:125]
	v_mfma_f32_16x16x32_bf16 v[114:117], v[158:161], v[198:201], v[114:117]
	v_mfma_f32_16x16x32_bf16 v[106:109], v[166:169], v[198:201], v[106:109]
	v_mfma_f32_16x16x32_bf16 v[98:101], v[158:161], v[206:209], v[98:101]
	v_mfma_f32_16x16x32_bf16 v[90:93], v[166:169], v[206:209], v[90:93]
	v_mfma_f32_16x16x32_bf16 v[82:85], v[158:161], v[214:217], v[82:85]
	v_mfma_f32_16x16x32_bf16 v[74:77], v[166:169], v[214:217], v[74:77]
	s_setprio 0
	s_setprio 1
	v_mfma_f32_16x16x32_bf16 v[118:121], v[170:173], v[186:189], 0
	v_mfma_f32_16x16x32_bf16 v[110:113], v[178:181], v[186:189], 0
	v_mfma_f32_16x16x32_bf16 v[102:105], v[170:173], v[194:197], 0
	v_mfma_f32_16x16x32_bf16 v[94:97], v[178:181], v[194:197], 0
	v_mfma_f32_16x16x32_bf16 v[86:89], v[170:173], v[202:205], 0
	v_mfma_f32_16x16x32_bf16 v[78:81], v[178:181], v[202:205], 0
	v_mfma_f32_16x16x32_bf16 v[70:73], v[170:173], v[210:213], 0
	v_mfma_f32_16x16x32_bf16 v[66:69], v[178:181], v[210:213], 0
	v_mfma_f32_16x16x32_bf16 v[118:121], v[174:177], v[190:193], v[118:121]
	v_mfma_f32_16x16x32_bf16 v[110:113], v[182:185], v[190:193], v[110:113]
	v_mfma_f32_16x16x32_bf16 v[102:105], v[174:177], v[198:201], v[102:105]
	v_mfma_f32_16x16x32_bf16 v[94:97], v[182:185], v[198:201], v[94:97]
	v_mfma_f32_16x16x32_bf16 v[86:89], v[174:177], v[206:209], v[86:89]
	v_mfma_f32_16x16x32_bf16 v[78:81], v[182:185], v[206:209], v[78:81]
	v_mfma_f32_16x16x32_bf16 v[70:73], v[174:177], v[214:217], v[70:73]
	v_mfma_f32_16x16x32_bf16 v[66:69], v[182:185], v[214:217], v[66:69]
	s_setprio 0
	s_barrier
	s_add_i32 s20, s51, s13
	v_lshl_add_u64 v[150:151], s[24:25], 0, v[134:135]
	s_mov_b32 m0, s20
	ds_read_b128 v[186:189], v157 offset:16384
	ds_read_b128 v[190:193], v157 offset:17408
	ds_read_b128 v[194:197], v157 offset:18432
	ds_read_b128 v[198:201], v157 offset:19456
	ds_read_b128 v[202:205], v157 offset:20480
	ds_read_b128 v[206:209], v157 offset:21504
	ds_read_b128 v[210:213], v157 offset:22528
	ds_read_b128 v[214:217], v157 offset:23552
	global_load_lds_dwordx4 v[150:151], off
	s_add_i32 m0, s20, 0x2000
	s_add_u32 s20, s24, 0x160000
	v_lshl_add_u64 v[218:219], s[24:25], 0, v[130:131]
	s_addc_u32 s21, s25, 0
	s_add_i32 s60, s52, s13
	global_load_lds_dwordx4 v[218:219], off
	v_lshl_add_u64 v[220:221], s[20:21], 0, v[134:135]
	s_mov_b32 m0, s60
	v_lshl_add_u64 v[222:223], s[26:27], 0, v[132:133]
	global_load_lds_dwordx4 v[220:221], off
	v_lshl_add_u64 v[220:221], s[20:21], 0, v[130:131]
	s_add_i32 m0, s60, 0x2000
	s_nop 0
	global_load_lds_dwordx4 v[220:221], off
	v_lshl_add_u64 v[220:221], s[26:27], 0, v[136:137]
	s_mov_b32 m0, s28
	s_nop 0
	global_load_lds_dwordx4 v[220:221], off
	s_mov_b32 m0, s29
	s_nop 0
	global_load_lds_dwordx4 v[222:223], off
	s_waitcnt vmcnt(56)
	s_waitcnt lgkmcnt(0)
	s_barrier
; #define PG8_STAGE(bufoff, gbase, voff) do { _Pragma("unroll") for (int _i = 0; _i < 2; ++_i) \
;         __builtin_amdgcn_global_load_lds((const unsigned*)((const char*)(gbase) + (voff)[_i]), (PG8_LAS unsigned*)(lds + (bufoff) + ldsw + _i * 8192), 16, 0, 0); } while (0)
; #define PG8_LDA(dst, b, h) do { _Pragma("unroll") for (int m = 0; m < 4; ++m) _Pragma("unroll") for (int k = 0; k < 2; ++k) dst[m][k] = *(const PG8_LAS bf16x8*)(lds + PG8_SA(b, h) + aoff + m * 2048 + k * 1024); } while (0)
; #define PG8_LDB(dst, b, h) do { _Pragma("unroll") for (int n = 0; n < 2; ++n) _Pragma("unroll") for (int k = 0; k < 2; ++k) dst[n][k] = *(const PG8_LAS bf16x8*)(lds + PG8_SB(b, h) + boff + n * 2048 + k * 1024); } while (0)
; #define PG8_MMA(ai, bj, At, Bt) do { __builtin_amdgcn_s_setprio(1); _Pragma("unroll") for (int m = 0; m < 4; ++m) _Pragma("unroll") for (int n = 0; n < 2; ++n) _Pragma("unroll") for (int k = 0; k < 2; ++k) \
;         acc[ai][bj][m][n] = __builtin_amdgcn_mfma_f32_16x16x32_bf16(Bt[n][k], At[m][k], acc[ai][bj][m][n], 0, 0, 0); __builtin_amdgcn_s_setprio(0); } while (0)
; #define PG8_WAIT_V(n) asm volatile("s_waitcnt vmcnt(" #n ")" ::: "memory")
; #define PG8_WAIT_L(n) asm volatile("s_waitcnt lgkmcnt(" #n ")" ::: "memory")
; #define PG8_BAR __builtin_amdgcn_s_barrier()
; #define PG8_SCHED __builtin_amdgcn_sched_barrier(0)
; template <class Epi, class Sched, bool ALIGN_EPI = false, bool SP2 = false>
; __device__ __forceinline__ void gemm_phase(PG8_LAS unsigned char* lds, const Gemm g, const Sched& S, const Epi& E) {
;     ...
;             PG8_WAIT_V(8); PG8_WAIT_L(0); PG8_BAR; PG8_MMA(1, 0, At, B0); PG8_MMA(1, 1, At, B1); PG8_BAR; PG8_SCHED;
;             PG8_LDB(B0, 1, 0); PG8_LDB(B1, 1, 1); PG8_SCHED; PG8_LDA(At, 1, 0); PG8_STAGE(PG8_SA(0, 1), a2 + hstep, voffA);
;             PG8_WAIT_V(8); PG8_WAIT_L(0); PG8_BAR; PG8_MMA(0, 0, At, B0); PG8_MMA(0, 1, At, B1); PG8_BAR; PG8_SCHED;
;             PG8_LDA(At, 1, 1); PG8_STAGE(PG8_SB(1, 0), b3, voffB); PG8_STAGE(PG8_SB(1, 1), b3 + hstep, voffB); PG8_STAGE(PG8_SA(1, 0), a3, voffA);
	s_setprio 1
	s_waitcnt lgkmcnt(0)
	v_mfma_f32_16x16x32_bf16 v[62:65], v[146:149], v[186:189], 0
	v_mfma_f32_16x16x32_bf16 v[58:61], v[162:165], v[186:189], 0
	v_mfma_f32_16x16x32_bf16 v[50:53], v[146:149], v[194:197], 0
	v_mfma_f32_16x16x32_bf16 v[42:45], v[162:165], v[194:197], 0
	v_mfma_f32_16x16x32_bf16 v[34:37], v[146:149], v[202:205], 0
	v_mfma_f32_16x16x32_bf16 v[26:29], v[162:165], v[202:205], 0
	v_mfma_f32_16x16x32_bf16 v[18:21], v[146:149], v[210:213], 0
	v_mfma_f32_16x16x32_bf16 v[10:13], v[162:165], v[210:213], 0
	v_mfma_f32_16x16x32_bf16 v[62:65], v[158:161], v[190:193], v[62:65]
	v_mfma_f32_16x16x32_bf16 v[58:61], v[166:169], v[190:193], v[58:61]
	v_mfma_f32_16x16x32_bf16 v[50:53], v[158:161], v[198:201], v[50:53]
	v_mfma_f32_16x16x32_bf16 v[42:45], v[166:169], v[198:201], v[42:45]
	v_mfma_f32_16x16x32_bf16 v[34:37], v[158:161], v[206:209], v[34:37]
	v_mfma_f32_16x16x32_bf16 v[26:29], v[166:169], v[206:209], v[26:29]
	v_mfma_f32_16x16x32_bf16 v[18:21], v[158:161], v[214:217], v[18:21]
	v_mfma_f32_16x16x32_bf16 v[10:13], v[166:169], v[214:217], v[10:13]
	s_setprio 0
	s_setprio 1
	v_mfma_f32_16x16x32_bf16 v[54:57], v[170:173], v[186:189], 0
	v_mfma_f32_16x16x32_bf16 v[46:49], v[178:181], v[186:189], 0
	v_mfma_f32_16x16x32_bf16 v[38:41], v[170:173], v[194:197], 0
	v_mfma_f32_16x16x32_bf16 v[30:33], v[178:181], v[194:197], 0
	v_mfma_f32_16x16x32_bf16 v[22:25], v[170:173], v[202:205], 0
	v_mfma_f32_16x16x32_bf16 v[14:17], v[178:181], v[202:205], 0
	v_mfma_f32_16x16x32_bf16 v[6:9], v[170:173], v[210:213], 0
	v_mfma_f32_16x16x32_bf16 v[2:5], v[178:181], v[210:213], 0
	v_mfma_f32_16x16x32_bf16 v[54:57], v[174:177], v[190:193], v[54:57]
	v_mfma_f32_16x16x32_bf16 v[46:49], v[182:185], v[190:193], v[46:49]
	v_mfma_f32_16x16x32_bf16 v[38:41], v[174:177], v[198:201], v[38:41]
	v_mfma_f32_16x16x32_bf16 v[30:33], v[182:185], v[198:201], v[30:33]
	v_mfma_f32_16x16x32_bf16 v[22:25], v[174:177], v[206:209], v[22:25]
	v_mfma_f32_16x16x32_bf16 v[14:17], v[182:185], v[206:209], v[14:17]
	v_mfma_f32_16x16x32_bf16 v[6:9], v[174:177], v[214:217], v[6:9]
	v_mfma_f32_16x16x32_bf16 v[2:5], v[182:185], v[214:217], v[2:5]
	s_setprio 0
	s_barrier
	s_add_i32 s60, 0, 0x18000
	s_add_i32 s61, 0, 0x1c000
	v_add_u32_e32 v166, s60, v153
	v_add_u32_e32 v182, s61, v153
	ds_read_b128 v[146:149], v166
	ds_read_b128 v[158:161], v166 offset:1024
	ds_read_b128 v[162:165], v166 offset:2048
	ds_read_b128 v[166:169], v166 offset:3072
	ds_read_b128 v[170:173], v182
	ds_read_b128 v[174:177], v182 offset:1024
	ds_read_b128 v[178:181], v182 offset:2048
	ds_read_b128 v[182:185], v182 offset:3072
	s_add_u32 s20, s26, 0x160000
	s_addc_u32 s21, s27, 0
	s_mov_b32 m0, s33
	v_lshl_add_u64 v[224:225], s[20:21], 0, v[136:137]
	ds_read_b128 v[186:189], v157 offset:32768
	ds_read_b128 v[190:193], v157 offset:33792
	ds_read_b128 v[194:197], v157 offset:34816
	ds_read_b128 v[198:201], v157 offset:35840
	ds_read_b128 v[202:205], v157 offset:36864
	ds_read_b128 v[206:209], v157 offset:37888
	ds_read_b128 v[210:213], v157 offset:38912
	ds_read_b128 v[214:217], v157 offset:39936
	global_load_lds_dwordx4 v[224:225], off
	v_lshl_add_u64 v[224:225], s[20:21], 0, v[132:133]
	s_mov_b32 m0, s34
	s_nop 0
	global_load_lds_dwordx4 v[224:225], off
	s_waitcnt vmcnt(8)
	s_waitcnt lgkmcnt(0)
	s_barrier
	s_setprio 1
	s_waitcnt lgkmcnt(0)
	v_mfma_f32_16x16x32_bf16 v[126:129], v[146:149], v[186:189], v[126:129]
	v_mfma_f32_16x16x32_bf16 v[122:125], v[162:165], v[186:189], v[122:125]
	v_mfma_f32_16x16x32_bf16 v[114:117], v[146:149], v[194:197], v[114:117]
	v_mfma_f32_16x16x32_bf16 v[106:109], v[162:165], v[194:197], v[106:109]
	v_mfma_f32_16x16x32_bf16 v[98:101], v[146:149], v[202:205], v[98:101]
	v_mfma_f32_16x16x32_bf16 v[90:93], v[162:165], v[202:205], v[90:93]
	v_mfma_f32_16x16x32_bf16 v[82:85], v[146:149], v[210:213], v[82:85]
	v_mfma_f32_16x16x32_bf16 v[74:77], v[162:165], v[210:213], v[74:77]
	v_mfma_f32_16x16x32_bf16 v[126:129], v[158:161], v[190:193], v[126:129]
	v_mfma_f32_16x16x32_bf16 v[122:125], v[166:169], v[190:193], v[122:125]
	v_mfma_f32_16x16x32_bf16 v[114:117], v[158:161], v[198:201], v[114:117]
	v_mfma_f32_16x16x32_bf16 v[106:109], v[166:169], v[198:201], v[106:109]
	v_mfma_f32_16x16x32_bf16 v[98:101], v[158:161], v[206:209], v[98:101]
	v_mfma_f32_16x16x32_bf16 v[90:93], v[166:169], v[206:209], v[90:93]
	v_mfma_f32_16x16x32_bf16 v[82:85], v[158:161], v[214:217], v[82:85]
	v_mfma_f32_16x16x32_bf16 v[74:77], v[166:169], v[214:217], v[74:77]
	s_setprio 0
	s_setprio 1
	v_mfma_f32_16x16x32_bf16 v[118:121], v[170:173], v[186:189], v[118:121]
	v_mfma_f32_16x16x32_bf16 v[110:113], v[178:181], v[186:189], v[110:113]
	v_mfma_f32_16x16x32_bf16 v[102:105], v[170:173], v[194:197], v[102:105]
	v_mfma_f32_16x16x32_bf16 v[94:97], v[178:181], v[194:197], v[94:97]
	v_mfma_f32_16x16x32_bf16 v[86:89], v[170:173], v[202:205], v[86:89]
	v_mfma_f32_16x16x32_bf16 v[78:81], v[178:181], v[202:205], v[78:81]
	v_mfma_f32_16x16x32_bf16 v[70:73], v[170:173], v[210:213], v[70:73]
	v_mfma_f32_16x16x32_bf16 v[66:69], v[178:181], v[210:213], v[66:69]
	v_mfma_f32_16x16x32_bf16 v[118:121], v[174:177], v[190:193], v[118:121]
	v_mfma_f32_16x16x32_bf16 v[110:113], v[182:185], v[190:193], v[110:113]
	v_mfma_f32_16x16x32_bf16 v[102:105], v[174:177], v[198:201], v[102:105]
	v_mfma_f32_16x16x32_bf16 v[94:97], v[182:185], v[198:201], v[94:97]
	v_mfma_f32_16x16x32_bf16 v[86:89], v[174:177], v[206:209], v[86:89]
	v_mfma_f32_16x16x32_bf16 v[78:81], v[182:185], v[206:209], v[78:81]
	v_mfma_f32_16x16x32_bf16 v[70:73], v[174:177], v[214:217], v[70:73]
	v_mfma_f32_16x16x32_bf16 v[66:69], v[182:185], v[214:217], v[66:69]
	s_setprio 0
	s_barrier
; #define PG8_STAGE(bufoff, gbase, voff) do { _Pragma("unroll") for (int _i = 0; _i < 2; ++_i) \
;         __builtin_amdgcn_global_load_lds((const unsigned*)((const char*)(gbase) + (voff)[_i]), (PG8_LAS unsigned*)(lds + (bufoff) + ldsw + _i * 8192), 16, 0, 0); } while (0)
; #define PG8_LDA(dst, b, h) do { _Pragma("unroll") for (int m = 0; m < 4; ++m) _Pragma("unroll") for (int k = 0; k < 2; ++k) dst[m][k] = *(const PG8_LAS bf16x8*)(lds + PG8_SA(b, h) + aoff + m * 2048 + k * 1024); } while (0)
; #define PG8_MMA(ai, bj, At, Bt) do { __builtin_amdgcn_s_setprio(1); _Pragma("unroll") for (int m = 0; m < 4; ++m) _Pragma("unroll") for (int n = 0; n < 2; ++n) _Pragma("unroll") for (int k = 0; k < 2; ++k) \
;         acc[ai][bj][m][n] = __builtin_amdgcn_mfma_f32_16x16x32_bf16(Bt[n][k], At[m][k], acc[ai][bj][m][n], 0, 0, 0); __builtin_amdgcn_s_setprio(0); } while (0)
; #define PG8_WAIT_V(n) asm volatile("s_waitcnt vmcnt(" #n ")" ::: "memory")
; #define PG8_WAIT_L(n) asm volatile("s_waitcnt lgkmcnt(" #n ")" ::: "memory")
; #define PG8_BAR __builtin_amdgcn_s_barrier()
; #define PG8_SCHED __builtin_amdgcn_sched_barrier(0)
; template <class Epi, class Sched, bool ALIGN_EPI = false, bool SP2 = false>
; __device__ __forceinline__ void gemm_phase(PG8_LAS unsigned char* lds, const Gemm g, const Sched& S, const Epi& E) {
;     ...
;             PG8_LDA(At, 1, 1); PG8_STAGE(PG8_SB(1, 0), b3, voffB); PG8_STAGE(PG8_SB(1, 1), b3 + hstep, voffB); PG8_STAGE(PG8_SA(1, 0), a3, voffA);
;             PG8_WAIT_V(8); PG8_WAIT_L(0); PG8_BAR; PG8_MMA(1, 0, At, B0); PG8_MMA(1, 1, At, B1); PG8_BAR; PG8_SCHED;
	s_add_i32 s20, s60, s13
	v_lshl_add_u64 v[150:151], v[150:151], 0, s[10:11]
	s_mov_b32 m0, s20
	ds_read_b128 v[186:189], v157 offset:49152
	ds_read_b128 v[190:193], v157 offset:50176
	ds_read_b128 v[194:197], v157 offset:51200
	ds_read_b128 v[198:201], v157 offset:52224
	ds_read_b128 v[202:205], v157 offset:53248
	ds_read_b128 v[206:209], v157 offset:54272
	ds_read_b128 v[210:213], v157 offset:55296
	ds_read_b128 v[214:217], v157 offset:56320
	global_load_lds_dwordx4 v[150:151], off
	s_add_i32 m0, s20, 0x2000
	s_add_u32 s20, s24, 0x160080
	v_lshl_add_u64 v[150:151], v[218:219], 0, s[10:11]
	s_addc_u32 s21, s25, 0
	s_add_i32 s24, s61, s13
	global_load_lds_dwordx4 v[150:151], off
	v_lshl_add_u64 v[150:151], s[20:21], 0, v[134:135]
	s_mov_b32 m0, s24
	s_nop 0
	global_load_lds_dwordx4 v[150:151], off
	v_lshl_add_u64 v[150:151], s[20:21], 0, v[130:131]
	s_add_i32 m0, s24, 0x2000
	s_nop 0
	global_load_lds_dwordx4 v[150:151], off
	v_lshl_add_u64 v[150:151], v[220:221], 0, s[10:11]
	s_mov_b32 m0, s41
	s_nop 0
	global_load_lds_dwordx4 v[150:151], off
	v_lshl_add_u64 v[150:151], v[222:223], 0, s[10:11]
	s_mov_b32 m0, s50
	s_nop 0
	global_load_lds_dwordx4 v[150:151], off
	s_waitcnt vmcnt(8)
	s_waitcnt lgkmcnt(0)
	s_barrier
	s_setprio 1
	s_waitcnt lgkmcnt(0)
	v_mfma_f32_16x16x32_bf16 v[62:65], v[146:149], v[186:189], v[62:65]
	v_mfma_f32_16x16x32_bf16 v[58:61], v[162:165], v[186:189], v[58:61]
	v_mfma_f32_16x16x32_bf16 v[50:53], v[146:149], v[194:197], v[50:53]
	v_mfma_f32_16x16x32_bf16 v[42:45], v[162:165], v[194:197], v[42:45]
	v_mfma_f32_16x16x32_bf16 v[34:37], v[146:149], v[202:205], v[34:37]
	v_mfma_f32_16x16x32_bf16 v[26:29], v[162:165], v[202:205], v[26:29]
	v_mfma_f32_16x16x32_bf16 v[18:21], v[146:149], v[210:213], v[18:21]
	v_mfma_f32_16x16x32_bf16 v[10:13], v[162:165], v[210:213], v[10:13]
	v_mfma_f32_16x16x32_bf16 v[62:65], v[158:161], v[190:193], v[62:65]
	v_mfma_f32_16x16x32_bf16 v[58:61], v[166:169], v[190:193], v[58:61]
	v_mfma_f32_16x16x32_bf16 v[50:53], v[158:161], v[198:201], v[50:53]
	v_mfma_f32_16x16x32_bf16 v[42:45], v[166:169], v[198:201], v[42:45]
	v_mfma_f32_16x16x32_bf16 v[34:37], v[158:161], v[206:209], v[34:37]
	v_mfma_f32_16x16x32_bf16 v[26:29], v[166:169], v[206:209], v[26:29]
	v_mfma_f32_16x16x32_bf16 v[18:21], v[158:161], v[214:217], v[18:21]
	v_mfma_f32_16x16x32_bf16 v[10:13], v[166:169], v[214:217], v[10:13]
	s_setprio 0
	s_setprio 1
	v_mfma_f32_16x16x32_bf16 v[54:57], v[170:173], v[186:189], v[54:57]
	v_mfma_f32_16x16x32_bf16 v[46:49], v[178:181], v[186:189], v[46:49]
	v_mfma_f32_16x16x32_bf16 v[38:41], v[170:173], v[194:197], v[38:41]
	v_mfma_f32_16x16x32_bf16 v[30:33], v[178:181], v[194:197], v[30:33]
	v_mfma_f32_16x16x32_bf16 v[22:25], v[170:173], v[202:205], v[22:25]
	v_mfma_f32_16x16x32_bf16 v[14:17], v[178:181], v[202:205], v[14:17]
	v_mfma_f32_16x16x32_bf16 v[6:9], v[170:173], v[210:213], v[6:9]
	v_mfma_f32_16x16x32_bf16 v[2:5], v[178:181], v[210:213], v[2:5]
	v_mfma_f32_16x16x32_bf16 v[54:57], v[174:177], v[190:193], v[54:57]
	v_mfma_f32_16x16x32_bf16 v[46:49], v[182:185], v[190:193], v[46:49]
	v_mfma_f32_16x16x32_bf16 v[38:41], v[174:177], v[198:201], v[38:41]
	v_mfma_f32_16x16x32_bf16 v[30:33], v[182:185], v[198:201], v[30:33]
	v_mfma_f32_16x16x32_bf16 v[22:25], v[174:177], v[206:209], v[22:25]
	v_mfma_f32_16x16x32_bf16 v[14:17], v[182:185], v[206:209], v[14:17]
	v_mfma_f32_16x16x32_bf16 v[6:9], v[174:177], v[214:217], v[6:9]
	v_mfma_f32_16x16x32_bf16 v[2:5], v[182:185], v[214:217], v[2:5]
	s_setprio 0
	s_barrier
	s_add_i32 s59, s59, 2
	s_add_u32 s57, s57, 0x100
	s_addc_u32 s58, s58, 0
	s_cmpk_gt_u32 s59, 0x55
	s_mov_b64 s[20:21], s[22:23]
	s_branch .LBB0_208

; DI unsigned pk2(float lo, float hi) { f32x2 v = {lo, hi}; bf16x2_t b = __builtin_convertvector(v, bf16x2_t); return __builtin_bit_cast(unsigned, b); }
;     DI void operator()(const f32x4 (&acc)[2][2][4][2], const pg8::Unit& u, int wr, int wc, int fr, int fq) const {
;         const int row0 = u.pm * 256 + wr * 64 + fr, col0 = u.pn * 256 + wc * 32 + 8 * fq;
; #pragma unroll
;         for (int ai = 0; ai < 2; ++ai) {
;             f32x4 r[4][2][2];
; #pragma unroll
;             for (int m = 0; m < 4; ++m)
; #pragma unroll
;                 for (int bj = 0; bj < 2; ++bj)
; #pragma unroll
;                     for (int n = 0; n < 2; ++n) r[m][bj][n] = __builtin_nontemporal_load((const f32x4*)(res + (size_t)(row0 + ai * 128 + m * 16) * DM + col0 + bj * 128 + n * 4));
;             asm volatile("" ::: "memory");
; #pragma unroll
;             for (int m = 0; m < 4; ++m)
; #pragma unroll
;                 for (int bj = 0; bj < 2; ++bj) { const f32x4 a = r[m][bj][0] * ALPHA + acc[ai][bj][m][0] * sc, b = r[m][bj][1] * ALPHA + acc[ai][bj][m][1] * sc;
;                     *(u32x4*)(out + (size_t)(row0 + ai * 128 + m * 16) * DM + col0 + bj * 128) = (u32x4){pk2(a[0], a[1]), pk2(a[2], a[3]), pk2(b[0], b[1]), pk2(b[2], b[3])}; }
;         }
;     }
.LBB0_211:
	v_lshl_add_u32 v150, s55, 8, v152
	v_lshl_or_b32 v146, s56, 8, v154
	v_ashrrev_i32_e32 v147, 31, v146
	v_ashrrev_i32_e32 v151, 31, v150
	v_or_b32_e32 v206, 16, v150
	v_lshl_add_u64 v[148:149], v[146:147], 2, s[36:37]
	v_lshlrev_b64 v[158:159], 13, v[150:151]
	v_ashrrev_i32_e32 v207, 31, v206
	v_lshl_add_u64 v[170:171], v[148:149], 0, v[158:159]
	v_lshlrev_b64 v[174:175], 13, v[206:207]
	global_load_dwordx4 v[158:161], v[170:171], off nt
	global_load_dwordx4 v[162:165], v[170:171], off offset:16 nt
	global_load_dwordx4 v[166:169], v[170:171], off offset:512 nt
	s_nop 0
	global_load_dwordx4 v[170:173], v[170:171], off offset:528 nt
	v_lshl_add_u64 v[186:187], v[148:149], 0, v[174:175]
	global_load_dwordx4 v[174:177], v[186:187], off nt
	global_load_dwordx4 v[178:181], v[186:187], off offset:16 nt
	global_load_dwordx4 v[182:185], v[186:187], off offset:512 nt
	s_nop 0
	global_load_dwordx4 v[186:189], v[186:187], off offset:528 nt
	v_or_b32_e32 v222, 32, v150
	v_ashrrev_i32_e32 v223, 31, v222
	v_lshlrev_b64 v[190:191], 13, v[222:223]
	v_lshl_add_u64 v[202:203], v[148:149], 0, v[190:191]
	global_load_dwordx4 v[190:193], v[202:203], off nt
	global_load_dwordx4 v[194:197], v[202:203], off offset:16 nt
	global_load_dwordx4 v[198:201], v[202:203], off offset:528 nt
	s_nop 0
	global_load_dwordx4 v[202:205], v[202:203], off offset:512 nt
	v_or_b32_e32 v224, 48, v150
	v_ashrrev_i32_e32 v225, 31, v224
	v_readlane_b32 s20, v253, 55
	v_lshlrev_b64 v[208:209], 12, v[150:151]
	v_lshlrev_b64 v[210:211], 13, v[224:225]
	v_readlane_b32 s21, v253, 56
	v_lshlrev_b64 v[146:147], 1, v[146:147]
	v_lshlrev_b64 v[206:207], 12, v[206:207]
	v_lshl_add_u64 v[208:209], s[20:21], 0, v[208:209]
	v_lshl_add_u64 v[218:219], v[148:149], 0, v[210:211]
	v_lshl_add_u64 v[226:227], v[208:209], 0, v[146:147]
	v_lshl_add_u64 v[228:229], s[20:21], 0, v[206:207]
	global_load_dwordx4 v[206:209], v[218:219], off offset:16 nt
	global_load_dwordx4 v[210:213], v[218:219], off nt
	global_load_dwordx4 v[214:217], v[218:219], off offset:528 nt
	s_nop 0
	global_load_dwordx4 v[218:221], v[218:219], off offset:512 nt
	v_lshl_add_u64 v[228:229], v[228:229], 0, v[146:147]
	s_and_b64 vcc, exec, s[0:1]
	s_mov_b64 s[0:1], -1
	s_waitcnt vmcnt(0)
	v_pk_mul_f32 v[160:161], v[160:161], s[16:17] op_sel_hi:[1,0]
	v_pk_mul_f32 v[158:159], v[158:159], s[16:17] op_sel_hi:[1,0]
	v_pk_mul_f32 v[164:165], v[164:165], s[16:17] op_sel_hi:[1,0]
	v_pk_mul_f32 v[162:163], v[162:163], s[16:17] op_sel_hi:[1,0]
	v_pk_mul_f32 v[168:169], v[168:169], s[16:17] op_sel_hi:[1,0]
	v_pk_mul_f32 v[166:167], v[166:167], s[16:17] op_sel_hi:[1,0]
	v_pk_mul_f32 v[172:173], v[172:173], s[16:17] op_sel_hi:[1,0]
	v_pk_mul_f32 v[170:171], v[170:171], s[16:17] op_sel_hi:[1,0]
	v_pk_fma_f32 v[128:129], v[128:129], 0.5, v[160:161] op_sel_hi:[1,0,1]
	v_pk_fma_f32 v[126:127], v[126:127], 0.5, v[158:159] op_sel_hi:[1,0,1]
	v_pk_fma_f32 v[124:125], v[124:125], 0.5, v[164:165] op_sel_hi:[1,0,1]
	v_pk_fma_f32 v[122:123], v[122:123], 0.5, v[162:163] op_sel_hi:[1,0,1]
	v_pk_fma_f32 v[120:121], v[120:121], 0.5, v[168:169] op_sel_hi:[1,0,1]
	v_pk_fma_f32 v[118:119], v[118:119], 0.5, v[166:167] op_sel_hi:[1,0,1]
	v_pk_fma_f32 v[158:159], v[112:113], 0.5, v[172:173] op_sel_hi:[1,0,1]
	v_pk_fma_f32 v[160:161], v[110:111], 0.5, v[170:171] op_sel_hi:[1,0,1]
	v_pk_mul_f32 v[162:163], v[176:177], s[16:17] op_sel_hi:[1,0]
	v_pk_mul_f32 v[164:165], v[174:175], s[16:17] op_sel_hi:[1,0]
	v_pk_mul_f32 v[166:167], v[180:181], s[16:17] op_sel_hi:[1,0]
	v_pk_mul_f32 v[168:169], v[178:179], s[16:17] op_sel_hi:[1,0]
	v_pk_mul_f32 v[170:171], v[184:185], s[16:17] op_sel_hi:[1,0]
	v_pk_mul_f32 v[172:173], v[182:183], s[16:17] op_sel_hi:[1,0]
	v_pk_mul_f32 v[174:175], v[188:189], s[16:17] op_sel_hi:[1,0]
	v_pk_mul_f32 v[176:177], v[186:187], s[16:17] op_sel_hi:[1,0]
	v_cvt_pk_bf16_f32 v110, v126, v127
	v_cvt_pk_bf16_f32 v112, v122, v123
	v_cvt_pk_bf16_f32 v113, v124, v125
	v_pk_fma_f32 v[116:117], v[116:117], 0.5, v[162:163] op_sel_hi:[1,0,1]
	v_pk_fma_f32 v[114:115], v[114:115], 0.5, v[164:165] op_sel_hi:[1,0,1]
	v_pk_fma_f32 v[108:109], v[108:109], 0.5, v[166:167] op_sel_hi:[1,0,1]
	v_pk_fma_f32 v[106:107], v[106:107], 0.5, v[168:169] op_sel_hi:[1,0,1]
	v_pk_fma_f32 v[122:123], v[104:105], 0.5, v[170:171] op_sel_hi:[1,0,1]
	v_pk_fma_f32 v[124:125], v[102:103], 0.5, v[172:173] op_sel_hi:[1,0,1]
	v_pk_fma_f32 v[126:127], v[96:97], 0.5, v[174:175] op_sel_hi:[1,0,1]
	v_pk_fma_f32 v[96:97], v[94:95], 0.5, v[176:177] op_sel_hi:[1,0,1]
	v_cvt_pk_bf16_f32 v111, v128, v129
	v_cvt_pk_bf16_f32 v102, v114, v115
	v_cvt_pk_bf16_f32 v103, v116, v117
	v_cvt_pk_bf16_f32 v104, v106, v107
	v_cvt_pk_bf16_f32 v105, v108, v109
	v_cvt_pk_bf16_f32 v94, v124, v125
	v_cvt_pk_bf16_f32 v95, v122, v123
	v_cvt_pk_bf16_f32 v96, v96, v97
	v_cvt_pk_bf16_f32 v97, v126, v127
	v_cvt_pk_bf16_f32 v118, v118, v119
	v_cvt_pk_bf16_f32 v119, v120, v121
	v_cvt_pk_bf16_f32 v120, v160, v161
	v_cvt_pk_bf16_f32 v121, v158, v159
	global_store_dwordx4 v[226:227], v[110:113], off
	global_store_dwordx4 v[226:227], v[118:121], off offset:256
	global_store_dwordx4 v[228:229], v[102:105], off
	global_store_dwordx4 v[228:229], v[94:97], off offset:256
	v_add_u32_e32 v158, 0x80, v150
	v_pk_mul_f32 v[102:103], v[190:191], s[16:17] op_sel_hi:[1,0]
	v_pk_mul_f32 v[96:97], v[192:193], s[16:17] op_sel_hi:[1,0]
	v_lshlrev_b64 v[94:95], 12, v[222:223]
	v_pk_fma_f32 v[96:97], v[100:101], 0.5, v[96:97] op_sel_hi:[1,0,1]
	v_pk_fma_f32 v[98:99], v[98:99], 0.5, v[102:103] op_sel_hi:[1,0,1]
	v_pk_mul_f32 v[100:101], v[196:197], s[16:17] op_sel_hi:[1,0]
	v_pk_mul_f32 v[102:103], v[194:195], s[16:17] op_sel_hi:[1,0]
; DI unsigned pk2(float lo, float hi) { f32x2 v = {lo, hi}; bf16x2_t b = __builtin_convertvector(v, bf16x2_t); return __builtin_bit_cast(unsigned, b); }
;     DI void operator()(const f32x4 (&acc)[2][2][4][2], const pg8::Unit& u, int wr, int wc, int fr, int fq) const {
;         const int row0 = u.pm * 256 + wr * 64 + fr, col0 = u.pn * 256 + wc * 32 + 8 * fq;
; #pragma unroll
;         for (int ai = 0; ai < 2; ++ai) {
;             f32x4 r[4][2][2];
; #pragma unroll
;             for (int m = 0; m < 4; ++m)
; #pragma unroll
;                 for (int bj = 0; bj < 2; ++bj)
; #pragma unroll
;                     for (int n = 0; n < 2; ++n) r[m][bj][n] = __builtin_nontemporal_load((const f32x4*)(res + (size_t)(row0 + ai * 128 + m * 16) * DM + col0 + bj * 128 + n * 4));
;             asm volatile("" ::: "memory");
; #pragma unroll
;             for (int m = 0; m < 4; ++m)
; #pragma unroll
;                 for (int bj = 0; bj < 2; ++bj) { const f32x4 a = r[m][bj][0] * ALPHA + acc[ai][bj][m][0] * sc, b = r[m][bj][1] * ALPHA + acc[ai][bj][m][1] * sc;
;                     *(u32x4*)(out + (size_t)(row0 + ai * 128 + m * 16) * DM + col0 + bj * 128) = (u32x4){pk2(a[0], a[1]), pk2(a[2], a[3]), pk2(b[0], b[1]), pk2(b[2], b[3])}; }
;         }
;     }
	v_pk_fma_f32 v[100:101], v[92:93], 0.5, v[100:101] op_sel_hi:[1,0,1]
	v_pk_fma_f32 v[92:93], v[90:91], 0.5, v[102:103] op_sel_hi:[1,0,1]
	v_lshl_add_u64 v[94:95], s[20:21], 0, v[94:95]
	v_cvt_pk_bf16_f32 v90, v98, v99
	v_cvt_pk_bf16_f32 v91, v96, v97
	v_cvt_pk_bf16_f32 v92, v92, v93
	v_cvt_pk_bf16_f32 v93, v100, v101
	v_lshl_add_u64 v[94:95], v[94:95], 0, v[146:147]
	global_store_dwordx4 v[94:95], v[90:93], off
	v_ashrrev_i32_e32 v159, 31, v158
	v_add_u32_e32 v160, 0x90, v150
	v_pk_mul_f32 v[90:91], v[204:205], s[16:17] op_sel_hi:[1,0]
	v_pk_mul_f32 v[92:93], v[202:203], s[16:17] op_sel_hi:[1,0]
	v_pk_fma_f32 v[88:89], v[88:89], 0.5, v[90:91] op_sel_hi:[1,0,1]
	v_pk_fma_f32 v[86:87], v[86:87], 0.5, v[92:93] op_sel_hi:[1,0,1]
	v_pk_mul_f32 v[90:91], v[200:201], s[16:17] op_sel_hi:[1,0]
	v_pk_mul_f32 v[92:93], v[198:199], s[16:17] op_sel_hi:[1,0]
	v_pk_fma_f32 v[90:91], v[80:81], 0.5, v[90:91] op_sel_hi:[1,0,1]
	v_pk_fma_f32 v[80:81], v[78:79], 0.5, v[92:93] op_sel_hi:[1,0,1]
	v_cvt_pk_bf16_f32 v78, v86, v87
	v_cvt_pk_bf16_f32 v79, v88, v89
	v_cvt_pk_bf16_f32 v80, v80, v81
	v_cvt_pk_bf16_f32 v81, v90, v91
	global_store_dwordx4 v[94:95], v[78:81], off offset:256
	v_pk_mul_f32 v[86:87], v[210:211], s[16:17] op_sel_hi:[1,0]
	v_ashrrev_i32_e32 v161, 31, v160
	v_pk_mul_f32 v[80:81], v[212:213], s[16:17] op_sel_hi:[1,0]
	v_lshlrev_b64 v[78:79], 12, v[224:225]
	v_pk_fma_f32 v[80:81], v[84:85], 0.5, v[80:81] op_sel_hi:[1,0,1]
	v_pk_fma_f32 v[82:83], v[82:83], 0.5, v[86:87] op_sel_hi:[1,0,1]
	v_pk_mul_f32 v[84:85], v[208:209], s[16:17] op_sel_hi:[1,0]
	v_pk_mul_f32 v[86:87], v[206:207], s[16:17] op_sel_hi:[1,0]
	v_pk_fma_f32 v[84:85], v[76:77], 0.5, v[84:85] op_sel_hi:[1,0,1]
	v_pk_fma_f32 v[76:77], v[74:75], 0.5, v[86:87] op_sel_hi:[1,0,1]
	v_lshl_add_u64 v[78:79], s[20:21], 0, v[78:79]
	v_cvt_pk_bf16_f32 v74, v82, v83
	v_cvt_pk_bf16_f32 v75, v80, v81
	v_cvt_pk_bf16_f32 v76, v76, v77
	v_cvt_pk_bf16_f32 v77, v84, v85
	v_lshl_add_u64 v[78:79], v[78:79], 0, v[146:147]
	global_store_dwordx4 v[78:79], v[74:77], off
	v_lshlrev_b64 v[82:83], 13, v[160:161]
	v_lshl_add_u64 v[94:95], v[148:149], 0, v[82:83]
	v_pk_mul_f32 v[74:75], v[220:221], s[16:17] op_sel_hi:[1,0]
	v_pk_mul_f32 v[76:77], v[218:219], s[16:17] op_sel_hi:[1,0]
	v_pk_fma_f32 v[72:73], v[72:73], 0.5, v[74:75] op_sel_hi:[1,0,1]
	v_pk_fma_f32 v[70:71], v[70:71], 0.5, v[76:77] op_sel_hi:[1,0,1]
	v_pk_mul_f32 v[74:75], v[216:217], s[16:17] op_sel_hi:[1,0]
	v_pk_mul_f32 v[76:77], v[214:215], s[16:17] op_sel_hi:[1,0]
	v_pk_fma_f32 v[74:75], v[68:69], 0.5, v[74:75] op_sel_hi:[1,0,1]
	v_pk_fma_f32 v[68:69], v[66:67], 0.5, v[76:77] op_sel_hi:[1,0,1]
	v_cvt_pk_bf16_f32 v66, v70, v71
	v_cvt_pk_bf16_f32 v67, v72, v73
	v_cvt_pk_bf16_f32 v68, v68, v69
	v_cvt_pk_bf16_f32 v69, v74, v75
	global_store_dwordx4 v[78:79], v[66:69], off offset:256
	v_add_u32_e32 v162, 0xa0, v150
	v_ashrrev_i32_e32 v163, 31, v162
	v_lshlrev_b64 v[66:67], 13, v[158:159]
	v_lshl_add_u64 v[78:79], v[148:149], 0, v[66:67]
	global_load_dwordx4 v[66:69], v[78:79], off nt
	global_load_dwordx4 v[70:73], v[78:79], off offset:16 nt
	global_load_dwordx4 v[74:77], v[78:79], off offset:512 nt
	s_nop 0
	global_load_dwordx4 v[78:81], v[78:79], off offset:528 nt
	s_nop 0
	global_load_dwordx4 v[82:85], v[94:95], off nt
	global_load_dwordx4 v[86:89], v[94:95], off offset:16 nt
	global_load_dwordx4 v[90:93], v[94:95], off offset:512 nt
	s_nop 0
	global_load_dwordx4 v[94:97], v[94:95], off offset:528 nt
	v_lshlrev_b64 v[98:99], 13, v[162:163]
	v_lshl_add_u64 v[110:111], v[148:149], 0, v[98:99]
	global_load_dwordx4 v[98:101], v[110:111], off nt
	global_load_dwordx4 v[102:105], v[110:111], off offset:16 nt
	global_load_dwordx4 v[106:109], v[110:111], off offset:528 nt
	s_nop 0
	global_load_dwordx4 v[110:113], v[110:111], off offset:512 nt
	v_add_u32_e32 v150, 0xb0, v150
	v_ashrrev_i32_e32 v151, 31, v150
	v_lshlrev_b64 v[114:115], 13, v[150:151]
	v_lshl_add_u64 v[126:127], v[148:149], 0, v[114:115]
	global_load_dwordx4 v[114:117], v[126:127], off offset:16 nt
	global_load_dwordx4 v[118:121], v[126:127], off nt
	global_load_dwordx4 v[122:125], v[126:127], off offset:528 nt
	s_nop 0
	global_load_dwordx4 v[126:129], v[126:127], off offset:512 nt
	v_lshlrev_b64 v[148:149], 12, v[158:159]
	s_waitcnt vmcnt(15)
	v_pk_mul_f32 v[68:69], v[68:69], s[16:17] op_sel_hi:[1,0]
	v_pk_mul_f32 v[66:67], v[66:67], s[16:17] op_sel_hi:[1,0]
	v_pk_fma_f32 v[64:65], v[64:65], 0.5, v[68:69] op_sel_hi:[1,0,1]
	v_pk_fma_f32 v[62:63], v[62:63], 0.5, v[66:67] op_sel_hi:[1,0,1]
	s_waitcnt vmcnt(14)
	v_pk_mul_f32 v[66:67], v[72:73], s[16:17] op_sel_hi:[1,0]
	v_pk_mul_f32 v[68:69], v[70:71], s[16:17] op_sel_hi:[1,0]
	v_pk_fma_f32 v[66:67], v[60:61], 0.5, v[66:67] op_sel_hi:[1,0,1]
	v_pk_fma_f32 v[60:61], v[58:59], 0.5, v[68:69] op_sel_hi:[1,0,1]
	v_cvt_pk_bf16_f32 v58, v62, v63
	v_lshl_add_u64 v[62:63], s[20:21], 0, v[148:149]
	v_cvt_pk_bf16_f32 v59, v64, v65
	v_cvt_pk_bf16_f32 v60, v60, v61
	v_cvt_pk_bf16_f32 v61, v66, v67
	v_lshl_add_u64 v[62:63], v[62:63], 0, v[146:147]
	global_store_dwordx4 v[62:63], v[58:61], off
	s_waitcnt vmcnt(14)
	s_nop 0
	v_pk_mul_f32 v[58:59], v[76:77], s[16:17] op_sel_hi:[1,0]
	v_pk_mul_f32 v[60:61], v[74:75], s[16:17] op_sel_hi:[1,0]
	v_pk_fma_f32 v[56:57], v[56:57], 0.5, v[58:59] op_sel_hi:[1,0,1]
	v_pk_fma_f32 v[54:55], v[54:55], 0.5, v[60:61] op_sel_hi:[1,0,1]
	s_waitcnt vmcnt(13)
; DI unsigned pk2(float lo, float hi) { f32x2 v = {lo, hi}; bf16x2_t b = __builtin_convertvector(v, bf16x2_t); return __builtin_bit_cast(unsigned, b); }
; template <class Epi, class Sched, bool ALIGN_EPI = false, bool SP2 = false>
; __device__ __forceinline__ void gemm_phase(PG8_LAS unsigned char* lds, const Gemm g, const Sched& S, const Epi& E) {
;     ...
;         if constexpr (!Epi::AFTER_DRAIN) { E(acc, cur, wr, wc, fr, fq); S.done(cur); }
;         if (!has_next) break;
;     DI void operator()(const f32x4 (&acc)[2][2][4][2], const pg8::Unit& u, int wr, int wc, int fr, int fq) const {
;     ...
;                     for (int n = 0; n < 2; ++n) r[m][bj][n] = __builtin_nontemporal_load((const f32x4*)(res + (size_t)(row0 + ai * 128 + m * 16) * DM + col0 + bj * 128 + n * 4));
;             asm volatile("" ::: "memory");
; #pragma unroll
;             for (int m = 0; m < 4; ++m)
; #pragma unroll
;                 for (int bj = 0; bj < 2; ++bj) { const f32x4 a = r[m][bj][0] * ALPHA + acc[ai][bj][m][0] * sc, b = r[m][bj][1] * ALPHA + acc[ai][bj][m][1] * sc;
;                     *(u32x4*)(out + (size_t)(row0 + ai * 128 + m * 16) * DM + col0 + bj * 128) = (u32x4){pk2(a[0], a[1]), pk2(a[2], a[3]), pk2(b[0], b[1]), pk2(b[2], b[3])}; }
;         }
	v_pk_mul_f32 v[58:59], v[80:81], s[16:17] op_sel_hi:[1,0]
	v_pk_mul_f32 v[60:61], v[78:79], s[16:17] op_sel_hi:[1,0]
	v_pk_fma_f32 v[58:59], v[48:49], 0.5, v[58:59] op_sel_hi:[1,0,1]
	v_pk_fma_f32 v[48:49], v[46:47], 0.5, v[60:61] op_sel_hi:[1,0,1]
	v_cvt_pk_bf16_f32 v46, v54, v55
	v_cvt_pk_bf16_f32 v47, v56, v57
	v_cvt_pk_bf16_f32 v48, v48, v49
	v_cvt_pk_bf16_f32 v49, v58, v59
	global_store_dwordx4 v[62:63], v[46:49], off offset:256
	s_waitcnt vmcnt(13)
	v_pk_mul_f32 v[54:55], v[82:83], s[16:17] op_sel_hi:[1,0]
	v_pk_mul_f32 v[48:49], v[84:85], s[16:17] op_sel_hi:[1,0]
	v_lshlrev_b64 v[46:47], 12, v[160:161]
	v_pk_fma_f32 v[48:49], v[52:53], 0.5, v[48:49] op_sel_hi:[1,0,1]
	v_pk_fma_f32 v[50:51], v[50:51], 0.5, v[54:55] op_sel_hi:[1,0,1]
	s_waitcnt vmcnt(12)
	v_pk_mul_f32 v[52:53], v[88:89], s[16:17] op_sel_hi:[1,0]
	v_pk_mul_f32 v[54:55], v[86:87], s[16:17] op_sel_hi:[1,0]
	v_pk_fma_f32 v[52:53], v[44:45], 0.5, v[52:53] op_sel_hi:[1,0,1]
	v_pk_fma_f32 v[44:45], v[42:43], 0.5, v[54:55] op_sel_hi:[1,0,1]
	v_lshl_add_u64 v[46:47], s[20:21], 0, v[46:47]
	v_cvt_pk_bf16_f32 v42, v50, v51
	v_cvt_pk_bf16_f32 v43, v48, v49
	v_cvt_pk_bf16_f32 v44, v44, v45
	v_cvt_pk_bf16_f32 v45, v52, v53
	v_lshl_add_u64 v[46:47], v[46:47], 0, v[146:147]
	global_store_dwordx4 v[46:47], v[42:45], off
	s_waitcnt vmcnt(12)
	s_nop 0
	v_pk_mul_f32 v[42:43], v[92:93], s[16:17] op_sel_hi:[1,0]
	v_pk_mul_f32 v[44:45], v[90:91], s[16:17] op_sel_hi:[1,0]
	v_pk_fma_f32 v[40:41], v[40:41], 0.5, v[42:43] op_sel_hi:[1,0,1]
	v_pk_fma_f32 v[38:39], v[38:39], 0.5, v[44:45] op_sel_hi:[1,0,1]
	s_waitcnt vmcnt(11)
	v_pk_mul_f32 v[42:43], v[96:97], s[16:17] op_sel_hi:[1,0]
	v_pk_mul_f32 v[44:45], v[94:95], s[16:17] op_sel_hi:[1,0]
	v_pk_fma_f32 v[42:43], v[32:33], 0.5, v[42:43] op_sel_hi:[1,0,1]
	v_pk_fma_f32 v[32:33], v[30:31], 0.5, v[44:45] op_sel_hi:[1,0,1]
	v_cvt_pk_bf16_f32 v30, v38, v39
	v_cvt_pk_bf16_f32 v31, v40, v41
	v_cvt_pk_bf16_f32 v32, v32, v33
	v_cvt_pk_bf16_f32 v33, v42, v43
	global_store_dwordx4 v[46:47], v[30:33], off offset:256
	s_waitcnt vmcnt(11)
	v_pk_mul_f32 v[38:39], v[98:99], s[16:17] op_sel_hi:[1,0]
	v_pk_mul_f32 v[32:33], v[100:101], s[16:17] op_sel_hi:[1,0]
	v_lshlrev_b64 v[30:31], 12, v[162:163]
	v_pk_fma_f32 v[32:33], v[36:37], 0.5, v[32:33] op_sel_hi:[1,0,1]
	v_pk_fma_f32 v[34:35], v[34:35], 0.5, v[38:39] op_sel_hi:[1,0,1]
	s_waitcnt vmcnt(10)
	v_pk_mul_f32 v[36:37], v[104:105], s[16:17] op_sel_hi:[1,0]
	v_pk_mul_f32 v[38:39], v[102:103], s[16:17] op_sel_hi:[1,0]
	v_pk_fma_f32 v[36:37], v[28:29], 0.5, v[36:37] op_sel_hi:[1,0,1]
	v_pk_fma_f32 v[28:29], v[26:27], 0.5, v[38:39] op_sel_hi:[1,0,1]
	v_lshl_add_u64 v[30:31], s[20:21], 0, v[30:31]
	v_cvt_pk_bf16_f32 v26, v34, v35
	v_cvt_pk_bf16_f32 v27, v32, v33
	v_cvt_pk_bf16_f32 v28, v28, v29
	v_cvt_pk_bf16_f32 v29, v36, v37
	v_lshl_add_u64 v[30:31], v[30:31], 0, v[146:147]
	global_store_dwordx4 v[30:31], v[26:29], off
	s_waitcnt vmcnt(9)
	s_nop 0
	v_pk_mul_f32 v[26:27], v[112:113], s[16:17] op_sel_hi:[1,0]
	v_pk_mul_f32 v[28:29], v[110:111], s[16:17] op_sel_hi:[1,0]
	v_pk_fma_f32 v[24:25], v[24:25], 0.5, v[26:27] op_sel_hi:[1,0,1]
	v_pk_fma_f32 v[22:23], v[22:23], 0.5, v[28:29] op_sel_hi:[1,0,1]
	v_pk_mul_f32 v[26:27], v[108:109], s[16:17] op_sel_hi:[1,0]
	v_pk_mul_f32 v[28:29], v[106:107], s[16:17] op_sel_hi:[1,0]
	v_pk_fma_f32 v[26:27], v[16:17], 0.5, v[26:27] op_sel_hi:[1,0,1]
	v_pk_fma_f32 v[16:17], v[14:15], 0.5, v[28:29] op_sel_hi:[1,0,1]
	v_cvt_pk_bf16_f32 v14, v22, v23
	v_cvt_pk_bf16_f32 v15, v24, v25
	v_cvt_pk_bf16_f32 v16, v16, v17
	v_cvt_pk_bf16_f32 v17, v26, v27
	global_store_dwordx4 v[30:31], v[14:17], off offset:256
	s_waitcnt vmcnt(8)
	v_pk_mul_f32 v[22:23], v[118:119], s[16:17] op_sel_hi:[1,0]
	v_pk_mul_f32 v[16:17], v[120:121], s[16:17] op_sel_hi:[1,0]
	v_lshlrev_b64 v[14:15], 12, v[150:151]
	v_pk_fma_f32 v[16:17], v[20:21], 0.5, v[16:17] op_sel_hi:[1,0,1]
	v_pk_fma_f32 v[18:19], v[18:19], 0.5, v[22:23] op_sel_hi:[1,0,1]
	v_pk_mul_f32 v[20:21], v[116:117], s[16:17] op_sel_hi:[1,0]
	v_pk_mul_f32 v[22:23], v[114:115], s[16:17] op_sel_hi:[1,0]
	v_pk_fma_f32 v[20:21], v[12:13], 0.5, v[20:21] op_sel_hi:[1,0,1]
	v_pk_fma_f32 v[12:13], v[10:11], 0.5, v[22:23] op_sel_hi:[1,0,1]
	v_lshl_add_u64 v[14:15], s[20:21], 0, v[14:15]
	v_cvt_pk_bf16_f32 v10, v18, v19
	v_cvt_pk_bf16_f32 v11, v16, v17
	v_cvt_pk_bf16_f32 v12, v12, v13
	v_cvt_pk_bf16_f32 v13, v20, v21
	v_lshl_add_u64 v[14:15], v[14:15], 0, v[146:147]
	global_store_dwordx4 v[14:15], v[10:13], off
	s_waitcnt vmcnt(7)
	s_nop 0
	v_pk_mul_f32 v[10:11], v[128:129], s[16:17] op_sel_hi:[1,0]
	v_pk_mul_f32 v[12:13], v[126:127], s[16:17] op_sel_hi:[1,0]
	v_pk_fma_f32 v[8:9], v[8:9], 0.5, v[10:11] op_sel_hi:[1,0,1]
	v_pk_fma_f32 v[6:7], v[6:7], 0.5, v[12:13] op_sel_hi:[1,0,1]
	v_pk_mul_f32 v[10:11], v[124:125], s[16:17] op_sel_hi:[1,0]
	v_pk_mul_f32 v[12:13], v[122:123], s[16:17] op_sel_hi:[1,0]
	v_pk_fma_f32 v[10:11], v[4:5], 0.5, v[10:11] op_sel_hi:[1,0,1]
	v_pk_fma_f32 v[4:5], v[2:3], 0.5, v[12:13] op_sel_hi:[1,0,1]
	v_cvt_pk_bf16_f32 v2, v6, v7
	v_cvt_pk_bf16_f32 v3, v8, v9
	v_cvt_pk_bf16_f32 v4, v4, v5
	v_cvt_pk_bf16_f32 v5, v10, v11
	global_store_dwordx4 v[14:15], v[2:5], off offset:256
	s_mov_b32 s98, 1
	s_cbranch_vccnz .LBB0_196
	s_andn2_b64 vcc, exec, s[8:9]
	s_cbranch_vccnz .LBB0_195
	s_barrier
	s_branch .LBB0_195

; #define PG8_STAGE(bufoff, gbase, voff) do { _Pragma("unroll") for (int _i = 0; _i < 2; ++_i) \
;         __builtin_amdgcn_global_load_lds((const unsigned*)((const char*)(gbase) + (voff)[_i]), (PG8_LAS unsigned*)(lds + (bufoff) + ldsw + _i * 8192), 16, 0, 0); } while (0)
; #define PG8_WAIT_V(n) asm volatile("s_waitcnt vmcnt(" #n ")" ::: "memory")
; #define PG8_BAR __builtin_amdgcn_s_barrier()
; template <class Epi, class Sched, bool ALIGN_EPI = false, bool SP2 = false>
; __device__ __forceinline__ void gemm_phase(PG8_LAS unsigned char* lds, const Gemm g, const Sched& S, const Epi& E) {
;     ...
;     if constexpr (SP2) {
;         PG8_STAGE(PG8_SB(0, 0), cB, voffB); PG8_STAGE(PG8_SB(0, 1), cB + hstep, voffB); PG8_STAGE(PG8_SA(0, 0), cA, voffA); PG8_STAGE(PG8_SA(0, 1), cA + hstep, voffA);
;         if (wr == 1) PG8_BAR;
;         PG8_WAIT_V(2); PG8_BAR;
;         PG8_STAGE(PG8_SB(1, 0), cB + kstep, voffB); PG8_STAGE(PG8_SA(1, 0), cA + kstep, voffA); PG8_STAGE(PG8_SB(1, 1), cB + hstep + kstep, voffB);
;         PG8_WAIT_V(6); PG8_BAR;
.LBB0_218:
	v_bfe_u32 v19, v18, 4, 2
	s_lshl_b32 s8, s8, 5
	v_and_b32_e32 v20, 15, v18
	v_lshlrev_b32_e32 v22, 4, v19
	v_lshlrev_b32_e32 v18, 2, v18
	s_and_b32 s15, s8, 0x60
	v_lshl_or_b32 v21, s9, 6, v20
	v_lshl_or_b32 v20, v20, 6, v22
	s_lshl_b32 s9, s9, 13
	v_and_b32_e32 v18, 32, v18
	s_lshl_b32 s8, s15, 7
	v_bitop3_b32 v22, v20, s9, v18 bitop3:0xde
	v_bitop3_b32 v18, v20, s8, v18 bitop3:0xde
	s_mov_b64 s[8:9], 0x80
	s_add_i32 m0, s26, 0x18000
	v_lshl_add_u64 v[8:9], v[8:9], 0, s[8:9]
	s_waitcnt vmcnt(2)
	s_barrier
	global_load_lds_dwordx4 v[8:9], off
	v_lshl_add_u64 v[6:7], v[6:7], 0, s[8:9]
	s_add_i32 m0, s26, 0x1a000
	s_add_i32 s37, s26, 0x8000
	s_add_i32 s40, s26, 0xa000
	global_load_lds_dwordx4 v[6:7], off
	v_lshl_add_u64 v[2:3], v[2:3], 0, s[8:9]
	s_mov_b32 m0, s37
	s_add_u32 s10, s20, 0x160080
	global_load_lds_dwordx4 v[2:3], off
	v_lshl_add_u64 v[2:3], v[4:5], 0, s[8:9]
	s_mov_b32 m0, s40
	s_addc_u32 s11, s21, 0
	global_load_lds_dwordx4 v[2:3], off
	s_add_i32 m0, s26, 0x1c000
	v_lshl_add_u64 v[2:3], s[10:11], 0, v[132:133]
	global_load_lds_dwordx4 v[2:3], off
	v_lshl_add_u64 v[2:3], s[10:11], 0, v[130:131]
	s_add_i32 m0, s26, 0x1e000
	s_mov_b64 s[16:17], 0x160080
	global_load_lds_dwordx4 v[2:3], off
	v_lshrrev_b32_e32 v3, 1, v15
	v_mul_lo_u32 v2, v14, s1
	v_mad_u64_u32 v[2:3], s[22:23], v3, s14, v[2:3]
	v_or_b32_e32 v2, v2, v16
	v_add_lshl_u32 v2, v2, v17, 1
	v_mov_b32_e32 v3, v133
	v_lshl_add_u64 v[134:135], v[2:3], 0, s[16:17]
	v_lshrrev_b32_e32 v3, 1, v10
	v_mul_lo_u32 v2, v11, s1
	s_cmpk_lt_u32 s0, 0x100
	v_mad_u64_u32 v[2:3], s[0:1], v3, s14, v[2:3]
	s_waitcnt vmcnt(6)
	s_cselect_b64 s[10:11], -1, 0
	v_or_b32_e32 v2, v2, v12
	s_add_i32 s51, 0, 0x10000
	s_add_i32 s53, 0, 0x14000
	v_add_lshl_u32 v2, v2, v13, 1
	v_mov_b32_e32 v3, v133
	v_add_u32_e32 v140, s51, v18
	v_add_u32_e32 v141, s53, v18
	s_add_i32 s51, s51, s13
	s_add_i32 s53, s53, s13
	s_add_i32 s55, 0, 0x18000
	s_add_i32 s56, 0, 0x1c000
	v_add_u32_e32 v138, 0xffffc000, v21
	v_lshl_or_b32 v139, v19, 2, s15
	v_lshl_add_u64 v[136:137], v[2:3], 0, s[16:17]
	v_add_u32_e32 v142, 0, v22
	s_add_i32 s41, s26, 0xc000
	s_add_i32 s50, s26, 0xe000
	s_add_i32 s52, s51, 0x2000
	s_add_i32 s54, s53, 0x2000
	v_add_u32_e32 v143, s55, v18
	v_add_u32_e32 v144, s56, v18
	s_barrier
	s_mov_b32 s98, 0
	s_branch .LBB0_221

; #define PG8_STAGE(bufoff, gbase, voff) do { _Pragma("unroll") for (int _i = 0; _i < 2; ++_i) \
;         __builtin_amdgcn_global_load_lds((const unsigned*)((const char*)(gbase) + (voff)[_i]), (PG8_LAS unsigned*)(lds + (bufoff) + ldsw + _i * 8192), 16, 0, 0); } while (0)
; #define PG8_LDA(dst, b, h) do { _Pragma("unroll") for (int m = 0; m < 4; ++m) _Pragma("unroll") for (int k = 0; k < 2; ++k) dst[m][k] = *(const PG8_LAS bf16x8*)(lds + PG8_SA(b, h) + aoff + m * 2048 + k * 1024); } while (0)
; #define PG8_LDB(dst, b, h) do { _Pragma("unroll") for (int n = 0; n < 2; ++n) _Pragma("unroll") for (int k = 0; k < 2; ++k) dst[n][k] = *(const PG8_LAS bf16x8*)(lds + PG8_SB(b, h) + boff + n * 2048 + k * 1024); } while (0)
; #define PG8_MMA(ai, bj, At, Bt) do { __builtin_amdgcn_s_setprio(1); _Pragma("unroll") for (int m = 0; m < 4; ++m) _Pragma("unroll") for (int n = 0; n < 2; ++n) _Pragma("unroll") for (int k = 0; k < 2; ++k) \
;         acc[ai][bj][m][n] = __builtin_amdgcn_mfma_f32_16x16x32_bf16(Bt[n][k], At[m][k], acc[ai][bj][m][n], 0, 0, 0); __builtin_amdgcn_s_setprio(0); } while (0)
; #define PG8_WAIT_V(n) asm volatile("s_waitcnt vmcnt(" #n ")" ::: "memory")
; #define PG8_WAIT_L(n) asm volatile("s_waitcnt lgkmcnt(" #n ")" ::: "memory")
; #define PG8_BAR __builtin_amdgcn_s_barrier()
; #define PG8_SCHED __builtin_amdgcn_sched_barrier(0)
; template <class Epi, class Sched, bool ALIGN_EPI = false, bool SP2 = false>
; __device__ __forceinline__ void gemm_phase(PG8_LAS unsigned char* lds, const Gemm g, const Sched& S, const Epi& E) {
;     ...
;             if constexpr (SP2) {
;             PG8_LDB(B0, 0, 0); PG8_LDB(B1, 0, 1); PG8_SCHED; PG8_LDA(At, 0, 0); PG8_STAGE(PG8_SA(1, 1), a1 + hstep, voffA);
;             PG8_WAIT_V(8); PG8_WAIT_L(0); PG8_BAR; PG8_MMA(0, 0, At, B0); PG8_MMA(0, 1, At, B1); PG8_BAR; PG8_SCHED;
;     ...
;         for (int a = 0; a < 2; ++a)
; #pragma unroll
;             for (int b = 0; b < 2; ++b)
; #pragma unroll
;                 for (int m = 0; m < 4; ++m)
; #pragma unroll
;                     for (int n = 0; n < 2; ++n) acc[a][b][m][n] = (f32x4){0.f, 0.f, 0.f, 0.f};
.LBB0_227:
	s_add_u32 s60, s20, 0x100
	v_mov_b32_e32 v2, 0
	s_addc_u32 s61, s21, 0
	s_mov_b32 s62, -2
	s_cmp_lg_u32 s98, 0
	s_cbranch_scc1 .Lpeel_4
	v_mov_b32_e32 v3, v2
	v_mov_b32_e32 v4, v2
	v_mov_b32_e32 v5, v2
	v_mov_b32_e32 v6, v2
	v_mov_b32_e32 v7, v2
	v_mov_b32_e32 v8, v2
	v_mov_b32_e32 v9, v2
	v_mov_b32_e32 v10, v2
	v_mov_b32_e32 v11, v2
	v_mov_b32_e32 v12, v2
	v_mov_b32_e32 v13, v2
	v_mov_b32_e32 v14, v2
	v_mov_b32_e32 v15, v2
	v_mov_b32_e32 v16, v2
	v_mov_b32_e32 v17, v2
	v_mov_b32_e32 v26, v2
	v_mov_b32_e32 v27, v2
	v_mov_b32_e32 v28, v2
	v_mov_b32_e32 v29, v2
	v_mov_b32_e32 v30, v2
	v_mov_b32_e32 v31, v2
	v_mov_b32_e32 v32, v2
	v_mov_b32_e32 v33, v2
	v_mov_b32_e32 v42, v2
	v_mov_b32_e32 v43, v2
	v_mov_b32_e32 v44, v2
	v_mov_b32_e32 v45, v2
	v_mov_b32_e32 v46, v2
	v_mov_b32_e32 v47, v2
	v_mov_b32_e32 v48, v2
	v_mov_b32_e32 v49, v2
	v_mov_b32_e32 v18, v2
	v_mov_b32_e32 v19, v2
	v_mov_b32_e32 v20, v2
	v_mov_b32_e32 v21, v2
	v_mov_b32_e32 v22, v2
	v_mov_b32_e32 v23, v2
	v_mov_b32_e32 v24, v2
	v_mov_b32_e32 v25, v2
	v_mov_b32_e32 v34, v2
	v_mov_b32_e32 v35, v2
	v_mov_b32_e32 v36, v2
	v_mov_b32_e32 v37, v2
	v_mov_b32_e32 v38, v2
	v_mov_b32_e32 v39, v2
	v_mov_b32_e32 v40, v2
	v_mov_b32_e32 v41, v2
	v_mov_b32_e32 v50, v2
	v_mov_b32_e32 v51, v2
	v_mov_b32_e32 v52, v2
	v_mov_b32_e32 v53, v2
	v_mov_b32_e32 v54, v2
	v_mov_b32_e32 v55, v2
	v_mov_b32_e32 v56, v2
	v_mov_b32_e32 v57, v2
	v_mov_b32_e32 v58, v2
	v_mov_b32_e32 v59, v2
	v_mov_b32_e32 v60, v2
	v_mov_b32_e32 v61, v2
	v_mov_b32_e32 v62, v2
	v_mov_b32_e32 v63, v2
	v_mov_b32_e32 v64, v2
	v_mov_b32_e32 v65, v2
	v_mov_b32_e32 v66, v2
	v_mov_b32_e32 v67, v2
	v_mov_b32_e32 v68, v2
	v_mov_b32_e32 v69, v2
	v_mov_b32_e32 v70, v2
	v_mov_b32_e32 v71, v2
	v_mov_b32_e32 v72, v2
	v_mov_b32_e32 v73, v2
	v_mov_b32_e32 v74, v2
	v_mov_b32_e32 v75, v2
	v_mov_b32_e32 v76, v2
	v_mov_b32_e32 v77, v2
	v_mov_b32_e32 v78, v2
	v_mov_b32_e32 v79, v2
	v_mov_b32_e32 v80, v2
	v_mov_b32_e32 v81, v2
	v_mov_b32_e32 v86, v2
	v_mov_b32_e32 v87, v2
	v_mov_b32_e32 v88, v2
	v_mov_b32_e32 v89, v2
	v_mov_b32_e32 v94, v2
	v_mov_b32_e32 v95, v2
	v_mov_b32_e32 v96, v2
	v_mov_b32_e32 v97, v2
	v_mov_b32_e32 v102, v2
	v_mov_b32_e32 v103, v2
	v_mov_b32_e32 v104, v2
	v_mov_b32_e32 v105, v2
	v_mov_b32_e32 v110, v2
	v_mov_b32_e32 v111, v2
	v_mov_b32_e32 v112, v2
	v_mov_b32_e32 v113, v2
	v_mov_b32_e32 v82, v2
	v_mov_b32_e32 v83, v2
	v_mov_b32_e32 v84, v2
	v_mov_b32_e32 v85, v2
	v_mov_b32_e32 v90, v2
	v_mov_b32_e32 v91, v2
	v_mov_b32_e32 v92, v2
	v_mov_b32_e32 v93, v2
	v_mov_b32_e32 v98, v2
	v_mov_b32_e32 v99, v2
	v_mov_b32_e32 v100, v2
	v_mov_b32_e32 v101, v2
	v_mov_b32_e32 v106, v2
	v_mov_b32_e32 v107, v2
	v_mov_b32_e32 v108, v2
	v_mov_b32_e32 v109, v2
	v_mov_b32_e32 v114, v2
	v_mov_b32_e32 v115, v2
	v_mov_b32_e32 v116, v2
	v_mov_b32_e32 v117, v2
	v_mov_b32_e32 v118, v2
	v_mov_b32_e32 v119, v2
	v_mov_b32_e32 v120, v2
	v_mov_b32_e32 v121, v2
	v_mov_b32_e32 v122, v2
	v_mov_b32_e32 v123, v2
	v_mov_b32_e32 v124, v2
	v_mov_b32_e32 v125, v2
	v_mov_b32_e32 v126, v2
	v_mov_b32_e32 v127, v2
	v_mov_b32_e32 v128, v2
	v_mov_b32_e32 v129, v2
.LBB0_228:
	ds_read_b128 v[146:149], v140
	ds_read_b128 v[150:153], v140 offset:1024
	ds_read_b128 v[154:157], v140 offset:2048
	ds_read_b128 v[158:161], v140 offset:3072
	ds_read_b128 v[162:165], v141
	ds_read_b128 v[166:169], v141 offset:1024
	ds_read_b128 v[170:173], v141 offset:2048
	ds_read_b128 v[174:177], v141 offset:3072
	s_add_u32 s20, s18, 0x100
	s_addc_u32 s21, s19, 0
	s_cmp_eq_u32 s62, 18
	s_cselect_b32 s25, s15, s21
	s_cselect_b32 s24, s14, s20
	s_cselect_b32 s23, s17, s61
	s_cselect_b32 s22, s16, s60
	s_mov_b32 m0, s41
	v_lshl_add_u64 v[210:211], s[18:19], 0, v[134:135]
	ds_read_b128 v[178:181], v142
	ds_read_b128 v[182:185], v142 offset:1024
	ds_read_b128 v[186:189], v142 offset:2048
	ds_read_b128 v[190:193], v142 offset:3072
	ds_read_b128 v[194:197], v142 offset:4096
	ds_read_b128 v[198:201], v142 offset:5120
	ds_read_b128 v[202:205], v142 offset:6144
	ds_read_b128 v[206:209], v142 offset:7168
	global_load_lds_dwordx4 v[210:211], off
	v_lshl_add_u64 v[210:211], s[18:19], 0, v[136:137]
	s_mov_b32 m0, s50
	s_nop 0
	global_load_lds_dwordx4 v[210:211], off
	s_waitcnt vmcnt(8)
	s_waitcnt lgkmcnt(0)
	s_barrier
	s_setprio 1
	s_waitcnt lgkmcnt(0)
	v_mfma_f32_16x16x32_bf16 v[126:129], v[146:149], v[178:181], v[126:129]
	v_mfma_f32_16x16x32_bf16 v[122:125], v[154:157], v[178:181], v[122:125]
	v_mfma_f32_16x16x32_bf16 v[118:121], v[146:149], v[186:189], v[118:121]
	v_mfma_f32_16x16x32_bf16 v[114:117], v[154:157], v[186:189], v[114:117]
	v_mfma_f32_16x16x32_bf16 v[106:109], v[146:149], v[194:197], v[106:109]
	v_mfma_f32_16x16x32_bf16 v[98:101], v[154:157], v[194:197], v[98:101]
	v_mfma_f32_16x16x32_bf16 v[90:93], v[146:149], v[202:205], v[90:93]
	v_mfma_f32_16x16x32_bf16 v[82:85], v[154:157], v[202:205], v[82:85]
	v_mfma_f32_16x16x32_bf16 v[126:129], v[150:153], v[182:185], v[126:129]
	v_mfma_f32_16x16x32_bf16 v[122:125], v[158:161], v[182:185], v[122:125]
	v_mfma_f32_16x16x32_bf16 v[118:121], v[150:153], v[190:193], v[118:121]
	v_mfma_f32_16x16x32_bf16 v[114:117], v[158:161], v[190:193], v[114:117]
	v_mfma_f32_16x16x32_bf16 v[106:109], v[150:153], v[198:201], v[106:109]
	v_mfma_f32_16x16x32_bf16 v[98:101], v[158:161], v[198:201], v[98:101]
	v_mfma_f32_16x16x32_bf16 v[90:93], v[150:153], v[206:209], v[90:93]
	v_mfma_f32_16x16x32_bf16 v[82:85], v[158:161], v[206:209], v[82:85]
	s_setprio 0
	s_setprio 1
	v_mfma_f32_16x16x32_bf16 v[110:113], v[162:165], v[178:181], v[110:113]
	v_mfma_f32_16x16x32_bf16 v[102:105], v[170:173], v[178:181], v[102:105]
	v_mfma_f32_16x16x32_bf16 v[94:97], v[162:165], v[186:189], v[94:97]
	v_mfma_f32_16x16x32_bf16 v[86:89], v[170:173], v[186:189], v[86:89]
	v_mfma_f32_16x16x32_bf16 v[78:81], v[162:165], v[194:197], v[78:81]
	v_mfma_f32_16x16x32_bf16 v[74:77], v[170:173], v[194:197], v[74:77]
	v_mfma_f32_16x16x32_bf16 v[70:73], v[162:165], v[202:205], v[70:73]
	v_mfma_f32_16x16x32_bf16 v[66:69], v[170:173], v[202:205], v[66:69]
	v_mfma_f32_16x16x32_bf16 v[110:113], v[166:169], v[182:185], v[110:113]
	v_mfma_f32_16x16x32_bf16 v[102:105], v[174:177], v[182:185], v[102:105]
	v_mfma_f32_16x16x32_bf16 v[94:97], v[166:169], v[190:193], v[94:97]
	v_mfma_f32_16x16x32_bf16 v[86:89], v[174:177], v[190:193], v[86:89]
	v_mfma_f32_16x16x32_bf16 v[78:81], v[166:169], v[198:201], v[78:81]
	v_mfma_f32_16x16x32_bf16 v[74:77], v[174:177], v[198:201], v[74:77]
	v_mfma_f32_16x16x32_bf16 v[70:73], v[166:169], v[206:209], v[70:73]
	v_mfma_f32_16x16x32_bf16 v[66:69], v[174:177], v[206:209], v[66:69]
	s_setprio 0
	s_barrier
; #define PG8_STAGE(bufoff, gbase, voff) do { _Pragma("unroll") for (int _i = 0; _i < 2; ++_i) \
;         __builtin_amdgcn_global_load_lds((const unsigned*)((const char*)(gbase) + (voff)[_i]), (PG8_LAS unsigned*)(lds + (bufoff) + ldsw + _i * 8192), 16, 0, 0); } while (0)
; #define PG8_LDA(dst, b, h) do { _Pragma("unroll") for (int m = 0; m < 4; ++m) _Pragma("unroll") for (int k = 0; k < 2; ++k) dst[m][k] = *(const PG8_LAS bf16x8*)(lds + PG8_SA(b, h) + aoff + m * 2048 + k * 1024); } while (0)
; #define PG8_LDB(dst, b, h) do { _Pragma("unroll") for (int n = 0; n < 2; ++n) _Pragma("unroll") for (int k = 0; k < 2; ++k) dst[n][k] = *(const PG8_LAS bf16x8*)(lds + PG8_SB(b, h) + boff + n * 2048 + k * 1024); } while (0)
; #define PG8_MMA(ai, bj, At, Bt) do { __builtin_amdgcn_s_setprio(1); _Pragma("unroll") for (int m = 0; m < 4; ++m) _Pragma("unroll") for (int n = 0; n < 2; ++n) _Pragma("unroll") for (int k = 0; k < 2; ++k) \
;         acc[ai][bj][m][n] = __builtin_amdgcn_mfma_f32_16x16x32_bf16(Bt[n][k], At[m][k], acc[ai][bj][m][n], 0, 0, 0); __builtin_amdgcn_s_setprio(0); } while (0)
; #define PG8_WAIT_V(n) asm volatile("s_waitcnt vmcnt(" #n ")" ::: "memory")
; #define PG8_WAIT_L(n) asm volatile("s_waitcnt lgkmcnt(" #n ")" ::: "memory")
; #define PG8_BAR __builtin_amdgcn_s_barrier()
; #define PG8_SCHED __builtin_amdgcn_sched_barrier(0)
; template <class Epi, class Sched, bool ALIGN_EPI = false, bool SP2 = false>
; __device__ __forceinline__ void gemm_phase(PG8_LAS unsigned char* lds, const Gemm g, const Sched& S, const Epi& E) {
;     ...
;             PG8_LDA(At, 0, 1); PG8_STAGE(PG8_SB(0, 0), b2, voffB); PG8_STAGE(PG8_SB(0, 1), b2 + hstep, voffB); PG8_STAGE(PG8_SA(0, 0), a2, voffA);
;             PG8_WAIT_V(8); PG8_WAIT_L(0); PG8_BAR; PG8_MMA(1, 0, At, B0); PG8_MMA(1, 1, At, B1); PG8_BAR; PG8_SCHED;
;             PG8_LDB(B0, 1, 0); PG8_LDB(B1, 1, 1); PG8_SCHED; PG8_LDA(At, 1, 0); PG8_STAGE(PG8_SA(0, 1), a2 + hstep, voffA);
;             PG8_WAIT_V(8); PG8_WAIT_L(0); PG8_BAR; PG8_MMA(0, 0, At, B0); PG8_MMA(0, 1, At, B1); PG8_BAR; PG8_SCHED;
	s_mov_b32 m0, s51
	v_lshl_add_u64 v[210:211], s[22:23], 0, v[132:133]
	s_add_u32 s18, s22, 0x160000
	ds_read_b128 v[178:181], v142 offset:16384
	ds_read_b128 v[182:185], v142 offset:17408
	ds_read_b128 v[186:189], v142 offset:18432
	ds_read_b128 v[190:193], v142 offset:19456
	ds_read_b128 v[194:197], v142 offset:20480
	ds_read_b128 v[198:201], v142 offset:21504
	ds_read_b128 v[202:205], v142 offset:22528
	ds_read_b128 v[206:209], v142 offset:23552
	global_load_lds_dwordx4 v[210:211], off
	v_lshl_add_u64 v[212:213], s[22:23], 0, v[130:131]
	s_mov_b32 m0, s52
	s_addc_u32 s19, s23, 0
	global_load_lds_dwordx4 v[212:213], off
	v_lshl_add_u64 v[214:215], s[18:19], 0, v[132:133]
	s_mov_b32 m0, s53
	v_lshl_add_u64 v[216:217], s[24:25], 0, v[130:131]
	global_load_lds_dwordx4 v[214:215], off
	v_lshl_add_u64 v[214:215], s[18:19], 0, v[130:131]
	s_mov_b32 m0, s54
	s_nop 0
	global_load_lds_dwordx4 v[214:215], off
	v_lshl_add_u64 v[214:215], s[24:25], 0, v[132:133]
	s_mov_b32 m0, s26
	s_nop 0
	global_load_lds_dwordx4 v[214:215], off
	s_mov_b32 m0, s27
	s_nop 0
	global_load_lds_dwordx4 v[216:217], off
	s_waitcnt vmcnt(8)
	s_waitcnt lgkmcnt(0)
	s_barrier
	s_setprio 1
	s_waitcnt lgkmcnt(0)
	v_mfma_f32_16x16x32_bf16 v[62:65], v[146:149], v[178:181], v[62:65]
	v_mfma_f32_16x16x32_bf16 v[58:61], v[154:157], v[178:181], v[58:61]
	v_mfma_f32_16x16x32_bf16 v[54:57], v[146:149], v[186:189], v[54:57]
	v_mfma_f32_16x16x32_bf16 v[50:53], v[154:157], v[186:189], v[50:53]
	v_mfma_f32_16x16x32_bf16 v[38:41], v[146:149], v[194:197], v[38:41]
	v_mfma_f32_16x16x32_bf16 v[34:37], v[154:157], v[194:197], v[34:37]
	v_mfma_f32_16x16x32_bf16 v[22:25], v[146:149], v[202:205], v[22:25]
	v_mfma_f32_16x16x32_bf16 v[18:21], v[154:157], v[202:205], v[18:21]
	v_mfma_f32_16x16x32_bf16 v[62:65], v[150:153], v[182:185], v[62:65]
	v_mfma_f32_16x16x32_bf16 v[58:61], v[158:161], v[182:185], v[58:61]
	v_mfma_f32_16x16x32_bf16 v[54:57], v[150:153], v[190:193], v[54:57]
	v_mfma_f32_16x16x32_bf16 v[50:53], v[158:161], v[190:193], v[50:53]
	v_mfma_f32_16x16x32_bf16 v[38:41], v[150:153], v[198:201], v[38:41]
	v_mfma_f32_16x16x32_bf16 v[34:37], v[158:161], v[198:201], v[34:37]
	v_mfma_f32_16x16x32_bf16 v[22:25], v[150:153], v[206:209], v[22:25]
	v_mfma_f32_16x16x32_bf16 v[18:21], v[158:161], v[206:209], v[18:21]
	s_setprio 0
	s_setprio 1
	v_mfma_f32_16x16x32_bf16 v[46:49], v[162:165], v[178:181], v[46:49]
	v_mfma_f32_16x16x32_bf16 v[42:45], v[170:173], v[178:181], v[42:45]
	v_mfma_f32_16x16x32_bf16 v[30:33], v[162:165], v[186:189], v[30:33]
	v_mfma_f32_16x16x32_bf16 v[26:29], v[170:173], v[186:189], v[26:29]
	v_mfma_f32_16x16x32_bf16 v[14:17], v[162:165], v[194:197], v[14:17]
	v_mfma_f32_16x16x32_bf16 v[10:13], v[170:173], v[194:197], v[10:13]
	v_mfma_f32_16x16x32_bf16 v[6:9], v[162:165], v[202:205], v[6:9]
	v_mfma_f32_16x16x32_bf16 v[2:5], v[170:173], v[202:205], v[2:5]
	v_mfma_f32_16x16x32_bf16 v[46:49], v[166:169], v[182:185], v[46:49]
	v_mfma_f32_16x16x32_bf16 v[42:45], v[174:177], v[182:185], v[42:45]
	v_mfma_f32_16x16x32_bf16 v[30:33], v[166:169], v[190:193], v[30:33]
	v_mfma_f32_16x16x32_bf16 v[26:29], v[174:177], v[190:193], v[26:29]
	v_mfma_f32_16x16x32_bf16 v[14:17], v[166:169], v[198:201], v[14:17]
	v_mfma_f32_16x16x32_bf16 v[10:13], v[174:177], v[198:201], v[10:13]
	v_mfma_f32_16x16x32_bf16 v[6:9], v[166:169], v[206:209], v[6:9]
	v_mfma_f32_16x16x32_bf16 v[2:5], v[174:177], v[206:209], v[2:5]
	s_setprio 0
	s_barrier
	ds_read_b128 v[146:149], v143
	ds_read_b128 v[150:153], v143 offset:1024
	ds_read_b128 v[154:157], v143 offset:2048
	ds_read_b128 v[158:161], v143 offset:3072
	ds_read_b128 v[162:165], v144
	ds_read_b128 v[166:169], v144 offset:1024
	ds_read_b128 v[170:173], v144 offset:2048
	ds_read_b128 v[174:177], v144 offset:3072
	s_add_u32 s18, s24, 0x160000
	s_addc_u32 s19, s25, 0
	s_mov_b32 m0, s28
	v_lshl_add_u64 v[218:219], s[18:19], 0, v[132:133]
	ds_read_b128 v[178:181], v142 offset:32768
	ds_read_b128 v[182:185], v142 offset:33792
	ds_read_b128 v[186:189], v142 offset:34816
	ds_read_b128 v[190:193], v142 offset:35840
	ds_read_b128 v[194:197], v142 offset:36864
	ds_read_b128 v[198:201], v142 offset:37888
	ds_read_b128 v[202:205], v142 offset:38912
	ds_read_b128 v[206:209], v142 offset:39936
	global_load_lds_dwordx4 v[218:219], off
	v_lshl_add_u64 v[218:219], s[18:19], 0, v[130:131]
	s_mov_b32 m0, s29
	s_nop 0
	global_load_lds_dwordx4 v[218:219], off
	s_waitcnt vmcnt(8)
	s_waitcnt lgkmcnt(0)
	s_barrier
	s_setprio 1
	s_waitcnt lgkmcnt(0)
	v_mfma_f32_16x16x32_bf16 v[126:129], v[146:149], v[178:181], v[126:129]
	v_mfma_f32_16x16x32_bf16 v[122:125], v[154:157], v[178:181], v[122:125]
	v_mfma_f32_16x16x32_bf16 v[118:121], v[146:149], v[186:189], v[118:121]
	v_mfma_f32_16x16x32_bf16 v[114:117], v[154:157], v[186:189], v[114:117]
	v_mfma_f32_16x16x32_bf16 v[106:109], v[146:149], v[194:197], v[106:109]
	v_mfma_f32_16x16x32_bf16 v[98:101], v[154:157], v[194:197], v[98:101]
	v_mfma_f32_16x16x32_bf16 v[90:93], v[146:149], v[202:205], v[90:93]
	v_mfma_f32_16x16x32_bf16 v[82:85], v[154:157], v[202:205], v[82:85]
	v_mfma_f32_16x16x32_bf16 v[126:129], v[150:153], v[182:185], v[126:129]
	v_mfma_f32_16x16x32_bf16 v[122:125], v[158:161], v[182:185], v[122:125]
	v_mfma_f32_16x16x32_bf16 v[118:121], v[150:153], v[190:193], v[118:121]
	v_mfma_f32_16x16x32_bf16 v[114:117], v[158:161], v[190:193], v[114:117]
	v_mfma_f32_16x16x32_bf16 v[106:109], v[150:153], v[198:201], v[106:109]
	v_mfma_f32_16x16x32_bf16 v[98:101], v[158:161], v[198:201], v[98:101]
	v_mfma_f32_16x16x32_bf16 v[90:93], v[150:153], v[206:209], v[90:93]
	v_mfma_f32_16x16x32_bf16 v[82:85], v[158:161], v[206:209], v[82:85]
	s_setprio 0
	s_setprio 1
	v_mfma_f32_16x16x32_bf16 v[110:113], v[162:165], v[178:181], v[110:113]
	v_mfma_f32_16x16x32_bf16 v[102:105], v[170:173], v[178:181], v[102:105]
	v_mfma_f32_16x16x32_bf16 v[94:97], v[162:165], v[186:189], v[94:97]
	v_mfma_f32_16x16x32_bf16 v[86:89], v[170:173], v[186:189], v[86:89]
	v_mfma_f32_16x16x32_bf16 v[78:81], v[162:165], v[194:197], v[78:81]
	v_mfma_f32_16x16x32_bf16 v[74:77], v[170:173], v[194:197], v[74:77]
	v_mfma_f32_16x16x32_bf16 v[70:73], v[162:165], v[202:205], v[70:73]
	v_mfma_f32_16x16x32_bf16 v[66:69], v[170:173], v[202:205], v[66:69]
	v_mfma_f32_16x16x32_bf16 v[110:113], v[166:169], v[182:185], v[110:113]
	v_mfma_f32_16x16x32_bf16 v[102:105], v[174:177], v[182:185], v[102:105]
	v_mfma_f32_16x16x32_bf16 v[94:97], v[166:169], v[190:193], v[94:97]
	v_mfma_f32_16x16x32_bf16 v[86:89], v[174:177], v[190:193], v[86:89]
	v_mfma_f32_16x16x32_bf16 v[78:81], v[166:169], v[198:201], v[78:81]
	v_mfma_f32_16x16x32_bf16 v[74:77], v[174:177], v[198:201], v[74:77]
	v_mfma_f32_16x16x32_bf16 v[70:73], v[166:169], v[206:209], v[70:73]
	v_mfma_f32_16x16x32_bf16 v[66:69], v[174:177], v[206:209], v[66:69]
	s_setprio 0
	s_barrier
; #define PG8_STAGE(bufoff, gbase, voff) do { _Pragma("unroll") for (int _i = 0; _i < 2; ++_i) \
;         __builtin_amdgcn_global_load_lds((const unsigned*)((const char*)(gbase) + (voff)[_i]), (PG8_LAS unsigned*)(lds + (bufoff) + ldsw + _i * 8192), 16, 0, 0); } while (0)
; #define PG8_LDA(dst, b, h) do { _Pragma("unroll") for (int m = 0; m < 4; ++m) _Pragma("unroll") for (int k = 0; k < 2; ++k) dst[m][k] = *(const PG8_LAS bf16x8*)(lds + PG8_SA(b, h) + aoff + m * 2048 + k * 1024); } while (0)
; #define PG8_LDB(dst, b, h) do { _Pragma("unroll") for (int n = 0; n < 2; ++n) _Pragma("unroll") for (int k = 0; k < 2; ++k) dst[n][k] = *(const PG8_LAS bf16x8*)(lds + PG8_SB(b, h) + boff + n * 2048 + k * 1024); } while (0)
; #define PG8_MMA(ai, bj, At, Bt) do { __builtin_amdgcn_s_setprio(1); _Pragma("unroll") for (int m = 0; m < 4; ++m) _Pragma("unroll") for (int n = 0; n < 2; ++n) _Pragma("unroll") for (int k = 0; k < 2; ++k) \
;         acc[ai][bj][m][n] = __builtin_amdgcn_mfma_f32_16x16x32_bf16(Bt[n][k], At[m][k], acc[ai][bj][m][n], 0, 0, 0); __builtin_amdgcn_s_setprio(0); } while (0)
; #define PG8_WAIT_V(n) asm volatile("s_waitcnt vmcnt(" #n ")" ::: "memory")
; #define PG8_BAR __builtin_amdgcn_s_barrier()
; template <class Epi, class Sched, bool ALIGN_EPI = false, bool SP2 = false>
; __device__ __forceinline__ void gemm_phase(PG8_LAS unsigned char* lds, const Gemm g, const Sched& S, const Epi& E) {
;     ...
;         for (int t = 0; t < nt; t += 2) {
;             const bool last = (t == nt - 2);
;             const char* a1 = cA + (size_t)(t + 1) * kstep;
;             const char* a2 = last ? nA : cA + (size_t)(t + 2) * kstep; const char* b2 = last ? nB : cB + (size_t)(t + 2) * kstep;
;             const char* a3 = a2 + kstep; const char* b3 = b2 + kstep;
;             if (last && has_next) S.a_ready(nxt);
;             if constexpr (SP2) {
;             PG8_LDB(B0, 0, 0); PG8_LDB(B1, 0, 1); PG8_SCHED; PG8_LDA(At, 0, 0); PG8_STAGE(PG8_SA(1, 1), a1 + hstep, voffA);
;             PG8_WAIT_V(8); PG8_WAIT_L(0); PG8_BAR; PG8_MMA(0, 0, At, B0); PG8_MMA(0, 1, At, B1); PG8_BAR; PG8_SCHED;
;     ...
;             PG8_LDA(At, 1, 1); PG8_STAGE(PG8_SB(1, 0), b3, voffB); PG8_STAGE(PG8_SB(1, 1), b3 + hstep, voffB); PG8_STAGE(PG8_SA(1, 0), a3, voffA);
;             PG8_WAIT_V(8); PG8_WAIT_L(0); PG8_BAR; PG8_MMA(1, 0, At, B0); PG8_MMA(1, 1, At, B1); PG8_BAR; PG8_SCHED;
	s_add_i32 s18, s55, s13
	v_lshl_add_u64 v[210:211], v[210:211], 0, s[8:9]
	s_mov_b32 m0, s18
	ds_read_b128 v[178:181], v142 offset:49152
	ds_read_b128 v[182:185], v142 offset:50176
	ds_read_b128 v[186:189], v142 offset:51200
	ds_read_b128 v[190:193], v142 offset:52224
	ds_read_b128 v[194:197], v142 offset:53248
	ds_read_b128 v[198:201], v142 offset:54272
	ds_read_b128 v[202:205], v142 offset:55296
	ds_read_b128 v[206:209], v142 offset:56320
	global_load_lds_dwordx4 v[210:211], off
	s_add_i32 m0, s18, 0x2000
	s_add_u32 s18, s22, 0x160080
	v_lshl_add_u64 v[210:211], v[212:213], 0, s[8:9]
	s_addc_u32 s19, s23, 0
	s_add_i32 s22, s56, s13
	global_load_lds_dwordx4 v[210:211], off
	v_lshl_add_u64 v[210:211], s[18:19], 0, v[132:133]
	s_mov_b32 m0, s22
	s_nop 0
	global_load_lds_dwordx4 v[210:211], off
	v_lshl_add_u64 v[210:211], s[18:19], 0, v[130:131]
	s_add_i32 m0, s22, 0x2000
	s_nop 0
	global_load_lds_dwordx4 v[210:211], off
	v_lshl_add_u64 v[210:211], v[214:215], 0, s[8:9]
	s_mov_b32 m0, s37
	s_nop 0
	global_load_lds_dwordx4 v[210:211], off
	v_lshl_add_u64 v[210:211], v[216:217], 0, s[8:9]
	s_mov_b32 m0, s40
	s_nop 0
	global_load_lds_dwordx4 v[210:211], off
	s_waitcnt vmcnt(8)
	s_waitcnt lgkmcnt(0)
	s_barrier
	s_setprio 1
	s_waitcnt lgkmcnt(0)
	v_mfma_f32_16x16x32_bf16 v[62:65], v[146:149], v[178:181], v[62:65]
	v_mfma_f32_16x16x32_bf16 v[58:61], v[154:157], v[178:181], v[58:61]
	v_mfma_f32_16x16x32_bf16 v[54:57], v[146:149], v[186:189], v[54:57]
	v_mfma_f32_16x16x32_bf16 v[50:53], v[154:157], v[186:189], v[50:53]
	v_mfma_f32_16x16x32_bf16 v[38:41], v[146:149], v[194:197], v[38:41]
	v_mfma_f32_16x16x32_bf16 v[34:37], v[154:157], v[194:197], v[34:37]
	v_mfma_f32_16x16x32_bf16 v[22:25], v[146:149], v[202:205], v[22:25]
	v_mfma_f32_16x16x32_bf16 v[18:21], v[154:157], v[202:205], v[18:21]
	v_mfma_f32_16x16x32_bf16 v[62:65], v[150:153], v[182:185], v[62:65]
	v_mfma_f32_16x16x32_bf16 v[58:61], v[158:161], v[182:185], v[58:61]
	v_mfma_f32_16x16x32_bf16 v[54:57], v[150:153], v[190:193], v[54:57]
	v_mfma_f32_16x16x32_bf16 v[50:53], v[158:161], v[190:193], v[50:53]
	v_mfma_f32_16x16x32_bf16 v[38:41], v[150:153], v[198:201], v[38:41]
	v_mfma_f32_16x16x32_bf16 v[34:37], v[158:161], v[198:201], v[34:37]
	v_mfma_f32_16x16x32_bf16 v[22:25], v[150:153], v[206:209], v[22:25]
	v_mfma_f32_16x16x32_bf16 v[18:21], v[158:161], v[206:209], v[18:21]
	s_setprio 0
	s_setprio 1
	v_mfma_f32_16x16x32_bf16 v[46:49], v[162:165], v[178:181], v[46:49]
	v_mfma_f32_16x16x32_bf16 v[42:45], v[170:173], v[178:181], v[42:45]
	v_mfma_f32_16x16x32_bf16 v[30:33], v[162:165], v[186:189], v[30:33]
	v_mfma_f32_16x16x32_bf16 v[26:29], v[170:173], v[186:189], v[26:29]
	v_mfma_f32_16x16x32_bf16 v[14:17], v[162:165], v[194:197], v[14:17]
	v_mfma_f32_16x16x32_bf16 v[10:13], v[170:173], v[194:197], v[10:13]
	v_mfma_f32_16x16x32_bf16 v[6:9], v[162:165], v[202:205], v[6:9]
	v_mfma_f32_16x16x32_bf16 v[2:5], v[170:173], v[202:205], v[2:5]
	v_mfma_f32_16x16x32_bf16 v[46:49], v[166:169], v[182:185], v[46:49]
	v_mfma_f32_16x16x32_bf16 v[42:45], v[174:177], v[182:185], v[42:45]
	v_mfma_f32_16x16x32_bf16 v[30:33], v[166:169], v[190:193], v[30:33]
	v_mfma_f32_16x16x32_bf16 v[26:29], v[174:177], v[190:193], v[26:29]
	v_mfma_f32_16x16x32_bf16 v[14:17], v[166:169], v[198:201], v[14:17]
	v_mfma_f32_16x16x32_bf16 v[10:13], v[174:177], v[198:201], v[10:13]
	v_mfma_f32_16x16x32_bf16 v[6:9], v[166:169], v[206:209], v[6:9]
	v_mfma_f32_16x16x32_bf16 v[2:5], v[174:177], v[206:209], v[2:5]
	s_setprio 0
	s_barrier
	s_add_i32 s62, s62, 2
	s_add_u32 s60, s60, 0x100
	s_addc_u32 s61, s61, 0
	s_cmp_gt_u32 s62, 19
	s_mov_b64 s[18:19], s[20:21]
	s_cbranch_scc0 .LBB0_228
	s_branch .Lpeel_after_4
.Lpeel_4:
	ds_read_b128 v[146:149], v140
	ds_read_b128 v[150:153], v140 offset:1024
	ds_read_b128 v[154:157], v140 offset:2048
	ds_read_b128 v[158:161], v140 offset:3072
	ds_read_b128 v[162:165], v141
	ds_read_b128 v[166:169], v141 offset:1024
	ds_read_b128 v[170:173], v141 offset:2048
	ds_read_b128 v[174:177], v141 offset:3072
	s_add_u32 s20, s18, 0x100
	s_addc_u32 s21, s19, 0
	s_cmp_eq_u32 s62, 18
	s_cselect_b32 s25, s15, s21
	s_cselect_b32 s24, s14, s20
	s_cselect_b32 s23, s17, s61
	s_cselect_b32 s22, s16, s60
	s_mov_b32 m0, s41
	v_lshl_add_u64 v[210:211], s[18:19], 0, v[134:135]
	ds_read_b128 v[178:181], v142
	ds_read_b128 v[182:185], v142 offset:1024
	ds_read_b128 v[186:189], v142 offset:2048
	ds_read_b128 v[190:193], v142 offset:3072
	ds_read_b128 v[194:197], v142 offset:4096
	ds_read_b128 v[198:201], v142 offset:5120
	ds_read_b128 v[202:205], v142 offset:6144
	ds_read_b128 v[206:209], v142 offset:7168
	global_load_lds_dwordx4 v[210:211], off
	v_lshl_add_u64 v[210:211], s[18:19], 0, v[136:137]
	s_mov_b32 m0, s50
	s_nop 0
	global_load_lds_dwordx4 v[210:211], off
	s_waitcnt vmcnt(40)
	s_waitcnt lgkmcnt(0)
	s_barrier
; #define PG8_STAGE(bufoff, gbase, voff) do { _Pragma("unroll") for (int _i = 0; _i < 2; ++_i) \
;         __builtin_amdgcn_global_load_lds((const unsigned*)((const char*)(gbase) + (voff)[_i]), (PG8_LAS unsigned*)(lds + (bufoff) + ldsw + _i * 8192), 16, 0, 0); } while (0)
; #define PG8_LDA(dst, b, h) do { _Pragma("unroll") for (int m = 0; m < 4; ++m) _Pragma("unroll") for (int k = 0; k < 2; ++k) dst[m][k] = *(const PG8_LAS bf16x8*)(lds + PG8_SA(b, h) + aoff + m * 2048 + k * 1024); } while (0)
; #define PG8_MMA(ai, bj, At, Bt) do { __builtin_amdgcn_s_setprio(1); _Pragma("unroll") for (int m = 0; m < 4; ++m) _Pragma("unroll") for (int n = 0; n < 2; ++n) _Pragma("unroll") for (int k = 0; k < 2; ++k) \
;         acc[ai][bj][m][n] = __builtin_amdgcn_mfma_f32_16x16x32_bf16(Bt[n][k], At[m][k], acc[ai][bj][m][n], 0, 0, 0); __builtin_amdgcn_s_setprio(0); } while (0)
; #define PG8_WAIT_V(n) asm volatile("s_waitcnt vmcnt(" #n ")" ::: "memory")
; #define PG8_WAIT_L(n) asm volatile("s_waitcnt lgkmcnt(" #n ")" ::: "memory")
; #define PG8_BAR __builtin_amdgcn_s_barrier()
; #define PG8_SCHED __builtin_amdgcn_sched_barrier(0)
; template <class Epi, class Sched, bool ALIGN_EPI = false, bool SP2 = false>
; __device__ __forceinline__ void gemm_phase(PG8_LAS unsigned char* lds, const Gemm g, const Sched& S, const Epi& E) {
;     ...
;             PG8_WAIT_V(8); PG8_WAIT_L(0); PG8_BAR; PG8_MMA(0, 0, At, B0); PG8_MMA(0, 1, At, B1); PG8_BAR; PG8_SCHED;
;             PG8_LDA(At, 0, 1); PG8_STAGE(PG8_SB(0, 0), b2, voffB); PG8_STAGE(PG8_SB(0, 1), b2 + hstep, voffB); PG8_STAGE(PG8_SA(0, 0), a2, voffA);
;             PG8_WAIT_V(8); PG8_WAIT_L(0); PG8_BAR; PG8_MMA(1, 0, At, B0); PG8_MMA(1, 1, At, B1); PG8_BAR; PG8_SCHED;
	s_setprio 1
	s_waitcnt lgkmcnt(0)
	v_mfma_f32_16x16x32_bf16 v[126:129], v[146:149], v[178:181], 0
	v_mfma_f32_16x16x32_bf16 v[122:125], v[154:157], v[178:181], 0
	v_mfma_f32_16x16x32_bf16 v[118:121], v[146:149], v[186:189], 0
	v_mfma_f32_16x16x32_bf16 v[114:117], v[154:157], v[186:189], 0
	v_mfma_f32_16x16x32_bf16 v[106:109], v[146:149], v[194:197], 0
	v_mfma_f32_16x16x32_bf16 v[98:101], v[154:157], v[194:197], 0
	v_mfma_f32_16x16x32_bf16 v[90:93], v[146:149], v[202:205], 0
	v_mfma_f32_16x16x32_bf16 v[82:85], v[154:157], v[202:205], 0
	v_mfma_f32_16x16x32_bf16 v[126:129], v[150:153], v[182:185], v[126:129]
	v_mfma_f32_16x16x32_bf16 v[122:125], v[158:161], v[182:185], v[122:125]
	v_mfma_f32_16x16x32_bf16 v[118:121], v[150:153], v[190:193], v[118:121]
	v_mfma_f32_16x16x32_bf16 v[114:117], v[158:161], v[190:193], v[114:117]
	v_mfma_f32_16x16x32_bf16 v[106:109], v[150:153], v[198:201], v[106:109]
	v_mfma_f32_16x16x32_bf16 v[98:101], v[158:161], v[198:201], v[98:101]
	v_mfma_f32_16x16x32_bf16 v[90:93], v[150:153], v[206:209], v[90:93]
	v_mfma_f32_16x16x32_bf16 v[82:85], v[158:161], v[206:209], v[82:85]
	s_setprio 0
	s_setprio 1
	v_mfma_f32_16x16x32_bf16 v[110:113], v[162:165], v[178:181], 0
	v_mfma_f32_16x16x32_bf16 v[102:105], v[170:173], v[178:181], 0
	v_mfma_f32_16x16x32_bf16 v[94:97], v[162:165], v[186:189], 0
	v_mfma_f32_16x16x32_bf16 v[86:89], v[170:173], v[186:189], 0
	v_mfma_f32_16x16x32_bf16 v[78:81], v[162:165], v[194:197], 0
	v_mfma_f32_16x16x32_bf16 v[74:77], v[170:173], v[194:197], 0
	v_mfma_f32_16x16x32_bf16 v[70:73], v[162:165], v[202:205], 0
	v_mfma_f32_16x16x32_bf16 v[66:69], v[170:173], v[202:205], 0
	v_mfma_f32_16x16x32_bf16 v[110:113], v[166:169], v[182:185], v[110:113]
	v_mfma_f32_16x16x32_bf16 v[102:105], v[174:177], v[182:185], v[102:105]
	v_mfma_f32_16x16x32_bf16 v[94:97], v[166:169], v[190:193], v[94:97]
	v_mfma_f32_16x16x32_bf16 v[86:89], v[174:177], v[190:193], v[86:89]
	v_mfma_f32_16x16x32_bf16 v[78:81], v[166:169], v[198:201], v[78:81]
	v_mfma_f32_16x16x32_bf16 v[74:77], v[174:177], v[198:201], v[74:77]
	v_mfma_f32_16x16x32_bf16 v[70:73], v[166:169], v[206:209], v[70:73]
	v_mfma_f32_16x16x32_bf16 v[66:69], v[174:177], v[206:209], v[66:69]
	s_setprio 0
	s_barrier
	s_mov_b32 m0, s51
	v_lshl_add_u64 v[210:211], s[22:23], 0, v[132:133]
	s_add_u32 s18, s22, 0x160000
	ds_read_b128 v[178:181], v142 offset:16384
	ds_read_b128 v[182:185], v142 offset:17408
	ds_read_b128 v[186:189], v142 offset:18432
	ds_read_b128 v[190:193], v142 offset:19456
	ds_read_b128 v[194:197], v142 offset:20480
	ds_read_b128 v[198:201], v142 offset:21504
	ds_read_b128 v[202:205], v142 offset:22528
	ds_read_b128 v[206:209], v142 offset:23552
	global_load_lds_dwordx4 v[210:211], off
	v_lshl_add_u64 v[212:213], s[22:23], 0, v[130:131]
	s_mov_b32 m0, s52
	s_addc_u32 s19, s23, 0
	global_load_lds_dwordx4 v[212:213], off
	v_lshl_add_u64 v[214:215], s[18:19], 0, v[132:133]
	s_mov_b32 m0, s53
	v_lshl_add_u64 v[216:217], s[24:25], 0, v[130:131]
	global_load_lds_dwordx4 v[214:215], off
	v_lshl_add_u64 v[214:215], s[18:19], 0, v[130:131]
	s_mov_b32 m0, s54
	s_nop 0
	global_load_lds_dwordx4 v[214:215], off
	v_lshl_add_u64 v[214:215], s[24:25], 0, v[132:133]
	s_mov_b32 m0, s26
	s_nop 0
	global_load_lds_dwordx4 v[214:215], off
	s_mov_b32 m0, s27
	s_nop 0
	global_load_lds_dwordx4 v[216:217], off
	s_waitcnt vmcnt(40)
	s_waitcnt lgkmcnt(0)
	s_barrier
	s_setprio 1
	s_waitcnt lgkmcnt(0)
	v_mfma_f32_16x16x32_bf16 v[62:65], v[146:149], v[178:181], 0
	v_mfma_f32_16x16x32_bf16 v[58:61], v[154:157], v[178:181], 0
	v_mfma_f32_16x16x32_bf16 v[54:57], v[146:149], v[186:189], 0
	v_mfma_f32_16x16x32_bf16 v[50:53], v[154:157], v[186:189], 0
	v_mfma_f32_16x16x32_bf16 v[38:41], v[146:149], v[194:197], 0
	v_mfma_f32_16x16x32_bf16 v[34:37], v[154:157], v[194:197], 0
	v_mfma_f32_16x16x32_bf16 v[22:25], v[146:149], v[202:205], 0
	v_mfma_f32_16x16x32_bf16 v[18:21], v[154:157], v[202:205], 0
	v_mfma_f32_16x16x32_bf16 v[62:65], v[150:153], v[182:185], v[62:65]
	v_mfma_f32_16x16x32_bf16 v[58:61], v[158:161], v[182:185], v[58:61]
	v_mfma_f32_16x16x32_bf16 v[54:57], v[150:153], v[190:193], v[54:57]
	v_mfma_f32_16x16x32_bf16 v[50:53], v[158:161], v[190:193], v[50:53]
	v_mfma_f32_16x16x32_bf16 v[38:41], v[150:153], v[198:201], v[38:41]
	v_mfma_f32_16x16x32_bf16 v[34:37], v[158:161], v[198:201], v[34:37]
	v_mfma_f32_16x16x32_bf16 v[22:25], v[150:153], v[206:209], v[22:25]
	v_mfma_f32_16x16x32_bf16 v[18:21], v[158:161], v[206:209], v[18:21]
	s_setprio 0
	s_setprio 1
	v_mfma_f32_16x16x32_bf16 v[46:49], v[162:165], v[178:181], 0
	v_mfma_f32_16x16x32_bf16 v[42:45], v[170:173], v[178:181], 0
	v_mfma_f32_16x16x32_bf16 v[30:33], v[162:165], v[186:189], 0
	v_mfma_f32_16x16x32_bf16 v[26:29], v[170:173], v[186:189], 0
	v_mfma_f32_16x16x32_bf16 v[14:17], v[162:165], v[194:197], 0
	v_mfma_f32_16x16x32_bf16 v[10:13], v[170:173], v[194:197], 0
	v_mfma_f32_16x16x32_bf16 v[6:9], v[162:165], v[202:205], 0
	v_mfma_f32_16x16x32_bf16 v[2:5], v[170:173], v[202:205], 0
	v_mfma_f32_16x16x32_bf16 v[46:49], v[166:169], v[182:185], v[46:49]
	v_mfma_f32_16x16x32_bf16 v[42:45], v[174:177], v[182:185], v[42:45]
	v_mfma_f32_16x16x32_bf16 v[30:33], v[166:169], v[190:193], v[30:33]
	v_mfma_f32_16x16x32_bf16 v[26:29], v[174:177], v[190:193], v[26:29]
	v_mfma_f32_16x16x32_bf16 v[14:17], v[166:169], v[198:201], v[14:17]
	v_mfma_f32_16x16x32_bf16 v[10:13], v[174:177], v[198:201], v[10:13]
	v_mfma_f32_16x16x32_bf16 v[6:9], v[166:169], v[206:209], v[6:9]
	v_mfma_f32_16x16x32_bf16 v[2:5], v[174:177], v[206:209], v[2:5]
	s_setprio 0
	s_barrier
; #define PG8_STAGE(bufoff, gbase, voff) do { _Pragma("unroll") for (int _i = 0; _i < 2; ++_i) \
;         __builtin_amdgcn_global_load_lds((const unsigned*)((const char*)(gbase) + (voff)[_i]), (PG8_LAS unsigned*)(lds + (bufoff) + ldsw + _i * 8192), 16, 0, 0); } while (0)
; #define PG8_LDA(dst, b, h) do { _Pragma("unroll") for (int m = 0; m < 4; ++m) _Pragma("unroll") for (int k = 0; k < 2; ++k) dst[m][k] = *(const PG8_LAS bf16x8*)(lds + PG8_SA(b, h) + aoff + m * 2048 + k * 1024); } while (0)
; #define PG8_LDB(dst, b, h) do { _Pragma("unroll") for (int n = 0; n < 2; ++n) _Pragma("unroll") for (int k = 0; k < 2; ++k) dst[n][k] = *(const PG8_LAS bf16x8*)(lds + PG8_SB(b, h) + boff + n * 2048 + k * 1024); } while (0)
; #define PG8_MMA(ai, bj, At, Bt) do { __builtin_amdgcn_s_setprio(1); _Pragma("unroll") for (int m = 0; m < 4; ++m) _Pragma("unroll") for (int n = 0; n < 2; ++n) _Pragma("unroll") for (int k = 0; k < 2; ++k) \
;         acc[ai][bj][m][n] = __builtin_amdgcn_mfma_f32_16x16x32_bf16(Bt[n][k], At[m][k], acc[ai][bj][m][n], 0, 0, 0); __builtin_amdgcn_s_setprio(0); } while (0)
; #define PG8_WAIT_V(n) asm volatile("s_waitcnt vmcnt(" #n ")" ::: "memory")
; #define PG8_WAIT_L(n) asm volatile("s_waitcnt lgkmcnt(" #n ")" ::: "memory")
; #define PG8_BAR __builtin_amdgcn_s_barrier()
; #define PG8_SCHED __builtin_amdgcn_sched_barrier(0)
; template <class Epi, class Sched, bool ALIGN_EPI = false, bool SP2 = false>
; __device__ __forceinline__ void gemm_phase(PG8_LAS unsigned char* lds, const Gemm g, const Sched& S, const Epi& E) {
;     ...
;             PG8_LDB(B0, 1, 0); PG8_LDB(B1, 1, 1); PG8_SCHED; PG8_LDA(At, 1, 0); PG8_STAGE(PG8_SA(0, 1), a2 + hstep, voffA);
;             PG8_WAIT_V(8); PG8_WAIT_L(0); PG8_BAR; PG8_MMA(0, 0, At, B0); PG8_MMA(0, 1, At, B1); PG8_BAR; PG8_SCHED;
;             PG8_LDA(At, 1, 1); PG8_STAGE(PG8_SB(1, 0), b3, voffB); PG8_STAGE(PG8_SB(1, 1), b3 + hstep, voffB); PG8_STAGE(PG8_SA(1, 0), a3, voffA);
;             PG8_WAIT_V(8); PG8_WAIT_L(0); PG8_BAR; PG8_MMA(1, 0, At, B0); PG8_MMA(1, 1, At, B1); PG8_BAR; PG8_SCHED;
	ds_read_b128 v[146:149], v143
	ds_read_b128 v[150:153], v143 offset:1024
	ds_read_b128 v[154:157], v143 offset:2048
	ds_read_b128 v[158:161], v143 offset:3072
	ds_read_b128 v[162:165], v144
	ds_read_b128 v[166:169], v144 offset:1024
	ds_read_b128 v[170:173], v144 offset:2048
	ds_read_b128 v[174:177], v144 offset:3072
	s_add_u32 s18, s24, 0x160000
	s_addc_u32 s19, s25, 0
	s_mov_b32 m0, s28
	v_lshl_add_u64 v[218:219], s[18:19], 0, v[132:133]
	ds_read_b128 v[178:181], v142 offset:32768
	ds_read_b128 v[182:185], v142 offset:33792
	ds_read_b128 v[186:189], v142 offset:34816
	ds_read_b128 v[190:193], v142 offset:35840
	ds_read_b128 v[194:197], v142 offset:36864
	ds_read_b128 v[198:201], v142 offset:37888
	ds_read_b128 v[202:205], v142 offset:38912
	ds_read_b128 v[206:209], v142 offset:39936
	global_load_lds_dwordx4 v[218:219], off
	v_lshl_add_u64 v[218:219], s[18:19], 0, v[130:131]
	s_mov_b32 m0, s29
	s_nop 0
	global_load_lds_dwordx4 v[218:219], off
	s_waitcnt vmcnt(8)
	s_waitcnt lgkmcnt(0)
	s_barrier
	s_setprio 1
	s_waitcnt lgkmcnt(0)
	v_mfma_f32_16x16x32_bf16 v[126:129], v[146:149], v[178:181], v[126:129]
	v_mfma_f32_16x16x32_bf16 v[122:125], v[154:157], v[178:181], v[122:125]
	v_mfma_f32_16x16x32_bf16 v[118:121], v[146:149], v[186:189], v[118:121]
	v_mfma_f32_16x16x32_bf16 v[114:117], v[154:157], v[186:189], v[114:117]
	v_mfma_f32_16x16x32_bf16 v[106:109], v[146:149], v[194:197], v[106:109]
	v_mfma_f32_16x16x32_bf16 v[98:101], v[154:157], v[194:197], v[98:101]
	v_mfma_f32_16x16x32_bf16 v[90:93], v[146:149], v[202:205], v[90:93]
	v_mfma_f32_16x16x32_bf16 v[82:85], v[154:157], v[202:205], v[82:85]
	v_mfma_f32_16x16x32_bf16 v[126:129], v[150:153], v[182:185], v[126:129]
	v_mfma_f32_16x16x32_bf16 v[122:125], v[158:161], v[182:185], v[122:125]
	v_mfma_f32_16x16x32_bf16 v[118:121], v[150:153], v[190:193], v[118:121]
	v_mfma_f32_16x16x32_bf16 v[114:117], v[158:161], v[190:193], v[114:117]
	v_mfma_f32_16x16x32_bf16 v[106:109], v[150:153], v[198:201], v[106:109]
	v_mfma_f32_16x16x32_bf16 v[98:101], v[158:161], v[198:201], v[98:101]
	v_mfma_f32_16x16x32_bf16 v[90:93], v[150:153], v[206:209], v[90:93]
	v_mfma_f32_16x16x32_bf16 v[82:85], v[158:161], v[206:209], v[82:85]
	s_setprio 0
	s_setprio 1
	v_mfma_f32_16x16x32_bf16 v[110:113], v[162:165], v[178:181], v[110:113]
	v_mfma_f32_16x16x32_bf16 v[102:105], v[170:173], v[178:181], v[102:105]
	v_mfma_f32_16x16x32_bf16 v[94:97], v[162:165], v[186:189], v[94:97]
	v_mfma_f32_16x16x32_bf16 v[86:89], v[170:173], v[186:189], v[86:89]
	v_mfma_f32_16x16x32_bf16 v[78:81], v[162:165], v[194:197], v[78:81]
	v_mfma_f32_16x16x32_bf16 v[74:77], v[170:173], v[194:197], v[74:77]
	v_mfma_f32_16x16x32_bf16 v[70:73], v[162:165], v[202:205], v[70:73]
	v_mfma_f32_16x16x32_bf16 v[66:69], v[170:173], v[202:205], v[66:69]
	v_mfma_f32_16x16x32_bf16 v[110:113], v[166:169], v[182:185], v[110:113]
	v_mfma_f32_16x16x32_bf16 v[102:105], v[174:177], v[182:185], v[102:105]
	v_mfma_f32_16x16x32_bf16 v[94:97], v[166:169], v[190:193], v[94:97]
	v_mfma_f32_16x16x32_bf16 v[86:89], v[174:177], v[190:193], v[86:89]
	v_mfma_f32_16x16x32_bf16 v[78:81], v[166:169], v[198:201], v[78:81]
	v_mfma_f32_16x16x32_bf16 v[74:77], v[174:177], v[198:201], v[74:77]
	v_mfma_f32_16x16x32_bf16 v[70:73], v[166:169], v[206:209], v[70:73]
	v_mfma_f32_16x16x32_bf16 v[66:69], v[174:177], v[206:209], v[66:69]
	s_setprio 0
	s_barrier
	s_add_i32 s18, s55, s13
	v_lshl_add_u64 v[210:211], v[210:211], 0, s[8:9]
	s_mov_b32 m0, s18
	ds_read_b128 v[178:181], v142 offset:49152
	ds_read_b128 v[182:185], v142 offset:50176
	ds_read_b128 v[186:189], v142 offset:51200
	ds_read_b128 v[190:193], v142 offset:52224
	ds_read_b128 v[194:197], v142 offset:53248
	ds_read_b128 v[198:201], v142 offset:54272
	ds_read_b128 v[202:205], v142 offset:55296
	ds_read_b128 v[206:209], v142 offset:56320
	global_load_lds_dwordx4 v[210:211], off
	s_add_i32 m0, s18, 0x2000
	s_add_u32 s18, s22, 0x160080
	v_lshl_add_u64 v[210:211], v[212:213], 0, s[8:9]
	s_addc_u32 s19, s23, 0
	s_add_i32 s22, s56, s13
	global_load_lds_dwordx4 v[210:211], off
	v_lshl_add_u64 v[210:211], s[18:19], 0, v[132:133]
	s_mov_b32 m0, s22
	s_nop 0
	global_load_lds_dwordx4 v[210:211], off
	v_lshl_add_u64 v[210:211], s[18:19], 0, v[130:131]
	s_add_i32 m0, s22, 0x2000
	s_nop 0
	global_load_lds_dwordx4 v[210:211], off
	v_lshl_add_u64 v[210:211], v[214:215], 0, s[8:9]
	s_mov_b32 m0, s37
	s_nop 0
	global_load_lds_dwordx4 v[210:211], off
	v_lshl_add_u64 v[210:211], v[216:217], 0, s[8:9]
	s_mov_b32 m0, s40
	s_nop 0
	global_load_lds_dwordx4 v[210:211], off
	s_waitcnt vmcnt(8)
	s_waitcnt lgkmcnt(0)
	s_barrier
	s_setprio 1
	s_waitcnt lgkmcnt(0)
	v_mfma_f32_16x16x32_bf16 v[62:65], v[146:149], v[178:181], v[62:65]
	v_mfma_f32_16x16x32_bf16 v[58:61], v[154:157], v[178:181], v[58:61]
	v_mfma_f32_16x16x32_bf16 v[54:57], v[146:149], v[186:189], v[54:57]
	v_mfma_f32_16x16x32_bf16 v[50:53], v[154:157], v[186:189], v[50:53]
	v_mfma_f32_16x16x32_bf16 v[38:41], v[146:149], v[194:197], v[38:41]
	v_mfma_f32_16x16x32_bf16 v[34:37], v[154:157], v[194:197], v[34:37]
	v_mfma_f32_16x16x32_bf16 v[22:25], v[146:149], v[202:205], v[22:25]
	v_mfma_f32_16x16x32_bf16 v[18:21], v[154:157], v[202:205], v[18:21]
	v_mfma_f32_16x16x32_bf16 v[62:65], v[150:153], v[182:185], v[62:65]
	v_mfma_f32_16x16x32_bf16 v[58:61], v[158:161], v[182:185], v[58:61]
	v_mfma_f32_16x16x32_bf16 v[54:57], v[150:153], v[190:193], v[54:57]
	v_mfma_f32_16x16x32_bf16 v[50:53], v[158:161], v[190:193], v[50:53]
	v_mfma_f32_16x16x32_bf16 v[38:41], v[150:153], v[198:201], v[38:41]
	v_mfma_f32_16x16x32_bf16 v[34:37], v[158:161], v[198:201], v[34:37]
	v_mfma_f32_16x16x32_bf16 v[22:25], v[150:153], v[206:209], v[22:25]
	v_mfma_f32_16x16x32_bf16 v[18:21], v[158:161], v[206:209], v[18:21]
	s_setprio 0
	s_setprio 1
	v_mfma_f32_16x16x32_bf16 v[46:49], v[162:165], v[178:181], v[46:49]
	v_mfma_f32_16x16x32_bf16 v[42:45], v[170:173], v[178:181], v[42:45]
	v_mfma_f32_16x16x32_bf16 v[30:33], v[162:165], v[186:189], v[30:33]
	v_mfma_f32_16x16x32_bf16 v[26:29], v[170:173], v[186:189], v[26:29]
	v_mfma_f32_16x16x32_bf16 v[14:17], v[162:165], v[194:197], v[14:17]
	v_mfma_f32_16x16x32_bf16 v[10:13], v[170:173], v[194:197], v[10:13]
	v_mfma_f32_16x16x32_bf16 v[6:9], v[162:165], v[202:205], v[6:9]
	v_mfma_f32_16x16x32_bf16 v[2:5], v[170:173], v[202:205], v[2:5]
	v_mfma_f32_16x16x32_bf16 v[46:49], v[166:169], v[182:185], v[46:49]
	v_mfma_f32_16x16x32_bf16 v[42:45], v[174:177], v[182:185], v[42:45]
	v_mfma_f32_16x16x32_bf16 v[30:33], v[166:169], v[190:193], v[30:33]
	v_mfma_f32_16x16x32_bf16 v[26:29], v[174:177], v[190:193], v[26:29]
	v_mfma_f32_16x16x32_bf16 v[14:17], v[166:169], v[198:201], v[14:17]
	v_mfma_f32_16x16x32_bf16 v[10:13], v[174:177], v[198:201], v[10:13]
	v_mfma_f32_16x16x32_bf16 v[6:9], v[166:169], v[206:209], v[6:9]
	v_mfma_f32_16x16x32_bf16 v[2:5], v[174:177], v[206:209], v[2:5]
	s_setprio 0
	s_barrier
	s_add_i32 s62, s62, 2
	s_add_u32 s60, s60, 0x100
	s_addc_u32 s61, s61, 0
	s_cmp_gt_u32 s62, 19
	s_mov_b64 s[18:19], s[20:21]
	s_branch .LBB0_228
; #define PG8_BAR __builtin_amdgcn_s_barrier()
; template <class Epi, class Sched, bool ALIGN_EPI = false, bool SP2 = false>
; __device__ __forceinline__ void gemm_phase(PG8_LAS unsigned char* lds, const Gemm g, const Sched& S, const Epi& E) {
;     ...
;         if constexpr (ALIGN_EPI) { if (wr == 0) PG8_BAR; }
;         if constexpr (!Epi::AFTER_DRAIN) { E(acc, cur, wr, wc, fr, fq); S.done(cur); }
;         if (!has_next) break;
;     DI void operator()(const f32x4 (&acc)[2][2][4][2], const pg8::Unit& u, int wr, int wc, int fr, int fq) const {
;         const int row0 = (u.pm - MP / 256) * 256 + wr * 64 + fr, col0 = u.pn * 256 + wc * 32 + 4 * fq;
;         float* dst = slab + (size_t)(u.kb / kslice_bytes) * MS * DM;
; #pragma unroll
;         for (int ai = 0; ai < 2; ++ai)
; #pragma unroll
;             for (int m = 0; m < 4; ++m) {
;                 const size_t off = (size_t)(row0 + ai * 128 + m * 16) * DM + col0;
; #pragma unroll
;                 for (int bj = 0; bj < 2; ++bj)
; #pragma unroll
;                     for (int n = 0; n < 2; ++n) *(f32x4*)(dst + off + bj * 128 + n * 16) = acc[ai][bj][m][n];
;             }
.Lpeel_after_4:
	s_and_b64 vcc, exec, s[10:11]
	s_cbranch_vccz .LBB0_231
	s_barrier
.LBB0_231:
	s_mul_hi_i32 s18, s35, 0x2e8ba2e9
	s_lshr_b32 s19, s18, 31
	s_ashr_i32 s18, s18, 9
	s_add_i32 s18, s18, s19
	s_ashr_i32 s19, s18, 31
	s_lshl_b64 s[18:19], s[18:19], 23
	v_readlane_b32 s20, v253, 57
	v_lshl_or_b32 v146, s36, 8, v139
	s_add_u32 s18, s20, s18
	v_readlane_b32 s20, v253, 58
	v_lshl_add_u32 v148, s34, 8, v138
	s_addc_u32 s19, s20, s19
	v_ashrrev_i32_e32 v147, 31, v146
	v_ashrrev_i32_e32 v149, 31, v148
	v_lshl_add_u64 v[146:147], v[146:147], 2, s[18:19]
	v_lshlrev_b64 v[150:151], 13, v[148:149]
	v_lshl_add_u64 v[150:151], v[146:147], 0, v[150:151]
	global_store_dwordx4 v[150:151], v[126:129], off
	global_store_dwordx4 v[150:151], v[122:125], off offset:64
	global_store_dwordx4 v[150:151], v[110:113], off offset:512
	global_store_dwordx4 v[150:151], v[102:105], off offset:576
	s_mov_b64 s[18:19], 0x100000
	v_readlane_b32 s62, v253, 53
	v_or_b32_e32 v102, 16, v148
	v_ashrrev_i32_e32 v103, 31, v102
	v_lshlrev_b64 v[102:103], 13, v[102:103]
	v_lshl_add_u64 v[102:103], v[146:147], 0, v[102:103]
	global_store_dwordx4 v[102:103], v[118:121], off
	global_store_dwordx4 v[102:103], v[114:117], off offset:64
	global_store_dwordx4 v[102:103], v[94:97], off offset:512
	global_store_dwordx4 v[102:103], v[86:89], off offset:576
	v_readlane_b32 s63, v253, 54
	s_nop 0
	v_or_b32_e32 v86, 32, v148
	v_ashrrev_i32_e32 v87, 31, v86
	v_lshlrev_b64 v[86:87], 13, v[86:87]
	v_lshl_add_u64 v[86:87], v[146:147], 0, v[86:87]
	global_store_dwordx4 v[86:87], v[106:109], off
	global_store_dwordx4 v[86:87], v[98:101], off offset:64
	global_store_dwordx4 v[86:87], v[78:81], off offset:512
	global_store_dwordx4 v[86:87], v[74:77], off offset:576
	s_nop 1
	v_or_b32_e32 v74, 48, v148
	v_ashrrev_i32_e32 v75, 31, v74
	v_lshlrev_b64 v[74:75], 13, v[74:75]
	v_lshl_add_u64 v[74:75], v[146:147], 0, v[74:75]
	global_store_dwordx4 v[74:75], v[90:93], off
	global_store_dwordx4 v[74:75], v[82:85], off offset:64
	global_store_dwordx4 v[74:75], v[70:73], off offset:512
	global_store_dwordx4 v[74:75], v[66:69], off offset:576
	s_nop 1
	v_lshl_add_u64 v[66:67], v[150:151], 0, s[18:19]
	s_mov_b32 s18, 0x100000
	v_add_co_u32_e32 v68, vcc, s18, v150
	s_mov_b64 s[18:19], 0x120000
	s_nop 0
	v_addc_co_u32_e32 v69, vcc, 0, v151, vcc
	global_store_dwordx4 v[68:69], v[62:65], off
	global_store_dwordx4 v[66:67], v[58:61], off offset:64
	global_store_dwordx4 v[66:67], v[46:49], off offset:512
	global_store_dwordx4 v[66:67], v[42:45], off offset:576
	s_nop 1
	v_lshl_add_u64 v[42:43], v[150:151], 0, s[18:19]
	s_mov_b32 s18, 0x120000
	v_add_co_u32_e32 v44, vcc, s18, v150
	s_mov_b64 s[18:19], 0x140000
	s_nop 0
	v_addc_co_u32_e32 v45, vcc, 0, v151, vcc
	global_store_dwordx4 v[44:45], v[54:57], off
	global_store_dwordx4 v[42:43], v[50:53], off offset:64
	global_store_dwordx4 v[42:43], v[30:33], off offset:512
	global_store_dwordx4 v[42:43], v[26:29], off offset:576
	s_nop 1
	v_lshl_add_u64 v[26:27], v[150:151], 0, s[18:19]
	s_mov_b32 s18, 0x140000
	v_add_co_u32_e32 v28, vcc, s18, v150
	s_mov_b64 s[18:19], 0x160000
	s_nop 0
	v_addc_co_u32_e32 v29, vcc, 0, v151, vcc
	global_store_dwordx4 v[28:29], v[38:41], off
	global_store_dwordx4 v[26:27], v[34:37], off offset:64
	global_store_dwordx4 v[26:27], v[14:17], off offset:512
	global_store_dwordx4 v[26:27], v[10:13], off offset:576
	s_nop 1
	v_add_co_u32_e32 v12, vcc, 0x160000, v150
	v_lshl_add_u64 v[10:11], v[150:151], 0, s[18:19]
	s_nop 0
	v_addc_co_u32_e32 v13, vcc, 0, v151, vcc
	s_and_b64 vcc, exec, s[0:1]
	s_mov_b64 s[0:1], -1
	global_store_dwordx4 v[12:13], v[22:25], off
	global_store_dwordx4 v[10:11], v[18:21], off offset:64
	global_store_dwordx4 v[10:11], v[6:9], off offset:512
	global_store_dwordx4 v[10:11], v[2:5], off offset:576
	s_mov_b32 s98, 1
	s_cbranch_vccnz .LBB0_220
	s_andn2_b64 vcc, exec, s[2:3]
	s_cbranch_vccnz .LBB0_219
	s_barrier
	s_branch .LBB0_219

; #define PG8_STAGE(bufoff, gbase, voff) do { _Pragma("unroll") for (int _i = 0; _i < 2; ++_i) \
;         __builtin_amdgcn_global_load_lds((const unsigned*)((const char*)(gbase) + (voff)[_i]), (PG8_LAS unsigned*)(lds + (bufoff) + ldsw + _i * 8192), 16, 0, 0); } while (0)
; #define PG8_WAIT_V(n) asm volatile("s_waitcnt vmcnt(" #n ")" ::: "memory")
; #define PG8_BAR __builtin_amdgcn_s_barrier()
; template <class Epi, class Sched, bool ALIGN_EPI = false, bool SP2 = false>
; __device__ __forceinline__ void gemm_phase(PG8_LAS unsigned char* lds, const Gemm g, const Sched& S, const Epi& E) {
;     ...
;     if constexpr (SP2) {
;         PG8_STAGE(PG8_SB(0, 0), cB, voffB); PG8_STAGE(PG8_SB(0, 1), cB + hstep, voffB); PG8_STAGE(PG8_SA(0, 0), cA, voffA); PG8_STAGE(PG8_SA(0, 1), cA + hstep, voffA);
;         if (wr == 1) PG8_BAR;
;         PG8_WAIT_V(2); PG8_BAR;
;         PG8_STAGE(PG8_SB(1, 0), cB + kstep, voffB); PG8_STAGE(PG8_SA(1, 0), cA + kstep, voffA); PG8_STAGE(PG8_SB(1, 1), cB + hstep + kstep, voffB);
;         PG8_WAIT_V(6); PG8_BAR;
.LBB0_1003:
	s_add_u32 s10, s2, 0x40080
	v_lshrrev_b32_e32 v18, 1, v16
	s_addc_u32 s11, s3, 0
	v_and_b32_e32 v18, 24, v18
	s_lshl_b32 s6, s6, 5
	v_and_b32_e32 v17, 15, v16
	v_lshlrev_b32_e32 v19, 1, v18
	v_lshlrev_b32_e32 v16, 2, v16
	s_and_b32 s12, s6, 0x60
	v_lshl_or_b32 v1, s7, 6, v17
	v_lshl_or_b32 v17, v17, 6, v19
	s_lshl_b32 s7, s7, 13
	v_and_b32_e32 v16, 32, v16
	s_lshl_b32 s6, s12, 7
	v_bitop3_b32 v19, v17, s7, v16 bitop3:0xde
	v_bitop3_b32 v144, v17, s6, v16 bitop3:0xde
	s_mov_b64 s[6:7], 0x80
	s_add_i32 m0, s20, 0x18000
	v_lshl_add_u64 v[4:5], v[4:5], 0, s[6:7]
	s_waitcnt vmcnt(2)
	s_barrier
	global_load_lds_dwordx4 v[4:5], off
	v_lshl_add_u64 v[2:3], v[2:3], 0, s[6:7]
	s_add_i32 m0, s20, 0x1a000
	s_add_i32 s25, s20, 0x8000
	global_load_lds_dwordx4 v[2:3], off
	v_lshl_add_u64 v[2:3], v[6:7], 0, s[6:7]
	s_mov_b32 m0, s25
	s_add_i32 s26, s20, 0xa000
	global_load_lds_dwordx4 v[2:3], off
	v_lshl_add_u64 v[2:3], v[8:9], 0, s[6:7]
	s_mov_b32 m0, s26
	v_mov_b32_e32 v141, v135
	global_load_lds_dwordx4 v[2:3], off
	s_add_i32 m0, s20, 0x1c000
	v_lshl_add_u64 v[2:3], s[10:11], 0, v[134:135]
	global_load_lds_dwordx4 v[2:3], off
	v_lshl_add_u64 v[2:3], s[10:11], 0, v[130:131]
	s_add_i32 m0, s20, 0x1e000
	s_cmpk_lt_u32 s8, 0x100
	global_load_lds_dwordx4 v[2:3], off
	v_or_b32_e32 v2, s12, v18
	v_lshlrev_b32_e32 v2, 1, v2
	v_mov_b32_e32 v3, v135
	v_lshl_add_u64 v[138:139], s[34:35], 0, v[2:3]
	v_lshlrev_b32_e32 v2, 14, v14
	v_and_b32_e32 v2, 0xffff8000, v2
	v_lshl_add_u32 v2, v13, 11, v2
	v_and_b32_e32 v3, 1, v14
	v_lshl_or_b32 v2, v3, 6, v2
	v_lshl_add_u32 v140, v15, 1, v2
	v_lshlrev_b32_e32 v2, 14, v10
	v_and_b32_e32 v2, 0xffff8000, v2
	s_waitcnt vmcnt(6)
	s_cselect_b64 s[8:9], -1, 0
	v_lshl_add_u32 v2, v11, 11, v2
	v_and_b32_e32 v3, 1, v10
	s_add_i32 s33, 0, 0x10000
	v_lshl_or_b32 v2, v3, 6, v2
	v_add_u32_e32 v145, s33, v144
	s_add_i32 s27, 0, 0x14000
	s_add_i32 s33, s33, s19
	v_lshl_add_u32 v142, v12, 1, v2
	v_mov_b32_e32 v143, v135
	v_add_u32_e32 v147, s27, v144
	v_add_u32_e32 v148, 0, v19
	s_add_i32 s28, s20, 0xc000
	s_add_i32 s29, s20, 0xe000
	s_add_i32 s40, s33, 0x2000
	v_readlane_b32 s41, v253, 2
	s_barrier
	s_mov_b32 s98, 0
	s_branch .LBB0_1006

; #define PG8_STAGE(bufoff, gbase, voff) do { _Pragma("unroll") for (int _i = 0; _i < 2; ++_i) \
;         __builtin_amdgcn_global_load_lds((const unsigned*)((const char*)(gbase) + (voff)[_i]), (PG8_LAS unsigned*)(lds + (bufoff) + ldsw + _i * 8192), 16, 0, 0); } while (0)
; #define PG8_LDA(dst, b, h) do { _Pragma("unroll") for (int m = 0; m < 4; ++m) _Pragma("unroll") for (int k = 0; k < 2; ++k) dst[m][k] = *(const PG8_LAS bf16x8*)(lds + PG8_SA(b, h) + aoff + m * 2048 + k * 1024); } while (0)
; #define PG8_LDB(dst, b, h) do { _Pragma("unroll") for (int n = 0; n < 2; ++n) _Pragma("unroll") for (int k = 0; k < 2; ++k) dst[n][k] = *(const PG8_LAS bf16x8*)(lds + PG8_SB(b, h) + boff + n * 2048 + k * 1024); } while (0)
; #define PG8_MMA(ai, bj, At, Bt) do { __builtin_amdgcn_s_setprio(1); _Pragma("unroll") for (int m = 0; m < 4; ++m) _Pragma("unroll") for (int n = 0; n < 2; ++n) _Pragma("unroll") for (int k = 0; k < 2; ++k) \
;         acc[ai][bj][m][n] = __builtin_amdgcn_mfma_f32_16x16x32_bf16(Bt[n][k], At[m][k], acc[ai][bj][m][n], 0, 0, 0); __builtin_amdgcn_s_setprio(0); } while (0)
; #define PG8_WAIT_V(n) asm volatile("s_waitcnt vmcnt(" #n ")" ::: "memory")
; #define PG8_WAIT_L(n) asm volatile("s_waitcnt lgkmcnt(" #n ")" ::: "memory")
; template <class Epi, class Sched, bool ALIGN_EPI = false, bool SP2 = false>
; __device__ __forceinline__ void gemm_phase(PG8_LAS unsigned char* lds, const Gemm g, const Sched& S, const Epi& E) {
;     ...
;         const bool has_next = S.next(ui + 1, nxt);
;         const char* nA = has_next ? (const char*)g.A + (size_t)nxt.pm * tstep + nxt.kb : cA; const char* nB = has_next ? (const char*)g.Bt + (size_t)nxt.pn * tstep + nxt.kb : cB;
;         for (int t = 0; t < nt; t += 2) {
;             const bool last = (t == nt - 2);
;             const char* a1 = cA + (size_t)(t + 1) * kstep;
;             const char* a2 = last ? nA : cA + (size_t)(t + 2) * kstep; const char* b2 = last ? nB : cB + (size_t)(t + 2) * kstep;
;             const char* a3 = a2 + kstep; const char* b3 = b2 + kstep;
;             if (last && has_next) S.a_ready(nxt);
;             if constexpr (SP2) {
;             PG8_LDB(B0, 0, 0); PG8_LDB(B1, 0, 1); PG8_SCHED; PG8_LDA(At, 0, 0); PG8_STAGE(PG8_SA(1, 1), a1 + hstep, voffA);
;             PG8_WAIT_V(8); PG8_WAIT_L(0); PG8_BAR; PG8_MMA(0, 0, At, B0); PG8_MMA(0, 1, At, B1); PG8_BAR; PG8_SCHED;
.LBB0_1006:
	s_add_i32 s24, s24, 1
	s_mov_b64 s[12:13], s[0:1]
	s_mul_i32 s0, s24, s78
	s_mov_b64 s[14:15], s[2:3]
	s_mov_b32 s3, s41
	s_mov_b32 s51, s41
	s_add_i32 s41, s0, s66
	s_cmpk_lt_i32 s41, 0x220
	s_mul_hi_i32 s0, s41, 0x78787879
	s_cselect_b64 s[10:11], -1, 0
	s_lshr_b32 s1, s0, 31
	s_ashr_i32 s0, s0, 7
	s_mov_b32 s2, s50
	s_add_i32 s50, s0, s1
	s_and_b64 s[0:1], s[10:11], exec
	s_cselect_b32 s0, s41, s3
	s_cselect_b32 s2, s50, s2
	s_ashr_i32 s1, s0, 31
	s_lshl_b64 s[0:1], s[0:1], 19
	s_add_u32 s0, s62, s0
	s_addc_u32 s1, s63, s1
	s_and_b64 s[16:17], s[10:11], exec
	s_cselect_b32 s52, s1, s13
	s_cselect_b32 s53, s0, s12
	s_ashr_i32 s3, s2, 31
	s_lshl_b64 s[2:3], s[2:3], 19
	s_add_u32 s2, s30, s2
	s_addc_u32 s3, s31, s3
	s_and_b64 s[16:17], s[10:11], exec
	s_cselect_b32 s54, s3, s15
	s_cselect_b32 s55, s2, s14
	s_add_u32 s12, s12, 0x40080
	s_addc_u32 s13, s13, 0
	s_add_u32 s56, s14, 0x100
	v_mov_b32_e32 v2, 0
	s_addc_u32 s57, s15, 0
	s_mov_b32 s58, -2
	s_cmp_lg_u32 s98, 0
	s_cbranch_scc1 .Lpeel_5
	v_mov_b32_e32 v3, v2
	v_mov_b32_e32 v4, v2
	v_mov_b32_e32 v5, v2
	v_mov_b32_e32 v6, v2
	v_mov_b32_e32 v7, v2
	v_mov_b32_e32 v8, v2
	v_mov_b32_e32 v9, v2
	v_mov_b32_e32 v10, v2
	v_mov_b32_e32 v11, v2
	v_mov_b32_e32 v12, v2
	v_mov_b32_e32 v13, v2
	v_mov_b32_e32 v14, v2
	v_mov_b32_e32 v15, v2
	v_mov_b32_e32 v16, v2
	v_mov_b32_e32 v17, v2
	v_mov_b32_e32 v26, v2
	v_mov_b32_e32 v27, v2
	v_mov_b32_e32 v28, v2
	v_mov_b32_e32 v29, v2
	v_mov_b32_e32 v30, v2
	v_mov_b32_e32 v31, v2
	v_mov_b32_e32 v32, v2
	v_mov_b32_e32 v33, v2
	v_mov_b32_e32 v42, v2
	v_mov_b32_e32 v43, v2
	v_mov_b32_e32 v44, v2
	v_mov_b32_e32 v45, v2
	v_mov_b32_e32 v46, v2
	v_mov_b32_e32 v47, v2
	v_mov_b32_e32 v48, v2
	v_mov_b32_e32 v49, v2
	v_mov_b32_e32 v18, v2
	v_mov_b32_e32 v19, v2
	v_mov_b32_e32 v20, v2
	v_mov_b32_e32 v21, v2
	v_mov_b32_e32 v22, v2
	v_mov_b32_e32 v23, v2
	v_mov_b32_e32 v24, v2
	v_mov_b32_e32 v25, v2
	v_mov_b32_e32 v34, v2
	v_mov_b32_e32 v35, v2
	v_mov_b32_e32 v36, v2
	v_mov_b32_e32 v37, v2
	v_mov_b32_e32 v38, v2
	v_mov_b32_e32 v39, v2
	v_mov_b32_e32 v40, v2
	v_mov_b32_e32 v41, v2
	v_mov_b32_e32 v50, v2
	v_mov_b32_e32 v51, v2
	v_mov_b32_e32 v52, v2
	v_mov_b32_e32 v53, v2
	v_mov_b32_e32 v54, v2
	v_mov_b32_e32 v55, v2
	v_mov_b32_e32 v56, v2
	v_mov_b32_e32 v57, v2
	v_mov_b32_e32 v58, v2
	v_mov_b32_e32 v59, v2
	v_mov_b32_e32 v60, v2
	v_mov_b32_e32 v61, v2
	v_mov_b32_e32 v62, v2
	v_mov_b32_e32 v63, v2
	v_mov_b32_e32 v64, v2
	v_mov_b32_e32 v65, v2
	v_mov_b32_e32 v66, v2
	v_mov_b32_e32 v67, v2
	v_mov_b32_e32 v68, v2
	v_mov_b32_e32 v69, v2
	v_mov_b32_e32 v70, v2
	v_mov_b32_e32 v71, v2
	v_mov_b32_e32 v72, v2
	v_mov_b32_e32 v73, v2
	v_mov_b32_e32 v74, v2
	v_mov_b32_e32 v75, v2
	v_mov_b32_e32 v76, v2
	v_mov_b32_e32 v77, v2
	v_mov_b32_e32 v78, v2
	v_mov_b32_e32 v79, v2
	v_mov_b32_e32 v80, v2
	v_mov_b32_e32 v81, v2
	v_mov_b32_e32 v90, v2
	v_mov_b32_e32 v91, v2
	v_mov_b32_e32 v92, v2
	v_mov_b32_e32 v93, v2
	v_mov_b32_e32 v94, v2
	v_mov_b32_e32 v95, v2
	v_mov_b32_e32 v96, v2
	v_mov_b32_e32 v97, v2
	v_mov_b32_e32 v106, v2
	v_mov_b32_e32 v107, v2
	v_mov_b32_e32 v108, v2
	v_mov_b32_e32 v109, v2
	v_mov_b32_e32 v110, v2
	v_mov_b32_e32 v111, v2
	v_mov_b32_e32 v112, v2
	v_mov_b32_e32 v113, v2
	v_mov_b32_e32 v82, v2
	v_mov_b32_e32 v83, v2
	v_mov_b32_e32 v84, v2
	v_mov_b32_e32 v85, v2
	v_mov_b32_e32 v86, v2
	v_mov_b32_e32 v87, v2
	v_mov_b32_e32 v88, v2
	v_mov_b32_e32 v89, v2
	v_mov_b32_e32 v98, v2
	v_mov_b32_e32 v99, v2
	v_mov_b32_e32 v100, v2
	v_mov_b32_e32 v101, v2
	v_mov_b32_e32 v102, v2
	v_mov_b32_e32 v103, v2
	v_mov_b32_e32 v104, v2
	v_mov_b32_e32 v105, v2
	v_mov_b32_e32 v114, v2
	v_mov_b32_e32 v115, v2
	v_mov_b32_e32 v116, v2
	v_mov_b32_e32 v117, v2
	v_mov_b32_e32 v118, v2
	v_mov_b32_e32 v119, v2
	v_mov_b32_e32 v120, v2
	v_mov_b32_e32 v121, v2
	v_mov_b32_e32 v122, v2
	v_mov_b32_e32 v123, v2
	v_mov_b32_e32 v124, v2
	v_mov_b32_e32 v125, v2
	v_mov_b32_e32 v126, v2
	v_mov_b32_e32 v127, v2
	v_mov_b32_e32 v128, v2
	v_mov_b32_e32 v129, v2
.LBB0_1007:
	ds_read_b128 v[150:153], v145
	ds_read_b128 v[154:157], v145 offset:1024
	ds_read_b128 v[158:161], v145 offset:2048
	ds_read_b128 v[162:165], v145 offset:3072
	ds_read_b128 v[166:169], v147
	ds_read_b128 v[170:173], v147 offset:1024
	ds_read_b128 v[174:177], v147 offset:2048
	ds_read_b128 v[178:181], v147 offset:3072
	s_add_u32 s14, s12, 0xfffc0080
	s_addc_u32 s15, s13, -1
	s_cmp_eq_u32 s58, 12
	s_cselect_b32 s17, s52, s15
	s_cselect_b32 s16, s53, s14
	s_cselect_b32 s15, s54, s57
	s_cselect_b32 s14, s55, s56
	s_mov_b32 m0, s28
	v_lshl_add_u64 v[214:215], s[12:13], 0, v[140:141]
	ds_read_b128 v[182:185], v148
	ds_read_b128 v[186:189], v148 offset:1024
	ds_read_b128 v[190:193], v148 offset:2048
	ds_read_b128 v[194:197], v148 offset:3072
	ds_read_b128 v[198:201], v148 offset:4096
	ds_read_b128 v[202:205], v148 offset:5120
	ds_read_b128 v[206:209], v148 offset:6144
	ds_read_b128 v[210:213], v148 offset:7168
	global_load_lds_dwordx4 v[214:215], off
	v_lshl_add_u64 v[214:215], s[12:13], 0, v[142:143]
	s_mov_b32 m0, s29
	s_nop 0
	global_load_lds_dwordx4 v[214:215], off
	s_waitcnt vmcnt(8)
	s_waitcnt lgkmcnt(0)
	s_barrier
; #define PG8_STAGE(bufoff, gbase, voff) do { _Pragma("unroll") for (int _i = 0; _i < 2; ++_i) \
;         __builtin_amdgcn_global_load_lds((const unsigned*)((const char*)(gbase) + (voff)[_i]), (PG8_LAS unsigned*)(lds + (bufoff) + ldsw + _i * 8192), 16, 0, 0); } while (0)
; #define PG8_LDA(dst, b, h) do { _Pragma("unroll") for (int m = 0; m < 4; ++m) _Pragma("unroll") for (int k = 0; k < 2; ++k) dst[m][k] = *(const PG8_LAS bf16x8*)(lds + PG8_SA(b, h) + aoff + m * 2048 + k * 1024); } while (0)
; #define PG8_LDB(dst, b, h) do { _Pragma("unroll") for (int n = 0; n < 2; ++n) _Pragma("unroll") for (int k = 0; k < 2; ++k) dst[n][k] = *(const PG8_LAS bf16x8*)(lds + PG8_SB(b, h) + boff + n * 2048 + k * 1024); } while (0)
; #define PG8_MMA(ai, bj, At, Bt) do { __builtin_amdgcn_s_setprio(1); _Pragma("unroll") for (int m = 0; m < 4; ++m) _Pragma("unroll") for (int n = 0; n < 2; ++n) _Pragma("unroll") for (int k = 0; k < 2; ++k) \
;         acc[ai][bj][m][n] = __builtin_amdgcn_mfma_f32_16x16x32_bf16(Bt[n][k], At[m][k], acc[ai][bj][m][n], 0, 0, 0); __builtin_amdgcn_s_setprio(0); } while (0)
; #define PG8_WAIT_V(n) asm volatile("s_waitcnt vmcnt(" #n ")" ::: "memory")
; #define PG8_WAIT_L(n) asm volatile("s_waitcnt lgkmcnt(" #n ")" ::: "memory")
; #define PG8_BAR __builtin_amdgcn_s_barrier()
; #define PG8_SCHED __builtin_amdgcn_sched_barrier(0)
; template <class Epi, class Sched, bool ALIGN_EPI = false, bool SP2 = false>
; __device__ __forceinline__ void gemm_phase(PG8_LAS unsigned char* lds, const Gemm g, const Sched& S, const Epi& E) {
;     ...
;             PG8_WAIT_V(8); PG8_WAIT_L(0); PG8_BAR; PG8_MMA(0, 0, At, B0); PG8_MMA(0, 1, At, B1); PG8_BAR; PG8_SCHED;
;             PG8_LDA(At, 0, 1); PG8_STAGE(PG8_SB(0, 0), b2, voffB); PG8_STAGE(PG8_SB(0, 1), b2 + hstep, voffB); PG8_STAGE(PG8_SA(0, 0), a2, voffA);
;             PG8_WAIT_V(8); PG8_WAIT_L(0); PG8_BAR; PG8_MMA(1, 0, At, B0); PG8_MMA(1, 1, At, B1); PG8_BAR; PG8_SCHED;
;             PG8_LDB(B0, 1, 0); PG8_LDB(B1, 1, 1); PG8_SCHED; PG8_LDA(At, 1, 0); PG8_STAGE(PG8_SA(0, 1), a2 + hstep, voffA);
;             PG8_WAIT_V(8); PG8_WAIT_L(0); PG8_BAR; PG8_MMA(0, 0, At, B0); PG8_MMA(0, 1, At, B1); PG8_BAR; PG8_SCHED;
	s_setprio 1
	s_waitcnt lgkmcnt(0)
	v_mfma_f32_16x16x32_bf16 v[126:129], v[150:153], v[182:185], v[126:129]
	v_mfma_f32_16x16x32_bf16 v[122:125], v[158:161], v[182:185], v[122:125]
	v_mfma_f32_16x16x32_bf16 v[118:121], v[150:153], v[190:193], v[118:121]
	v_mfma_f32_16x16x32_bf16 v[114:117], v[158:161], v[190:193], v[114:117]
	v_mfma_f32_16x16x32_bf16 v[102:105], v[150:153], v[198:201], v[102:105]
	v_mfma_f32_16x16x32_bf16 v[98:101], v[158:161], v[198:201], v[98:101]
	v_mfma_f32_16x16x32_bf16 v[86:89], v[150:153], v[206:209], v[86:89]
	v_mfma_f32_16x16x32_bf16 v[82:85], v[158:161], v[206:209], v[82:85]
	v_mfma_f32_16x16x32_bf16 v[126:129], v[154:157], v[186:189], v[126:129]
	v_mfma_f32_16x16x32_bf16 v[122:125], v[162:165], v[186:189], v[122:125]
	v_mfma_f32_16x16x32_bf16 v[118:121], v[154:157], v[194:197], v[118:121]
	v_mfma_f32_16x16x32_bf16 v[114:117], v[162:165], v[194:197], v[114:117]
	v_mfma_f32_16x16x32_bf16 v[102:105], v[154:157], v[202:205], v[102:105]
	v_mfma_f32_16x16x32_bf16 v[98:101], v[162:165], v[202:205], v[98:101]
	v_mfma_f32_16x16x32_bf16 v[86:89], v[154:157], v[210:213], v[86:89]
	v_mfma_f32_16x16x32_bf16 v[82:85], v[162:165], v[210:213], v[82:85]
	s_setprio 0
	s_setprio 1
	v_mfma_f32_16x16x32_bf16 v[110:113], v[166:169], v[182:185], v[110:113]
	v_mfma_f32_16x16x32_bf16 v[106:109], v[174:177], v[182:185], v[106:109]
	v_mfma_f32_16x16x32_bf16 v[94:97], v[166:169], v[190:193], v[94:97]
	v_mfma_f32_16x16x32_bf16 v[90:93], v[174:177], v[190:193], v[90:93]
	v_mfma_f32_16x16x32_bf16 v[78:81], v[166:169], v[198:201], v[78:81]
	v_mfma_f32_16x16x32_bf16 v[74:77], v[174:177], v[198:201], v[74:77]
	v_mfma_f32_16x16x32_bf16 v[70:73], v[166:169], v[206:209], v[70:73]
	v_mfma_f32_16x16x32_bf16 v[66:69], v[174:177], v[206:209], v[66:69]
	v_mfma_f32_16x16x32_bf16 v[110:113], v[170:173], v[186:189], v[110:113]
	v_mfma_f32_16x16x32_bf16 v[106:109], v[178:181], v[186:189], v[106:109]
	v_mfma_f32_16x16x32_bf16 v[94:97], v[170:173], v[194:197], v[94:97]
	v_mfma_f32_16x16x32_bf16 v[90:93], v[178:181], v[194:197], v[90:93]
	v_mfma_f32_16x16x32_bf16 v[78:81], v[170:173], v[202:205], v[78:81]
	v_mfma_f32_16x16x32_bf16 v[74:77], v[178:181], v[202:205], v[74:77]
	v_mfma_f32_16x16x32_bf16 v[70:73], v[170:173], v[210:213], v[70:73]
	v_mfma_f32_16x16x32_bf16 v[66:69], v[178:181], v[210:213], v[66:69]
	s_setprio 0
	s_barrier
	s_mov_b32 m0, s33
	v_lshl_add_u64 v[214:215], s[14:15], 0, v[134:135]
	s_add_u32 s60, s14, 0x40000
	ds_read_b128 v[182:185], v148 offset:16384
	ds_read_b128 v[186:189], v148 offset:17408
	ds_read_b128 v[190:193], v148 offset:18432
	ds_read_b128 v[194:197], v148 offset:19456
	ds_read_b128 v[198:201], v148 offset:20480
	ds_read_b128 v[202:205], v148 offset:21504
	ds_read_b128 v[206:209], v148 offset:22528
	ds_read_b128 v[210:213], v148 offset:23552
	global_load_lds_dwordx4 v[214:215], off
	v_lshl_add_u64 v[216:217], s[14:15], 0, v[130:131]
	s_mov_b32 m0, s40
	s_addc_u32 s61, s15, 0
	s_add_i32 s59, s27, s19
	global_load_lds_dwordx4 v[216:217], off
	v_lshl_add_u64 v[218:219], s[60:61], 0, v[134:135]
	s_mov_b32 m0, s59
	v_lshl_add_u64 v[220:221], s[16:17], 0, v[132:133]
	global_load_lds_dwordx4 v[218:219], off
	v_lshl_add_u64 v[218:219], s[60:61], 0, v[130:131]
	s_add_i32 m0, s59, 0x2000
	s_nop 0
	global_load_lds_dwordx4 v[218:219], off
	v_lshl_add_u64 v[218:219], s[16:17], 0, v[136:137]
	s_mov_b32 m0, s20
	s_nop 0
	global_load_lds_dwordx4 v[218:219], off
	s_mov_b32 m0, s21
	s_nop 0
	global_load_lds_dwordx4 v[220:221], off
	s_waitcnt vmcnt(8)
	s_waitcnt lgkmcnt(0)
	s_barrier
	s_setprio 1
	s_waitcnt lgkmcnt(0)
	v_mfma_f32_16x16x32_bf16 v[62:65], v[150:153], v[182:185], v[62:65]
	v_mfma_f32_16x16x32_bf16 v[58:61], v[158:161], v[182:185], v[58:61]
	v_mfma_f32_16x16x32_bf16 v[54:57], v[150:153], v[190:193], v[54:57]
	v_mfma_f32_16x16x32_bf16 v[50:53], v[158:161], v[190:193], v[50:53]
	v_mfma_f32_16x16x32_bf16 v[38:41], v[150:153], v[198:201], v[38:41]
	v_mfma_f32_16x16x32_bf16 v[34:37], v[158:161], v[198:201], v[34:37]
	v_mfma_f32_16x16x32_bf16 v[22:25], v[150:153], v[206:209], v[22:25]
	v_mfma_f32_16x16x32_bf16 v[18:21], v[158:161], v[206:209], v[18:21]
	v_mfma_f32_16x16x32_bf16 v[62:65], v[154:157], v[186:189], v[62:65]
	v_mfma_f32_16x16x32_bf16 v[58:61], v[162:165], v[186:189], v[58:61]
	v_mfma_f32_16x16x32_bf16 v[54:57], v[154:157], v[194:197], v[54:57]
	v_mfma_f32_16x16x32_bf16 v[50:53], v[162:165], v[194:197], v[50:53]
	v_mfma_f32_16x16x32_bf16 v[38:41], v[154:157], v[202:205], v[38:41]
	v_mfma_f32_16x16x32_bf16 v[34:37], v[162:165], v[202:205], v[34:37]
	v_mfma_f32_16x16x32_bf16 v[22:25], v[154:157], v[210:213], v[22:25]
	v_mfma_f32_16x16x32_bf16 v[18:21], v[162:165], v[210:213], v[18:21]
	s_setprio 0
	s_setprio 1
	v_mfma_f32_16x16x32_bf16 v[46:49], v[166:169], v[182:185], v[46:49]
	v_mfma_f32_16x16x32_bf16 v[42:45], v[174:177], v[182:185], v[42:45]
	v_mfma_f32_16x16x32_bf16 v[30:33], v[166:169], v[190:193], v[30:33]
	v_mfma_f32_16x16x32_bf16 v[26:29], v[174:177], v[190:193], v[26:29]
	v_mfma_f32_16x16x32_bf16 v[14:17], v[166:169], v[198:201], v[14:17]
	v_mfma_f32_16x16x32_bf16 v[10:13], v[174:177], v[198:201], v[10:13]
	v_mfma_f32_16x16x32_bf16 v[6:9], v[166:169], v[206:209], v[6:9]
	v_mfma_f32_16x16x32_bf16 v[2:5], v[174:177], v[206:209], v[2:5]
	v_mfma_f32_16x16x32_bf16 v[46:49], v[170:173], v[186:189], v[46:49]
	v_mfma_f32_16x16x32_bf16 v[42:45], v[178:181], v[186:189], v[42:45]
	v_mfma_f32_16x16x32_bf16 v[30:33], v[170:173], v[194:197], v[30:33]
	v_mfma_f32_16x16x32_bf16 v[26:29], v[178:181], v[194:197], v[26:29]
	v_mfma_f32_16x16x32_bf16 v[14:17], v[170:173], v[202:205], v[14:17]
	v_mfma_f32_16x16x32_bf16 v[10:13], v[178:181], v[202:205], v[10:13]
	v_mfma_f32_16x16x32_bf16 v[6:9], v[170:173], v[210:213], v[6:9]
	v_mfma_f32_16x16x32_bf16 v[2:5], v[178:181], v[210:213], v[2:5]
	s_setprio 0
	s_barrier
; #define PG8_STAGE(bufoff, gbase, voff) do { _Pragma("unroll") for (int _i = 0; _i < 2; ++_i) \
;         __builtin_amdgcn_global_load_lds((const unsigned*)((const char*)(gbase) + (voff)[_i]), (PG8_LAS unsigned*)(lds + (bufoff) + ldsw + _i * 8192), 16, 0, 0); } while (0)
; #define PG8_LDA(dst, b, h) do { _Pragma("unroll") for (int m = 0; m < 4; ++m) _Pragma("unroll") for (int k = 0; k < 2; ++k) dst[m][k] = *(const PG8_LAS bf16x8*)(lds + PG8_SA(b, h) + aoff + m * 2048 + k * 1024); } while (0)
; #define PG8_MMA(ai, bj, At, Bt) do { __builtin_amdgcn_s_setprio(1); _Pragma("unroll") for (int m = 0; m < 4; ++m) _Pragma("unroll") for (int n = 0; n < 2; ++n) _Pragma("unroll") for (int k = 0; k < 2; ++k) \
;         acc[ai][bj][m][n] = __builtin_amdgcn_mfma_f32_16x16x32_bf16(Bt[n][k], At[m][k], acc[ai][bj][m][n], 0, 0, 0); __builtin_amdgcn_s_setprio(0); } while (0)
; #define PG8_WAIT_V(n) asm volatile("s_waitcnt vmcnt(" #n ")" ::: "memory")
; #define PG8_WAIT_L(n) asm volatile("s_waitcnt lgkmcnt(" #n ")" ::: "memory")
; #define PG8_BAR __builtin_amdgcn_s_barrier()
; #define PG8_SCHED __builtin_amdgcn_sched_barrier(0)
; template <class Epi, class Sched, bool ALIGN_EPI = false, bool SP2 = false>
; __device__ __forceinline__ void gemm_phase(PG8_LAS unsigned char* lds, const Gemm g, const Sched& S, const Epi& E) {
;     ...
;             PG8_WAIT_V(8); PG8_WAIT_L(0); PG8_BAR; PG8_MMA(0, 0, At, B0); PG8_MMA(0, 1, At, B1); PG8_BAR; PG8_SCHED;
;             PG8_LDA(At, 1, 1); PG8_STAGE(PG8_SB(1, 0), b3, voffB); PG8_STAGE(PG8_SB(1, 1), b3 + hstep, voffB); PG8_STAGE(PG8_SA(1, 0), a3, voffA);
;             PG8_WAIT_V(8); PG8_WAIT_L(0); PG8_BAR; PG8_MMA(1, 0, At, B0); PG8_MMA(1, 1, At, B1); PG8_BAR; PG8_SCHED;
	s_add_i32 s59, 0, 0x18000
	v_add_u32_e32 v149, s59, v144
	s_add_i32 s60, 0, 0x1c000
	ds_read_b128 v[150:153], v149
	ds_read_b128 v[154:157], v149 offset:1024
	ds_read_b128 v[158:161], v149 offset:2048
	ds_read_b128 v[162:165], v149 offset:3072
	v_add_u32_e32 v149, s60, v144
	ds_read_b128 v[166:169], v149
	ds_read_b128 v[170:173], v149 offset:1024
	ds_read_b128 v[174:177], v149 offset:2048
	ds_read_b128 v[178:181], v149 offset:3072
	s_add_u32 s16, s16, 0x40000
	s_addc_u32 s17, s17, 0
	s_mov_b32 m0, s22
	v_lshl_add_u64 v[222:223], s[16:17], 0, v[136:137]
	ds_read_b128 v[182:185], v148 offset:32768
	ds_read_b128 v[186:189], v148 offset:33792
	ds_read_b128 v[190:193], v148 offset:34816
	ds_read_b128 v[194:197], v148 offset:35840
	ds_read_b128 v[198:201], v148 offset:36864
	ds_read_b128 v[202:205], v148 offset:37888
	ds_read_b128 v[206:209], v148 offset:38912
	ds_read_b128 v[210:213], v148 offset:39936
	global_load_lds_dwordx4 v[222:223], off
	v_lshl_add_u64 v[222:223], s[16:17], 0, v[132:133]
	s_mov_b32 m0, s23
	s_nop 0
	global_load_lds_dwordx4 v[222:223], off
	s_waitcnt vmcnt(8)
	s_waitcnt lgkmcnt(0)
	s_barrier
	s_setprio 1
	s_waitcnt lgkmcnt(0)
	v_mfma_f32_16x16x32_bf16 v[126:129], v[150:153], v[182:185], v[126:129]
	v_mfma_f32_16x16x32_bf16 v[122:125], v[158:161], v[182:185], v[122:125]
	v_mfma_f32_16x16x32_bf16 v[118:121], v[150:153], v[190:193], v[118:121]
	v_mfma_f32_16x16x32_bf16 v[114:117], v[158:161], v[190:193], v[114:117]
	v_mfma_f32_16x16x32_bf16 v[102:105], v[150:153], v[198:201], v[102:105]
	v_mfma_f32_16x16x32_bf16 v[98:101], v[158:161], v[198:201], v[98:101]
	v_mfma_f32_16x16x32_bf16 v[86:89], v[150:153], v[206:209], v[86:89]
	v_mfma_f32_16x16x32_bf16 v[82:85], v[158:161], v[206:209], v[82:85]
	v_mfma_f32_16x16x32_bf16 v[126:129], v[154:157], v[186:189], v[126:129]
	v_mfma_f32_16x16x32_bf16 v[122:125], v[162:165], v[186:189], v[122:125]
	v_mfma_f32_16x16x32_bf16 v[118:121], v[154:157], v[194:197], v[118:121]
	v_mfma_f32_16x16x32_bf16 v[114:117], v[162:165], v[194:197], v[114:117]
	v_mfma_f32_16x16x32_bf16 v[102:105], v[154:157], v[202:205], v[102:105]
	v_mfma_f32_16x16x32_bf16 v[98:101], v[162:165], v[202:205], v[98:101]
	v_mfma_f32_16x16x32_bf16 v[86:89], v[154:157], v[210:213], v[86:89]
	v_mfma_f32_16x16x32_bf16 v[82:85], v[162:165], v[210:213], v[82:85]
	s_setprio 0
	s_setprio 1
	v_mfma_f32_16x16x32_bf16 v[110:113], v[166:169], v[182:185], v[110:113]
	v_mfma_f32_16x16x32_bf16 v[106:109], v[174:177], v[182:185], v[106:109]
	v_mfma_f32_16x16x32_bf16 v[94:97], v[166:169], v[190:193], v[94:97]
	v_mfma_f32_16x16x32_bf16 v[90:93], v[174:177], v[190:193], v[90:93]
	v_mfma_f32_16x16x32_bf16 v[78:81], v[166:169], v[198:201], v[78:81]
	v_mfma_f32_16x16x32_bf16 v[74:77], v[174:177], v[198:201], v[74:77]
	v_mfma_f32_16x16x32_bf16 v[70:73], v[166:169], v[206:209], v[70:73]
	v_mfma_f32_16x16x32_bf16 v[66:69], v[174:177], v[206:209], v[66:69]
	v_mfma_f32_16x16x32_bf16 v[110:113], v[170:173], v[186:189], v[110:113]
	v_mfma_f32_16x16x32_bf16 v[106:109], v[178:181], v[186:189], v[106:109]
	v_mfma_f32_16x16x32_bf16 v[94:97], v[170:173], v[194:197], v[94:97]
	v_mfma_f32_16x16x32_bf16 v[90:93], v[178:181], v[194:197], v[90:93]
	v_mfma_f32_16x16x32_bf16 v[78:81], v[170:173], v[202:205], v[78:81]
	v_mfma_f32_16x16x32_bf16 v[74:77], v[178:181], v[202:205], v[74:77]
	v_mfma_f32_16x16x32_bf16 v[70:73], v[170:173], v[210:213], v[70:73]
	v_mfma_f32_16x16x32_bf16 v[66:69], v[178:181], v[210:213], v[66:69]
	s_setprio 0
	s_barrier
	s_add_i32 s16, s59, s19
	v_lshl_add_u64 v[214:215], v[214:215], 0, s[6:7]
	s_mov_b32 m0, s16
	ds_read_b128 v[182:185], v148 offset:49152
	ds_read_b128 v[186:189], v148 offset:50176
	ds_read_b128 v[190:193], v148 offset:51200
	ds_read_b128 v[194:197], v148 offset:52224
	ds_read_b128 v[198:201], v148 offset:53248
	ds_read_b128 v[202:205], v148 offset:54272
	ds_read_b128 v[206:209], v148 offset:55296
	ds_read_b128 v[210:213], v148 offset:56320
	global_load_lds_dwordx4 v[214:215], off
	s_add_i32 m0, s16, 0x2000
	s_add_u32 s14, s14, 0x40080
	v_lshl_add_u64 v[214:215], v[216:217], 0, s[6:7]
	s_addc_u32 s15, s15, 0
	s_add_i32 s16, s60, s19
	global_load_lds_dwordx4 v[214:215], off
	v_lshl_add_u64 v[214:215], s[14:15], 0, v[134:135]
	s_mov_b32 m0, s16
	s_nop 0
	global_load_lds_dwordx4 v[214:215], off
	v_lshl_add_u64 v[214:215], s[14:15], 0, v[130:131]
	s_add_i32 m0, s16, 0x2000
	s_nop 0
	global_load_lds_dwordx4 v[214:215], off
	v_lshl_add_u64 v[214:215], v[218:219], 0, s[6:7]
	s_mov_b32 m0, s25
	s_nop 0
	global_load_lds_dwordx4 v[214:215], off
	v_lshl_add_u64 v[214:215], v[220:221], 0, s[6:7]
	s_mov_b32 m0, s26
	s_nop 0
	global_load_lds_dwordx4 v[214:215], off
	s_waitcnt vmcnt(8)
	s_waitcnt lgkmcnt(0)
	s_barrier
; #define PG8_STAGE(bufoff, gbase, voff) do { _Pragma("unroll") for (int _i = 0; _i < 2; ++_i) \
;         __builtin_amdgcn_global_load_lds((const unsigned*)((const char*)(gbase) + (voff)[_i]), (PG8_LAS unsigned*)(lds + (bufoff) + ldsw + _i * 8192), 16, 0, 0); } while (0)
; #define PG8_LDA(dst, b, h) do { _Pragma("unroll") for (int m = 0; m < 4; ++m) _Pragma("unroll") for (int k = 0; k < 2; ++k) dst[m][k] = *(const PG8_LAS bf16x8*)(lds + PG8_SA(b, h) + aoff + m * 2048 + k * 1024); } while (0)
; #define PG8_LDB(dst, b, h) do { _Pragma("unroll") for (int n = 0; n < 2; ++n) _Pragma("unroll") for (int k = 0; k < 2; ++k) dst[n][k] = *(const PG8_LAS bf16x8*)(lds + PG8_SB(b, h) + boff + n * 2048 + k * 1024); } while (0)
; #define PG8_MMA(ai, bj, At, Bt) do { __builtin_amdgcn_s_setprio(1); _Pragma("unroll") for (int m = 0; m < 4; ++m) _Pragma("unroll") for (int n = 0; n < 2; ++n) _Pragma("unroll") for (int k = 0; k < 2; ++k) \
;         acc[ai][bj][m][n] = __builtin_amdgcn_mfma_f32_16x16x32_bf16(Bt[n][k], At[m][k], acc[ai][bj][m][n], 0, 0, 0); __builtin_amdgcn_s_setprio(0); } while (0)
; #define PG8_WAIT_V(n) asm volatile("s_waitcnt vmcnt(" #n ")" ::: "memory")
; #define PG8_WAIT_L(n) asm volatile("s_waitcnt lgkmcnt(" #n ")" ::: "memory")
; #define PG8_BAR __builtin_amdgcn_s_barrier()
; #define PG8_SCHED __builtin_amdgcn_sched_barrier(0)
; template <class Epi, class Sched, bool ALIGN_EPI = false, bool SP2 = false>
; __device__ __forceinline__ void gemm_phase(PG8_LAS unsigned char* lds, const Gemm g, const Sched& S, const Epi& E) {
;     ...
;             PG8_LDB(B0, 0, 0); PG8_LDB(B1, 0, 1); PG8_SCHED; PG8_LDA(At, 0, 0); PG8_STAGE(PG8_SA(1, 1), a1 + hstep, voffA);
;             PG8_WAIT_V(8); PG8_WAIT_L(0); PG8_BAR; PG8_MMA(0, 0, At, B0); PG8_MMA(0, 1, At, B1); PG8_BAR; PG8_SCHED;
;     ...
;             PG8_WAIT_V(8); PG8_WAIT_L(0); PG8_BAR; PG8_MMA(1, 0, At, B0); PG8_MMA(1, 1, At, B1); PG8_BAR; PG8_SCHED;
	s_setprio 1
	s_waitcnt lgkmcnt(0)
	v_mfma_f32_16x16x32_bf16 v[62:65], v[150:153], v[182:185], v[62:65]
	v_mfma_f32_16x16x32_bf16 v[58:61], v[158:161], v[182:185], v[58:61]
	v_mfma_f32_16x16x32_bf16 v[54:57], v[150:153], v[190:193], v[54:57]
	v_mfma_f32_16x16x32_bf16 v[50:53], v[158:161], v[190:193], v[50:53]
	v_mfma_f32_16x16x32_bf16 v[38:41], v[150:153], v[198:201], v[38:41]
	v_mfma_f32_16x16x32_bf16 v[34:37], v[158:161], v[198:201], v[34:37]
	v_mfma_f32_16x16x32_bf16 v[22:25], v[150:153], v[206:209], v[22:25]
	v_mfma_f32_16x16x32_bf16 v[18:21], v[158:161], v[206:209], v[18:21]
	v_mfma_f32_16x16x32_bf16 v[62:65], v[154:157], v[186:189], v[62:65]
	v_mfma_f32_16x16x32_bf16 v[58:61], v[162:165], v[186:189], v[58:61]
	v_mfma_f32_16x16x32_bf16 v[54:57], v[154:157], v[194:197], v[54:57]
	v_mfma_f32_16x16x32_bf16 v[50:53], v[162:165], v[194:197], v[50:53]
	v_mfma_f32_16x16x32_bf16 v[38:41], v[154:157], v[202:205], v[38:41]
	v_mfma_f32_16x16x32_bf16 v[34:37], v[162:165], v[202:205], v[34:37]
	v_mfma_f32_16x16x32_bf16 v[22:25], v[154:157], v[210:213], v[22:25]
	v_mfma_f32_16x16x32_bf16 v[18:21], v[162:165], v[210:213], v[18:21]
	s_setprio 0
	s_setprio 1
	v_mfma_f32_16x16x32_bf16 v[46:49], v[166:169], v[182:185], v[46:49]
	v_mfma_f32_16x16x32_bf16 v[42:45], v[174:177], v[182:185], v[42:45]
	v_mfma_f32_16x16x32_bf16 v[30:33], v[166:169], v[190:193], v[30:33]
	v_mfma_f32_16x16x32_bf16 v[26:29], v[174:177], v[190:193], v[26:29]
	v_mfma_f32_16x16x32_bf16 v[14:17], v[166:169], v[198:201], v[14:17]
	v_mfma_f32_16x16x32_bf16 v[10:13], v[174:177], v[198:201], v[10:13]
	v_mfma_f32_16x16x32_bf16 v[6:9], v[166:169], v[206:209], v[6:9]
	v_mfma_f32_16x16x32_bf16 v[2:5], v[174:177], v[206:209], v[2:5]
	v_mfma_f32_16x16x32_bf16 v[46:49], v[170:173], v[186:189], v[46:49]
	v_mfma_f32_16x16x32_bf16 v[42:45], v[178:181], v[186:189], v[42:45]
	v_mfma_f32_16x16x32_bf16 v[30:33], v[170:173], v[194:197], v[30:33]
	v_mfma_f32_16x16x32_bf16 v[26:29], v[178:181], v[194:197], v[26:29]
	v_mfma_f32_16x16x32_bf16 v[14:17], v[170:173], v[202:205], v[14:17]
	v_mfma_f32_16x16x32_bf16 v[10:13], v[178:181], v[202:205], v[10:13]
	v_mfma_f32_16x16x32_bf16 v[6:9], v[170:173], v[210:213], v[6:9]
	v_mfma_f32_16x16x32_bf16 v[2:5], v[178:181], v[210:213], v[2:5]
	s_setprio 0
	s_barrier
	s_add_i32 s58, s58, 2
	s_add_u32 s12, s12, 0x100
	s_addc_u32 s13, s13, 0
	s_add_u32 s56, s56, 0x100
	s_addc_u32 s57, s57, 0
	s_cmp_gt_u32 s58, 13
	s_cbranch_scc0 .LBB0_1007
	s_branch .Lpeel_after_5
.Lpeel_5:
	ds_read_b128 v[150:153], v145
	ds_read_b128 v[154:157], v145 offset:1024
	ds_read_b128 v[158:161], v145 offset:2048
	ds_read_b128 v[162:165], v145 offset:3072
	ds_read_b128 v[166:169], v147
	ds_read_b128 v[170:173], v147 offset:1024
	ds_read_b128 v[174:177], v147 offset:2048
	ds_read_b128 v[178:181], v147 offset:3072
	s_add_u32 s14, s12, 0xfffc0080
	s_addc_u32 s15, s13, -1
	s_cmp_eq_u32 s58, 12
	s_cselect_b32 s17, s52, s15
	s_cselect_b32 s16, s53, s14
	s_cselect_b32 s15, s54, s57
	s_cselect_b32 s14, s55, s56
	s_mov_b32 m0, s28
	v_lshl_add_u64 v[214:215], s[12:13], 0, v[140:141]
	ds_read_b128 v[182:185], v148
	ds_read_b128 v[186:189], v148 offset:1024
	ds_read_b128 v[190:193], v148 offset:2048
	ds_read_b128 v[194:197], v148 offset:3072
	ds_read_b128 v[198:201], v148 offset:4096
	ds_read_b128 v[202:205], v148 offset:5120
	ds_read_b128 v[206:209], v148 offset:6144
	ds_read_b128 v[210:213], v148 offset:7168
	global_load_lds_dwordx4 v[214:215], off
	v_lshl_add_u64 v[214:215], s[12:13], 0, v[142:143]
	s_mov_b32 m0, s29
	s_nop 0
	global_load_lds_dwordx4 v[214:215], off
	s_waitcnt vmcnt(24)
	s_waitcnt lgkmcnt(0)
	s_barrier
	s_setprio 1
	s_waitcnt lgkmcnt(0)
	v_mfma_f32_16x16x32_bf16 v[126:129], v[150:153], v[182:185], 0
	v_mfma_f32_16x16x32_bf16 v[122:125], v[158:161], v[182:185], 0
	v_mfma_f32_16x16x32_bf16 v[118:121], v[150:153], v[190:193], 0
	v_mfma_f32_16x16x32_bf16 v[114:117], v[158:161], v[190:193], 0
	v_mfma_f32_16x16x32_bf16 v[102:105], v[150:153], v[198:201], 0
	v_mfma_f32_16x16x32_bf16 v[98:101], v[158:161], v[198:201], 0
	v_mfma_f32_16x16x32_bf16 v[86:89], v[150:153], v[206:209], 0
	v_mfma_f32_16x16x32_bf16 v[82:85], v[158:161], v[206:209], 0
	v_mfma_f32_16x16x32_bf16 v[126:129], v[154:157], v[186:189], v[126:129]
	v_mfma_f32_16x16x32_bf16 v[122:125], v[162:165], v[186:189], v[122:125]
	v_mfma_f32_16x16x32_bf16 v[118:121], v[154:157], v[194:197], v[118:121]
	v_mfma_f32_16x16x32_bf16 v[114:117], v[162:165], v[194:197], v[114:117]
	v_mfma_f32_16x16x32_bf16 v[102:105], v[154:157], v[202:205], v[102:105]
	v_mfma_f32_16x16x32_bf16 v[98:101], v[162:165], v[202:205], v[98:101]
	v_mfma_f32_16x16x32_bf16 v[86:89], v[154:157], v[210:213], v[86:89]
	v_mfma_f32_16x16x32_bf16 v[82:85], v[162:165], v[210:213], v[82:85]
	s_setprio 0
	s_setprio 1
	v_mfma_f32_16x16x32_bf16 v[110:113], v[166:169], v[182:185], 0
	v_mfma_f32_16x16x32_bf16 v[106:109], v[174:177], v[182:185], 0
	v_mfma_f32_16x16x32_bf16 v[94:97], v[166:169], v[190:193], 0
	v_mfma_f32_16x16x32_bf16 v[90:93], v[174:177], v[190:193], 0
	v_mfma_f32_16x16x32_bf16 v[78:81], v[166:169], v[198:201], 0
	v_mfma_f32_16x16x32_bf16 v[74:77], v[174:177], v[198:201], 0
	v_mfma_f32_16x16x32_bf16 v[70:73], v[166:169], v[206:209], 0
	v_mfma_f32_16x16x32_bf16 v[66:69], v[174:177], v[206:209], 0
	v_mfma_f32_16x16x32_bf16 v[110:113], v[170:173], v[186:189], v[110:113]
	v_mfma_f32_16x16x32_bf16 v[106:109], v[178:181], v[186:189], v[106:109]
	v_mfma_f32_16x16x32_bf16 v[94:97], v[170:173], v[194:197], v[94:97]
	v_mfma_f32_16x16x32_bf16 v[90:93], v[178:181], v[194:197], v[90:93]
	v_mfma_f32_16x16x32_bf16 v[78:81], v[170:173], v[202:205], v[78:81]
	v_mfma_f32_16x16x32_bf16 v[74:77], v[178:181], v[202:205], v[74:77]
	v_mfma_f32_16x16x32_bf16 v[70:73], v[170:173], v[210:213], v[70:73]
	v_mfma_f32_16x16x32_bf16 v[66:69], v[178:181], v[210:213], v[66:69]
	s_setprio 0
	s_barrier
; #define PG8_STAGE(bufoff, gbase, voff) do { _Pragma("unroll") for (int _i = 0; _i < 2; ++_i) \
;         __builtin_amdgcn_global_load_lds((const unsigned*)((const char*)(gbase) + (voff)[_i]), (PG8_LAS unsigned*)(lds + (bufoff) + ldsw + _i * 8192), 16, 0, 0); } while (0)
; #define PG8_LDA(dst, b, h) do { _Pragma("unroll") for (int m = 0; m < 4; ++m) _Pragma("unroll") for (int k = 0; k < 2; ++k) dst[m][k] = *(const PG8_LAS bf16x8*)(lds + PG8_SA(b, h) + aoff + m * 2048 + k * 1024); } while (0)
; #define PG8_LDB(dst, b, h) do { _Pragma("unroll") for (int n = 0; n < 2; ++n) _Pragma("unroll") for (int k = 0; k < 2; ++k) dst[n][k] = *(const PG8_LAS bf16x8*)(lds + PG8_SB(b, h) + boff + n * 2048 + k * 1024); } while (0)
; #define PG8_MMA(ai, bj, At, Bt) do { __builtin_amdgcn_s_setprio(1); _Pragma("unroll") for (int m = 0; m < 4; ++m) _Pragma("unroll") for (int n = 0; n < 2; ++n) _Pragma("unroll") for (int k = 0; k < 2; ++k) \
;         acc[ai][bj][m][n] = __builtin_amdgcn_mfma_f32_16x16x32_bf16(Bt[n][k], At[m][k], acc[ai][bj][m][n], 0, 0, 0); __builtin_amdgcn_s_setprio(0); } while (0)
; #define PG8_WAIT_V(n) asm volatile("s_waitcnt vmcnt(" #n ")" ::: "memory")
; #define PG8_WAIT_L(n) asm volatile("s_waitcnt lgkmcnt(" #n ")" ::: "memory")
; #define PG8_BAR __builtin_amdgcn_s_barrier()
; #define PG8_SCHED __builtin_amdgcn_sched_barrier(0)
; template <class Epi, class Sched, bool ALIGN_EPI = false, bool SP2 = false>
; __device__ __forceinline__ void gemm_phase(PG8_LAS unsigned char* lds, const Gemm g, const Sched& S, const Epi& E) {
;     ...
;             PG8_LDA(At, 0, 1); PG8_STAGE(PG8_SB(0, 0), b2, voffB); PG8_STAGE(PG8_SB(0, 1), b2 + hstep, voffB); PG8_STAGE(PG8_SA(0, 0), a2, voffA);
;             PG8_WAIT_V(8); PG8_WAIT_L(0); PG8_BAR; PG8_MMA(1, 0, At, B0); PG8_MMA(1, 1, At, B1); PG8_BAR; PG8_SCHED;
;             PG8_LDB(B0, 1, 0); PG8_LDB(B1, 1, 1); PG8_SCHED; PG8_LDA(At, 1, 0); PG8_STAGE(PG8_SA(0, 1), a2 + hstep, voffA);
;             PG8_WAIT_V(8); PG8_WAIT_L(0); PG8_BAR; PG8_MMA(0, 0, At, B0); PG8_MMA(0, 1, At, B1); PG8_BAR; PG8_SCHED;
	s_mov_b32 m0, s33
	v_lshl_add_u64 v[214:215], s[14:15], 0, v[134:135]
	s_add_u32 s60, s14, 0x40000
	ds_read_b128 v[182:185], v148 offset:16384
	ds_read_b128 v[186:189], v148 offset:17408
	ds_read_b128 v[190:193], v148 offset:18432
	ds_read_b128 v[194:197], v148 offset:19456
	ds_read_b128 v[198:201], v148 offset:20480
	ds_read_b128 v[202:205], v148 offset:21504
	ds_read_b128 v[206:209], v148 offset:22528
	ds_read_b128 v[210:213], v148 offset:23552
	global_load_lds_dwordx4 v[214:215], off
	v_lshl_add_u64 v[216:217], s[14:15], 0, v[130:131]
	s_mov_b32 m0, s40
	s_addc_u32 s61, s15, 0
	s_add_i32 s59, s27, s19
	global_load_lds_dwordx4 v[216:217], off
	v_lshl_add_u64 v[218:219], s[60:61], 0, v[134:135]
	s_mov_b32 m0, s59
	v_lshl_add_u64 v[220:221], s[16:17], 0, v[132:133]
	global_load_lds_dwordx4 v[218:219], off
	v_lshl_add_u64 v[218:219], s[60:61], 0, v[130:131]
	s_add_i32 m0, s59, 0x2000
	s_nop 0
	global_load_lds_dwordx4 v[218:219], off
	v_lshl_add_u64 v[218:219], s[16:17], 0, v[136:137]
	s_mov_b32 m0, s20
	s_nop 0
	global_load_lds_dwordx4 v[218:219], off
	s_mov_b32 m0, s21
	s_nop 0
	global_load_lds_dwordx4 v[220:221], off
	s_waitcnt vmcnt(24)
	s_waitcnt lgkmcnt(0)
	s_barrier
	s_setprio 1
	s_waitcnt lgkmcnt(0)
	v_mfma_f32_16x16x32_bf16 v[62:65], v[150:153], v[182:185], 0
	v_mfma_f32_16x16x32_bf16 v[58:61], v[158:161], v[182:185], 0
	v_mfma_f32_16x16x32_bf16 v[54:57], v[150:153], v[190:193], 0
	v_mfma_f32_16x16x32_bf16 v[50:53], v[158:161], v[190:193], 0
	v_mfma_f32_16x16x32_bf16 v[38:41], v[150:153], v[198:201], 0
	v_mfma_f32_16x16x32_bf16 v[34:37], v[158:161], v[198:201], 0
	v_mfma_f32_16x16x32_bf16 v[22:25], v[150:153], v[206:209], 0
	v_mfma_f32_16x16x32_bf16 v[18:21], v[158:161], v[206:209], 0
	v_mfma_f32_16x16x32_bf16 v[62:65], v[154:157], v[186:189], v[62:65]
	v_mfma_f32_16x16x32_bf16 v[58:61], v[162:165], v[186:189], v[58:61]
	v_mfma_f32_16x16x32_bf16 v[54:57], v[154:157], v[194:197], v[54:57]
	v_mfma_f32_16x16x32_bf16 v[50:53], v[162:165], v[194:197], v[50:53]
	v_mfma_f32_16x16x32_bf16 v[38:41], v[154:157], v[202:205], v[38:41]
	v_mfma_f32_16x16x32_bf16 v[34:37], v[162:165], v[202:205], v[34:37]
	v_mfma_f32_16x16x32_bf16 v[22:25], v[154:157], v[210:213], v[22:25]
	v_mfma_f32_16x16x32_bf16 v[18:21], v[162:165], v[210:213], v[18:21]
	s_setprio 0
	s_setprio 1
	v_mfma_f32_16x16x32_bf16 v[46:49], v[166:169], v[182:185], 0
	v_mfma_f32_16x16x32_bf16 v[42:45], v[174:177], v[182:185], 0
	v_mfma_f32_16x16x32_bf16 v[30:33], v[166:169], v[190:193], 0
	v_mfma_f32_16x16x32_bf16 v[26:29], v[174:177], v[190:193], 0
	v_mfma_f32_16x16x32_bf16 v[14:17], v[166:169], v[198:201], 0
	v_mfma_f32_16x16x32_bf16 v[10:13], v[174:177], v[198:201], 0
	v_mfma_f32_16x16x32_bf16 v[6:9], v[166:169], v[206:209], 0
	v_mfma_f32_16x16x32_bf16 v[2:5], v[174:177], v[206:209], 0
	v_mfma_f32_16x16x32_bf16 v[46:49], v[170:173], v[186:189], v[46:49]
	v_mfma_f32_16x16x32_bf16 v[42:45], v[178:181], v[186:189], v[42:45]
	v_mfma_f32_16x16x32_bf16 v[30:33], v[170:173], v[194:197], v[30:33]
	v_mfma_f32_16x16x32_bf16 v[26:29], v[178:181], v[194:197], v[26:29]
	v_mfma_f32_16x16x32_bf16 v[14:17], v[170:173], v[202:205], v[14:17]
	v_mfma_f32_16x16x32_bf16 v[10:13], v[178:181], v[202:205], v[10:13]
	v_mfma_f32_16x16x32_bf16 v[6:9], v[170:173], v[210:213], v[6:9]
	v_mfma_f32_16x16x32_bf16 v[2:5], v[178:181], v[210:213], v[2:5]
	s_setprio 0
	s_barrier
	s_add_i32 s59, 0, 0x18000
	v_add_u32_e32 v149, s59, v144
	s_add_i32 s60, 0, 0x1c000
	ds_read_b128 v[150:153], v149
	ds_read_b128 v[154:157], v149 offset:1024
	ds_read_b128 v[158:161], v149 offset:2048
	ds_read_b128 v[162:165], v149 offset:3072
	v_add_u32_e32 v149, s60, v144
	ds_read_b128 v[166:169], v149
	ds_read_b128 v[170:173], v149 offset:1024
	ds_read_b128 v[174:177], v149 offset:2048
	ds_read_b128 v[178:181], v149 offset:3072
	s_add_u32 s16, s16, 0x40000
	s_addc_u32 s17, s17, 0
	s_mov_b32 m0, s22
	v_lshl_add_u64 v[222:223], s[16:17], 0, v[136:137]
	ds_read_b128 v[182:185], v148 offset:32768
	ds_read_b128 v[186:189], v148 offset:33792
	ds_read_b128 v[190:193], v148 offset:34816
	ds_read_b128 v[194:197], v148 offset:35840
	ds_read_b128 v[198:201], v148 offset:36864
	ds_read_b128 v[202:205], v148 offset:37888
	ds_read_b128 v[206:209], v148 offset:38912
	ds_read_b128 v[210:213], v148 offset:39936
	global_load_lds_dwordx4 v[222:223], off
	v_lshl_add_u64 v[222:223], s[16:17], 0, v[132:133]
	s_mov_b32 m0, s23
	s_nop 0
	global_load_lds_dwordx4 v[222:223], off
	s_waitcnt vmcnt(8)
	s_waitcnt lgkmcnt(0)
	s_barrier
; #define PG8_STAGE(bufoff, gbase, voff) do { _Pragma("unroll") for (int _i = 0; _i < 2; ++_i) \
;         __builtin_amdgcn_global_load_lds((const unsigned*)((const char*)(gbase) + (voff)[_i]), (PG8_LAS unsigned*)(lds + (bufoff) + ldsw + _i * 8192), 16, 0, 0); } while (0)
; #define PG8_LDA(dst, b, h) do { _Pragma("unroll") for (int m = 0; m < 4; ++m) _Pragma("unroll") for (int k = 0; k < 2; ++k) dst[m][k] = *(const PG8_LAS bf16x8*)(lds + PG8_SA(b, h) + aoff + m * 2048 + k * 1024); } while (0)
; #define PG8_MMA(ai, bj, At, Bt) do { __builtin_amdgcn_s_setprio(1); _Pragma("unroll") for (int m = 0; m < 4; ++m) _Pragma("unroll") for (int n = 0; n < 2; ++n) _Pragma("unroll") for (int k = 0; k < 2; ++k) \
;         acc[ai][bj][m][n] = __builtin_amdgcn_mfma_f32_16x16x32_bf16(Bt[n][k], At[m][k], acc[ai][bj][m][n], 0, 0, 0); __builtin_amdgcn_s_setprio(0); } while (0)
; #define PG8_WAIT_V(n) asm volatile("s_waitcnt vmcnt(" #n ")" ::: "memory")
; #define PG8_WAIT_L(n) asm volatile("s_waitcnt lgkmcnt(" #n ")" ::: "memory")
; #define PG8_BAR __builtin_amdgcn_s_barrier()
; #define PG8_SCHED __builtin_amdgcn_sched_barrier(0)
; template <class Epi, class Sched, bool ALIGN_EPI = false, bool SP2 = false>
; __device__ __forceinline__ void gemm_phase(PG8_LAS unsigned char* lds, const Gemm g, const Sched& S, const Epi& E) {
;     ...
;             PG8_WAIT_V(8); PG8_WAIT_L(0); PG8_BAR; PG8_MMA(0, 0, At, B0); PG8_MMA(0, 1, At, B1); PG8_BAR; PG8_SCHED;
;             PG8_LDA(At, 1, 1); PG8_STAGE(PG8_SB(1, 0), b3, voffB); PG8_STAGE(PG8_SB(1, 1), b3 + hstep, voffB); PG8_STAGE(PG8_SA(1, 0), a3, voffA);
;             PG8_WAIT_V(8); PG8_WAIT_L(0); PG8_BAR; PG8_MMA(1, 0, At, B0); PG8_MMA(1, 1, At, B1); PG8_BAR; PG8_SCHED;
	s_setprio 1
	s_waitcnt lgkmcnt(0)
	v_mfma_f32_16x16x32_bf16 v[126:129], v[150:153], v[182:185], v[126:129]
	v_mfma_f32_16x16x32_bf16 v[122:125], v[158:161], v[182:185], v[122:125]
	v_mfma_f32_16x16x32_bf16 v[118:121], v[150:153], v[190:193], v[118:121]
	v_mfma_f32_16x16x32_bf16 v[114:117], v[158:161], v[190:193], v[114:117]
	v_mfma_f32_16x16x32_bf16 v[102:105], v[150:153], v[198:201], v[102:105]
	v_mfma_f32_16x16x32_bf16 v[98:101], v[158:161], v[198:201], v[98:101]
	v_mfma_f32_16x16x32_bf16 v[86:89], v[150:153], v[206:209], v[86:89]
	v_mfma_f32_16x16x32_bf16 v[82:85], v[158:161], v[206:209], v[82:85]
	v_mfma_f32_16x16x32_bf16 v[126:129], v[154:157], v[186:189], v[126:129]
	v_mfma_f32_16x16x32_bf16 v[122:125], v[162:165], v[186:189], v[122:125]
	v_mfma_f32_16x16x32_bf16 v[118:121], v[154:157], v[194:197], v[118:121]
	v_mfma_f32_16x16x32_bf16 v[114:117], v[162:165], v[194:197], v[114:117]
	v_mfma_f32_16x16x32_bf16 v[102:105], v[154:157], v[202:205], v[102:105]
	v_mfma_f32_16x16x32_bf16 v[98:101], v[162:165], v[202:205], v[98:101]
	v_mfma_f32_16x16x32_bf16 v[86:89], v[154:157], v[210:213], v[86:89]
	v_mfma_f32_16x16x32_bf16 v[82:85], v[162:165], v[210:213], v[82:85]
	s_setprio 0
	s_setprio 1
	v_mfma_f32_16x16x32_bf16 v[110:113], v[166:169], v[182:185], v[110:113]
	v_mfma_f32_16x16x32_bf16 v[106:109], v[174:177], v[182:185], v[106:109]
	v_mfma_f32_16x16x32_bf16 v[94:97], v[166:169], v[190:193], v[94:97]
	v_mfma_f32_16x16x32_bf16 v[90:93], v[174:177], v[190:193], v[90:93]
	v_mfma_f32_16x16x32_bf16 v[78:81], v[166:169], v[198:201], v[78:81]
	v_mfma_f32_16x16x32_bf16 v[74:77], v[174:177], v[198:201], v[74:77]
	v_mfma_f32_16x16x32_bf16 v[70:73], v[166:169], v[206:209], v[70:73]
	v_mfma_f32_16x16x32_bf16 v[66:69], v[174:177], v[206:209], v[66:69]
	v_mfma_f32_16x16x32_bf16 v[110:113], v[170:173], v[186:189], v[110:113]
	v_mfma_f32_16x16x32_bf16 v[106:109], v[178:181], v[186:189], v[106:109]
	v_mfma_f32_16x16x32_bf16 v[94:97], v[170:173], v[194:197], v[94:97]
	v_mfma_f32_16x16x32_bf16 v[90:93], v[178:181], v[194:197], v[90:93]
	v_mfma_f32_16x16x32_bf16 v[78:81], v[170:173], v[202:205], v[78:81]
	v_mfma_f32_16x16x32_bf16 v[74:77], v[178:181], v[202:205], v[74:77]
	v_mfma_f32_16x16x32_bf16 v[70:73], v[170:173], v[210:213], v[70:73]
	v_mfma_f32_16x16x32_bf16 v[66:69], v[178:181], v[210:213], v[66:69]
	s_setprio 0
	s_barrier
	s_add_i32 s16, s59, s19
	v_lshl_add_u64 v[214:215], v[214:215], 0, s[6:7]
	s_mov_b32 m0, s16
	ds_read_b128 v[182:185], v148 offset:49152
	ds_read_b128 v[186:189], v148 offset:50176
	ds_read_b128 v[190:193], v148 offset:51200
	ds_read_b128 v[194:197], v148 offset:52224
	ds_read_b128 v[198:201], v148 offset:53248
	ds_read_b128 v[202:205], v148 offset:54272
	ds_read_b128 v[206:209], v148 offset:55296
	ds_read_b128 v[210:213], v148 offset:56320
	global_load_lds_dwordx4 v[214:215], off
	s_add_i32 m0, s16, 0x2000
	s_add_u32 s14, s14, 0x40080
	v_lshl_add_u64 v[214:215], v[216:217], 0, s[6:7]
	s_addc_u32 s15, s15, 0
	s_add_i32 s16, s60, s19
	global_load_lds_dwordx4 v[214:215], off
	v_lshl_add_u64 v[214:215], s[14:15], 0, v[134:135]
	s_mov_b32 m0, s16
	s_nop 0
	global_load_lds_dwordx4 v[214:215], off
	v_lshl_add_u64 v[214:215], s[14:15], 0, v[130:131]
	s_add_i32 m0, s16, 0x2000
	s_nop 0
	global_load_lds_dwordx4 v[214:215], off
	v_lshl_add_u64 v[214:215], v[218:219], 0, s[6:7]
	s_mov_b32 m0, s25
	s_nop 0
	global_load_lds_dwordx4 v[214:215], off
	v_lshl_add_u64 v[214:215], v[220:221], 0, s[6:7]
	s_mov_b32 m0, s26
	s_nop 0
	global_load_lds_dwordx4 v[214:215], off
	s_waitcnt vmcnt(8)
	s_waitcnt lgkmcnt(0)
	s_barrier
	s_setprio 1
	s_waitcnt lgkmcnt(0)
	v_mfma_f32_16x16x32_bf16 v[62:65], v[150:153], v[182:185], v[62:65]
	v_mfma_f32_16x16x32_bf16 v[58:61], v[158:161], v[182:185], v[58:61]
	v_mfma_f32_16x16x32_bf16 v[54:57], v[150:153], v[190:193], v[54:57]
	v_mfma_f32_16x16x32_bf16 v[50:53], v[158:161], v[190:193], v[50:53]
	v_mfma_f32_16x16x32_bf16 v[38:41], v[150:153], v[198:201], v[38:41]
	v_mfma_f32_16x16x32_bf16 v[34:37], v[158:161], v[198:201], v[34:37]
	v_mfma_f32_16x16x32_bf16 v[22:25], v[150:153], v[206:209], v[22:25]
	v_mfma_f32_16x16x32_bf16 v[18:21], v[158:161], v[206:209], v[18:21]
	v_mfma_f32_16x16x32_bf16 v[62:65], v[154:157], v[186:189], v[62:65]
	v_mfma_f32_16x16x32_bf16 v[58:61], v[162:165], v[186:189], v[58:61]
	v_mfma_f32_16x16x32_bf16 v[54:57], v[154:157], v[194:197], v[54:57]
	v_mfma_f32_16x16x32_bf16 v[50:53], v[162:165], v[194:197], v[50:53]
	v_mfma_f32_16x16x32_bf16 v[38:41], v[154:157], v[202:205], v[38:41]
	v_mfma_f32_16x16x32_bf16 v[34:37], v[162:165], v[202:205], v[34:37]
	v_mfma_f32_16x16x32_bf16 v[22:25], v[154:157], v[210:213], v[22:25]
	v_mfma_f32_16x16x32_bf16 v[18:21], v[162:165], v[210:213], v[18:21]
	s_setprio 0
	s_setprio 1
	v_mfma_f32_16x16x32_bf16 v[46:49], v[166:169], v[182:185], v[46:49]
	v_mfma_f32_16x16x32_bf16 v[42:45], v[174:177], v[182:185], v[42:45]
	v_mfma_f32_16x16x32_bf16 v[30:33], v[166:169], v[190:193], v[30:33]
	v_mfma_f32_16x16x32_bf16 v[26:29], v[174:177], v[190:193], v[26:29]
	v_mfma_f32_16x16x32_bf16 v[14:17], v[166:169], v[198:201], v[14:17]
	v_mfma_f32_16x16x32_bf16 v[10:13], v[174:177], v[198:201], v[10:13]
	v_mfma_f32_16x16x32_bf16 v[6:9], v[166:169], v[206:209], v[6:9]
	v_mfma_f32_16x16x32_bf16 v[2:5], v[174:177], v[206:209], v[2:5]
	v_mfma_f32_16x16x32_bf16 v[46:49], v[170:173], v[186:189], v[46:49]
	v_mfma_f32_16x16x32_bf16 v[42:45], v[178:181], v[186:189], v[42:45]
	v_mfma_f32_16x16x32_bf16 v[30:33], v[170:173], v[194:197], v[30:33]
	v_mfma_f32_16x16x32_bf16 v[26:29], v[178:181], v[194:197], v[26:29]
	v_mfma_f32_16x16x32_bf16 v[14:17], v[170:173], v[202:205], v[14:17]
	v_mfma_f32_16x16x32_bf16 v[10:13], v[178:181], v[202:205], v[10:13]
	v_mfma_f32_16x16x32_bf16 v[6:9], v[170:173], v[210:213], v[6:9]
	v_mfma_f32_16x16x32_bf16 v[2:5], v[178:181], v[210:213], v[2:5]
	s_setprio 0
	s_barrier
	s_add_i32 s58, s58, 2
	s_add_u32 s12, s12, 0x100
	s_addc_u32 s13, s13, 0
	s_add_u32 s56, s56, 0x100
	s_addc_u32 s57, s57, 0
	s_cmp_gt_u32 s58, 13
	s_branch .LBB0_1007
; DI unsigned pk2(float lo, float hi) { f32x2 v = {lo, hi}; bf16x2_t b = __builtin_convertvector(v, bf16x2_t); return __builtin_bit_cast(unsigned, b); }
; template <class Epi, class Sched, bool ALIGN_EPI = false, bool SP2 = false>
; __device__ __forceinline__ void gemm_phase(PG8_LAS unsigned char* lds, const Gemm g, const Sched& S, const Epi& E) {
;     ...
;         if constexpr (!Epi::AFTER_DRAIN) { E(acc, cur, wr, wc, fr, fq); S.done(cur); }
;         if (!has_next) break;
;     DI void operator()(const f32x4 (&acc)[2][2][4][2], const pg8::Unit& u, int wr, int wc, int fr, int fq) const {
;         const int row0 = u.pm * 256 + wr * 64 + fr, col0 = wc * 32 + 8 * fq;
; #pragma unroll
;         for (int ai = 0; ai < 2; ++ai)
; #pragma unroll
;             for (int m = 0; m < 4; ++m) {
;                 const size_t off = (size_t)(row0 + ai * 128 + m * 16) * 256 + col0;
; #pragma unroll
;                 for (int bj = 0; bj < 2; ++bj) { const f32x4 a = acc[ai][bj][m][0], b = acc[ai][bj][m][1];
;                     *(u32x4*)(Z + off + bj * 128) = (u32x4){pk2(a[0], a[1]), pk2(a[2], a[3]), pk2(b[0], b[1]), pk2(b[2], b[3])}; }
;             }
.Lpeel_after_5:
	s_and_b64 vcc, exec, s[8:9]
	s_cbranch_vccz .LBB0_1010
	s_barrier
.LBB0_1010:
	v_lshl_add_u32 v150, s51, 8, v1
	v_ashrrev_i32_e32 v151, 31, v150
	v_lshlrev_b64 v[152:153], 9, v[150:151]
	v_cvt_pk_bf16_f32 v126, v126, v127
	v_cvt_pk_bf16_f32 v127, v128, v129
	v_cvt_pk_bf16_f32 v128, v122, v123
	v_lshl_add_u64 v[122:123], v[138:139], 0, v[152:153]
	s_mov_b64 s[12:13], 0x10000
	v_cvt_pk_bf16_f32 v62, v62, v63
	v_cvt_pk_bf16_f32 v63, v64, v65
	v_cvt_pk_bf16_f32 v64, v58, v59
	v_lshl_add_u64 v[58:59], v[122:123], 0, s[12:13]
	s_mov_b32 s12, 0x10000
	v_cvt_pk_bf16_f32 v65, v60, v61
	v_add_co_u32_e32 v60, vcc, s12, v122
	v_cvt_pk_bf16_f32 v46, v46, v47
	v_cvt_pk_bf16_f32 v47, v48, v49
	v_cvt_pk_bf16_f32 v48, v42, v43
	v_cvt_pk_bf16_f32 v49, v44, v45
	s_mov_b64 s[12:13], 0x12000
	v_cvt_pk_bf16_f32 v110, v110, v111
	v_cvt_pk_bf16_f32 v111, v112, v113
	v_cvt_pk_bf16_f32 v112, v106, v107
	v_or_b32_e32 v106, 16, v150
	v_addc_co_u32_e32 v61, vcc, 0, v123, vcc
	global_store_dwordx4 v[58:59], v[46:49], off offset:256
	v_cvt_pk_bf16_f32 v113, v108, v109
	v_ashrrev_i32_e32 v107, 31, v106
	v_lshl_add_u64 v[46:47], v[122:123], 0, s[12:13]
	s_mov_b32 s12, 0x12000
	v_add_co_u32_e32 v48, vcc, s12, v122
	v_cvt_pk_bf16_f32 v30, v30, v31
	v_cvt_pk_bf16_f32 v31, v32, v33
	v_cvt_pk_bf16_f32 v32, v26, v27
	v_cvt_pk_bf16_f32 v33, v28, v29
	s_mov_b64 s[12:13], 0x14000
	global_store_dwordx4 v[122:123], v[110:113], off offset:256
	v_cvt_pk_bf16_f32 v94, v94, v95
	v_cvt_pk_bf16_f32 v95, v96, v97
	v_lshlrev_b64 v[110:111], 9, v[106:107]
	v_cvt_pk_bf16_f32 v96, v90, v91
	v_or_b32_e32 v90, 32, v150
	v_addc_co_u32_e32 v49, vcc, 0, v123, vcc
	global_store_dwordx4 v[46:47], v[30:33], off offset:256
	v_lshl_add_u64 v[110:111], v[138:139], 0, v[110:111]
	v_cvt_pk_bf16_f32 v97, v92, v93
	v_lshl_add_u64 v[30:31], v[122:123], 0, s[12:13]
	s_mov_b32 s12, 0x14000
	v_ashrrev_i32_e32 v91, 31, v90
	v_add_co_u32_e32 v32, vcc, s12, v122
	v_cvt_pk_bf16_f32 v14, v14, v15
	v_cvt_pk_bf16_f32 v15, v16, v17
	v_cvt_pk_bf16_f32 v16, v10, v11
	v_cvt_pk_bf16_f32 v17, v12, v13
	s_mov_b64 s[12:13], 0x16000
	global_store_dwordx4 v[110:111], v[94:97], off offset:256
	v_cvt_pk_bf16_f32 v78, v78, v79
	v_cvt_pk_bf16_f32 v79, v80, v81
	v_lshlrev_b64 v[94:95], 9, v[90:91]
	v_cvt_pk_bf16_f32 v80, v74, v75
	v_or_b32_e32 v74, 48, v150
	v_addc_co_u32_e32 v33, vcc, 0, v123, vcc
	global_store_dwordx4 v[30:31], v[14:17], off offset:256
	v_lshl_add_u64 v[94:95], v[138:139], 0, v[94:95]
	v_cvt_pk_bf16_f32 v81, v76, v77
	v_lshl_add_u64 v[14:15], v[122:123], 0, s[12:13]
	s_mov_b32 s12, 0x16000
	v_ashrrev_i32_e32 v75, 31, v74
	v_add_co_u32_e32 v16, vcc, s12, v122
	global_store_dwordx4 v[94:95], v[78:81], off offset:256
	s_nop 0
	v_addc_co_u32_e32 v17, vcc, 0, v123, vcc
	v_lshlrev_b64 v[78:79], 9, v[74:75]
	v_cvt_pk_bf16_f32 v129, v124, v125
	v_cvt_pk_bf16_f32 v106, v118, v119
	v_cvt_pk_bf16_f32 v107, v120, v121
	v_cvt_pk_bf16_f32 v108, v114, v115
	v_cvt_pk_bf16_f32 v109, v116, v117
	v_cvt_pk_bf16_f32 v90, v102, v103
	v_cvt_pk_bf16_f32 v91, v104, v105
	v_cvt_pk_bf16_f32 v92, v98, v99
	v_cvt_pk_bf16_f32 v93, v100, v101
	v_cvt_pk_bf16_f32 v74, v86, v87
	v_cvt_pk_bf16_f32 v75, v88, v89
	v_cvt_pk_bf16_f32 v76, v82, v83
	v_cvt_pk_bf16_f32 v77, v84, v85
	v_lshl_add_u64 v[78:79], v[138:139], 0, v[78:79]
	v_cvt_pk_bf16_f32 v70, v70, v71
	v_cvt_pk_bf16_f32 v71, v72, v73
	v_cvt_pk_bf16_f32 v72, v66, v67
	v_cvt_pk_bf16_f32 v73, v68, v69
	v_cvt_pk_bf16_f32 v42, v54, v55
	v_cvt_pk_bf16_f32 v43, v56, v57
	v_cvt_pk_bf16_f32 v44, v50, v51
	v_cvt_pk_bf16_f32 v45, v52, v53
	v_cvt_pk_bf16_f32 v26, v38, v39
	v_cvt_pk_bf16_f32 v27, v40, v41
	v_cvt_pk_bf16_f32 v28, v34, v35
	v_cvt_pk_bf16_f32 v29, v36, v37
	v_cvt_pk_bf16_f32 v10, v22, v23
	v_cvt_pk_bf16_f32 v11, v24, v25
	v_cvt_pk_bf16_f32 v12, v18, v19
	v_cvt_pk_bf16_f32 v13, v20, v21
	v_cvt_pk_bf16_f32 v6, v6, v7
	v_cvt_pk_bf16_f32 v7, v8, v9
	v_cvt_pk_bf16_f32 v8, v2, v3
	v_cvt_pk_bf16_f32 v9, v4, v5
	s_andn2_b64 vcc, exec, s[10:11]
	s_mov_b64 s[10:11], -1
	global_store_dwordx4 v[122:123], v[126:129], off
	global_store_dwordx4 v[110:111], v[106:109], off
	global_store_dwordx4 v[94:95], v[90:93], off
	global_store_dwordx4 v[78:79], v[74:77], off
	global_store_dwordx4 v[78:79], v[70:73], off offset:256
	global_store_dwordx4 v[60:61], v[62:65], off
	global_store_dwordx4 v[48:49], v[42:45], off
	global_store_dwordx4 v[32:33], v[26:29], off
	global_store_dwordx4 v[16:17], v[10:13], off
	global_store_dwordx4 v[14:15], v[6:9], off offset:256
	s_mov_b32 s98, 1
	s_cbranch_vccnz .LBB0_1005
	s_andn2_b64 vcc, exec, s[4:5]
	s_cbranch_vccnz .LBB0_1004
	s_barrier
	s_branch .LBB0_1004

; #define PG8_STAGE(bufoff, gbase, voff) do { _Pragma("unroll") for (int _i = 0; _i < 2; ++_i) \
;         __builtin_amdgcn_global_load_lds((const unsigned*)((const char*)(gbase) + (voff)[_i]), (PG8_LAS unsigned*)(lds + (bufoff) + ldsw + _i * 8192), 16, 0, 0); } while (0)
; #define PG8_WAIT_V(n) asm volatile("s_waitcnt vmcnt(" #n ")" ::: "memory")
; #define PG8_BAR __builtin_amdgcn_s_barrier()
; template <class Epi, class Sched, bool ALIGN_EPI = false, bool SP2 = false>
; __device__ __forceinline__ void gemm_phase(PG8_LAS unsigned char* lds, const Gemm g, const Sched& S, const Epi& E) {
;     ...
;     if constexpr (SP2) {
;         PG8_STAGE(PG8_SB(0, 0), cB, voffB); PG8_STAGE(PG8_SB(0, 1), cB + hstep, voffB); PG8_STAGE(PG8_SA(0, 0), cA, voffA); PG8_STAGE(PG8_SA(0, 1), cA + hstep, voffA);
;         if (wr == 1) PG8_BAR;
;         PG8_WAIT_V(2); PG8_BAR;
;         PG8_STAGE(PG8_SB(1, 0), cB + kstep, voffB); PG8_STAGE(PG8_SA(1, 0), cA + kstep, voffA); PG8_STAGE(PG8_SB(1, 1), cB + hstep + kstep, voffB);
;         PG8_WAIT_V(6); PG8_BAR;
.LBB0_1083:
	s_add_u32 s12, s2, 0x40080
	s_mov_b64 s[6:7], 0x80
	s_addc_u32 s13, s3, 0
	s_add_i32 m0, s19, 0x18000
	v_lshl_add_u64 v[4:5], v[4:5], 0, s[6:7]
	s_waitcnt vmcnt(2)
	s_barrier
	global_load_lds_dwordx4 v[4:5], off
	v_lshl_add_u64 v[2:3], v[2:3], 0, s[6:7]
	s_add_i32 m0, s19, 0x1a000
	s_add_i32 s24, s19, 0x8000
	global_load_lds_dwordx4 v[2:3], off
	v_lshl_add_u64 v[2:3], v[6:7], 0, s[6:7]
	s_mov_b32 m0, s24
	s_add_i32 s25, s19, 0xa000
	global_load_lds_dwordx4 v[2:3], off
	v_lshl_add_u64 v[2:3], v[8:9], 0, s[6:7]
	s_mov_b32 m0, s25
	s_lshl_b32 s9, s9, 5
	global_load_lds_dwordx4 v[2:3], off
	s_add_i32 m0, s19, 0x1c000
	v_lshl_add_u64 v[2:3], s[12:13], 0, v[134:135]
	global_load_lds_dwordx4 v[2:3], off
	v_lshl_add_u64 v[2:3], s[12:13], 0, v[130:131]
	s_add_i32 m0, s19, 0x1e000
	v_mov_b32_e32 v141, v135
	global_load_lds_dwordx4 v[2:3], off
	v_lshrrev_b32_e32 v3, 1, v12
	v_and_b32_e32 v3, 24, v3
	v_and_b32_e32 v2, 15, v12
	v_lshlrev_b32_e32 v4, 1, v3
	v_lshl_or_b32 v1, s10, 6, v2
	v_lshl_or_b32 v2, v2, 6, v4
	v_lshlrev_b32_e32 v4, 2, v12
	s_lshl_b32 s10, s10, 13
	v_and_b32_e32 v4, 32, v4
	v_bitop3_b32 v5, v2, s10, v4 bitop3:0xde
	s_and_b32 s10, s9, 0x60
	s_lshl_b32 s9, s10, 7
	v_bitop3_b32 v144, v2, s9, v4 bitop3:0xde
	v_or_b32_e32 v2, s10, v3
	v_lshlrev_b32_e32 v2, 1, v2
	v_mov_b32_e32 v3, v135
	v_lshl_add_u64 v[138:139], s[34:35], 0, v[2:3]
	v_lshlrev_b32_e32 v2, 14, v15
	v_and_b32_e32 v2, 0xffff8000, v2
	v_lshl_add_u32 v2, v14, 11, v2
	v_and_b32_e32 v3, 1, v15
	v_lshl_or_b32 v2, v3, 6, v2
	v_lshl_add_u32 v140, v16, 1, v2
	v_lshlrev_b32_e32 v2, 14, v10
	s_cmpk_lt_u32 s8, 0x100
	v_and_b32_e32 v2, 0xffff8000, v2
	s_waitcnt vmcnt(6)
	s_cselect_b64 s[8:9], -1, 0
	v_lshl_add_u32 v2, v11, 11, v2
	v_and_b32_e32 v3, 1, v10
	s_add_i32 s29, 0, 0x10000
	v_lshl_or_b32 v2, v3, 6, v2
	v_add_u32_e32 v145, s29, v144
	s_add_i32 s26, 0, 0x14000
	s_add_i32 s29, s29, s18
	v_lshl_add_u32 v142, v13, 1, v2
	v_mov_b32_e32 v143, v135
	v_add_u32_e32 v147, s26, v144
	v_add_u32_e32 v148, 0, v5
	s_add_i32 s27, s19, 0xc000
	s_add_i32 s28, s19, 0xe000
	s_add_i32 s33, s29, 0x2000
	s_barrier
	s_waitcnt vmcnt(0)
	s_mov_b32 s98, 0
	s_branch .LBB0_1086

; #define PG8_STAGE(bufoff, gbase, voff) do { _Pragma("unroll") for (int _i = 0; _i < 2; ++_i) \
;         __builtin_amdgcn_global_load_lds((const unsigned*)((const char*)(gbase) + (voff)[_i]), (PG8_LAS unsigned*)(lds + (bufoff) + ldsw + _i * 8192), 16, 0, 0); } while (0)
; #define PG8_LDA(dst, b, h) do { _Pragma("unroll") for (int m = 0; m < 4; ++m) _Pragma("unroll") for (int k = 0; k < 2; ++k) dst[m][k] = *(const PG8_LAS bf16x8*)(lds + PG8_SA(b, h) + aoff + m * 2048 + k * 1024); } while (0)
; #define PG8_LDB(dst, b, h) do { _Pragma("unroll") for (int n = 0; n < 2; ++n) _Pragma("unroll") for (int k = 0; k < 2; ++k) dst[n][k] = *(const PG8_LAS bf16x8*)(lds + PG8_SB(b, h) + boff + n * 2048 + k * 1024); } while (0)
; #define PG8_MMA(ai, bj, At, Bt) do { __builtin_amdgcn_s_setprio(1); _Pragma("unroll") for (int m = 0; m < 4; ++m) _Pragma("unroll") for (int n = 0; n < 2; ++n) _Pragma("unroll") for (int k = 0; k < 2; ++k) \
;         acc[ai][bj][m][n] = __builtin_amdgcn_mfma_f32_16x16x32_bf16(Bt[n][k], At[m][k], acc[ai][bj][m][n], 0, 0, 0); __builtin_amdgcn_s_setprio(0); } while (0)
; #define PG8_WAIT_V(n) asm volatile("s_waitcnt vmcnt(" #n ")" ::: "memory")
; #define PG8_WAIT_L(n) asm volatile("s_waitcnt lgkmcnt(" #n ")" ::: "memory")
; template <class Epi, class Sched, bool ALIGN_EPI = false, bool SP2 = false>
; __device__ __forceinline__ void gemm_phase(PG8_LAS unsigned char* lds, const Gemm g, const Sched& S, const Epi& E) {
;     ...
;         const bool has_next = S.next(ui + 1, nxt);
;         const char* nA = has_next ? (const char*)g.A + (size_t)nxt.pm * tstep + nxt.kb : cA; const char* nB = has_next ? (const char*)g.Bt + (size_t)nxt.pn * tstep + nxt.kb : cB;
;         for (int t = 0; t < nt; t += 2) {
;             const bool last = (t == nt - 2);
;             const char* a1 = cA + (size_t)(t + 1) * kstep;
;             const char* a2 = last ? nA : cA + (size_t)(t + 2) * kstep; const char* b2 = last ? nB : cB + (size_t)(t + 2) * kstep;
;             const char* a3 = a2 + kstep; const char* b3 = b2 + kstep;
;             if (last && has_next) S.a_ready(nxt);
;             if constexpr (SP2) {
;             PG8_LDB(B0, 0, 0); PG8_LDB(B1, 0, 1); PG8_SCHED; PG8_LDA(At, 0, 0); PG8_STAGE(PG8_SA(1, 1), a1 + hstep, voffA);
;             PG8_WAIT_V(8); PG8_WAIT_L(0); PG8_BAR; PG8_MMA(0, 0, At, B0); PG8_MMA(0, 1, At, B1); PG8_BAR; PG8_SCHED;
.LBB0_1086:
	s_add_i32 s23, s23, 1
	s_mov_b64 s[12:13], s[0:1]
	s_mul_i32 s0, s23, s78
	s_add_i32 s16, s0, s66
	s_cmpk_lt_i32 s16, 0x220
	s_mul_hi_i32 s0, s16, 0x78787879
	s_cselect_b64 s[10:11], -1, 0
	s_lshr_b32 s1, s0, 31
	s_ashr_i32 s0, s0, 7
	s_mov_b64 s[14:15], s[2:3]
	s_mov_b32 s2, s38
	s_add_i32 s38, s0, s1
	v_readlane_b32 s39, v253, 2
	s_and_b64 s[0:1], s[10:11], exec
	s_cselect_b32 s0, s16, s39
	s_cselect_b32 s2, s38, s2
	s_ashr_i32 s1, s0, 31
	s_lshl_b64 s[0:1], s[0:1], 19
	s_add_u32 s0, s56, s0
	s_addc_u32 s1, s57, s1
	v_writelane_b32 v253, s16, 2
	s_and_b64 s[16:17], s[10:11], exec
	s_cselect_b32 s40, s1, s13
	s_cselect_b32 s41, s0, s12
	s_ashr_i32 s3, s2, 31
	s_lshl_b64 s[2:3], s[2:3], 19
	s_add_u32 s2, s30, s2
	s_addc_u32 s3, s31, s3
	s_and_b64 s[16:17], s[10:11], exec
	s_cselect_b32 s46, s3, s15
	s_cselect_b32 s47, s2, s14
	s_add_u32 s12, s12, 0x40080
	s_addc_u32 s13, s13, 0
	s_add_u32 s50, s14, 0x100
	v_mov_b32_e32 v2, 0
	s_addc_u32 s51, s15, 0
	s_mov_b32 s52, -2
	s_cmp_lg_u32 s98, 0
	s_cbranch_scc1 .Lpeel_6
	v_mov_b32_e32 v3, v2
	v_mov_b32_e32 v4, v2
	v_mov_b32_e32 v5, v2
	v_mov_b32_e32 v6, v2
	v_mov_b32_e32 v7, v2
	v_mov_b32_e32 v8, v2
	v_mov_b32_e32 v9, v2
	v_mov_b32_e32 v10, v2
	v_mov_b32_e32 v11, v2
	v_mov_b32_e32 v12, v2
	v_mov_b32_e32 v13, v2
	v_mov_b32_e32 v14, v2
	v_mov_b32_e32 v15, v2
	v_mov_b32_e32 v16, v2
	v_mov_b32_e32 v17, v2
	v_mov_b32_e32 v26, v2
	v_mov_b32_e32 v27, v2
	v_mov_b32_e32 v28, v2
	v_mov_b32_e32 v29, v2
	v_mov_b32_e32 v30, v2
	v_mov_b32_e32 v31, v2
	v_mov_b32_e32 v32, v2
	v_mov_b32_e32 v33, v2
	v_mov_b32_e32 v42, v2
	v_mov_b32_e32 v43, v2
	v_mov_b32_e32 v44, v2
	v_mov_b32_e32 v45, v2
	v_mov_b32_e32 v46, v2
	v_mov_b32_e32 v47, v2
	v_mov_b32_e32 v48, v2
	v_mov_b32_e32 v49, v2
	v_mov_b32_e32 v18, v2
	v_mov_b32_e32 v19, v2
	v_mov_b32_e32 v20, v2
	v_mov_b32_e32 v21, v2
	v_mov_b32_e32 v22, v2
	v_mov_b32_e32 v23, v2
	v_mov_b32_e32 v24, v2
	v_mov_b32_e32 v25, v2
	v_mov_b32_e32 v34, v2
	v_mov_b32_e32 v35, v2
	v_mov_b32_e32 v36, v2
	v_mov_b32_e32 v37, v2
	v_mov_b32_e32 v38, v2
	v_mov_b32_e32 v39, v2
	v_mov_b32_e32 v40, v2
	v_mov_b32_e32 v41, v2
	v_mov_b32_e32 v50, v2
	v_mov_b32_e32 v51, v2
	v_mov_b32_e32 v52, v2
	v_mov_b32_e32 v53, v2
	v_mov_b32_e32 v54, v2
	v_mov_b32_e32 v55, v2
	v_mov_b32_e32 v56, v2
	v_mov_b32_e32 v57, v2
	v_mov_b32_e32 v58, v2
	v_mov_b32_e32 v59, v2
	v_mov_b32_e32 v60, v2
	v_mov_b32_e32 v61, v2
	v_mov_b32_e32 v62, v2
	v_mov_b32_e32 v63, v2
	v_mov_b32_e32 v64, v2
	v_mov_b32_e32 v65, v2
	v_mov_b32_e32 v66, v2
	v_mov_b32_e32 v67, v2
	v_mov_b32_e32 v68, v2
	v_mov_b32_e32 v69, v2
	v_mov_b32_e32 v70, v2
	v_mov_b32_e32 v71, v2
	v_mov_b32_e32 v72, v2
	v_mov_b32_e32 v73, v2
	v_mov_b32_e32 v74, v2
	v_mov_b32_e32 v75, v2
	v_mov_b32_e32 v76, v2
	v_mov_b32_e32 v77, v2
	v_mov_b32_e32 v78, v2
	v_mov_b32_e32 v79, v2
	v_mov_b32_e32 v80, v2
	v_mov_b32_e32 v81, v2
	v_mov_b32_e32 v90, v2
	v_mov_b32_e32 v91, v2
	v_mov_b32_e32 v92, v2
	v_mov_b32_e32 v93, v2
	v_mov_b32_e32 v94, v2
	v_mov_b32_e32 v95, v2
	v_mov_b32_e32 v96, v2
	v_mov_b32_e32 v97, v2
	v_mov_b32_e32 v106, v2
	v_mov_b32_e32 v107, v2
	v_mov_b32_e32 v108, v2
	v_mov_b32_e32 v109, v2
	v_mov_b32_e32 v110, v2
	v_mov_b32_e32 v111, v2
	v_mov_b32_e32 v112, v2
	v_mov_b32_e32 v113, v2
	v_mov_b32_e32 v82, v2
	v_mov_b32_e32 v83, v2
	v_mov_b32_e32 v84, v2
	v_mov_b32_e32 v85, v2
	v_mov_b32_e32 v86, v2
	v_mov_b32_e32 v87, v2
	v_mov_b32_e32 v88, v2
	v_mov_b32_e32 v89, v2
	v_mov_b32_e32 v98, v2
	v_mov_b32_e32 v99, v2
	v_mov_b32_e32 v100, v2
	v_mov_b32_e32 v101, v2
	v_mov_b32_e32 v102, v2
	v_mov_b32_e32 v103, v2
	v_mov_b32_e32 v104, v2
	v_mov_b32_e32 v105, v2
	v_mov_b32_e32 v114, v2
	v_mov_b32_e32 v115, v2
	v_mov_b32_e32 v116, v2
	v_mov_b32_e32 v117, v2
	v_mov_b32_e32 v118, v2
	v_mov_b32_e32 v119, v2
	v_mov_b32_e32 v120, v2
	v_mov_b32_e32 v121, v2
	v_mov_b32_e32 v122, v2
	v_mov_b32_e32 v123, v2
	v_mov_b32_e32 v124, v2
	v_mov_b32_e32 v125, v2
	v_mov_b32_e32 v126, v2
	v_mov_b32_e32 v127, v2
	v_mov_b32_e32 v128, v2
	v_mov_b32_e32 v129, v2
.LBB0_1087:
	ds_read_b128 v[150:153], v145
	ds_read_b128 v[154:157], v145 offset:1024
	ds_read_b128 v[158:161], v145 offset:2048
	ds_read_b128 v[162:165], v145 offset:3072
	ds_read_b128 v[166:169], v147
	ds_read_b128 v[170:173], v147 offset:1024
	ds_read_b128 v[174:177], v147 offset:2048
	ds_read_b128 v[178:181], v147 offset:3072
	s_add_u32 s14, s12, 0xfffc0080
	s_addc_u32 s15, s13, -1
	s_cmp_eq_u32 s52, 12
	s_cselect_b32 s17, s40, s15
	s_cselect_b32 s16, s41, s14
	s_cselect_b32 s15, s46, s51
	s_cselect_b32 s14, s47, s50
	s_mov_b32 m0, s27
	v_lshl_add_u64 v[214:215], s[12:13], 0, v[140:141]
	ds_read_b128 v[182:185], v148
	ds_read_b128 v[186:189], v148 offset:1024
	ds_read_b128 v[190:193], v148 offset:2048
	ds_read_b128 v[194:197], v148 offset:3072
	ds_read_b128 v[198:201], v148 offset:4096
	ds_read_b128 v[202:205], v148 offset:5120
	ds_read_b128 v[206:209], v148 offset:6144
	ds_read_b128 v[210:213], v148 offset:7168
	global_load_lds_dwordx4 v[214:215], off
	v_lshl_add_u64 v[214:215], s[12:13], 0, v[142:143]
	s_mov_b32 m0, s28
	s_nop 0
	global_load_lds_dwordx4 v[214:215], off
	s_waitcnt vmcnt(8)
	s_waitcnt lgkmcnt(0)
	s_barrier
; #define PG8_STAGE(bufoff, gbase, voff) do { _Pragma("unroll") for (int _i = 0; _i < 2; ++_i) \
;         __builtin_amdgcn_global_load_lds((const unsigned*)((const char*)(gbase) + (voff)[_i]), (PG8_LAS unsigned*)(lds + (bufoff) + ldsw + _i * 8192), 16, 0, 0); } while (0)
; #define PG8_LDA(dst, b, h) do { _Pragma("unroll") for (int m = 0; m < 4; ++m) _Pragma("unroll") for (int k = 0; k < 2; ++k) dst[m][k] = *(const PG8_LAS bf16x8*)(lds + PG8_SA(b, h) + aoff + m * 2048 + k * 1024); } while (0)
; #define PG8_LDB(dst, b, h) do { _Pragma("unroll") for (int n = 0; n < 2; ++n) _Pragma("unroll") for (int k = 0; k < 2; ++k) dst[n][k] = *(const PG8_LAS bf16x8*)(lds + PG8_SB(b, h) + boff + n * 2048 + k * 1024); } while (0)
; #define PG8_MMA(ai, bj, At, Bt) do { __builtin_amdgcn_s_setprio(1); _Pragma("unroll") for (int m = 0; m < 4; ++m) _Pragma("unroll") for (int n = 0; n < 2; ++n) _Pragma("unroll") for (int k = 0; k < 2; ++k) \
;         acc[ai][bj][m][n] = __builtin_amdgcn_mfma_f32_16x16x32_bf16(Bt[n][k], At[m][k], acc[ai][bj][m][n], 0, 0, 0); __builtin_amdgcn_s_setprio(0); } while (0)
; #define PG8_WAIT_V(n) asm volatile("s_waitcnt vmcnt(" #n ")" ::: "memory")
; #define PG8_WAIT_L(n) asm volatile("s_waitcnt lgkmcnt(" #n ")" ::: "memory")
; #define PG8_BAR __builtin_amdgcn_s_barrier()
; #define PG8_SCHED __builtin_amdgcn_sched_barrier(0)
; template <class Epi, class Sched, bool ALIGN_EPI = false, bool SP2 = false>
; __device__ __forceinline__ void gemm_phase(PG8_LAS unsigned char* lds, const Gemm g, const Sched& S, const Epi& E) {
;     ...
;             PG8_WAIT_V(8); PG8_WAIT_L(0); PG8_BAR; PG8_MMA(0, 0, At, B0); PG8_MMA(0, 1, At, B1); PG8_BAR; PG8_SCHED;
;             PG8_LDA(At, 0, 1); PG8_STAGE(PG8_SB(0, 0), b2, voffB); PG8_STAGE(PG8_SB(0, 1), b2 + hstep, voffB); PG8_STAGE(PG8_SA(0, 0), a2, voffA);
;             PG8_WAIT_V(8); PG8_WAIT_L(0); PG8_BAR; PG8_MMA(1, 0, At, B0); PG8_MMA(1, 1, At, B1); PG8_BAR; PG8_SCHED;
;             PG8_LDB(B0, 1, 0); PG8_LDB(B1, 1, 1); PG8_SCHED; PG8_LDA(At, 1, 0); PG8_STAGE(PG8_SA(0, 1), a2 + hstep, voffA);
;             PG8_WAIT_V(8); PG8_WAIT_L(0); PG8_BAR; PG8_MMA(0, 0, At, B0); PG8_MMA(0, 1, At, B1); PG8_BAR; PG8_SCHED;
	s_setprio 1
	s_waitcnt lgkmcnt(0)
	v_mfma_f32_16x16x32_bf16 v[126:129], v[150:153], v[182:185], v[126:129]
	v_mfma_f32_16x16x32_bf16 v[122:125], v[158:161], v[182:185], v[122:125]
	v_mfma_f32_16x16x32_bf16 v[118:121], v[150:153], v[190:193], v[118:121]
	v_mfma_f32_16x16x32_bf16 v[114:117], v[158:161], v[190:193], v[114:117]
	v_mfma_f32_16x16x32_bf16 v[102:105], v[150:153], v[198:201], v[102:105]
	v_mfma_f32_16x16x32_bf16 v[98:101], v[158:161], v[198:201], v[98:101]
	v_mfma_f32_16x16x32_bf16 v[86:89], v[150:153], v[206:209], v[86:89]
	v_mfma_f32_16x16x32_bf16 v[82:85], v[158:161], v[206:209], v[82:85]
	v_mfma_f32_16x16x32_bf16 v[126:129], v[154:157], v[186:189], v[126:129]
	v_mfma_f32_16x16x32_bf16 v[122:125], v[162:165], v[186:189], v[122:125]
	v_mfma_f32_16x16x32_bf16 v[118:121], v[154:157], v[194:197], v[118:121]
	v_mfma_f32_16x16x32_bf16 v[114:117], v[162:165], v[194:197], v[114:117]
	v_mfma_f32_16x16x32_bf16 v[102:105], v[154:157], v[202:205], v[102:105]
	v_mfma_f32_16x16x32_bf16 v[98:101], v[162:165], v[202:205], v[98:101]
	v_mfma_f32_16x16x32_bf16 v[86:89], v[154:157], v[210:213], v[86:89]
	v_mfma_f32_16x16x32_bf16 v[82:85], v[162:165], v[210:213], v[82:85]
	s_setprio 0
	s_setprio 1
	v_mfma_f32_16x16x32_bf16 v[110:113], v[166:169], v[182:185], v[110:113]
	v_mfma_f32_16x16x32_bf16 v[106:109], v[174:177], v[182:185], v[106:109]
	v_mfma_f32_16x16x32_bf16 v[94:97], v[166:169], v[190:193], v[94:97]
	v_mfma_f32_16x16x32_bf16 v[90:93], v[174:177], v[190:193], v[90:93]
	v_mfma_f32_16x16x32_bf16 v[78:81], v[166:169], v[198:201], v[78:81]
	v_mfma_f32_16x16x32_bf16 v[74:77], v[174:177], v[198:201], v[74:77]
	v_mfma_f32_16x16x32_bf16 v[70:73], v[166:169], v[206:209], v[70:73]
	v_mfma_f32_16x16x32_bf16 v[66:69], v[174:177], v[206:209], v[66:69]
	v_mfma_f32_16x16x32_bf16 v[110:113], v[170:173], v[186:189], v[110:113]
	v_mfma_f32_16x16x32_bf16 v[106:109], v[178:181], v[186:189], v[106:109]
	v_mfma_f32_16x16x32_bf16 v[94:97], v[170:173], v[194:197], v[94:97]
	v_mfma_f32_16x16x32_bf16 v[90:93], v[178:181], v[194:197], v[90:93]
	v_mfma_f32_16x16x32_bf16 v[78:81], v[170:173], v[202:205], v[78:81]
	v_mfma_f32_16x16x32_bf16 v[74:77], v[178:181], v[202:205], v[74:77]
	v_mfma_f32_16x16x32_bf16 v[70:73], v[170:173], v[210:213], v[70:73]
	v_mfma_f32_16x16x32_bf16 v[66:69], v[178:181], v[210:213], v[66:69]
	s_setprio 0
	s_barrier
	s_mov_b32 m0, s29
	v_lshl_add_u64 v[214:215], s[14:15], 0, v[134:135]
	s_add_u32 s54, s14, 0x40000
	ds_read_b128 v[182:185], v148 offset:16384
	ds_read_b128 v[186:189], v148 offset:17408
	ds_read_b128 v[190:193], v148 offset:18432
	ds_read_b128 v[194:197], v148 offset:19456
	ds_read_b128 v[198:201], v148 offset:20480
	ds_read_b128 v[202:205], v148 offset:21504
	ds_read_b128 v[206:209], v148 offset:22528
	ds_read_b128 v[210:213], v148 offset:23552
	global_load_lds_dwordx4 v[214:215], off
	v_lshl_add_u64 v[216:217], s[14:15], 0, v[130:131]
	s_mov_b32 m0, s33
	s_addc_u32 s55, s15, 0
	s_add_i32 s53, s26, s18
	global_load_lds_dwordx4 v[216:217], off
	v_lshl_add_u64 v[218:219], s[54:55], 0, v[134:135]
	s_mov_b32 m0, s53
	v_lshl_add_u64 v[220:221], s[16:17], 0, v[132:133]
	global_load_lds_dwordx4 v[218:219], off
	v_lshl_add_u64 v[218:219], s[54:55], 0, v[130:131]
	s_add_i32 m0, s53, 0x2000
	s_nop 0
	global_load_lds_dwordx4 v[218:219], off
	v_lshl_add_u64 v[218:219], s[16:17], 0, v[136:137]
	s_mov_b32 m0, s19
	s_nop 0
	global_load_lds_dwordx4 v[218:219], off
	s_mov_b32 m0, s20
	s_nop 0
	global_load_lds_dwordx4 v[220:221], off
	s_waitcnt vmcnt(8)
	s_waitcnt lgkmcnt(0)
	s_barrier
	s_setprio 1
	s_waitcnt lgkmcnt(0)
	v_mfma_f32_16x16x32_bf16 v[62:65], v[150:153], v[182:185], v[62:65]
	v_mfma_f32_16x16x32_bf16 v[58:61], v[158:161], v[182:185], v[58:61]
	v_mfma_f32_16x16x32_bf16 v[54:57], v[150:153], v[190:193], v[54:57]
	v_mfma_f32_16x16x32_bf16 v[50:53], v[158:161], v[190:193], v[50:53]
	v_mfma_f32_16x16x32_bf16 v[38:41], v[150:153], v[198:201], v[38:41]
	v_mfma_f32_16x16x32_bf16 v[34:37], v[158:161], v[198:201], v[34:37]
	v_mfma_f32_16x16x32_bf16 v[22:25], v[150:153], v[206:209], v[22:25]
	v_mfma_f32_16x16x32_bf16 v[18:21], v[158:161], v[206:209], v[18:21]
	v_mfma_f32_16x16x32_bf16 v[62:65], v[154:157], v[186:189], v[62:65]
	v_mfma_f32_16x16x32_bf16 v[58:61], v[162:165], v[186:189], v[58:61]
	v_mfma_f32_16x16x32_bf16 v[54:57], v[154:157], v[194:197], v[54:57]
	v_mfma_f32_16x16x32_bf16 v[50:53], v[162:165], v[194:197], v[50:53]
	v_mfma_f32_16x16x32_bf16 v[38:41], v[154:157], v[202:205], v[38:41]
	v_mfma_f32_16x16x32_bf16 v[34:37], v[162:165], v[202:205], v[34:37]
	v_mfma_f32_16x16x32_bf16 v[22:25], v[154:157], v[210:213], v[22:25]
	v_mfma_f32_16x16x32_bf16 v[18:21], v[162:165], v[210:213], v[18:21]
	s_setprio 0
	s_setprio 1
	v_mfma_f32_16x16x32_bf16 v[46:49], v[166:169], v[182:185], v[46:49]
	v_mfma_f32_16x16x32_bf16 v[42:45], v[174:177], v[182:185], v[42:45]
	v_mfma_f32_16x16x32_bf16 v[30:33], v[166:169], v[190:193], v[30:33]
	v_mfma_f32_16x16x32_bf16 v[26:29], v[174:177], v[190:193], v[26:29]
	v_mfma_f32_16x16x32_bf16 v[14:17], v[166:169], v[198:201], v[14:17]
	v_mfma_f32_16x16x32_bf16 v[10:13], v[174:177], v[198:201], v[10:13]
	v_mfma_f32_16x16x32_bf16 v[6:9], v[166:169], v[206:209], v[6:9]
	v_mfma_f32_16x16x32_bf16 v[2:5], v[174:177], v[206:209], v[2:5]
	v_mfma_f32_16x16x32_bf16 v[46:49], v[170:173], v[186:189], v[46:49]
	v_mfma_f32_16x16x32_bf16 v[42:45], v[178:181], v[186:189], v[42:45]
	v_mfma_f32_16x16x32_bf16 v[30:33], v[170:173], v[194:197], v[30:33]
	v_mfma_f32_16x16x32_bf16 v[26:29], v[178:181], v[194:197], v[26:29]
	v_mfma_f32_16x16x32_bf16 v[14:17], v[170:173], v[202:205], v[14:17]
	v_mfma_f32_16x16x32_bf16 v[10:13], v[178:181], v[202:205], v[10:13]
	v_mfma_f32_16x16x32_bf16 v[6:9], v[170:173], v[210:213], v[6:9]
	v_mfma_f32_16x16x32_bf16 v[2:5], v[178:181], v[210:213], v[2:5]
	s_setprio 0
	s_barrier
; #define PG8_STAGE(bufoff, gbase, voff) do { _Pragma("unroll") for (int _i = 0; _i < 2; ++_i) \
;         __builtin_amdgcn_global_load_lds((const unsigned*)((const char*)(gbase) + (voff)[_i]), (PG8_LAS unsigned*)(lds + (bufoff) + ldsw + _i * 8192), 16, 0, 0); } while (0)
; #define PG8_LDA(dst, b, h) do { _Pragma("unroll") for (int m = 0; m < 4; ++m) _Pragma("unroll") for (int k = 0; k < 2; ++k) dst[m][k] = *(const PG8_LAS bf16x8*)(lds + PG8_SA(b, h) + aoff + m * 2048 + k * 1024); } while (0)
; #define PG8_MMA(ai, bj, At, Bt) do { __builtin_amdgcn_s_setprio(1); _Pragma("unroll") for (int m = 0; m < 4; ++m) _Pragma("unroll") for (int n = 0; n < 2; ++n) _Pragma("unroll") for (int k = 0; k < 2; ++k) \
;         acc[ai][bj][m][n] = __builtin_amdgcn_mfma_f32_16x16x32_bf16(Bt[n][k], At[m][k], acc[ai][bj][m][n], 0, 0, 0); __builtin_amdgcn_s_setprio(0); } while (0)
; #define PG8_WAIT_V(n) asm volatile("s_waitcnt vmcnt(" #n ")" ::: "memory")
; #define PG8_WAIT_L(n) asm volatile("s_waitcnt lgkmcnt(" #n ")" ::: "memory")
; #define PG8_BAR __builtin_amdgcn_s_barrier()
; #define PG8_SCHED __builtin_amdgcn_sched_barrier(0)
; template <class Epi, class Sched, bool ALIGN_EPI = false, bool SP2 = false>
; __device__ __forceinline__ void gemm_phase(PG8_LAS unsigned char* lds, const Gemm g, const Sched& S, const Epi& E) {
;     ...
;             PG8_WAIT_V(8); PG8_WAIT_L(0); PG8_BAR; PG8_MMA(0, 0, At, B0); PG8_MMA(0, 1, At, B1); PG8_BAR; PG8_SCHED;
;             PG8_LDA(At, 1, 1); PG8_STAGE(PG8_SB(1, 0), b3, voffB); PG8_STAGE(PG8_SB(1, 1), b3 + hstep, voffB); PG8_STAGE(PG8_SA(1, 0), a3, voffA);
;             PG8_WAIT_V(8); PG8_WAIT_L(0); PG8_BAR; PG8_MMA(1, 0, At, B0); PG8_MMA(1, 1, At, B1); PG8_BAR; PG8_SCHED;
	s_add_i32 s53, 0, 0x18000
	v_add_u32_e32 v149, s53, v144
	s_add_i32 s54, 0, 0x1c000
	ds_read_b128 v[150:153], v149
	ds_read_b128 v[154:157], v149 offset:1024
	ds_read_b128 v[158:161], v149 offset:2048
	ds_read_b128 v[162:165], v149 offset:3072
	v_add_u32_e32 v149, s54, v144
	ds_read_b128 v[166:169], v149
	ds_read_b128 v[170:173], v149 offset:1024
	ds_read_b128 v[174:177], v149 offset:2048
	ds_read_b128 v[178:181], v149 offset:3072
	s_add_u32 s16, s16, 0x40000
	s_addc_u32 s17, s17, 0
	s_mov_b32 m0, s21
	v_lshl_add_u64 v[222:223], s[16:17], 0, v[136:137]
	ds_read_b128 v[182:185], v148 offset:32768
	ds_read_b128 v[186:189], v148 offset:33792
	ds_read_b128 v[190:193], v148 offset:34816
	ds_read_b128 v[194:197], v148 offset:35840
	ds_read_b128 v[198:201], v148 offset:36864
	ds_read_b128 v[202:205], v148 offset:37888
	ds_read_b128 v[206:209], v148 offset:38912
	ds_read_b128 v[210:213], v148 offset:39936
	global_load_lds_dwordx4 v[222:223], off
	v_lshl_add_u64 v[222:223], s[16:17], 0, v[132:133]
	s_mov_b32 m0, s22
	s_nop 0
	global_load_lds_dwordx4 v[222:223], off
	s_waitcnt vmcnt(8)
	s_waitcnt lgkmcnt(0)
	s_barrier
	s_setprio 1
	s_waitcnt lgkmcnt(0)
	v_mfma_f32_16x16x32_bf16 v[126:129], v[150:153], v[182:185], v[126:129]
	v_mfma_f32_16x16x32_bf16 v[122:125], v[158:161], v[182:185], v[122:125]
	v_mfma_f32_16x16x32_bf16 v[118:121], v[150:153], v[190:193], v[118:121]
	v_mfma_f32_16x16x32_bf16 v[114:117], v[158:161], v[190:193], v[114:117]
	v_mfma_f32_16x16x32_bf16 v[102:105], v[150:153], v[198:201], v[102:105]
	v_mfma_f32_16x16x32_bf16 v[98:101], v[158:161], v[198:201], v[98:101]
	v_mfma_f32_16x16x32_bf16 v[86:89], v[150:153], v[206:209], v[86:89]
	v_mfma_f32_16x16x32_bf16 v[82:85], v[158:161], v[206:209], v[82:85]
	v_mfma_f32_16x16x32_bf16 v[126:129], v[154:157], v[186:189], v[126:129]
	v_mfma_f32_16x16x32_bf16 v[122:125], v[162:165], v[186:189], v[122:125]
	v_mfma_f32_16x16x32_bf16 v[118:121], v[154:157], v[194:197], v[118:121]
	v_mfma_f32_16x16x32_bf16 v[114:117], v[162:165], v[194:197], v[114:117]
	v_mfma_f32_16x16x32_bf16 v[102:105], v[154:157], v[202:205], v[102:105]
	v_mfma_f32_16x16x32_bf16 v[98:101], v[162:165], v[202:205], v[98:101]
	v_mfma_f32_16x16x32_bf16 v[86:89], v[154:157], v[210:213], v[86:89]
	v_mfma_f32_16x16x32_bf16 v[82:85], v[162:165], v[210:213], v[82:85]
	s_setprio 0
	s_setprio 1
	v_mfma_f32_16x16x32_bf16 v[110:113], v[166:169], v[182:185], v[110:113]
	v_mfma_f32_16x16x32_bf16 v[106:109], v[174:177], v[182:185], v[106:109]
	v_mfma_f32_16x16x32_bf16 v[94:97], v[166:169], v[190:193], v[94:97]
	v_mfma_f32_16x16x32_bf16 v[90:93], v[174:177], v[190:193], v[90:93]
	v_mfma_f32_16x16x32_bf16 v[78:81], v[166:169], v[198:201], v[78:81]
	v_mfma_f32_16x16x32_bf16 v[74:77], v[174:177], v[198:201], v[74:77]
	v_mfma_f32_16x16x32_bf16 v[70:73], v[166:169], v[206:209], v[70:73]
	v_mfma_f32_16x16x32_bf16 v[66:69], v[174:177], v[206:209], v[66:69]
	v_mfma_f32_16x16x32_bf16 v[110:113], v[170:173], v[186:189], v[110:113]
	v_mfma_f32_16x16x32_bf16 v[106:109], v[178:181], v[186:189], v[106:109]
	v_mfma_f32_16x16x32_bf16 v[94:97], v[170:173], v[194:197], v[94:97]
	v_mfma_f32_16x16x32_bf16 v[90:93], v[178:181], v[194:197], v[90:93]
	v_mfma_f32_16x16x32_bf16 v[78:81], v[170:173], v[202:205], v[78:81]
	v_mfma_f32_16x16x32_bf16 v[74:77], v[178:181], v[202:205], v[74:77]
	v_mfma_f32_16x16x32_bf16 v[70:73], v[170:173], v[210:213], v[70:73]
	v_mfma_f32_16x16x32_bf16 v[66:69], v[178:181], v[210:213], v[66:69]
	s_setprio 0
	s_barrier
	s_add_i32 s16, s53, s18
	v_lshl_add_u64 v[214:215], v[214:215], 0, s[6:7]
	s_mov_b32 m0, s16
	ds_read_b128 v[182:185], v148 offset:49152
	ds_read_b128 v[186:189], v148 offset:50176
	ds_read_b128 v[190:193], v148 offset:51200
	ds_read_b128 v[194:197], v148 offset:52224
	ds_read_b128 v[198:201], v148 offset:53248
	ds_read_b128 v[202:205], v148 offset:54272
	ds_read_b128 v[206:209], v148 offset:55296
	ds_read_b128 v[210:213], v148 offset:56320
	global_load_lds_dwordx4 v[214:215], off
	s_add_i32 m0, s16, 0x2000
	s_add_u32 s14, s14, 0x40080
	v_lshl_add_u64 v[214:215], v[216:217], 0, s[6:7]
	s_addc_u32 s15, s15, 0
	s_add_i32 s16, s54, s18
	global_load_lds_dwordx4 v[214:215], off
	v_lshl_add_u64 v[214:215], s[14:15], 0, v[134:135]
	s_mov_b32 m0, s16
	s_nop 0
	global_load_lds_dwordx4 v[214:215], off
	v_lshl_add_u64 v[214:215], s[14:15], 0, v[130:131]
	s_add_i32 m0, s16, 0x2000
	s_nop 0
	global_load_lds_dwordx4 v[214:215], off
	v_lshl_add_u64 v[214:215], v[218:219], 0, s[6:7]
	s_mov_b32 m0, s24
	s_nop 0
	global_load_lds_dwordx4 v[214:215], off
	v_lshl_add_u64 v[214:215], v[220:221], 0, s[6:7]
	s_mov_b32 m0, s25
	s_nop 0
	global_load_lds_dwordx4 v[214:215], off
	s_waitcnt vmcnt(8)
	s_waitcnt lgkmcnt(0)
	s_barrier
; #define PG8_STAGE(bufoff, gbase, voff) do { _Pragma("unroll") for (int _i = 0; _i < 2; ++_i) \
;         __builtin_amdgcn_global_load_lds((const unsigned*)((const char*)(gbase) + (voff)[_i]), (PG8_LAS unsigned*)(lds + (bufoff) + ldsw + _i * 8192), 16, 0, 0); } while (0)
; #define PG8_LDA(dst, b, h) do { _Pragma("unroll") for (int m = 0; m < 4; ++m) _Pragma("unroll") for (int k = 0; k < 2; ++k) dst[m][k] = *(const PG8_LAS bf16x8*)(lds + PG8_SA(b, h) + aoff + m * 2048 + k * 1024); } while (0)
; #define PG8_LDB(dst, b, h) do { _Pragma("unroll") for (int n = 0; n < 2; ++n) _Pragma("unroll") for (int k = 0; k < 2; ++k) dst[n][k] = *(const PG8_LAS bf16x8*)(lds + PG8_SB(b, h) + boff + n * 2048 + k * 1024); } while (0)
; #define PG8_MMA(ai, bj, At, Bt) do { __builtin_amdgcn_s_setprio(1); _Pragma("unroll") for (int m = 0; m < 4; ++m) _Pragma("unroll") for (int n = 0; n < 2; ++n) _Pragma("unroll") for (int k = 0; k < 2; ++k) \
;         acc[ai][bj][m][n] = __builtin_amdgcn_mfma_f32_16x16x32_bf16(Bt[n][k], At[m][k], acc[ai][bj][m][n], 0, 0, 0); __builtin_amdgcn_s_setprio(0); } while (0)
; #define PG8_WAIT_V(n) asm volatile("s_waitcnt vmcnt(" #n ")" ::: "memory")
; #define PG8_WAIT_L(n) asm volatile("s_waitcnt lgkmcnt(" #n ")" ::: "memory")
; #define PG8_BAR __builtin_amdgcn_s_barrier()
; #define PG8_SCHED __builtin_amdgcn_sched_barrier(0)
; template <class Epi, class Sched, bool ALIGN_EPI = false, bool SP2 = false>
; __device__ __forceinline__ void gemm_phase(PG8_LAS unsigned char* lds, const Gemm g, const Sched& S, const Epi& E) {
;     ...
;             PG8_LDB(B0, 0, 0); PG8_LDB(B1, 0, 1); PG8_SCHED; PG8_LDA(At, 0, 0); PG8_STAGE(PG8_SA(1, 1), a1 + hstep, voffA);
;             PG8_WAIT_V(8); PG8_WAIT_L(0); PG8_BAR; PG8_MMA(0, 0, At, B0); PG8_MMA(0, 1, At, B1); PG8_BAR; PG8_SCHED;
;     ...
;             PG8_WAIT_V(8); PG8_WAIT_L(0); PG8_BAR; PG8_MMA(1, 0, At, B0); PG8_MMA(1, 1, At, B1); PG8_BAR; PG8_SCHED;
	s_setprio 1
	s_waitcnt lgkmcnt(0)
	v_mfma_f32_16x16x32_bf16 v[62:65], v[150:153], v[182:185], v[62:65]
	v_mfma_f32_16x16x32_bf16 v[58:61], v[158:161], v[182:185], v[58:61]
	v_mfma_f32_16x16x32_bf16 v[54:57], v[150:153], v[190:193], v[54:57]
	v_mfma_f32_16x16x32_bf16 v[50:53], v[158:161], v[190:193], v[50:53]
	v_mfma_f32_16x16x32_bf16 v[38:41], v[150:153], v[198:201], v[38:41]
	v_mfma_f32_16x16x32_bf16 v[34:37], v[158:161], v[198:201], v[34:37]
	v_mfma_f32_16x16x32_bf16 v[22:25], v[150:153], v[206:209], v[22:25]
	v_mfma_f32_16x16x32_bf16 v[18:21], v[158:161], v[206:209], v[18:21]
	v_mfma_f32_16x16x32_bf16 v[62:65], v[154:157], v[186:189], v[62:65]
	v_mfma_f32_16x16x32_bf16 v[58:61], v[162:165], v[186:189], v[58:61]
	v_mfma_f32_16x16x32_bf16 v[54:57], v[154:157], v[194:197], v[54:57]
	v_mfma_f32_16x16x32_bf16 v[50:53], v[162:165], v[194:197], v[50:53]
	v_mfma_f32_16x16x32_bf16 v[38:41], v[154:157], v[202:205], v[38:41]
	v_mfma_f32_16x16x32_bf16 v[34:37], v[162:165], v[202:205], v[34:37]
	v_mfma_f32_16x16x32_bf16 v[22:25], v[154:157], v[210:213], v[22:25]
	v_mfma_f32_16x16x32_bf16 v[18:21], v[162:165], v[210:213], v[18:21]
	s_setprio 0
	s_setprio 1
	v_mfma_f32_16x16x32_bf16 v[46:49], v[166:169], v[182:185], v[46:49]
	v_mfma_f32_16x16x32_bf16 v[42:45], v[174:177], v[182:185], v[42:45]
	v_mfma_f32_16x16x32_bf16 v[30:33], v[166:169], v[190:193], v[30:33]
	v_mfma_f32_16x16x32_bf16 v[26:29], v[174:177], v[190:193], v[26:29]
	v_mfma_f32_16x16x32_bf16 v[14:17], v[166:169], v[198:201], v[14:17]
	v_mfma_f32_16x16x32_bf16 v[10:13], v[174:177], v[198:201], v[10:13]
	v_mfma_f32_16x16x32_bf16 v[6:9], v[166:169], v[206:209], v[6:9]
	v_mfma_f32_16x16x32_bf16 v[2:5], v[174:177], v[206:209], v[2:5]
	v_mfma_f32_16x16x32_bf16 v[46:49], v[170:173], v[186:189], v[46:49]
	v_mfma_f32_16x16x32_bf16 v[42:45], v[178:181], v[186:189], v[42:45]
	v_mfma_f32_16x16x32_bf16 v[30:33], v[170:173], v[194:197], v[30:33]
	v_mfma_f32_16x16x32_bf16 v[26:29], v[178:181], v[194:197], v[26:29]
	v_mfma_f32_16x16x32_bf16 v[14:17], v[170:173], v[202:205], v[14:17]
	v_mfma_f32_16x16x32_bf16 v[10:13], v[178:181], v[202:205], v[10:13]
	v_mfma_f32_16x16x32_bf16 v[6:9], v[170:173], v[210:213], v[6:9]
	v_mfma_f32_16x16x32_bf16 v[2:5], v[178:181], v[210:213], v[2:5]
	s_setprio 0
	s_barrier
	s_add_i32 s52, s52, 2
	s_add_u32 s12, s12, 0x100
	s_addc_u32 s13, s13, 0
	s_add_u32 s50, s50, 0x100
	s_addc_u32 s51, s51, 0
	s_cmp_gt_u32 s52, 13
	s_cbranch_scc0 .LBB0_1087
	s_branch .Lpeel_after_6
.Lpeel_6:
	ds_read_b128 v[150:153], v145
	ds_read_b128 v[154:157], v145 offset:1024
	ds_read_b128 v[158:161], v145 offset:2048
	ds_read_b128 v[162:165], v145 offset:3072
	ds_read_b128 v[166:169], v147
	ds_read_b128 v[170:173], v147 offset:1024
	ds_read_b128 v[174:177], v147 offset:2048
	ds_read_b128 v[178:181], v147 offset:3072
	s_add_u32 s14, s12, 0xfffc0080
	s_addc_u32 s15, s13, -1
	s_cmp_eq_u32 s52, 12
	s_cselect_b32 s17, s40, s15
	s_cselect_b32 s16, s41, s14
	s_cselect_b32 s15, s46, s51
	s_cselect_b32 s14, s47, s50
	s_mov_b32 m0, s27
	v_lshl_add_u64 v[214:215], s[12:13], 0, v[140:141]
	ds_read_b128 v[182:185], v148
	ds_read_b128 v[186:189], v148 offset:1024
	ds_read_b128 v[190:193], v148 offset:2048
	ds_read_b128 v[194:197], v148 offset:3072
	ds_read_b128 v[198:201], v148 offset:4096
	ds_read_b128 v[202:205], v148 offset:5120
	ds_read_b128 v[206:209], v148 offset:6144
	ds_read_b128 v[210:213], v148 offset:7168
	global_load_lds_dwordx4 v[214:215], off
	v_lshl_add_u64 v[214:215], s[12:13], 0, v[142:143]
	s_mov_b32 m0, s28
	s_nop 0
	global_load_lds_dwordx4 v[214:215], off
	s_waitcnt vmcnt(24)
	s_waitcnt lgkmcnt(0)
	s_barrier
	s_setprio 1
	s_waitcnt lgkmcnt(0)
	v_mfma_f32_16x16x32_bf16 v[126:129], v[150:153], v[182:185], 0
	v_mfma_f32_16x16x32_bf16 v[122:125], v[158:161], v[182:185], 0
	v_mfma_f32_16x16x32_bf16 v[118:121], v[150:153], v[190:193], 0
	v_mfma_f32_16x16x32_bf16 v[114:117], v[158:161], v[190:193], 0
	v_mfma_f32_16x16x32_bf16 v[102:105], v[150:153], v[198:201], 0
	v_mfma_f32_16x16x32_bf16 v[98:101], v[158:161], v[198:201], 0
	v_mfma_f32_16x16x32_bf16 v[86:89], v[150:153], v[206:209], 0
	v_mfma_f32_16x16x32_bf16 v[82:85], v[158:161], v[206:209], 0
	v_mfma_f32_16x16x32_bf16 v[126:129], v[154:157], v[186:189], v[126:129]
	v_mfma_f32_16x16x32_bf16 v[122:125], v[162:165], v[186:189], v[122:125]
	v_mfma_f32_16x16x32_bf16 v[118:121], v[154:157], v[194:197], v[118:121]
	v_mfma_f32_16x16x32_bf16 v[114:117], v[162:165], v[194:197], v[114:117]
	v_mfma_f32_16x16x32_bf16 v[102:105], v[154:157], v[202:205], v[102:105]
	v_mfma_f32_16x16x32_bf16 v[98:101], v[162:165], v[202:205], v[98:101]
	v_mfma_f32_16x16x32_bf16 v[86:89], v[154:157], v[210:213], v[86:89]
	v_mfma_f32_16x16x32_bf16 v[82:85], v[162:165], v[210:213], v[82:85]
	s_setprio 0
	s_setprio 1
	v_mfma_f32_16x16x32_bf16 v[110:113], v[166:169], v[182:185], 0
	v_mfma_f32_16x16x32_bf16 v[106:109], v[174:177], v[182:185], 0
	v_mfma_f32_16x16x32_bf16 v[94:97], v[166:169], v[190:193], 0
	v_mfma_f32_16x16x32_bf16 v[90:93], v[174:177], v[190:193], 0
	v_mfma_f32_16x16x32_bf16 v[78:81], v[166:169], v[198:201], 0
	v_mfma_f32_16x16x32_bf16 v[74:77], v[174:177], v[198:201], 0
	v_mfma_f32_16x16x32_bf16 v[70:73], v[166:169], v[206:209], 0
	v_mfma_f32_16x16x32_bf16 v[66:69], v[174:177], v[206:209], 0
	v_mfma_f32_16x16x32_bf16 v[110:113], v[170:173], v[186:189], v[110:113]
	v_mfma_f32_16x16x32_bf16 v[106:109], v[178:181], v[186:189], v[106:109]
	v_mfma_f32_16x16x32_bf16 v[94:97], v[170:173], v[194:197], v[94:97]
	v_mfma_f32_16x16x32_bf16 v[90:93], v[178:181], v[194:197], v[90:93]
	v_mfma_f32_16x16x32_bf16 v[78:81], v[170:173], v[202:205], v[78:81]
	v_mfma_f32_16x16x32_bf16 v[74:77], v[178:181], v[202:205], v[74:77]
	v_mfma_f32_16x16x32_bf16 v[70:73], v[170:173], v[210:213], v[70:73]
	v_mfma_f32_16x16x32_bf16 v[66:69], v[178:181], v[210:213], v[66:69]
	s_setprio 0
	s_barrier
; #define PG8_STAGE(bufoff, gbase, voff) do { _Pragma("unroll") for (int _i = 0; _i < 2; ++_i) \
;         __builtin_amdgcn_global_load_lds((const unsigned*)((const char*)(gbase) + (voff)[_i]), (PG8_LAS unsigned*)(lds + (bufoff) + ldsw + _i * 8192), 16, 0, 0); } while (0)
; #define PG8_LDA(dst, b, h) do { _Pragma("unroll") for (int m = 0; m < 4; ++m) _Pragma("unroll") for (int k = 0; k < 2; ++k) dst[m][k] = *(const PG8_LAS bf16x8*)(lds + PG8_SA(b, h) + aoff + m * 2048 + k * 1024); } while (0)
; #define PG8_LDB(dst, b, h) do { _Pragma("unroll") for (int n = 0; n < 2; ++n) _Pragma("unroll") for (int k = 0; k < 2; ++k) dst[n][k] = *(const PG8_LAS bf16x8*)(lds + PG8_SB(b, h) + boff + n * 2048 + k * 1024); } while (0)
; #define PG8_MMA(ai, bj, At, Bt) do { __builtin_amdgcn_s_setprio(1); _Pragma("unroll") for (int m = 0; m < 4; ++m) _Pragma("unroll") for (int n = 0; n < 2; ++n) _Pragma("unroll") for (int k = 0; k < 2; ++k) \
;         acc[ai][bj][m][n] = __builtin_amdgcn_mfma_f32_16x16x32_bf16(Bt[n][k], At[m][k], acc[ai][bj][m][n], 0, 0, 0); __builtin_amdgcn_s_setprio(0); } while (0)
; #define PG8_WAIT_V(n) asm volatile("s_waitcnt vmcnt(" #n ")" ::: "memory")
; #define PG8_WAIT_L(n) asm volatile("s_waitcnt lgkmcnt(" #n ")" ::: "memory")
; #define PG8_BAR __builtin_amdgcn_s_barrier()
; #define PG8_SCHED __builtin_amdgcn_sched_barrier(0)
; template <class Epi, class Sched, bool ALIGN_EPI = false, bool SP2 = false>
; __device__ __forceinline__ void gemm_phase(PG8_LAS unsigned char* lds, const Gemm g, const Sched& S, const Epi& E) {
;     ...
;             PG8_LDA(At, 0, 1); PG8_STAGE(PG8_SB(0, 0), b2, voffB); PG8_STAGE(PG8_SB(0, 1), b2 + hstep, voffB); PG8_STAGE(PG8_SA(0, 0), a2, voffA);
;             PG8_WAIT_V(8); PG8_WAIT_L(0); PG8_BAR; PG8_MMA(1, 0, At, B0); PG8_MMA(1, 1, At, B1); PG8_BAR; PG8_SCHED;
;             PG8_LDB(B0, 1, 0); PG8_LDB(B1, 1, 1); PG8_SCHED; PG8_LDA(At, 1, 0); PG8_STAGE(PG8_SA(0, 1), a2 + hstep, voffA);
;             PG8_WAIT_V(8); PG8_WAIT_L(0); PG8_BAR; PG8_MMA(0, 0, At, B0); PG8_MMA(0, 1, At, B1); PG8_BAR; PG8_SCHED;
	s_mov_b32 m0, s29
	v_lshl_add_u64 v[214:215], s[14:15], 0, v[134:135]
	s_add_u32 s54, s14, 0x40000
	ds_read_b128 v[182:185], v148 offset:16384
	ds_read_b128 v[186:189], v148 offset:17408
	ds_read_b128 v[190:193], v148 offset:18432
	ds_read_b128 v[194:197], v148 offset:19456
	ds_read_b128 v[198:201], v148 offset:20480
	ds_read_b128 v[202:205], v148 offset:21504
	ds_read_b128 v[206:209], v148 offset:22528
	ds_read_b128 v[210:213], v148 offset:23552
	global_load_lds_dwordx4 v[214:215], off
	v_lshl_add_u64 v[216:217], s[14:15], 0, v[130:131]
	s_mov_b32 m0, s33
	s_addc_u32 s55, s15, 0
	s_add_i32 s53, s26, s18
	global_load_lds_dwordx4 v[216:217], off
	v_lshl_add_u64 v[218:219], s[54:55], 0, v[134:135]
	s_mov_b32 m0, s53
	v_lshl_add_u64 v[220:221], s[16:17], 0, v[132:133]
	global_load_lds_dwordx4 v[218:219], off
	v_lshl_add_u64 v[218:219], s[54:55], 0, v[130:131]
	s_add_i32 m0, s53, 0x2000
	s_nop 0
	global_load_lds_dwordx4 v[218:219], off
	v_lshl_add_u64 v[218:219], s[16:17], 0, v[136:137]
	s_mov_b32 m0, s19
	s_nop 0
	global_load_lds_dwordx4 v[218:219], off
	s_mov_b32 m0, s20
	s_nop 0
	global_load_lds_dwordx4 v[220:221], off
	s_waitcnt vmcnt(24)
	s_waitcnt lgkmcnt(0)
	s_barrier
	s_setprio 1
	s_waitcnt lgkmcnt(0)
	v_mfma_f32_16x16x32_bf16 v[62:65], v[150:153], v[182:185], 0
	v_mfma_f32_16x16x32_bf16 v[58:61], v[158:161], v[182:185], 0
	v_mfma_f32_16x16x32_bf16 v[54:57], v[150:153], v[190:193], 0
	v_mfma_f32_16x16x32_bf16 v[50:53], v[158:161], v[190:193], 0
	v_mfma_f32_16x16x32_bf16 v[38:41], v[150:153], v[198:201], 0
	v_mfma_f32_16x16x32_bf16 v[34:37], v[158:161], v[198:201], 0
	v_mfma_f32_16x16x32_bf16 v[22:25], v[150:153], v[206:209], 0
	v_mfma_f32_16x16x32_bf16 v[18:21], v[158:161], v[206:209], 0
	v_mfma_f32_16x16x32_bf16 v[62:65], v[154:157], v[186:189], v[62:65]
	v_mfma_f32_16x16x32_bf16 v[58:61], v[162:165], v[186:189], v[58:61]
	v_mfma_f32_16x16x32_bf16 v[54:57], v[154:157], v[194:197], v[54:57]
	v_mfma_f32_16x16x32_bf16 v[50:53], v[162:165], v[194:197], v[50:53]
	v_mfma_f32_16x16x32_bf16 v[38:41], v[154:157], v[202:205], v[38:41]
	v_mfma_f32_16x16x32_bf16 v[34:37], v[162:165], v[202:205], v[34:37]
	v_mfma_f32_16x16x32_bf16 v[22:25], v[154:157], v[210:213], v[22:25]
	v_mfma_f32_16x16x32_bf16 v[18:21], v[162:165], v[210:213], v[18:21]
	s_setprio 0
	s_setprio 1
	v_mfma_f32_16x16x32_bf16 v[46:49], v[166:169], v[182:185], 0
	v_mfma_f32_16x16x32_bf16 v[42:45], v[174:177], v[182:185], 0
	v_mfma_f32_16x16x32_bf16 v[30:33], v[166:169], v[190:193], 0
	v_mfma_f32_16x16x32_bf16 v[26:29], v[174:177], v[190:193], 0
	v_mfma_f32_16x16x32_bf16 v[14:17], v[166:169], v[198:201], 0
	v_mfma_f32_16x16x32_bf16 v[10:13], v[174:177], v[198:201], 0
	v_mfma_f32_16x16x32_bf16 v[6:9], v[166:169], v[206:209], 0
	v_mfma_f32_16x16x32_bf16 v[2:5], v[174:177], v[206:209], 0
	v_mfma_f32_16x16x32_bf16 v[46:49], v[170:173], v[186:189], v[46:49]
	v_mfma_f32_16x16x32_bf16 v[42:45], v[178:181], v[186:189], v[42:45]
	v_mfma_f32_16x16x32_bf16 v[30:33], v[170:173], v[194:197], v[30:33]
	v_mfma_f32_16x16x32_bf16 v[26:29], v[178:181], v[194:197], v[26:29]
	v_mfma_f32_16x16x32_bf16 v[14:17], v[170:173], v[202:205], v[14:17]
	v_mfma_f32_16x16x32_bf16 v[10:13], v[178:181], v[202:205], v[10:13]
	v_mfma_f32_16x16x32_bf16 v[6:9], v[170:173], v[210:213], v[6:9]
	v_mfma_f32_16x16x32_bf16 v[2:5], v[178:181], v[210:213], v[2:5]
	s_setprio 0
	s_barrier
	s_add_i32 s53, 0, 0x18000
	v_add_u32_e32 v149, s53, v144
	s_add_i32 s54, 0, 0x1c000
	ds_read_b128 v[150:153], v149
	ds_read_b128 v[154:157], v149 offset:1024
	ds_read_b128 v[158:161], v149 offset:2048
	ds_read_b128 v[162:165], v149 offset:3072
	v_add_u32_e32 v149, s54, v144
	ds_read_b128 v[166:169], v149
	ds_read_b128 v[170:173], v149 offset:1024
	ds_read_b128 v[174:177], v149 offset:2048
	ds_read_b128 v[178:181], v149 offset:3072
	s_add_u32 s16, s16, 0x40000
	s_addc_u32 s17, s17, 0
	s_mov_b32 m0, s21
	v_lshl_add_u64 v[222:223], s[16:17], 0, v[136:137]
	ds_read_b128 v[182:185], v148 offset:32768
	ds_read_b128 v[186:189], v148 offset:33792
	ds_read_b128 v[190:193], v148 offset:34816
	ds_read_b128 v[194:197], v148 offset:35840
	ds_read_b128 v[198:201], v148 offset:36864
	ds_read_b128 v[202:205], v148 offset:37888
	ds_read_b128 v[206:209], v148 offset:38912
	ds_read_b128 v[210:213], v148 offset:39936
	global_load_lds_dwordx4 v[222:223], off
	v_lshl_add_u64 v[222:223], s[16:17], 0, v[132:133]
	s_mov_b32 m0, s22
	s_nop 0
	global_load_lds_dwordx4 v[222:223], off
	s_waitcnt vmcnt(8)
	s_waitcnt lgkmcnt(0)
	s_barrier
; #define PG8_STAGE(bufoff, gbase, voff) do { _Pragma("unroll") for (int _i = 0; _i < 2; ++_i) \
;         __builtin_amdgcn_global_load_lds((const unsigned*)((const char*)(gbase) + (voff)[_i]), (PG8_LAS unsigned*)(lds + (bufoff) + ldsw + _i * 8192), 16, 0, 0); } while (0)
; #define PG8_LDA(dst, b, h) do { _Pragma("unroll") for (int m = 0; m < 4; ++m) _Pragma("unroll") for (int k = 0; k < 2; ++k) dst[m][k] = *(const PG8_LAS bf16x8*)(lds + PG8_SA(b, h) + aoff + m * 2048 + k * 1024); } while (0)
; #define PG8_MMA(ai, bj, At, Bt) do { __builtin_amdgcn_s_setprio(1); _Pragma("unroll") for (int m = 0; m < 4; ++m) _Pragma("unroll") for (int n = 0; n < 2; ++n) _Pragma("unroll") for (int k = 0; k < 2; ++k) \
;         acc[ai][bj][m][n] = __builtin_amdgcn_mfma_f32_16x16x32_bf16(Bt[n][k], At[m][k], acc[ai][bj][m][n], 0, 0, 0); __builtin_amdgcn_s_setprio(0); } while (0)
; #define PG8_WAIT_V(n) asm volatile("s_waitcnt vmcnt(" #n ")" ::: "memory")
; #define PG8_WAIT_L(n) asm volatile("s_waitcnt lgkmcnt(" #n ")" ::: "memory")
; #define PG8_BAR __builtin_amdgcn_s_barrier()
; #define PG8_SCHED __builtin_amdgcn_sched_barrier(0)
; template <class Epi, class Sched, bool ALIGN_EPI = false, bool SP2 = false>
; __device__ __forceinline__ void gemm_phase(PG8_LAS unsigned char* lds, const Gemm g, const Sched& S, const Epi& E) {
;     ...
;             PG8_WAIT_V(8); PG8_WAIT_L(0); PG8_BAR; PG8_MMA(0, 0, At, B0); PG8_MMA(0, 1, At, B1); PG8_BAR; PG8_SCHED;
;             PG8_LDA(At, 1, 1); PG8_STAGE(PG8_SB(1, 0), b3, voffB); PG8_STAGE(PG8_SB(1, 1), b3 + hstep, voffB); PG8_STAGE(PG8_SA(1, 0), a3, voffA);
;             PG8_WAIT_V(8); PG8_WAIT_L(0); PG8_BAR; PG8_MMA(1, 0, At, B0); PG8_MMA(1, 1, At, B1); PG8_BAR; PG8_SCHED;
	s_setprio 1
	s_waitcnt lgkmcnt(0)
	v_mfma_f32_16x16x32_bf16 v[126:129], v[150:153], v[182:185], v[126:129]
	v_mfma_f32_16x16x32_bf16 v[122:125], v[158:161], v[182:185], v[122:125]
	v_mfma_f32_16x16x32_bf16 v[118:121], v[150:153], v[190:193], v[118:121]
	v_mfma_f32_16x16x32_bf16 v[114:117], v[158:161], v[190:193], v[114:117]
	v_mfma_f32_16x16x32_bf16 v[102:105], v[150:153], v[198:201], v[102:105]
	v_mfma_f32_16x16x32_bf16 v[98:101], v[158:161], v[198:201], v[98:101]
	v_mfma_f32_16x16x32_bf16 v[86:89], v[150:153], v[206:209], v[86:89]
	v_mfma_f32_16x16x32_bf16 v[82:85], v[158:161], v[206:209], v[82:85]
	v_mfma_f32_16x16x32_bf16 v[126:129], v[154:157], v[186:189], v[126:129]
	v_mfma_f32_16x16x32_bf16 v[122:125], v[162:165], v[186:189], v[122:125]
	v_mfma_f32_16x16x32_bf16 v[118:121], v[154:157], v[194:197], v[118:121]
	v_mfma_f32_16x16x32_bf16 v[114:117], v[162:165], v[194:197], v[114:117]
	v_mfma_f32_16x16x32_bf16 v[102:105], v[154:157], v[202:205], v[102:105]
	v_mfma_f32_16x16x32_bf16 v[98:101], v[162:165], v[202:205], v[98:101]
	v_mfma_f32_16x16x32_bf16 v[86:89], v[154:157], v[210:213], v[86:89]
	v_mfma_f32_16x16x32_bf16 v[82:85], v[162:165], v[210:213], v[82:85]
	s_setprio 0
	s_setprio 1
	v_mfma_f32_16x16x32_bf16 v[110:113], v[166:169], v[182:185], v[110:113]
	v_mfma_f32_16x16x32_bf16 v[106:109], v[174:177], v[182:185], v[106:109]
	v_mfma_f32_16x16x32_bf16 v[94:97], v[166:169], v[190:193], v[94:97]
	v_mfma_f32_16x16x32_bf16 v[90:93], v[174:177], v[190:193], v[90:93]
	v_mfma_f32_16x16x32_bf16 v[78:81], v[166:169], v[198:201], v[78:81]
	v_mfma_f32_16x16x32_bf16 v[74:77], v[174:177], v[198:201], v[74:77]
	v_mfma_f32_16x16x32_bf16 v[70:73], v[166:169], v[206:209], v[70:73]
	v_mfma_f32_16x16x32_bf16 v[66:69], v[174:177], v[206:209], v[66:69]
	v_mfma_f32_16x16x32_bf16 v[110:113], v[170:173], v[186:189], v[110:113]
	v_mfma_f32_16x16x32_bf16 v[106:109], v[178:181], v[186:189], v[106:109]
	v_mfma_f32_16x16x32_bf16 v[94:97], v[170:173], v[194:197], v[94:97]
	v_mfma_f32_16x16x32_bf16 v[90:93], v[178:181], v[194:197], v[90:93]
	v_mfma_f32_16x16x32_bf16 v[78:81], v[170:173], v[202:205], v[78:81]
	v_mfma_f32_16x16x32_bf16 v[74:77], v[178:181], v[202:205], v[74:77]
	v_mfma_f32_16x16x32_bf16 v[70:73], v[170:173], v[210:213], v[70:73]
	v_mfma_f32_16x16x32_bf16 v[66:69], v[178:181], v[210:213], v[66:69]
	s_setprio 0
	s_barrier
	s_add_i32 s16, s53, s18
	v_lshl_add_u64 v[214:215], v[214:215], 0, s[6:7]
	s_mov_b32 m0, s16
	ds_read_b128 v[182:185], v148 offset:49152
	ds_read_b128 v[186:189], v148 offset:50176
	ds_read_b128 v[190:193], v148 offset:51200
	ds_read_b128 v[194:197], v148 offset:52224
	ds_read_b128 v[198:201], v148 offset:53248
	ds_read_b128 v[202:205], v148 offset:54272
	ds_read_b128 v[206:209], v148 offset:55296
	ds_read_b128 v[210:213], v148 offset:56320
	global_load_lds_dwordx4 v[214:215], off
	s_add_i32 m0, s16, 0x2000
	s_add_u32 s14, s14, 0x40080
	v_lshl_add_u64 v[214:215], v[216:217], 0, s[6:7]
	s_addc_u32 s15, s15, 0
	s_add_i32 s16, s54, s18
	global_load_lds_dwordx4 v[214:215], off
	v_lshl_add_u64 v[214:215], s[14:15], 0, v[134:135]
	s_mov_b32 m0, s16
	s_nop 0
	global_load_lds_dwordx4 v[214:215], off
	v_lshl_add_u64 v[214:215], s[14:15], 0, v[130:131]
	s_add_i32 m0, s16, 0x2000
	s_nop 0
	global_load_lds_dwordx4 v[214:215], off
	v_lshl_add_u64 v[214:215], v[218:219], 0, s[6:7]
	s_mov_b32 m0, s24
	s_nop 0
	global_load_lds_dwordx4 v[214:215], off
	v_lshl_add_u64 v[214:215], v[220:221], 0, s[6:7]
	s_mov_b32 m0, s25
	s_nop 0
	global_load_lds_dwordx4 v[214:215], off
	s_waitcnt vmcnt(8)
	s_waitcnt lgkmcnt(0)
	s_barrier
	s_setprio 1
	s_waitcnt lgkmcnt(0)
	v_mfma_f32_16x16x32_bf16 v[62:65], v[150:153], v[182:185], v[62:65]
	v_mfma_f32_16x16x32_bf16 v[58:61], v[158:161], v[182:185], v[58:61]
	v_mfma_f32_16x16x32_bf16 v[54:57], v[150:153], v[190:193], v[54:57]
	v_mfma_f32_16x16x32_bf16 v[50:53], v[158:161], v[190:193], v[50:53]
	v_mfma_f32_16x16x32_bf16 v[38:41], v[150:153], v[198:201], v[38:41]
	v_mfma_f32_16x16x32_bf16 v[34:37], v[158:161], v[198:201], v[34:37]
	v_mfma_f32_16x16x32_bf16 v[22:25], v[150:153], v[206:209], v[22:25]
	v_mfma_f32_16x16x32_bf16 v[18:21], v[158:161], v[206:209], v[18:21]
	v_mfma_f32_16x16x32_bf16 v[62:65], v[154:157], v[186:189], v[62:65]
	v_mfma_f32_16x16x32_bf16 v[58:61], v[162:165], v[186:189], v[58:61]
	v_mfma_f32_16x16x32_bf16 v[54:57], v[154:157], v[194:197], v[54:57]
	v_mfma_f32_16x16x32_bf16 v[50:53], v[162:165], v[194:197], v[50:53]
	v_mfma_f32_16x16x32_bf16 v[38:41], v[154:157], v[202:205], v[38:41]
	v_mfma_f32_16x16x32_bf16 v[34:37], v[162:165], v[202:205], v[34:37]
	v_mfma_f32_16x16x32_bf16 v[22:25], v[154:157], v[210:213], v[22:25]
	v_mfma_f32_16x16x32_bf16 v[18:21], v[162:165], v[210:213], v[18:21]
	s_setprio 0
	s_setprio 1
	v_mfma_f32_16x16x32_bf16 v[46:49], v[166:169], v[182:185], v[46:49]
	v_mfma_f32_16x16x32_bf16 v[42:45], v[174:177], v[182:185], v[42:45]
	v_mfma_f32_16x16x32_bf16 v[30:33], v[166:169], v[190:193], v[30:33]
	v_mfma_f32_16x16x32_bf16 v[26:29], v[174:177], v[190:193], v[26:29]
	v_mfma_f32_16x16x32_bf16 v[14:17], v[166:169], v[198:201], v[14:17]
	v_mfma_f32_16x16x32_bf16 v[10:13], v[174:177], v[198:201], v[10:13]
	v_mfma_f32_16x16x32_bf16 v[6:9], v[166:169], v[206:209], v[6:9]
	v_mfma_f32_16x16x32_bf16 v[2:5], v[174:177], v[206:209], v[2:5]
	v_mfma_f32_16x16x32_bf16 v[46:49], v[170:173], v[186:189], v[46:49]
	v_mfma_f32_16x16x32_bf16 v[42:45], v[178:181], v[186:189], v[42:45]
	v_mfma_f32_16x16x32_bf16 v[30:33], v[170:173], v[194:197], v[30:33]
	v_mfma_f32_16x16x32_bf16 v[26:29], v[178:181], v[194:197], v[26:29]
	v_mfma_f32_16x16x32_bf16 v[14:17], v[170:173], v[202:205], v[14:17]
	v_mfma_f32_16x16x32_bf16 v[10:13], v[178:181], v[202:205], v[10:13]
	v_mfma_f32_16x16x32_bf16 v[6:9], v[170:173], v[210:213], v[6:9]
	v_mfma_f32_16x16x32_bf16 v[2:5], v[178:181], v[210:213], v[2:5]
	s_setprio 0
	s_barrier
	s_add_i32 s52, s52, 2
	s_add_u32 s12, s12, 0x100
	s_addc_u32 s13, s13, 0
	s_add_u32 s50, s50, 0x100
	s_addc_u32 s51, s51, 0
	s_cmp_gt_u32 s52, 13
	s_branch .LBB0_1087

; DI unsigned pk2(float lo, float hi) { f32x2 v = {lo, hi}; bf16x2_t b = __builtin_convertvector(v, bf16x2_t); return __builtin_bit_cast(unsigned, b); }
; template <class Epi, class Sched, bool ALIGN_EPI = false, bool SP2 = false>
; __device__ __forceinline__ void gemm_phase(PG8_LAS unsigned char* lds, const Gemm g, const Sched& S, const Epi& E) {
;     ...
;         if constexpr (!Epi::AFTER_DRAIN) { E(acc, cur, wr, wc, fr, fq); S.done(cur); }
;         if (!has_next) break;
;     DI void operator()(const f32x4 (&acc)[2][2][4][2], const pg8::Unit& u, int wr, int wc, int fr, int fq) const {
;         const int row0 = u.pm * 256 + wr * 64 + fr, col0 = wc * 32 + 8 * fq;
; #pragma unroll
;         for (int ai = 0; ai < 2; ++ai)
; #pragma unroll
;             for (int m = 0; m < 4; ++m) {
;                 const size_t off = (size_t)(row0 + ai * 128 + m * 16) * 256 + col0;
; #pragma unroll
;                 for (int bj = 0; bj < 2; ++bj) { const f32x4 a = acc[ai][bj][m][0], b = acc[ai][bj][m][1];
;                     *(u32x4*)(Z + off + bj * 128) = (u32x4){pk2(a[0], a[1]), pk2(a[2], a[3]), pk2(b[0], b[1]), pk2(b[2], b[3])}; }
;             }
.LBB0_1090:
	v_lshl_add_u32 v150, s39, 8, v1
	v_ashrrev_i32_e32 v151, 31, v150
	v_lshlrev_b64 v[152:153], 9, v[150:151]
	v_cvt_pk_bf16_f32 v126, v126, v127
	v_cvt_pk_bf16_f32 v127, v128, v129
	v_cvt_pk_bf16_f32 v128, v122, v123
	v_lshl_add_u64 v[122:123], v[138:139], 0, v[152:153]
	s_mov_b64 s[12:13], 0x10000
	v_cvt_pk_bf16_f32 v62, v62, v63
	v_cvt_pk_bf16_f32 v63, v64, v65
	v_cvt_pk_bf16_f32 v64, v58, v59
	v_lshl_add_u64 v[58:59], v[122:123], 0, s[12:13]
	s_mov_b32 s12, 0x10000
	v_cvt_pk_bf16_f32 v65, v60, v61
	v_add_co_u32_e32 v60, vcc, s12, v122
	v_cvt_pk_bf16_f32 v46, v46, v47
	v_cvt_pk_bf16_f32 v47, v48, v49
	v_cvt_pk_bf16_f32 v48, v42, v43
	v_cvt_pk_bf16_f32 v49, v44, v45
	s_mov_b64 s[12:13], 0x12000
	v_cvt_pk_bf16_f32 v110, v110, v111
	v_cvt_pk_bf16_f32 v111, v112, v113
	v_cvt_pk_bf16_f32 v112, v106, v107
	v_or_b32_e32 v106, 16, v150
	v_addc_co_u32_e32 v61, vcc, 0, v123, vcc
	global_store_dwordx4 v[58:59], v[46:49], off offset:256
	v_cvt_pk_bf16_f32 v113, v108, v109
	v_ashrrev_i32_e32 v107, 31, v106
	v_lshl_add_u64 v[46:47], v[122:123], 0, s[12:13]
	s_mov_b32 s12, 0x12000
	v_add_co_u32_e32 v48, vcc, s12, v122
	v_cvt_pk_bf16_f32 v30, v30, v31
	v_cvt_pk_bf16_f32 v31, v32, v33
	v_cvt_pk_bf16_f32 v32, v26, v27
	v_cvt_pk_bf16_f32 v33, v28, v29
	s_mov_b64 s[12:13], 0x14000
	global_store_dwordx4 v[122:123], v[110:113], off offset:256
	v_cvt_pk_bf16_f32 v94, v94, v95
	v_cvt_pk_bf16_f32 v95, v96, v97
	v_lshlrev_b64 v[110:111], 9, v[106:107]
	v_cvt_pk_bf16_f32 v96, v90, v91
	v_or_b32_e32 v90, 32, v150
	v_addc_co_u32_e32 v49, vcc, 0, v123, vcc
	global_store_dwordx4 v[46:47], v[30:33], off offset:256
	v_lshl_add_u64 v[110:111], v[138:139], 0, v[110:111]
	v_cvt_pk_bf16_f32 v97, v92, v93
	v_lshl_add_u64 v[30:31], v[122:123], 0, s[12:13]
	s_mov_b32 s12, 0x14000
	v_ashrrev_i32_e32 v91, 31, v90
	v_add_co_u32_e32 v32, vcc, s12, v122
	v_cvt_pk_bf16_f32 v14, v14, v15
	v_cvt_pk_bf16_f32 v15, v16, v17
	v_cvt_pk_bf16_f32 v16, v10, v11
	v_cvt_pk_bf16_f32 v17, v12, v13
	s_mov_b64 s[12:13], 0x16000
	global_store_dwordx4 v[110:111], v[94:97], off offset:256
	v_cvt_pk_bf16_f32 v78, v78, v79
	v_cvt_pk_bf16_f32 v79, v80, v81
	v_lshlrev_b64 v[94:95], 9, v[90:91]
	v_cvt_pk_bf16_f32 v80, v74, v75
	v_or_b32_e32 v74, 48, v150
	v_addc_co_u32_e32 v33, vcc, 0, v123, vcc
	global_store_dwordx4 v[30:31], v[14:17], off offset:256
	v_lshl_add_u64 v[94:95], v[138:139], 0, v[94:95]
	v_cvt_pk_bf16_f32 v81, v76, v77
	v_lshl_add_u64 v[14:15], v[122:123], 0, s[12:13]
	s_mov_b32 s12, 0x16000
	v_ashrrev_i32_e32 v75, 31, v74
	v_add_co_u32_e32 v16, vcc, s12, v122
	global_store_dwordx4 v[94:95], v[78:81], off offset:256
	s_nop 0
	v_addc_co_u32_e32 v17, vcc, 0, v123, vcc
	v_lshlrev_b64 v[78:79], 9, v[74:75]
	v_cvt_pk_bf16_f32 v129, v124, v125
	v_cvt_pk_bf16_f32 v106, v118, v119
	v_cvt_pk_bf16_f32 v107, v120, v121
	v_cvt_pk_bf16_f32 v108, v114, v115
	v_cvt_pk_bf16_f32 v109, v116, v117
	v_cvt_pk_bf16_f32 v90, v102, v103
	v_cvt_pk_bf16_f32 v91, v104, v105
	v_cvt_pk_bf16_f32 v92, v98, v99
	v_cvt_pk_bf16_f32 v93, v100, v101
	v_cvt_pk_bf16_f32 v74, v86, v87
	v_cvt_pk_bf16_f32 v75, v88, v89
	v_cvt_pk_bf16_f32 v76, v82, v83
	v_cvt_pk_bf16_f32 v77, v84, v85
	v_lshl_add_u64 v[78:79], v[138:139], 0, v[78:79]
	v_cvt_pk_bf16_f32 v70, v70, v71
	v_cvt_pk_bf16_f32 v71, v72, v73
	v_cvt_pk_bf16_f32 v72, v66, v67
	v_cvt_pk_bf16_f32 v73, v68, v69
	v_cvt_pk_bf16_f32 v42, v54, v55
	v_cvt_pk_bf16_f32 v43, v56, v57
	v_cvt_pk_bf16_f32 v44, v50, v51
	v_cvt_pk_bf16_f32 v45, v52, v53
	v_cvt_pk_bf16_f32 v26, v38, v39
	v_cvt_pk_bf16_f32 v27, v40, v41
	v_cvt_pk_bf16_f32 v28, v34, v35
	v_cvt_pk_bf16_f32 v29, v36, v37
	v_cvt_pk_bf16_f32 v10, v22, v23
	v_cvt_pk_bf16_f32 v11, v24, v25
	v_cvt_pk_bf16_f32 v12, v18, v19
	v_cvt_pk_bf16_f32 v13, v20, v21
	v_cvt_pk_bf16_f32 v6, v6, v7
	v_cvt_pk_bf16_f32 v7, v8, v9
	v_cvt_pk_bf16_f32 v8, v2, v3
	v_cvt_pk_bf16_f32 v9, v4, v5
	s_andn2_b64 vcc, exec, s[10:11]
	s_mov_b64 s[10:11], -1
	global_store_dwordx4 v[122:123], v[126:129], off
	global_store_dwordx4 v[110:111], v[106:109], off
	global_store_dwordx4 v[94:95], v[90:93], off
	global_store_dwordx4 v[78:79], v[74:77], off
	global_store_dwordx4 v[78:79], v[70:73], off offset:256
	global_store_dwordx4 v[60:61], v[62:65], off
	global_store_dwordx4 v[48:49], v[42:45], off
	global_store_dwordx4 v[32:33], v[26:29], off
	global_store_dwordx4 v[16:17], v[10:13], off
	global_store_dwordx4 v[14:15], v[6:9], off offset:256
	s_mov_b32 s98, 1
	s_cbranch_vccnz .LBB0_1085
	s_andn2_b64 vcc, exec, s[4:5]
	s_cbranch_vccnz .LBB0_1084
	s_barrier
	s_branch .LBB0_1084

; #define PG8_STAGE(bufoff, gbase, voff) do { _Pragma("unroll") for (int _i = 0; _i < 2; ++_i) \
;         __builtin_amdgcn_global_load_lds((const unsigned*)((const char*)(gbase) + (voff)[_i]), (PG8_LAS unsigned*)(lds + (bufoff) + ldsw + _i * 8192), 16, 0, 0); } while (0)
; #define PG8_WAIT_V(n) asm volatile("s_waitcnt vmcnt(" #n ")" ::: "memory")
; #define PG8_BAR __builtin_amdgcn_s_barrier()
; template <class Epi, class Sched, bool ALIGN_EPI = false, bool SP2 = false>
; __device__ __forceinline__ void gemm_phase(PG8_LAS unsigned char* lds, const Gemm g, const Sched& S, const Epi& E) {
;     ...
;     if constexpr (SP2) {
;         PG8_STAGE(PG8_SB(0, 0), cB, voffB); PG8_STAGE(PG8_SB(0, 1), cB + hstep, voffB); PG8_STAGE(PG8_SA(0, 0), cA, voffA); PG8_STAGE(PG8_SA(0, 1), cA + hstep, voffA);
;         if (wr == 1) PG8_BAR;
;         PG8_WAIT_V(2); PG8_BAR;
;         PG8_STAGE(PG8_SB(1, 0), cB + kstep, voffB); PG8_STAGE(PG8_SA(1, 0), cA + kstep, voffA); PG8_STAGE(PG8_SB(1, 1), cB + hstep + kstep, voffB);
;         PG8_WAIT_V(6); PG8_BAR;
.LBB0_1787:
	s_lshl_b32 s1, s1, 5
	s_mov_b64 s[8:9], 0x80
	s_and_b32 s1, s1, 0x60
	s_add_i32 m0, s29, 0x18000
	v_lshl_add_u64 v[8:9], v[8:9], 0, s[8:9]
	s_lshl_b32 s12, s11, 13
	s_lshl_b32 s16, s1, 7
	s_waitcnt vmcnt(2)
	s_barrier
	global_load_lds_dwordx4 v[8:9], off
	v_lshl_add_u64 v[4:5], v[4:5], 0, s[8:9]
	s_add_i32 m0, s29, 0x1a000
	s_add_i32 s43, s29, 0x8000
	s_add_i32 s46, s29, 0xa000
	global_load_lds_dwordx4 v[4:5], off
	v_lshl_add_u64 v[2:3], v[2:3], 0, s[8:9]
	s_mov_b32 m0, s43
	s_add_u32 s14, s34, 0x80080
	global_load_lds_dwordx4 v[2:3], off
	v_lshl_add_u64 v[2:3], v[6:7], 0, s[8:9]
	s_mov_b32 m0, s46
	s_addc_u32 s15, s35, 0
	global_load_lds_dwordx4 v[2:3], off
	s_add_i32 m0, s29, 0x1c000
	v_lshl_add_u64 v[2:3], s[14:15], 0, v[148:149]
	global_load_lds_dwordx4 v[2:3], off
	v_lshl_add_u64 v[2:3], s[14:15], 0, v[152:153]
	s_add_i32 m0, s29, 0x1e000
	s_cmpk_lt_u32 s10, 0x100
	global_load_lds_dwordx4 v[2:3], off
	v_lshrrev_b32_e32 v3, 1, v10
	v_and_b32_e32 v3, 24, v3
	v_and_b32_e32 v2, 15, v10
	v_lshlrev_b32_e32 v4, 1, v3
	v_lshl_or_b32 v172, s11, 6, v2
	v_lshl_or_b32 v2, v2, 6, v4
	v_lshlrev_b32_e32 v4, 2, v10
	v_and_b32_e32 v4, 32, v4
	v_bitop3_b32 v5, v2, s12, v4 bitop3:0xde
	v_bitop3_b32 v173, v2, s16, v4 bitop3:0xde
	v_lshlrev_b32_e32 v2, 15, v11
	v_and_b32_e32 v2, 0xffff0000, v2
	v_or_b32_e32 v174, s1, v3
	v_lshl_add_u32 v2, v12, 12, v2
	v_and_b32_e32 v3, 1, v11
	v_lshl_or_b32 v2, v3, 6, v2
	v_lshl_add_u32 v154, v13, 1, v2
	v_lshlrev_b32_e32 v2, 15, v14
	v_and_b32_e32 v2, 0xffff0000, v2
	s_waitcnt vmcnt(6)
	v_lshl_add_u32 v2, v15, 12, v2
	v_and_b32_e32 v3, 1, v14
	s_cselect_b64 s[10:11], -1, 0
	v_lshl_or_b32 v2, v3, 6, v2
	s_add_i32 s48, 0, 0x10000
	s_add_i32 s49, 0, 0x14000
	s_sext_i32_i8 s50, s0
	s_ashr_i32 s47, s78, 31
	v_mov_b32_e32 v155, v149
	v_lshl_add_u32 v156, v16, 1, v2
	v_mov_b32_e32 v157, v149
	v_mov_b64_e32 v[158:159], 0x200
	v_mov_b64_e32 v[160:161], 0x1ff
	v_add_u32_e32 v175, s48, v173
	v_add_u32_e32 v176, s49, v173
	v_add_u32_e32 v177, 0, v5
	s_mov_b32 s12, 0x3f9837f0
	s_mov_b64 s[14:15], 0x90000
	s_mov_b64 s[16:17], 0xa0000
	s_mov_b64 s[18:19], 0xb0000
	s_barrier
	s_mov_b32 s98, 0
	s_branch .LBB0_1790

; #define PG8_STAGE(bufoff, gbase, voff) do { _Pragma("unroll") for (int _i = 0; _i < 2; ++_i) \
;         __builtin_amdgcn_global_load_lds((const unsigned*)((const char*)(gbase) + (voff)[_i]), (PG8_LAS unsigned*)(lds + (bufoff) + ldsw + _i * 8192), 16, 0, 0); } while (0)
; #define PG8_LDA(dst, b, h) do { _Pragma("unroll") for (int m = 0; m < 4; ++m) _Pragma("unroll") for (int k = 0; k < 2; ++k) dst[m][k] = *(const PG8_LAS bf16x8*)(lds + PG8_SA(b, h) + aoff + m * 2048 + k * 1024); } while (0)
; #define PG8_LDB(dst, b, h) do { _Pragma("unroll") for (int n = 0; n < 2; ++n) _Pragma("unroll") for (int k = 0; k < 2; ++k) dst[n][k] = *(const PG8_LAS bf16x8*)(lds + PG8_SB(b, h) + boff + n * 2048 + k * 1024); } while (0)
; #define PG8_WAIT_V(n) asm volatile("s_waitcnt vmcnt(" #n ")" ::: "memory")
; #define PG8_WAIT_L(n) asm volatile("s_waitcnt lgkmcnt(" #n ")" ::: "memory")
; #define PG8_BAR __builtin_amdgcn_s_barrier()
; #define PG8_SCHED __builtin_amdgcn_sched_barrier(0)
; template <class Epi, class Sched, bool ALIGN_EPI = false, bool SP2 = false>
; __device__ __forceinline__ void gemm_phase(PG8_LAS unsigned char* lds, const Gemm g, const Sched& S, const Epi& E) {
;     ...
;         const bool has_next = S.next(ui + 1, nxt);
;         const char* nA = has_next ? (const char*)g.A + (size_t)nxt.pm * tstep + nxt.kb : cA; const char* nB = has_next ? (const char*)g.Bt + (size_t)nxt.pn * tstep + nxt.kb : cB;
;         for (int t = 0; t < nt; t += 2) {
;             const bool last = (t == nt - 2);
;             const char* a1 = cA + (size_t)(t + 1) * kstep;
;             const char* a2 = last ? nA : cA + (size_t)(t + 2) * kstep; const char* b2 = last ? nB : cB + (size_t)(t + 2) * kstep;
;             const char* a3 = a2 + kstep; const char* b3 = b2 + kstep;
;             if (last && has_next) S.a_ready(nxt);
;             if constexpr (SP2) {
;             PG8_LDB(B0, 0, 0); PG8_LDB(B1, 0, 1); PG8_SCHED; PG8_LDA(At, 0, 0); PG8_STAGE(PG8_SA(1, 1), a1 + hstep, voffA);
;             PG8_WAIT_V(8); PG8_WAIT_L(0); PG8_BAR; PG8_MMA(0, 0, At, B0); PG8_MMA(0, 1, At, B1); PG8_BAR; PG8_SCHED;
;     ...
; #pragma unroll
;         for (int a = 0; a < 2; ++a)
; #pragma unroll
;             for (int b = 0; b < 2; ++b)
; #pragma unroll
;                 for (int m = 0; m < 4; ++m)
; #pragma unroll
;                     for (int n = 0; n < 2; ++n) acc[a][b][m][n] = (f32x4){0.f, 0.f, 0.f, 0.f};
.LBB0_1796:
	s_ashr_i32 s23, s22, 31
	s_lshl_b64 s[24:25], s[22:23], 20
	s_add_u32 s24, s76, s24
	s_addc_u32 s25, s77, s25
	s_and_b64 s[26:27], s[0:1], exec
	s_cselect_b32 s23, s25, s31
	s_cselect_b32 s51, s24, s30
	s_ashr_i32 s21, s20, 31
	s_lshl_b64 s[26:27], s[20:21], 20
	v_readlane_b32 s36, v253, 43
	v_readlane_b32 s37, v253, 44
	s_add_u32 s26, s36, s26
	s_addc_u32 s27, s37, s27
	s_and_b64 s[36:37], s[0:1], exec
	s_cselect_b32 s21, s27, s35
	s_cselect_b32 s52, s26, s34
	s_add_u32 s30, s30, 0x80080
	s_addc_u32 s31, s31, 0
	s_add_u32 s53, s34, 0x100
	v_mov_b32_e32 v2, 0
	s_addc_u32 s54, s35, 0
	s_mov_b32 s55, -2
	s_cmp_lg_u32 s98, 0
	s_cbranch_scc1 .Lpeel_7
	v_mov_b32_e32 v3, v2
	v_mov_b32_e32 v4, v2
	v_mov_b32_e32 v5, v2
	v_mov_b32_e32 v6, v2
	v_mov_b32_e32 v7, v2
	v_mov_b32_e32 v8, v2
	v_mov_b32_e32 v9, v2
	v_mov_b32_e32 v14, v2
	v_mov_b32_e32 v15, v2
	v_mov_b32_e32 v16, v2
	v_mov_b32_e32 v17, v2
	v_mov_b32_e32 v22, v2
	v_mov_b32_e32 v23, v2
	v_mov_b32_e32 v24, v2
	v_mov_b32_e32 v25, v2
	v_mov_b32_e32 v30, v2
	v_mov_b32_e32 v31, v2
	v_mov_b32_e32 v32, v2
	v_mov_b32_e32 v33, v2
	v_mov_b32_e32 v38, v2
	v_mov_b32_e32 v39, v2
	v_mov_b32_e32 v40, v2
	v_mov_b32_e32 v41, v2
	v_mov_b32_e32 v46, v2
	v_mov_b32_e32 v47, v2
	v_mov_b32_e32 v48, v2
	v_mov_b32_e32 v49, v2
	v_mov_b32_e32 v54, v2
	v_mov_b32_e32 v55, v2
	v_mov_b32_e32 v56, v2
	v_mov_b32_e32 v57, v2
	v_mov_b32_e32 v10, v2
	v_mov_b32_e32 v11, v2
	v_mov_b32_e32 v12, v2
	v_mov_b32_e32 v13, v2
	v_mov_b32_e32 v18, v2
	v_mov_b32_e32 v19, v2
	v_mov_b32_e32 v20, v2
	v_mov_b32_e32 v21, v2
	v_mov_b32_e32 v26, v2
	v_mov_b32_e32 v27, v2
	v_mov_b32_e32 v28, v2
	v_mov_b32_e32 v29, v2
	v_mov_b32_e32 v34, v2
	v_mov_b32_e32 v35, v2
	v_mov_b32_e32 v36, v2
	v_mov_b32_e32 v37, v2
	v_mov_b32_e32 v42, v2
	v_mov_b32_e32 v43, v2
	v_mov_b32_e32 v44, v2
	v_mov_b32_e32 v45, v2
	v_mov_b32_e32 v50, v2
	v_mov_b32_e32 v51, v2
	v_mov_b32_e32 v52, v2
	v_mov_b32_e32 v53, v2
	v_mov_b32_e32 v58, v2
	v_mov_b32_e32 v59, v2
	v_mov_b32_e32 v60, v2
	v_mov_b32_e32 v61, v2
	v_mov_b32_e32 v62, v2
	v_mov_b32_e32 v63, v2
	v_mov_b32_e32 v64, v2
	v_mov_b32_e32 v65, v2
	v_mov_b32_e32 v66, v2
	v_mov_b32_e32 v67, v2
	v_mov_b32_e32 v68, v2
	v_mov_b32_e32 v69, v2
	v_mov_b32_e32 v70, v2
	v_mov_b32_e32 v71, v2
	v_mov_b32_e32 v72, v2
	v_mov_b32_e32 v73, v2
	v_mov_b32_e32 v74, v2
	v_mov_b32_e32 v75, v2
	v_mov_b32_e32 v76, v2
	v_mov_b32_e32 v77, v2
	v_mov_b32_e32 v82, v2
	v_mov_b32_e32 v83, v2
	v_mov_b32_e32 v84, v2
	v_mov_b32_e32 v85, v2
	v_mov_b32_e32 v94, v2
	v_mov_b32_e32 v95, v2
	v_mov_b32_e32 v96, v2
	v_mov_b32_e32 v97, v2
	v_mov_b32_e32 v102, v2
	v_mov_b32_e32 v103, v2
	v_mov_b32_e32 v104, v2
	v_mov_b32_e32 v105, v2
	v_mov_b32_e32 v106, v2
	v_mov_b32_e32 v107, v2
	v_mov_b32_e32 v108, v2
	v_mov_b32_e32 v109, v2
	v_mov_b32_e32 v110, v2
	v_mov_b32_e32 v111, v2
	v_mov_b32_e32 v112, v2
	v_mov_b32_e32 v113, v2
	v_mov_b32_e32 v78, v2
	v_mov_b32_e32 v79, v2
	v_mov_b32_e32 v80, v2
	v_mov_b32_e32 v81, v2
	v_mov_b32_e32 v86, v2
	v_mov_b32_e32 v87, v2
	v_mov_b32_e32 v88, v2
	v_mov_b32_e32 v89, v2
	v_mov_b32_e32 v90, v2
	v_mov_b32_e32 v91, v2
	v_mov_b32_e32 v92, v2
	v_mov_b32_e32 v93, v2
	v_mov_b32_e32 v98, v2
	v_mov_b32_e32 v99, v2
	v_mov_b32_e32 v100, v2
	v_mov_b32_e32 v101, v2
	v_mov_b32_e32 v114, v2
	v_mov_b32_e32 v115, v2
	v_mov_b32_e32 v116, v2
	v_mov_b32_e32 v117, v2
	v_mov_b32_e32 v118, v2
	v_mov_b32_e32 v119, v2
	v_mov_b32_e32 v120, v2
	v_mov_b32_e32 v121, v2
	v_mov_b32_e32 v122, v2
	v_mov_b32_e32 v123, v2
	v_mov_b32_e32 v124, v2
	v_mov_b32_e32 v125, v2
	v_mov_b32_e32 v126, v2
	v_mov_b32_e32 v127, v2
	v_mov_b32_e32 v128, v2
	v_mov_b32_e32 v129, v2
.LBB0_1797:
	ds_read_b128 v[130:133], v175
	ds_read_b128 v[134:137], v175 offset:1024
	ds_read_b128 v[138:141], v175 offset:2048
	ds_read_b128 v[142:145], v175 offset:3072
	ds_read_b128 v[162:165], v176
	ds_read_b128 v[166:169], v176 offset:1024
	ds_read_b128 v[178:181], v176 offset:2048
	ds_read_b128 v[182:185], v176 offset:3072
	s_add_u32 s34, s30, 0xfff80080
	s_addc_u32 s35, s31, -1
	s_cmp_eq_u32 s55, 28
	s_cselect_b32 s37, s23, s35
	s_cselect_b32 s36, s51, s34
	s_cselect_b32 s35, s21, s54
	s_cselect_b32 s34, s52, s53
	v_lshl_add_u64 v[170:171], s[30:31], 0, v[154:155]
	s_add_i32 m0, s29, 0xc000
	ds_read_b128 v[186:189], v177
	ds_read_b128 v[190:193], v177 offset:1024
	ds_read_b128 v[194:197], v177 offset:2048
	ds_read_b128 v[198:201], v177 offset:3072
	ds_read_b128 v[202:205], v177 offset:4096
	ds_read_b128 v[206:209], v177 offset:5120
	ds_read_b128 v[210:213], v177 offset:6144
	ds_read_b128 v[214:217], v177 offset:7168
	global_load_lds_dwordx4 v[170:171], off
	v_lshl_add_u64 v[170:171], s[30:31], 0, v[156:157]
	s_add_i32 m0, s29, 0xe000
	s_nop 0
	global_load_lds_dwordx4 v[170:171], off
	s_waitcnt vmcnt(8)
	s_waitcnt lgkmcnt(0)
	s_barrier
; #define PG8_STAGE(bufoff, gbase, voff) do { _Pragma("unroll") for (int _i = 0; _i < 2; ++_i) \
;         __builtin_amdgcn_global_load_lds((const unsigned*)((const char*)(gbase) + (voff)[_i]), (PG8_LAS unsigned*)(lds + (bufoff) + ldsw + _i * 8192), 16, 0, 0); } while (0)
; #define PG8_LDA(dst, b, h) do { _Pragma("unroll") for (int m = 0; m < 4; ++m) _Pragma("unroll") for (int k = 0; k < 2; ++k) dst[m][k] = *(const PG8_LAS bf16x8*)(lds + PG8_SA(b, h) + aoff + m * 2048 + k * 1024); } while (0)
; #define PG8_MMA(ai, bj, At, Bt) do { __builtin_amdgcn_s_setprio(1); _Pragma("unroll") for (int m = 0; m < 4; ++m) _Pragma("unroll") for (int n = 0; n < 2; ++n) _Pragma("unroll") for (int k = 0; k < 2; ++k) \
;         acc[ai][bj][m][n] = __builtin_amdgcn_mfma_f32_16x16x32_bf16(Bt[n][k], At[m][k], acc[ai][bj][m][n], 0, 0, 0); __builtin_amdgcn_s_setprio(0); } while (0)
; #define PG8_WAIT_V(n) asm volatile("s_waitcnt vmcnt(" #n ")" ::: "memory")
; #define PG8_WAIT_L(n) asm volatile("s_waitcnt lgkmcnt(" #n ")" ::: "memory")
; #define PG8_BAR __builtin_amdgcn_s_barrier()
; #define PG8_SCHED __builtin_amdgcn_sched_barrier(0)
; template <class Epi, class Sched, bool ALIGN_EPI = false, bool SP2 = false>
; __device__ __forceinline__ void gemm_phase(PG8_LAS unsigned char* lds, const Gemm g, const Sched& S, const Epi& E) {
;     ...
;             PG8_WAIT_V(8); PG8_WAIT_L(0); PG8_BAR; PG8_MMA(0, 0, At, B0); PG8_MMA(0, 1, At, B1); PG8_BAR; PG8_SCHED;
;             PG8_LDA(At, 0, 1); PG8_STAGE(PG8_SB(0, 0), b2, voffB); PG8_STAGE(PG8_SB(0, 1), b2 + hstep, voffB); PG8_STAGE(PG8_SA(0, 0), a2, voffA);
;             PG8_WAIT_V(8); PG8_WAIT_L(0); PG8_BAR; PG8_MMA(1, 0, At, B0); PG8_MMA(1, 1, At, B1); PG8_BAR; PG8_SCHED;
	s_setprio 1
	s_waitcnt lgkmcnt(0)
	v_mfma_f32_16x16x32_bf16 v[126:129], v[130:133], v[186:189], v[126:129]
	v_mfma_f32_16x16x32_bf16 v[122:125], v[138:141], v[186:189], v[122:125]
	v_mfma_f32_16x16x32_bf16 v[118:121], v[130:133], v[194:197], v[118:121]
	v_mfma_f32_16x16x32_bf16 v[114:117], v[138:141], v[194:197], v[114:117]
	v_mfma_f32_16x16x32_bf16 v[98:101], v[130:133], v[202:205], v[98:101]
	v_mfma_f32_16x16x32_bf16 v[90:93], v[138:141], v[202:205], v[90:93]
	v_mfma_f32_16x16x32_bf16 v[86:89], v[130:133], v[210:213], v[86:89]
	v_mfma_f32_16x16x32_bf16 v[78:81], v[138:141], v[210:213], v[78:81]
	v_mfma_f32_16x16x32_bf16 v[126:129], v[134:137], v[190:193], v[126:129]
	v_mfma_f32_16x16x32_bf16 v[122:125], v[142:145], v[190:193], v[122:125]
	v_mfma_f32_16x16x32_bf16 v[118:121], v[134:137], v[198:201], v[118:121]
	v_mfma_f32_16x16x32_bf16 v[114:117], v[142:145], v[198:201], v[114:117]
	v_mfma_f32_16x16x32_bf16 v[98:101], v[134:137], v[206:209], v[98:101]
	v_mfma_f32_16x16x32_bf16 v[90:93], v[142:145], v[206:209], v[90:93]
	v_mfma_f32_16x16x32_bf16 v[86:89], v[134:137], v[214:217], v[86:89]
	v_mfma_f32_16x16x32_bf16 v[78:81], v[142:145], v[214:217], v[78:81]
	s_setprio 0
	s_setprio 1
	v_mfma_f32_16x16x32_bf16 v[110:113], v[162:165], v[186:189], v[110:113]
	v_mfma_f32_16x16x32_bf16 v[106:109], v[178:181], v[186:189], v[106:109]
	v_mfma_f32_16x16x32_bf16 v[102:105], v[162:165], v[194:197], v[102:105]
	v_mfma_f32_16x16x32_bf16 v[94:97], v[178:181], v[194:197], v[94:97]
	v_mfma_f32_16x16x32_bf16 v[82:85], v[162:165], v[202:205], v[82:85]
	v_mfma_f32_16x16x32_bf16 v[74:77], v[178:181], v[202:205], v[74:77]
	v_mfma_f32_16x16x32_bf16 v[70:73], v[162:165], v[210:213], v[70:73]
	v_mfma_f32_16x16x32_bf16 v[66:69], v[178:181], v[210:213], v[66:69]
	v_mfma_f32_16x16x32_bf16 v[110:113], v[166:169], v[190:193], v[110:113]
	v_mfma_f32_16x16x32_bf16 v[106:109], v[182:185], v[190:193], v[106:109]
	v_mfma_f32_16x16x32_bf16 v[102:105], v[166:169], v[198:201], v[102:105]
	v_mfma_f32_16x16x32_bf16 v[94:97], v[182:185], v[198:201], v[94:97]
	v_mfma_f32_16x16x32_bf16 v[82:85], v[166:169], v[206:209], v[82:85]
	v_mfma_f32_16x16x32_bf16 v[74:77], v[182:185], v[206:209], v[74:77]
	v_mfma_f32_16x16x32_bf16 v[70:73], v[166:169], v[214:217], v[70:73]
	v_mfma_f32_16x16x32_bf16 v[66:69], v[182:185], v[214:217], v[66:69]
	s_setprio 0
	s_barrier
	s_add_i32 s56, s48, s38
	v_lshl_add_u64 v[170:171], s[34:35], 0, v[148:149]
	s_mov_b32 m0, s56
	ds_read_b128 v[186:189], v177 offset:16384
	ds_read_b128 v[190:193], v177 offset:17408
	ds_read_b128 v[194:197], v177 offset:18432
	ds_read_b128 v[198:201], v177 offset:19456
	ds_read_b128 v[202:205], v177 offset:20480
	ds_read_b128 v[206:209], v177 offset:21504
	ds_read_b128 v[210:213], v177 offset:22528
	ds_read_b128 v[214:217], v177 offset:23552
	global_load_lds_dwordx4 v[170:171], off
	s_add_i32 m0, s56, 0x2000
	s_add_u32 s56, s34, 0x80000
	v_lshl_add_u64 v[220:221], s[34:35], 0, v[152:153]
	s_addc_u32 s57, s35, 0
	s_add_i32 s58, s49, s38
	global_load_lds_dwordx4 v[220:221], off
	v_lshl_add_u64 v[222:223], s[56:57], 0, v[148:149]
	s_mov_b32 m0, s58
	v_lshl_add_u64 v[224:225], s[36:37], 0, v[150:151]
	global_load_lds_dwordx4 v[222:223], off
	v_lshl_add_u64 v[222:223], s[56:57], 0, v[152:153]
	s_add_i32 m0, s58, 0x2000
	s_nop 0
	global_load_lds_dwordx4 v[222:223], off
	v_lshl_add_u64 v[222:223], s[36:37], 0, v[146:147]
	s_mov_b32 m0, s29
	s_nop 0
	global_load_lds_dwordx4 v[222:223], off
	s_mov_b32 m0, s39
	s_nop 0
	global_load_lds_dwordx4 v[224:225], off
	s_waitcnt vmcnt(8)
	s_waitcnt lgkmcnt(0)
	s_barrier
	s_setprio 1
	s_waitcnt lgkmcnt(0)
	v_mfma_f32_16x16x32_bf16 v[62:65], v[130:133], v[186:189], v[62:65]
	v_mfma_f32_16x16x32_bf16 v[58:61], v[138:141], v[186:189], v[58:61]
	v_mfma_f32_16x16x32_bf16 v[50:53], v[130:133], v[194:197], v[50:53]
	v_mfma_f32_16x16x32_bf16 v[42:45], v[138:141], v[194:197], v[42:45]
	v_mfma_f32_16x16x32_bf16 v[34:37], v[130:133], v[202:205], v[34:37]
	v_mfma_f32_16x16x32_bf16 v[26:29], v[138:141], v[202:205], v[26:29]
	v_mfma_f32_16x16x32_bf16 v[18:21], v[130:133], v[210:213], v[18:21]
	v_mfma_f32_16x16x32_bf16 v[10:13], v[138:141], v[210:213], v[10:13]
	v_mfma_f32_16x16x32_bf16 v[62:65], v[134:137], v[190:193], v[62:65]
	v_mfma_f32_16x16x32_bf16 v[58:61], v[142:145], v[190:193], v[58:61]
	v_mfma_f32_16x16x32_bf16 v[50:53], v[134:137], v[198:201], v[50:53]
	v_mfma_f32_16x16x32_bf16 v[42:45], v[142:145], v[198:201], v[42:45]
	v_mfma_f32_16x16x32_bf16 v[34:37], v[134:137], v[206:209], v[34:37]
	v_mfma_f32_16x16x32_bf16 v[26:29], v[142:145], v[206:209], v[26:29]
	v_mfma_f32_16x16x32_bf16 v[18:21], v[134:137], v[214:217], v[18:21]
	v_mfma_f32_16x16x32_bf16 v[10:13], v[142:145], v[214:217], v[10:13]
	s_setprio 0
	s_setprio 1
	v_mfma_f32_16x16x32_bf16 v[54:57], v[162:165], v[186:189], v[54:57]
	v_mfma_f32_16x16x32_bf16 v[46:49], v[178:181], v[186:189], v[46:49]
	v_mfma_f32_16x16x32_bf16 v[38:41], v[162:165], v[194:197], v[38:41]
	v_mfma_f32_16x16x32_bf16 v[30:33], v[178:181], v[194:197], v[30:33]
	v_mfma_f32_16x16x32_bf16 v[22:25], v[162:165], v[202:205], v[22:25]
	v_mfma_f32_16x16x32_bf16 v[14:17], v[178:181], v[202:205], v[14:17]
	v_mfma_f32_16x16x32_bf16 v[6:9], v[162:165], v[210:213], v[6:9]
	v_mfma_f32_16x16x32_bf16 v[2:5], v[178:181], v[210:213], v[2:5]
	v_mfma_f32_16x16x32_bf16 v[54:57], v[166:169], v[190:193], v[54:57]
	v_mfma_f32_16x16x32_bf16 v[46:49], v[182:185], v[190:193], v[46:49]
	v_mfma_f32_16x16x32_bf16 v[38:41], v[166:169], v[198:201], v[38:41]
	v_mfma_f32_16x16x32_bf16 v[30:33], v[182:185], v[198:201], v[30:33]
	v_mfma_f32_16x16x32_bf16 v[22:25], v[166:169], v[206:209], v[22:25]
	v_mfma_f32_16x16x32_bf16 v[14:17], v[182:185], v[206:209], v[14:17]
	v_mfma_f32_16x16x32_bf16 v[6:9], v[166:169], v[214:217], v[6:9]
	v_mfma_f32_16x16x32_bf16 v[2:5], v[182:185], v[214:217], v[2:5]
	s_setprio 0
	s_barrier
; #define PG8_STAGE(bufoff, gbase, voff) do { _Pragma("unroll") for (int _i = 0; _i < 2; ++_i) \
;         __builtin_amdgcn_global_load_lds((const unsigned*)((const char*)(gbase) + (voff)[_i]), (PG8_LAS unsigned*)(lds + (bufoff) + ldsw + _i * 8192), 16, 0, 0); } while (0)
; #define PG8_LDA(dst, b, h) do { _Pragma("unroll") for (int m = 0; m < 4; ++m) _Pragma("unroll") for (int k = 0; k < 2; ++k) dst[m][k] = *(const PG8_LAS bf16x8*)(lds + PG8_SA(b, h) + aoff + m * 2048 + k * 1024); } while (0)
; #define PG8_LDB(dst, b, h) do { _Pragma("unroll") for (int n = 0; n < 2; ++n) _Pragma("unroll") for (int k = 0; k < 2; ++k) dst[n][k] = *(const PG8_LAS bf16x8*)(lds + PG8_SB(b, h) + boff + n * 2048 + k * 1024); } while (0)
; #define PG8_MMA(ai, bj, At, Bt) do { __builtin_amdgcn_s_setprio(1); _Pragma("unroll") for (int m = 0; m < 4; ++m) _Pragma("unroll") for (int n = 0; n < 2; ++n) _Pragma("unroll") for (int k = 0; k < 2; ++k) \
;         acc[ai][bj][m][n] = __builtin_amdgcn_mfma_f32_16x16x32_bf16(Bt[n][k], At[m][k], acc[ai][bj][m][n], 0, 0, 0); __builtin_amdgcn_s_setprio(0); } while (0)
; #define PG8_WAIT_V(n) asm volatile("s_waitcnt vmcnt(" #n ")" ::: "memory")
; #define PG8_WAIT_L(n) asm volatile("s_waitcnt lgkmcnt(" #n ")" ::: "memory")
; #define PG8_BAR __builtin_amdgcn_s_barrier()
; #define PG8_SCHED __builtin_amdgcn_sched_barrier(0)
; template <class Epi, class Sched, bool ALIGN_EPI = false, bool SP2 = false>
; __device__ __forceinline__ void gemm_phase(PG8_LAS unsigned char* lds, const Gemm g, const Sched& S, const Epi& E) {
;     ...
;             PG8_LDB(B0, 1, 0); PG8_LDB(B1, 1, 1); PG8_SCHED; PG8_LDA(At, 1, 0); PG8_STAGE(PG8_SA(0, 1), a2 + hstep, voffA);
;             PG8_WAIT_V(8); PG8_WAIT_L(0); PG8_BAR; PG8_MMA(0, 0, At, B0); PG8_MMA(0, 1, At, B1); PG8_BAR; PG8_SCHED;
;             PG8_LDA(At, 1, 1); PG8_STAGE(PG8_SB(1, 0), b3, voffB); PG8_STAGE(PG8_SB(1, 1), b3 + hstep, voffB); PG8_STAGE(PG8_SA(1, 0), a3, voffA);
	s_add_i32 s56, 0, 0x18000
	s_add_i32 s57, 0, 0x1c000
	v_add_u32_e32 v142, s56, v173
	v_add_u32_e32 v182, s57, v173
	ds_read_b128 v[130:133], v142
	ds_read_b128 v[134:137], v142 offset:1024
	ds_read_b128 v[138:141], v142 offset:2048
	ds_read_b128 v[142:145], v142 offset:3072
	ds_read_b128 v[162:165], v182
	ds_read_b128 v[166:169], v182 offset:1024
	ds_read_b128 v[178:181], v182 offset:2048
	ds_read_b128 v[182:185], v182 offset:3072
	s_add_u32 s36, s36, 0x80000
	s_addc_u32 s37, s37, 0
	s_mov_b32 m0, s40
	v_lshl_add_u64 v[226:227], s[36:37], 0, v[146:147]
	ds_read_b128 v[186:189], v177 offset:32768
	ds_read_b128 v[190:193], v177 offset:33792
	ds_read_b128 v[194:197], v177 offset:34816
	ds_read_b128 v[198:201], v177 offset:35840
	ds_read_b128 v[202:205], v177 offset:36864
	ds_read_b128 v[206:209], v177 offset:37888
	ds_read_b128 v[210:213], v177 offset:38912
	ds_read_b128 v[214:217], v177 offset:39936
	global_load_lds_dwordx4 v[226:227], off
	v_lshl_add_u64 v[226:227], s[36:37], 0, v[150:151]
	s_mov_b32 m0, s41
	s_nop 0
	global_load_lds_dwordx4 v[226:227], off
	s_waitcnt vmcnt(8)
	s_waitcnt lgkmcnt(0)
	s_barrier
	s_setprio 1
	s_waitcnt lgkmcnt(0)
	v_mfma_f32_16x16x32_bf16 v[126:129], v[130:133], v[186:189], v[126:129]
	v_mfma_f32_16x16x32_bf16 v[122:125], v[138:141], v[186:189], v[122:125]
	v_mfma_f32_16x16x32_bf16 v[118:121], v[130:133], v[194:197], v[118:121]
	v_mfma_f32_16x16x32_bf16 v[114:117], v[138:141], v[194:197], v[114:117]
	v_mfma_f32_16x16x32_bf16 v[98:101], v[130:133], v[202:205], v[98:101]
	v_mfma_f32_16x16x32_bf16 v[90:93], v[138:141], v[202:205], v[90:93]
	v_mfma_f32_16x16x32_bf16 v[86:89], v[130:133], v[210:213], v[86:89]
	v_mfma_f32_16x16x32_bf16 v[78:81], v[138:141], v[210:213], v[78:81]
	v_mfma_f32_16x16x32_bf16 v[126:129], v[134:137], v[190:193], v[126:129]
	v_mfma_f32_16x16x32_bf16 v[122:125], v[142:145], v[190:193], v[122:125]
	v_mfma_f32_16x16x32_bf16 v[118:121], v[134:137], v[198:201], v[118:121]
	v_mfma_f32_16x16x32_bf16 v[114:117], v[142:145], v[198:201], v[114:117]
	v_mfma_f32_16x16x32_bf16 v[98:101], v[134:137], v[206:209], v[98:101]
	v_mfma_f32_16x16x32_bf16 v[90:93], v[142:145], v[206:209], v[90:93]
	v_mfma_f32_16x16x32_bf16 v[86:89], v[134:137], v[214:217], v[86:89]
	v_mfma_f32_16x16x32_bf16 v[78:81], v[142:145], v[214:217], v[78:81]
	s_setprio 0
	s_setprio 1
	v_mfma_f32_16x16x32_bf16 v[110:113], v[162:165], v[186:189], v[110:113]
	v_mfma_f32_16x16x32_bf16 v[106:109], v[178:181], v[186:189], v[106:109]
	v_mfma_f32_16x16x32_bf16 v[102:105], v[162:165], v[194:197], v[102:105]
	v_mfma_f32_16x16x32_bf16 v[94:97], v[178:181], v[194:197], v[94:97]
	v_mfma_f32_16x16x32_bf16 v[82:85], v[162:165], v[202:205], v[82:85]
	v_mfma_f32_16x16x32_bf16 v[74:77], v[178:181], v[202:205], v[74:77]
	v_mfma_f32_16x16x32_bf16 v[70:73], v[162:165], v[210:213], v[70:73]
	v_mfma_f32_16x16x32_bf16 v[66:69], v[178:181], v[210:213], v[66:69]
	v_mfma_f32_16x16x32_bf16 v[110:113], v[166:169], v[190:193], v[110:113]
	v_mfma_f32_16x16x32_bf16 v[106:109], v[182:185], v[190:193], v[106:109]
	v_mfma_f32_16x16x32_bf16 v[102:105], v[166:169], v[198:201], v[102:105]
	v_mfma_f32_16x16x32_bf16 v[94:97], v[182:185], v[198:201], v[94:97]
	v_mfma_f32_16x16x32_bf16 v[82:85], v[166:169], v[206:209], v[82:85]
	v_mfma_f32_16x16x32_bf16 v[74:77], v[182:185], v[206:209], v[74:77]
	v_mfma_f32_16x16x32_bf16 v[70:73], v[166:169], v[214:217], v[70:73]
	v_mfma_f32_16x16x32_bf16 v[66:69], v[182:185], v[214:217], v[66:69]
	s_setprio 0
	s_barrier
	s_add_i32 s36, s56, s38
	v_lshl_add_u64 v[170:171], v[170:171], 0, s[8:9]
	s_mov_b32 m0, s36
	ds_read_b128 v[186:189], v177 offset:49152
	ds_read_b128 v[190:193], v177 offset:50176
	ds_read_b128 v[194:197], v177 offset:51200
	ds_read_b128 v[198:201], v177 offset:52224
	ds_read_b128 v[202:205], v177 offset:53248
	ds_read_b128 v[206:209], v177 offset:54272
	ds_read_b128 v[210:213], v177 offset:55296
	ds_read_b128 v[214:217], v177 offset:56320
	global_load_lds_dwordx4 v[170:171], off
	s_add_i32 m0, s36, 0x2000
	s_add_u32 s34, s34, 0x80080
	v_lshl_add_u64 v[170:171], v[220:221], 0, s[8:9]
	s_addc_u32 s35, s35, 0
	s_add_i32 s36, s57, s38
	global_load_lds_dwordx4 v[170:171], off
	v_lshl_add_u64 v[170:171], s[34:35], 0, v[148:149]
	s_mov_b32 m0, s36
	s_nop 0
	global_load_lds_dwordx4 v[170:171], off
	v_lshl_add_u64 v[170:171], s[34:35], 0, v[152:153]
	s_add_i32 m0, s36, 0x2000
	s_nop 0
	global_load_lds_dwordx4 v[170:171], off
	v_lshl_add_u64 v[170:171], v[222:223], 0, s[8:9]
	s_mov_b32 m0, s43
	s_nop 0
	global_load_lds_dwordx4 v[170:171], off
	v_lshl_add_u64 v[170:171], v[224:225], 0, s[8:9]
	s_mov_b32 m0, s46
	s_nop 0
	global_load_lds_dwordx4 v[170:171], off
	s_waitcnt vmcnt(8)
	s_waitcnt lgkmcnt(0)
	s_barrier
; #define PG8_STAGE(bufoff, gbase, voff) do { _Pragma("unroll") for (int _i = 0; _i < 2; ++_i) \
;         __builtin_amdgcn_global_load_lds((const unsigned*)((const char*)(gbase) + (voff)[_i]), (PG8_LAS unsigned*)(lds + (bufoff) + ldsw + _i * 8192), 16, 0, 0); } while (0)
; #define PG8_LDA(dst, b, h) do { _Pragma("unroll") for (int m = 0; m < 4; ++m) _Pragma("unroll") for (int k = 0; k < 2; ++k) dst[m][k] = *(const PG8_LAS bf16x8*)(lds + PG8_SA(b, h) + aoff + m * 2048 + k * 1024); } while (0)
; #define PG8_LDB(dst, b, h) do { _Pragma("unroll") for (int n = 0; n < 2; ++n) _Pragma("unroll") for (int k = 0; k < 2; ++k) dst[n][k] = *(const PG8_LAS bf16x8*)(lds + PG8_SB(b, h) + boff + n * 2048 + k * 1024); } while (0)
; #define PG8_MMA(ai, bj, At, Bt) do { __builtin_amdgcn_s_setprio(1); _Pragma("unroll") for (int m = 0; m < 4; ++m) _Pragma("unroll") for (int n = 0; n < 2; ++n) _Pragma("unroll") for (int k = 0; k < 2; ++k) \
;         acc[ai][bj][m][n] = __builtin_amdgcn_mfma_f32_16x16x32_bf16(Bt[n][k], At[m][k], acc[ai][bj][m][n], 0, 0, 0); __builtin_amdgcn_s_setprio(0); } while (0)
; #define PG8_WAIT_V(n) asm volatile("s_waitcnt vmcnt(" #n ")" ::: "memory")
; template <class Epi, class Sched, bool ALIGN_EPI = false, bool SP2 = false>
; __device__ __forceinline__ void gemm_phase(PG8_LAS unsigned char* lds, const Gemm g, const Sched& S, const Epi& E) {
;     ...
;             PG8_LDB(B0, 0, 0); PG8_LDB(B1, 0, 1); PG8_SCHED; PG8_LDA(At, 0, 0); PG8_STAGE(PG8_SA(1, 1), a1 + hstep, voffA);
;             PG8_WAIT_V(8); PG8_WAIT_L(0); PG8_BAR; PG8_MMA(0, 0, At, B0); PG8_MMA(0, 1, At, B1); PG8_BAR; PG8_SCHED;
;             PG8_LDA(At, 0, 1); PG8_STAGE(PG8_SB(0, 0), b2, voffB); PG8_STAGE(PG8_SB(0, 1), b2 + hstep, voffB); PG8_STAGE(PG8_SA(0, 0), a2, voffA);
;             PG8_WAIT_V(8); PG8_WAIT_L(0); PG8_BAR; PG8_MMA(1, 0, At, B0); PG8_MMA(1, 1, At, B1); PG8_BAR; PG8_SCHED;
;             PG8_LDB(B0, 1, 0); PG8_LDB(B1, 1, 1); PG8_SCHED; PG8_LDA(At, 1, 0); PG8_STAGE(PG8_SA(0, 1), a2 + hstep, voffA);
;             PG8_WAIT_V(8); PG8_WAIT_L(0); PG8_BAR; PG8_MMA(0, 0, At, B0); PG8_MMA(0, 1, At, B1); PG8_BAR; PG8_SCHED;
;             PG8_LDA(At, 1, 1); PG8_STAGE(PG8_SB(1, 0), b3, voffB); PG8_STAGE(PG8_SB(1, 1), b3 + hstep, voffB); PG8_STAGE(PG8_SA(1, 0), a3, voffA);
;             PG8_WAIT_V(8); PG8_WAIT_L(0); PG8_BAR; PG8_MMA(1, 0, At, B0); PG8_MMA(1, 1, At, B1); PG8_BAR; PG8_SCHED;
	s_setprio 1
	s_waitcnt lgkmcnt(0)
	v_mfma_f32_16x16x32_bf16 v[62:65], v[130:133], v[186:189], v[62:65]
	v_mfma_f32_16x16x32_bf16 v[58:61], v[138:141], v[186:189], v[58:61]
	v_mfma_f32_16x16x32_bf16 v[50:53], v[130:133], v[194:197], v[50:53]
	v_mfma_f32_16x16x32_bf16 v[42:45], v[138:141], v[194:197], v[42:45]
	v_mfma_f32_16x16x32_bf16 v[34:37], v[130:133], v[202:205], v[34:37]
	v_mfma_f32_16x16x32_bf16 v[26:29], v[138:141], v[202:205], v[26:29]
	v_mfma_f32_16x16x32_bf16 v[18:21], v[130:133], v[210:213], v[18:21]
	v_mfma_f32_16x16x32_bf16 v[10:13], v[138:141], v[210:213], v[10:13]
	v_mfma_f32_16x16x32_bf16 v[62:65], v[134:137], v[190:193], v[62:65]
	v_mfma_f32_16x16x32_bf16 v[58:61], v[142:145], v[190:193], v[58:61]
	v_mfma_f32_16x16x32_bf16 v[50:53], v[134:137], v[198:201], v[50:53]
	v_mfma_f32_16x16x32_bf16 v[42:45], v[142:145], v[198:201], v[42:45]
	v_mfma_f32_16x16x32_bf16 v[34:37], v[134:137], v[206:209], v[34:37]
	v_mfma_f32_16x16x32_bf16 v[26:29], v[142:145], v[206:209], v[26:29]
	v_mfma_f32_16x16x32_bf16 v[18:21], v[134:137], v[214:217], v[18:21]
	v_mfma_f32_16x16x32_bf16 v[10:13], v[142:145], v[214:217], v[10:13]
	s_setprio 0
	s_setprio 1
	v_mfma_f32_16x16x32_bf16 v[54:57], v[162:165], v[186:189], v[54:57]
	v_mfma_f32_16x16x32_bf16 v[46:49], v[178:181], v[186:189], v[46:49]
	v_mfma_f32_16x16x32_bf16 v[38:41], v[162:165], v[194:197], v[38:41]
	v_mfma_f32_16x16x32_bf16 v[30:33], v[178:181], v[194:197], v[30:33]
	v_mfma_f32_16x16x32_bf16 v[22:25], v[162:165], v[202:205], v[22:25]
	v_mfma_f32_16x16x32_bf16 v[14:17], v[178:181], v[202:205], v[14:17]
	v_mfma_f32_16x16x32_bf16 v[6:9], v[162:165], v[210:213], v[6:9]
	v_mfma_f32_16x16x32_bf16 v[2:5], v[178:181], v[210:213], v[2:5]
	v_mfma_f32_16x16x32_bf16 v[54:57], v[166:169], v[190:193], v[54:57]
	v_mfma_f32_16x16x32_bf16 v[46:49], v[182:185], v[190:193], v[46:49]
	v_mfma_f32_16x16x32_bf16 v[38:41], v[166:169], v[198:201], v[38:41]
	v_mfma_f32_16x16x32_bf16 v[30:33], v[182:185], v[198:201], v[30:33]
	v_mfma_f32_16x16x32_bf16 v[22:25], v[166:169], v[206:209], v[22:25]
	v_mfma_f32_16x16x32_bf16 v[14:17], v[182:185], v[206:209], v[14:17]
	v_mfma_f32_16x16x32_bf16 v[6:9], v[166:169], v[214:217], v[6:9]
	v_mfma_f32_16x16x32_bf16 v[2:5], v[182:185], v[214:217], v[2:5]
	s_setprio 0
	s_barrier
	s_add_i32 s55, s55, 2
	s_add_u32 s30, s30, 0x100
	s_addc_u32 s31, s31, 0
	s_add_u32 s53, s53, 0x100
	s_addc_u32 s54, s54, 0
	s_cmp_gt_u32 s55, 29
	s_cbranch_scc0 .LBB0_1797
	s_branch .Lpeel_after_7
.Lpeel_7:
	ds_read_b128 v[130:133], v175
	ds_read_b128 v[134:137], v175 offset:1024
	ds_read_b128 v[138:141], v175 offset:2048
	ds_read_b128 v[142:145], v175 offset:3072
	ds_read_b128 v[162:165], v176
	ds_read_b128 v[166:169], v176 offset:1024
	ds_read_b128 v[178:181], v176 offset:2048
	ds_read_b128 v[182:185], v176 offset:3072
	s_add_u32 s34, s30, 0xfff80080
	s_addc_u32 s35, s31, -1
	s_cmp_eq_u32 s55, 28
	s_cselect_b32 s37, s23, s35
	s_cselect_b32 s36, s51, s34
	s_cselect_b32 s35, s21, s54
	s_cselect_b32 s34, s52, s53
	v_lshl_add_u64 v[170:171], s[30:31], 0, v[154:155]
	s_add_i32 m0, s29, 0xc000
	ds_read_b128 v[186:189], v177
	ds_read_b128 v[190:193], v177 offset:1024
	ds_read_b128 v[194:197], v177 offset:2048
	ds_read_b128 v[198:201], v177 offset:3072
	ds_read_b128 v[202:205], v177 offset:4096
	ds_read_b128 v[206:209], v177 offset:5120
	ds_read_b128 v[210:213], v177 offset:6144
	ds_read_b128 v[214:217], v177 offset:7168
	global_load_lds_dwordx4 v[170:171], off
	v_lshl_add_u64 v[170:171], s[30:31], 0, v[156:157]
	s_add_i32 m0, s29, 0xe000
	s_nop 0
	global_load_lds_dwordx4 v[170:171], off
	s_waitcnt vmcnt(40)
	s_waitcnt lgkmcnt(0)
	s_barrier
	s_setprio 1
	s_waitcnt lgkmcnt(0)
	v_mfma_f32_16x16x32_bf16 v[126:129], v[130:133], v[186:189], 0
	v_mfma_f32_16x16x32_bf16 v[122:125], v[138:141], v[186:189], 0
	v_mfma_f32_16x16x32_bf16 v[118:121], v[130:133], v[194:197], 0
	v_mfma_f32_16x16x32_bf16 v[114:117], v[138:141], v[194:197], 0
	v_mfma_f32_16x16x32_bf16 v[98:101], v[130:133], v[202:205], 0
	v_mfma_f32_16x16x32_bf16 v[90:93], v[138:141], v[202:205], 0
	v_mfma_f32_16x16x32_bf16 v[86:89], v[130:133], v[210:213], 0
	v_mfma_f32_16x16x32_bf16 v[78:81], v[138:141], v[210:213], 0
	v_mfma_f32_16x16x32_bf16 v[126:129], v[134:137], v[190:193], v[126:129]
	v_mfma_f32_16x16x32_bf16 v[122:125], v[142:145], v[190:193], v[122:125]
	v_mfma_f32_16x16x32_bf16 v[118:121], v[134:137], v[198:201], v[118:121]
	v_mfma_f32_16x16x32_bf16 v[114:117], v[142:145], v[198:201], v[114:117]
	v_mfma_f32_16x16x32_bf16 v[98:101], v[134:137], v[206:209], v[98:101]
	v_mfma_f32_16x16x32_bf16 v[90:93], v[142:145], v[206:209], v[90:93]
	v_mfma_f32_16x16x32_bf16 v[86:89], v[134:137], v[214:217], v[86:89]
	v_mfma_f32_16x16x32_bf16 v[78:81], v[142:145], v[214:217], v[78:81]
	s_setprio 0
	s_setprio 1
	v_mfma_f32_16x16x32_bf16 v[110:113], v[162:165], v[186:189], 0
	v_mfma_f32_16x16x32_bf16 v[106:109], v[178:181], v[186:189], 0
	v_mfma_f32_16x16x32_bf16 v[102:105], v[162:165], v[194:197], 0
	v_mfma_f32_16x16x32_bf16 v[94:97], v[178:181], v[194:197], 0
	v_mfma_f32_16x16x32_bf16 v[82:85], v[162:165], v[202:205], 0
	v_mfma_f32_16x16x32_bf16 v[74:77], v[178:181], v[202:205], 0
	v_mfma_f32_16x16x32_bf16 v[70:73], v[162:165], v[210:213], 0
	v_mfma_f32_16x16x32_bf16 v[66:69], v[178:181], v[210:213], 0
	v_mfma_f32_16x16x32_bf16 v[110:113], v[166:169], v[190:193], v[110:113]
	v_mfma_f32_16x16x32_bf16 v[106:109], v[182:185], v[190:193], v[106:109]
	v_mfma_f32_16x16x32_bf16 v[102:105], v[166:169], v[198:201], v[102:105]
	v_mfma_f32_16x16x32_bf16 v[94:97], v[182:185], v[198:201], v[94:97]
	v_mfma_f32_16x16x32_bf16 v[82:85], v[166:169], v[206:209], v[82:85]
	v_mfma_f32_16x16x32_bf16 v[74:77], v[182:185], v[206:209], v[74:77]
	v_mfma_f32_16x16x32_bf16 v[70:73], v[166:169], v[214:217], v[70:73]
	v_mfma_f32_16x16x32_bf16 v[66:69], v[182:185], v[214:217], v[66:69]
	s_setprio 0
	s_barrier
; #define PG8_STAGE(bufoff, gbase, voff) do { _Pragma("unroll") for (int _i = 0; _i < 2; ++_i) \
;         __builtin_amdgcn_global_load_lds((const unsigned*)((const char*)(gbase) + (voff)[_i]), (PG8_LAS unsigned*)(lds + (bufoff) + ldsw + _i * 8192), 16, 0, 0); } while (0)
; #define PG8_LDA(dst, b, h) do { _Pragma("unroll") for (int m = 0; m < 4; ++m) _Pragma("unroll") for (int k = 0; k < 2; ++k) dst[m][k] = *(const PG8_LAS bf16x8*)(lds + PG8_SA(b, h) + aoff + m * 2048 + k * 1024); } while (0)
; #define PG8_LDB(dst, b, h) do { _Pragma("unroll") for (int n = 0; n < 2; ++n) _Pragma("unroll") for (int k = 0; k < 2; ++k) dst[n][k] = *(const PG8_LAS bf16x8*)(lds + PG8_SB(b, h) + boff + n * 2048 + k * 1024); } while (0)
; #define PG8_MMA(ai, bj, At, Bt) do { __builtin_amdgcn_s_setprio(1); _Pragma("unroll") for (int m = 0; m < 4; ++m) _Pragma("unroll") for (int n = 0; n < 2; ++n) _Pragma("unroll") for (int k = 0; k < 2; ++k) \
;         acc[ai][bj][m][n] = __builtin_amdgcn_mfma_f32_16x16x32_bf16(Bt[n][k], At[m][k], acc[ai][bj][m][n], 0, 0, 0); __builtin_amdgcn_s_setprio(0); } while (0)
; #define PG8_WAIT_V(n) asm volatile("s_waitcnt vmcnt(" #n ")" ::: "memory")
; #define PG8_WAIT_L(n) asm volatile("s_waitcnt lgkmcnt(" #n ")" ::: "memory")
; #define PG8_BAR __builtin_amdgcn_s_barrier()
; #define PG8_SCHED __builtin_amdgcn_sched_barrier(0)
; template <class Epi, class Sched, bool ALIGN_EPI = false, bool SP2 = false>
; __device__ __forceinline__ void gemm_phase(PG8_LAS unsigned char* lds, const Gemm g, const Sched& S, const Epi& E) {
;     ...
;             PG8_LDA(At, 0, 1); PG8_STAGE(PG8_SB(0, 0), b2, voffB); PG8_STAGE(PG8_SB(0, 1), b2 + hstep, voffB); PG8_STAGE(PG8_SA(0, 0), a2, voffA);
;             PG8_WAIT_V(8); PG8_WAIT_L(0); PG8_BAR; PG8_MMA(1, 0, At, B0); PG8_MMA(1, 1, At, B1); PG8_BAR; PG8_SCHED;
;             PG8_LDB(B0, 1, 0); PG8_LDB(B1, 1, 1); PG8_SCHED; PG8_LDA(At, 1, 0); PG8_STAGE(PG8_SA(0, 1), a2 + hstep, voffA);
;             PG8_WAIT_V(8); PG8_WAIT_L(0); PG8_BAR; PG8_MMA(0, 0, At, B0); PG8_MMA(0, 1, At, B1); PG8_BAR; PG8_SCHED;
	s_add_i32 s56, s48, s38
	v_lshl_add_u64 v[170:171], s[34:35], 0, v[148:149]
	s_mov_b32 m0, s56
	ds_read_b128 v[186:189], v177 offset:16384
	ds_read_b128 v[190:193], v177 offset:17408
	ds_read_b128 v[194:197], v177 offset:18432
	ds_read_b128 v[198:201], v177 offset:19456
	ds_read_b128 v[202:205], v177 offset:20480
	ds_read_b128 v[206:209], v177 offset:21504
	ds_read_b128 v[210:213], v177 offset:22528
	ds_read_b128 v[214:217], v177 offset:23552
	global_load_lds_dwordx4 v[170:171], off
	s_add_i32 m0, s56, 0x2000
	s_add_u32 s56, s34, 0x80000
	v_lshl_add_u64 v[220:221], s[34:35], 0, v[152:153]
	s_addc_u32 s57, s35, 0
	s_add_i32 s58, s49, s38
	global_load_lds_dwordx4 v[220:221], off
	v_lshl_add_u64 v[222:223], s[56:57], 0, v[148:149]
	s_mov_b32 m0, s58
	v_lshl_add_u64 v[224:225], s[36:37], 0, v[150:151]
	global_load_lds_dwordx4 v[222:223], off
	v_lshl_add_u64 v[222:223], s[56:57], 0, v[152:153]
	s_add_i32 m0, s58, 0x2000
	s_nop 0
	global_load_lds_dwordx4 v[222:223], off
	v_lshl_add_u64 v[222:223], s[36:37], 0, v[146:147]
	s_mov_b32 m0, s29
	s_nop 0
	global_load_lds_dwordx4 v[222:223], off
	s_mov_b32 m0, s39
	s_nop 0
	global_load_lds_dwordx4 v[224:225], off
	s_waitcnt vmcnt(40)
	s_waitcnt lgkmcnt(0)
	s_barrier
	s_setprio 1
	s_waitcnt lgkmcnt(0)
	v_mfma_f32_16x16x32_bf16 v[62:65], v[130:133], v[186:189], 0
	v_mfma_f32_16x16x32_bf16 v[58:61], v[138:141], v[186:189], 0
	v_mfma_f32_16x16x32_bf16 v[50:53], v[130:133], v[194:197], 0
	v_mfma_f32_16x16x32_bf16 v[42:45], v[138:141], v[194:197], 0
	v_mfma_f32_16x16x32_bf16 v[34:37], v[130:133], v[202:205], 0
	v_mfma_f32_16x16x32_bf16 v[26:29], v[138:141], v[202:205], 0
	v_mfma_f32_16x16x32_bf16 v[18:21], v[130:133], v[210:213], 0
	v_mfma_f32_16x16x32_bf16 v[10:13], v[138:141], v[210:213], 0
	v_mfma_f32_16x16x32_bf16 v[62:65], v[134:137], v[190:193], v[62:65]
	v_mfma_f32_16x16x32_bf16 v[58:61], v[142:145], v[190:193], v[58:61]
	v_mfma_f32_16x16x32_bf16 v[50:53], v[134:137], v[198:201], v[50:53]
	v_mfma_f32_16x16x32_bf16 v[42:45], v[142:145], v[198:201], v[42:45]
	v_mfma_f32_16x16x32_bf16 v[34:37], v[134:137], v[206:209], v[34:37]
	v_mfma_f32_16x16x32_bf16 v[26:29], v[142:145], v[206:209], v[26:29]
	v_mfma_f32_16x16x32_bf16 v[18:21], v[134:137], v[214:217], v[18:21]
	v_mfma_f32_16x16x32_bf16 v[10:13], v[142:145], v[214:217], v[10:13]
	s_setprio 0
	s_setprio 1
	v_mfma_f32_16x16x32_bf16 v[54:57], v[162:165], v[186:189], 0
	v_mfma_f32_16x16x32_bf16 v[46:49], v[178:181], v[186:189], 0
	v_mfma_f32_16x16x32_bf16 v[38:41], v[162:165], v[194:197], 0
	v_mfma_f32_16x16x32_bf16 v[30:33], v[178:181], v[194:197], 0
	v_mfma_f32_16x16x32_bf16 v[22:25], v[162:165], v[202:205], 0
	v_mfma_f32_16x16x32_bf16 v[14:17], v[178:181], v[202:205], 0
	v_mfma_f32_16x16x32_bf16 v[6:9], v[162:165], v[210:213], 0
	v_mfma_f32_16x16x32_bf16 v[2:5], v[178:181], v[210:213], 0
	v_mfma_f32_16x16x32_bf16 v[54:57], v[166:169], v[190:193], v[54:57]
	v_mfma_f32_16x16x32_bf16 v[46:49], v[182:185], v[190:193], v[46:49]
	v_mfma_f32_16x16x32_bf16 v[38:41], v[166:169], v[198:201], v[38:41]
	v_mfma_f32_16x16x32_bf16 v[30:33], v[182:185], v[198:201], v[30:33]
	v_mfma_f32_16x16x32_bf16 v[22:25], v[166:169], v[206:209], v[22:25]
	v_mfma_f32_16x16x32_bf16 v[14:17], v[182:185], v[206:209], v[14:17]
	v_mfma_f32_16x16x32_bf16 v[6:9], v[166:169], v[214:217], v[6:9]
	v_mfma_f32_16x16x32_bf16 v[2:5], v[182:185], v[214:217], v[2:5]
	s_setprio 0
	s_barrier
	s_add_i32 s56, 0, 0x18000
	s_add_i32 s57, 0, 0x1c000
	v_add_u32_e32 v142, s56, v173
	v_add_u32_e32 v182, s57, v173
	ds_read_b128 v[130:133], v142
	ds_read_b128 v[134:137], v142 offset:1024
	ds_read_b128 v[138:141], v142 offset:2048
	ds_read_b128 v[142:145], v142 offset:3072
	ds_read_b128 v[162:165], v182
	ds_read_b128 v[166:169], v182 offset:1024
	ds_read_b128 v[178:181], v182 offset:2048
	ds_read_b128 v[182:185], v182 offset:3072
	s_add_u32 s36, s36, 0x80000
	s_addc_u32 s37, s37, 0
	s_mov_b32 m0, s40
	v_lshl_add_u64 v[226:227], s[36:37], 0, v[146:147]
	ds_read_b128 v[186:189], v177 offset:32768
	ds_read_b128 v[190:193], v177 offset:33792
	ds_read_b128 v[194:197], v177 offset:34816
	ds_read_b128 v[198:201], v177 offset:35840
	ds_read_b128 v[202:205], v177 offset:36864
	ds_read_b128 v[206:209], v177 offset:37888
	ds_read_b128 v[210:213], v177 offset:38912
	ds_read_b128 v[214:217], v177 offset:39936
	global_load_lds_dwordx4 v[226:227], off
	v_lshl_add_u64 v[226:227], s[36:37], 0, v[150:151]
	s_mov_b32 m0, s41
	s_nop 0
	global_load_lds_dwordx4 v[226:227], off
	s_waitcnt vmcnt(8)
	s_waitcnt lgkmcnt(0)
	s_barrier
; #define PG8_STAGE(bufoff, gbase, voff) do { _Pragma("unroll") for (int _i = 0; _i < 2; ++_i) \
;         __builtin_amdgcn_global_load_lds((const unsigned*)((const char*)(gbase) + (voff)[_i]), (PG8_LAS unsigned*)(lds + (bufoff) + ldsw + _i * 8192), 16, 0, 0); } while (0)
; #define PG8_LDA(dst, b, h) do { _Pragma("unroll") for (int m = 0; m < 4; ++m) _Pragma("unroll") for (int k = 0; k < 2; ++k) dst[m][k] = *(const PG8_LAS bf16x8*)(lds + PG8_SA(b, h) + aoff + m * 2048 + k * 1024); } while (0)
; #define PG8_MMA(ai, bj, At, Bt) do { __builtin_amdgcn_s_setprio(1); _Pragma("unroll") for (int m = 0; m < 4; ++m) _Pragma("unroll") for (int n = 0; n < 2; ++n) _Pragma("unroll") for (int k = 0; k < 2; ++k) \
;         acc[ai][bj][m][n] = __builtin_amdgcn_mfma_f32_16x16x32_bf16(Bt[n][k], At[m][k], acc[ai][bj][m][n], 0, 0, 0); __builtin_amdgcn_s_setprio(0); } while (0)
; #define PG8_WAIT_V(n) asm volatile("s_waitcnt vmcnt(" #n ")" ::: "memory")
; #define PG8_WAIT_L(n) asm volatile("s_waitcnt lgkmcnt(" #n ")" ::: "memory")
; #define PG8_BAR __builtin_amdgcn_s_barrier()
; #define PG8_SCHED __builtin_amdgcn_sched_barrier(0)
; template <class Epi, class Sched, bool ALIGN_EPI = false, bool SP2 = false>
; __device__ __forceinline__ void gemm_phase(PG8_LAS unsigned char* lds, const Gemm g, const Sched& S, const Epi& E) {
;     ...
;             PG8_WAIT_V(8); PG8_WAIT_L(0); PG8_BAR; PG8_MMA(0, 0, At, B0); PG8_MMA(0, 1, At, B1); PG8_BAR; PG8_SCHED;
;             PG8_LDA(At, 1, 1); PG8_STAGE(PG8_SB(1, 0), b3, voffB); PG8_STAGE(PG8_SB(1, 1), b3 + hstep, voffB); PG8_STAGE(PG8_SA(1, 0), a3, voffA);
;             PG8_WAIT_V(8); PG8_WAIT_L(0); PG8_BAR; PG8_MMA(1, 0, At, B0); PG8_MMA(1, 1, At, B1); PG8_BAR; PG8_SCHED;
	s_setprio 1
	s_waitcnt lgkmcnt(0)
	v_mfma_f32_16x16x32_bf16 v[126:129], v[130:133], v[186:189], v[126:129]
	v_mfma_f32_16x16x32_bf16 v[122:125], v[138:141], v[186:189], v[122:125]
	v_mfma_f32_16x16x32_bf16 v[118:121], v[130:133], v[194:197], v[118:121]
	v_mfma_f32_16x16x32_bf16 v[114:117], v[138:141], v[194:197], v[114:117]
	v_mfma_f32_16x16x32_bf16 v[98:101], v[130:133], v[202:205], v[98:101]
	v_mfma_f32_16x16x32_bf16 v[90:93], v[138:141], v[202:205], v[90:93]
	v_mfma_f32_16x16x32_bf16 v[86:89], v[130:133], v[210:213], v[86:89]
	v_mfma_f32_16x16x32_bf16 v[78:81], v[138:141], v[210:213], v[78:81]
	v_mfma_f32_16x16x32_bf16 v[126:129], v[134:137], v[190:193], v[126:129]
	v_mfma_f32_16x16x32_bf16 v[122:125], v[142:145], v[190:193], v[122:125]
	v_mfma_f32_16x16x32_bf16 v[118:121], v[134:137], v[198:201], v[118:121]
	v_mfma_f32_16x16x32_bf16 v[114:117], v[142:145], v[198:201], v[114:117]
	v_mfma_f32_16x16x32_bf16 v[98:101], v[134:137], v[206:209], v[98:101]
	v_mfma_f32_16x16x32_bf16 v[90:93], v[142:145], v[206:209], v[90:93]
	v_mfma_f32_16x16x32_bf16 v[86:89], v[134:137], v[214:217], v[86:89]
	v_mfma_f32_16x16x32_bf16 v[78:81], v[142:145], v[214:217], v[78:81]
	s_setprio 0
	s_setprio 1
	v_mfma_f32_16x16x32_bf16 v[110:113], v[162:165], v[186:189], v[110:113]
	v_mfma_f32_16x16x32_bf16 v[106:109], v[178:181], v[186:189], v[106:109]
	v_mfma_f32_16x16x32_bf16 v[102:105], v[162:165], v[194:197], v[102:105]
	v_mfma_f32_16x16x32_bf16 v[94:97], v[178:181], v[194:197], v[94:97]
	v_mfma_f32_16x16x32_bf16 v[82:85], v[162:165], v[202:205], v[82:85]
	v_mfma_f32_16x16x32_bf16 v[74:77], v[178:181], v[202:205], v[74:77]
	v_mfma_f32_16x16x32_bf16 v[70:73], v[162:165], v[210:213], v[70:73]
	v_mfma_f32_16x16x32_bf16 v[66:69], v[178:181], v[210:213], v[66:69]
	v_mfma_f32_16x16x32_bf16 v[110:113], v[166:169], v[190:193], v[110:113]
	v_mfma_f32_16x16x32_bf16 v[106:109], v[182:185], v[190:193], v[106:109]
	v_mfma_f32_16x16x32_bf16 v[102:105], v[166:169], v[198:201], v[102:105]
	v_mfma_f32_16x16x32_bf16 v[94:97], v[182:185], v[198:201], v[94:97]
	v_mfma_f32_16x16x32_bf16 v[82:85], v[166:169], v[206:209], v[82:85]
	v_mfma_f32_16x16x32_bf16 v[74:77], v[182:185], v[206:209], v[74:77]
	v_mfma_f32_16x16x32_bf16 v[70:73], v[166:169], v[214:217], v[70:73]
	v_mfma_f32_16x16x32_bf16 v[66:69], v[182:185], v[214:217], v[66:69]
	s_setprio 0
	s_barrier
	s_add_i32 s36, s56, s38
	v_lshl_add_u64 v[170:171], v[170:171], 0, s[8:9]
	s_mov_b32 m0, s36
	ds_read_b128 v[186:189], v177 offset:49152
	ds_read_b128 v[190:193], v177 offset:50176
	ds_read_b128 v[194:197], v177 offset:51200
	ds_read_b128 v[198:201], v177 offset:52224
	ds_read_b128 v[202:205], v177 offset:53248
	ds_read_b128 v[206:209], v177 offset:54272
	ds_read_b128 v[210:213], v177 offset:55296
	ds_read_b128 v[214:217], v177 offset:56320
	global_load_lds_dwordx4 v[170:171], off
	s_add_i32 m0, s36, 0x2000
	s_add_u32 s34, s34, 0x80080
	v_lshl_add_u64 v[170:171], v[220:221], 0, s[8:9]
	s_addc_u32 s35, s35, 0
	s_add_i32 s36, s57, s38
	global_load_lds_dwordx4 v[170:171], off
	v_lshl_add_u64 v[170:171], s[34:35], 0, v[148:149]
	s_mov_b32 m0, s36
	s_nop 0
	global_load_lds_dwordx4 v[170:171], off
	v_lshl_add_u64 v[170:171], s[34:35], 0, v[152:153]
	s_add_i32 m0, s36, 0x2000
	s_nop 0
	global_load_lds_dwordx4 v[170:171], off
	v_lshl_add_u64 v[170:171], v[222:223], 0, s[8:9]
	s_mov_b32 m0, s43
	s_nop 0
	global_load_lds_dwordx4 v[170:171], off
	v_lshl_add_u64 v[170:171], v[224:225], 0, s[8:9]
	s_mov_b32 m0, s46
	s_nop 0
	global_load_lds_dwordx4 v[170:171], off
	s_waitcnt vmcnt(8)
	s_waitcnt lgkmcnt(0)
	s_barrier
	s_setprio 1
	s_waitcnt lgkmcnt(0)
	v_mfma_f32_16x16x32_bf16 v[62:65], v[130:133], v[186:189], v[62:65]
	v_mfma_f32_16x16x32_bf16 v[58:61], v[138:141], v[186:189], v[58:61]
	v_mfma_f32_16x16x32_bf16 v[50:53], v[130:133], v[194:197], v[50:53]
	v_mfma_f32_16x16x32_bf16 v[42:45], v[138:141], v[194:197], v[42:45]
	v_mfma_f32_16x16x32_bf16 v[34:37], v[130:133], v[202:205], v[34:37]
	v_mfma_f32_16x16x32_bf16 v[26:29], v[138:141], v[202:205], v[26:29]
	v_mfma_f32_16x16x32_bf16 v[18:21], v[130:133], v[210:213], v[18:21]
	v_mfma_f32_16x16x32_bf16 v[10:13], v[138:141], v[210:213], v[10:13]
	v_mfma_f32_16x16x32_bf16 v[62:65], v[134:137], v[190:193], v[62:65]
	v_mfma_f32_16x16x32_bf16 v[58:61], v[142:145], v[190:193], v[58:61]
	v_mfma_f32_16x16x32_bf16 v[50:53], v[134:137], v[198:201], v[50:53]
	v_mfma_f32_16x16x32_bf16 v[42:45], v[142:145], v[198:201], v[42:45]
	v_mfma_f32_16x16x32_bf16 v[34:37], v[134:137], v[206:209], v[34:37]
	v_mfma_f32_16x16x32_bf16 v[26:29], v[142:145], v[206:209], v[26:29]
	v_mfma_f32_16x16x32_bf16 v[18:21], v[134:137], v[214:217], v[18:21]
	v_mfma_f32_16x16x32_bf16 v[10:13], v[142:145], v[214:217], v[10:13]
	s_setprio 0
	s_setprio 1
	v_mfma_f32_16x16x32_bf16 v[54:57], v[162:165], v[186:189], v[54:57]
	v_mfma_f32_16x16x32_bf16 v[46:49], v[178:181], v[186:189], v[46:49]
	v_mfma_f32_16x16x32_bf16 v[38:41], v[162:165], v[194:197], v[38:41]
	v_mfma_f32_16x16x32_bf16 v[30:33], v[178:181], v[194:197], v[30:33]
	v_mfma_f32_16x16x32_bf16 v[22:25], v[162:165], v[202:205], v[22:25]
	v_mfma_f32_16x16x32_bf16 v[14:17], v[178:181], v[202:205], v[14:17]
	v_mfma_f32_16x16x32_bf16 v[6:9], v[162:165], v[210:213], v[6:9]
	v_mfma_f32_16x16x32_bf16 v[2:5], v[178:181], v[210:213], v[2:5]
	v_mfma_f32_16x16x32_bf16 v[54:57], v[166:169], v[190:193], v[54:57]
	v_mfma_f32_16x16x32_bf16 v[46:49], v[182:185], v[190:193], v[46:49]
	v_mfma_f32_16x16x32_bf16 v[38:41], v[166:169], v[198:201], v[38:41]
	v_mfma_f32_16x16x32_bf16 v[30:33], v[182:185], v[198:201], v[30:33]
	v_mfma_f32_16x16x32_bf16 v[22:25], v[166:169], v[206:209], v[22:25]
	v_mfma_f32_16x16x32_bf16 v[14:17], v[182:185], v[206:209], v[14:17]
	v_mfma_f32_16x16x32_bf16 v[6:9], v[166:169], v[214:217], v[6:9]
	v_mfma_f32_16x16x32_bf16 v[2:5], v[182:185], v[214:217], v[2:5]
	s_setprio 0
	s_barrier
	s_add_i32 s55, s55, 2
	s_add_u32 s30, s30, 0x100
	s_addc_u32 s31, s31, 0
	s_add_u32 s53, s53, 0x100
	s_addc_u32 s54, s54, 0
	s_cmp_gt_u32 s55, 29
	s_branch .LBB0_1797

; DI unsigned pk2(float lo, float hi) { f32x2 v = {lo, hi}; bf16x2_t b = __builtin_convertvector(v, bf16x2_t); return __builtin_bit_cast(unsigned, b); }
; DI f32x4 bf4_lo(u32x4 q) { return (f32x4){__builtin_bit_cast(float, q.x << 16), __builtin_bit_cast(float, q.x & 0xffff0000u), __builtin_bit_cast(float, q.y << 16), __builtin_bit_cast(float, q.y & 0xffff0000u)}; }
; DI f32x4 bf4_hi(u32x4 q) { return (f32x4){__builtin_bit_cast(float, q.z << 16), __builtin_bit_cast(float, q.z & 0xffff0000u), __builtin_bit_cast(float, q.w << 16), __builtin_bit_cast(float, q.w & 0xffff0000u)}; }
;     DI void operator()(const f32x4 (&acc)[2][2][4][2], const pg8::Unit& u, int wr, int wc, int fr, int fq) const {
;         const int row0 = u.pm * 256 + wr * 64 + fr, col0 = u.pn * 256 + wc * 32 + 8 * fq;
; #pragma unroll
;         for (int ai = 0; ai < 2; ++ai) {
;             u32x4 r[4][2];
; #pragma unroll
;             for (int m = 0; m < 4; ++m)
; #pragma unroll
;                 for (int bj = 0; bj < 2; ++bj) r[m][bj] = *(const u32x4*)(res + (size_t)(row0 + ai * 128 + m * 16) * DM + col0 + bj * 128);
;             asm volatile("" ::: "memory");
; #pragma unroll
;             for (int m = 0; m < 4; ++m)
; #pragma unroll
;                 for (int bj = 0; bj < 2; ++bj) { const f32x4 a = bf4_lo(r[m][bj]) * ALPHA + acc[ai][bj][m][0] * sc, b = bf4_hi(r[m][bj]) * ALPHA + acc[ai][bj][m][1] * sc;
;                     *(u32x4*)(out + (size_t)(row0 + ai * 128 + m * 16) * DM + col0 + bj * 128) = (u32x4){pk2(a[0], a[1]), pk2(a[2], a[3]), pk2(b[0], b[1]), pk2(b[2], b[3])}; }
;         }
.LBB0_1800:
	v_lshl_or_b32 v132, s50, 8, v174
	v_lshl_add_u32 v130, s28, 8, v172
	v_ashrrev_i32_e32 v133, 31, v132
	v_readlane_b32 s30, v253, 41
	v_lshlrev_b64 v[162:163], 1, v[132:133]
	v_readlane_b32 s31, v253, 42
	v_ashrrev_i32_e32 v131, 31, v130
	v_lshlrev_b64 v[166:167], 12, v[130:131]
	v_lshl_add_u64 v[164:165], s[30:31], 0, v[162:163]
	v_lshl_add_u64 v[132:133], v[164:165], 0, v[166:167]
	global_load_dwordx4 v[178:181], v[132:133], off
	global_load_dwordx4 v[182:185], v[132:133], off offset:256
	v_or_b32_e32 v132, 16, v130
	v_ashrrev_i32_e32 v133, 31, v132
	v_lshlrev_b64 v[134:135], 12, v[132:133]
	v_lshl_add_u64 v[132:133], v[164:165], 0, v[134:135]
	global_load_dwordx4 v[186:189], v[132:133], off
	global_load_dwordx4 v[190:193], v[132:133], off offset:256
	v_or_b32_e32 v132, 32, v130
	v_ashrrev_i32_e32 v133, 31, v132
	v_lshlrev_b64 v[170:171], 12, v[132:133]
	v_lshl_add_u64 v[138:139], v[164:165], 0, v[170:171]
	v_or_b32_e32 v136, 48, v130
	global_load_dwordx4 v[130:133], v[138:139], off
	v_readlane_b32 s30, v253, 55
	v_ashrrev_i32_e32 v137, 31, v136
	v_readlane_b32 s31, v253, 56
	v_lshlrev_b64 v[168:169], 12, v[136:137]
	v_lshl_add_u64 v[194:195], v[164:165], 0, v[168:169]
	v_lshl_add_u64 v[136:137], s[30:31], 0, v[166:167]
	v_lshl_add_u64 v[196:197], v[136:137], 0, v[162:163]
	v_lshl_add_u64 v[198:199], s[30:31], 0, v[134:135]
	global_load_dwordx4 v[142:145], v[138:139], off offset:256
	s_nop 0
	global_load_dwordx4 v[138:141], v[194:195], off
	global_load_dwordx4 v[134:137], v[194:195], off offset:256
	v_lshl_add_u64 v[194:195], v[198:199], 0, v[162:163]
	s_andn2_b64 vcc, exec, s[0:1]
	s_mov_b64 s[0:1], -1
	s_waitcnt vmcnt(0)
	v_lshlrev_b32_e32 v198, 16, v178
	v_and_b32_e32 v199, 0xffff0000, v178
	v_lshlrev_b32_e32 v178, 16, v179
	v_and_b32_e32 v179, 0xffff0000, v179
	v_lshlrev_b32_e32 v200, 16, v180
	v_and_b32_e32 v201, 0xffff0000, v180
	v_lshlrev_b32_e32 v180, 16, v181
	v_and_b32_e32 v181, 0xffff0000, v181
	v_lshlrev_b32_e32 v202, 16, v182
	v_and_b32_e32 v203, 0xffff0000, v182
	v_lshlrev_b32_e32 v182, 16, v183
	v_and_b32_e32 v183, 0xffff0000, v183
	v_lshlrev_b32_e32 v204, 16, v184
	v_and_b32_e32 v205, 0xffff0000, v184
	v_lshlrev_b32_e32 v184, 16, v185
	v_and_b32_e32 v185, 0xffff0000, v185
	v_lshlrev_b32_e32 v206, 16, v186
	v_and_b32_e32 v207, 0xffff0000, v186
	v_lshlrev_b32_e32 v186, 16, v187
	v_and_b32_e32 v187, 0xffff0000, v187
	v_lshlrev_b32_e32 v208, 16, v188
	v_and_b32_e32 v209, 0xffff0000, v188
	v_lshlrev_b32_e32 v188, 16, v189
	v_and_b32_e32 v189, 0xffff0000, v189
	v_lshlrev_b32_e32 v210, 16, v190
	v_and_b32_e32 v211, 0xffff0000, v190
	v_lshlrev_b32_e32 v190, 16, v191
	v_and_b32_e32 v191, 0xffff0000, v191
	v_pk_fma_f32 v[128:129], v[178:179], s[12:13], v[128:129] op_sel_hi:[1,0,1]
	v_pk_fma_f32 v[126:127], v[198:199], s[12:13], v[126:127] op_sel_hi:[1,0,1]
	v_pk_fma_f32 v[124:125], v[180:181], s[12:13], v[124:125] op_sel_hi:[1,0,1]
	v_pk_fma_f32 v[122:123], v[200:201], s[12:13], v[122:123] op_sel_hi:[1,0,1]
	v_pk_fma_f32 v[112:113], v[182:183], s[12:13], v[112:113] op_sel_hi:[1,0,1]
	v_pk_fma_f32 v[110:111], v[202:203], s[12:13], v[110:111] op_sel_hi:[1,0,1]
	v_pk_fma_f32 v[178:179], v[184:185], s[12:13], v[108:109] op_sel_hi:[1,0,1]
	v_pk_fma_f32 v[180:181], v[204:205], s[12:13], v[106:107] op_sel_hi:[1,0,1]
	v_pk_fma_f32 v[120:121], v[186:187], s[12:13], v[120:121] op_sel_hi:[1,0,1]
	v_pk_fma_f32 v[118:119], v[206:207], s[12:13], v[118:119] op_sel_hi:[1,0,1]
	v_pk_fma_f32 v[116:117], v[188:189], s[12:13], v[116:117] op_sel_hi:[1,0,1]
	v_pk_fma_f32 v[114:115], v[208:209], s[12:13], v[114:115] op_sel_hi:[1,0,1]
	v_pk_fma_f32 v[182:183], v[190:191], s[12:13], v[104:105] op_sel_hi:[1,0,1]
	v_cvt_pk_bf16_f32 v104, v126, v127
	v_cvt_pk_bf16_f32 v105, v128, v129
	v_cvt_pk_bf16_f32 v106, v122, v123
	v_cvt_pk_bf16_f32 v107, v124, v125
	v_cvt_pk_bf16_f32 v108, v110, v111
	v_cvt_pk_bf16_f32 v109, v112, v113
	v_cvt_pk_bf16_f32 v110, v180, v181
	v_cvt_pk_bf16_f32 v111, v178, v179
	v_cvt_pk_bf16_f32 v112, v118, v119
	v_cvt_pk_bf16_f32 v113, v120, v121
	v_cvt_pk_bf16_f32 v114, v114, v115
	v_cvt_pk_bf16_f32 v115, v116, v117
	global_store_dwordx4 v[196:197], v[104:107], off
	global_store_dwordx4 v[196:197], v[108:111], off offset:256
	global_store_dwordx4 v[194:195], v[112:115], off
	v_lshlrev_b32_e32 v104, 16, v192
	v_and_b32_e32 v105, 0xffff0000, v192
	v_lshlrev_b32_e32 v106, 16, v193
	v_and_b32_e32 v107, 0xffff0000, v193
	v_pk_fma_f32 v[102:103], v[210:211], s[12:13], v[102:103] op_sel_hi:[1,0,1]
	v_pk_fma_f32 v[106:107], v[106:107], s[12:13], v[96:97] op_sel_hi:[1,0,1]
	v_pk_fma_f32 v[96:97], v[104:105], s[12:13], v[94:95] op_sel_hi:[1,0,1]
	v_cvt_pk_bf16_f32 v94, v102, v103
	v_cvt_pk_bf16_f32 v95, v182, v183
	v_cvt_pk_bf16_f32 v96, v96, v97
	v_cvt_pk_bf16_f32 v97, v106, v107
	v_lshl_add_u64 v[104:105], v[166:167], 0, s[4:5]
	global_store_dwordx4 v[194:195], v[94:97], off offset:256
	v_lshl_add_u64 v[106:107], v[164:165], 0, v[104:105]
	v_lshlrev_b32_e32 v102, 16, v132
	v_lshlrev_b32_e32 v94, 16, v130
	v_and_b32_e32 v95, 0xffff0000, v130
	v_lshlrev_b32_e32 v96, 16, v131
	v_and_b32_e32 v97, 0xffff0000, v131
	v_pk_fma_f32 v[100:101], v[96:97], s[12:13], v[100:101] op_sel_hi:[1,0,1]
	v_pk_fma_f32 v[98:99], v[94:95], s[12:13], v[98:99] op_sel_hi:[1,0,1]
	global_load_dwordx4 v[94:97], v[106:107], off
	v_and_b32_e32 v103, 0xffff0000, v132
	v_lshlrev_b32_e32 v108, 16, v133
	v_and_b32_e32 v109, 0xffff0000, v133
	v_pk_fma_f32 v[108:109], v[108:109], s[12:13], v[92:93] op_sel_hi:[1,0,1]
	v_pk_fma_f32 v[92:93], v[102:103], s[12:13], v[90:91] op_sel_hi:[1,0,1]
	v_cvt_pk_bf16_f32 v90, v98, v99
	v_lshl_add_u64 v[98:99], s[30:31], 0, v[170:171]
; DI unsigned pk2(float lo, float hi) { f32x2 v = {lo, hi}; bf16x2_t b = __builtin_convertvector(v, bf16x2_t); return __builtin_bit_cast(unsigned, b); }
; DI f32x4 bf4_lo(u32x4 q) { return (f32x4){__builtin_bit_cast(float, q.x << 16), __builtin_bit_cast(float, q.x & 0xffff0000u), __builtin_bit_cast(float, q.y << 16), __builtin_bit_cast(float, q.y & 0xffff0000u)}; }
; DI f32x4 bf4_hi(u32x4 q) { return (f32x4){__builtin_bit_cast(float, q.z << 16), __builtin_bit_cast(float, q.z & 0xffff0000u), __builtin_bit_cast(float, q.w << 16), __builtin_bit_cast(float, q.w & 0xffff0000u)}; }
;     DI void operator()(const f32x4 (&acc)[2][2][4][2], const pg8::Unit& u, int wr, int wc, int fr, int fq) const {
;     ...
;             for (int m = 0; m < 4; ++m)
; #pragma unroll
;                 for (int bj = 0; bj < 2; ++bj) r[m][bj] = *(const u32x4*)(res + (size_t)(row0 + ai * 128 + m * 16) * DM + col0 + bj * 128);
;             asm volatile("" ::: "memory");
; #pragma unroll
;             for (int m = 0; m < 4; ++m)
; #pragma unroll
;                 for (int bj = 0; bj < 2; ++bj) { const f32x4 a = bf4_lo(r[m][bj]) * ALPHA + acc[ai][bj][m][0] * sc, b = bf4_hi(r[m][bj]) * ALPHA + acc[ai][bj][m][1] * sc;
;                     *(u32x4*)(out + (size_t)(row0 + ai * 128 + m * 16) * DM + col0 + bj * 128) = (u32x4){pk2(a[0], a[1]), pk2(a[2], a[3]), pk2(b[0], b[1]), pk2(b[2], b[3])}; }
;         }
	v_cvt_pk_bf16_f32 v91, v100, v101
	v_cvt_pk_bf16_f32 v92, v92, v93
	v_cvt_pk_bf16_f32 v93, v108, v109
	v_lshl_add_u64 v[98:99], v[98:99], 0, v[162:163]
	global_store_dwordx4 v[98:99], v[90:93], off
	v_lshlrev_b32_e32 v100, 16, v144
	v_and_b32_e32 v101, 0xffff0000, v144
	v_lshlrev_b32_e32 v90, 16, v142
	v_and_b32_e32 v91, 0xffff0000, v142
	v_lshlrev_b32_e32 v92, 16, v143
	v_and_b32_e32 v93, 0xffff0000, v143
	v_lshlrev_b32_e32 v102, 16, v145
	v_and_b32_e32 v103, 0xffff0000, v145
	v_pk_fma_f32 v[92:93], v[92:93], s[12:13], v[84:85] op_sel_hi:[1,0,1]
	v_pk_fma_f32 v[90:91], v[90:91], s[12:13], v[82:83] op_sel_hi:[1,0,1]
	global_load_dwordx4 v[82:85], v[106:107], off offset:256
	v_pk_fma_f32 v[102:103], v[102:103], s[12:13], v[76:77] op_sel_hi:[1,0,1]
	v_pk_fma_f32 v[76:77], v[100:101], s[12:13], v[74:75] op_sel_hi:[1,0,1]
	v_cvt_pk_bf16_f32 v74, v90, v91
	v_cvt_pk_bf16_f32 v75, v92, v93
	v_cvt_pk_bf16_f32 v76, v76, v77
	v_cvt_pk_bf16_f32 v77, v102, v103
	global_store_dwordx4 v[98:99], v[74:77], off offset:256
	v_lshl_add_u64 v[98:99], v[166:167], 0, s[14:15]
	v_lshl_add_u64 v[100:101], v[164:165], 0, v[98:99]
	v_lshlrev_b32_e32 v90, 16, v138
	v_and_b32_e32 v91, 0xffff0000, v138
	v_lshlrev_b32_e32 v92, 16, v139
	global_load_dwordx4 v[74:77], v[100:101], off
	v_and_b32_e32 v93, 0xffff0000, v139
	v_pk_fma_f32 v[88:89], v[92:93], s[12:13], v[88:89] op_sel_hi:[1,0,1]
	v_pk_fma_f32 v[86:87], v[90:91], s[12:13], v[86:87] op_sel_hi:[1,0,1]
	v_lshlrev_b32_e32 v90, 16, v140
	v_and_b32_e32 v91, 0xffff0000, v140
	v_lshlrev_b32_e32 v92, 16, v141
	v_and_b32_e32 v93, 0xffff0000, v141
	v_pk_fma_f32 v[92:93], v[92:93], s[12:13], v[80:81] op_sel_hi:[1,0,1]
	v_pk_fma_f32 v[80:81], v[90:91], s[12:13], v[78:79] op_sel_hi:[1,0,1]
	v_cvt_pk_bf16_f32 v78, v86, v87
	v_lshl_add_u64 v[86:87], s[30:31], 0, v[168:169]
	v_cvt_pk_bf16_f32 v79, v88, v89
	v_cvt_pk_bf16_f32 v80, v80, v81
	v_cvt_pk_bf16_f32 v81, v92, v93
	v_lshl_add_u64 v[86:87], v[86:87], 0, v[162:163]
	global_store_dwordx4 v[86:87], v[78:81], off
	global_load_dwordx4 v[78:81], v[100:101], off offset:256
	v_lshlrev_b32_e32 v88, 16, v134
	v_and_b32_e32 v89, 0xffff0000, v134
	v_lshlrev_b32_e32 v90, 16, v135
	v_and_b32_e32 v91, 0xffff0000, v135
	v_pk_fma_f32 v[72:73], v[90:91], s[12:13], v[72:73] op_sel_hi:[1,0,1]
	v_pk_fma_f32 v[70:71], v[88:89], s[12:13], v[70:71] op_sel_hi:[1,0,1]
	v_lshlrev_b32_e32 v88, 16, v136
	v_and_b32_e32 v89, 0xffff0000, v136
	v_lshlrev_b32_e32 v90, 16, v137
	v_and_b32_e32 v91, 0xffff0000, v137
	v_lshl_add_u64 v[100:101], v[166:167], 0, s[16:17]
	v_pk_fma_f32 v[90:91], v[90:91], s[12:13], v[68:69] op_sel_hi:[1,0,1]
	v_pk_fma_f32 v[68:69], v[88:89], s[12:13], v[66:67] op_sel_hi:[1,0,1]
	v_lshl_add_u64 v[88:89], v[164:165], 0, v[100:101]
	v_cvt_pk_bf16_f32 v66, v70, v71
	v_cvt_pk_bf16_f32 v67, v72, v73
	global_load_dwordx4 v[70:73], v[88:89], off
	v_cvt_pk_bf16_f32 v68, v68, v69
	v_cvt_pk_bf16_f32 v69, v90, v91
	global_store_dwordx4 v[86:87], v[66:69], off offset:256
	global_load_dwordx4 v[86:89], v[88:89], off offset:256
	v_lshl_add_u64 v[102:103], v[166:167], 0, s[18:19]
	v_lshl_add_u64 v[66:67], v[164:165], 0, v[102:103]
	global_load_dwordx4 v[90:93], v[66:67], off
	s_nop 0
	global_load_dwordx4 v[66:69], v[66:67], off offset:256
	s_waitcnt vmcnt(11)
	v_lshlrev_b32_e32 v106, 16, v94
	v_and_b32_e32 v107, 0xffff0000, v94
	v_lshlrev_b32_e32 v94, 16, v95
	v_and_b32_e32 v95, 0xffff0000, v95
	v_pk_fma_f32 v[64:65], v[94:95], s[12:13], v[64:65] op_sel_hi:[1,0,1]
	v_pk_fma_f32 v[62:63], v[106:107], s[12:13], v[62:63] op_sel_hi:[1,0,1]
	v_lshlrev_b32_e32 v94, 16, v96
	v_and_b32_e32 v95, 0xffff0000, v96
	v_lshlrev_b32_e32 v96, 16, v97
	v_and_b32_e32 v97, 0xffff0000, v97
	v_pk_fma_f32 v[96:97], v[96:97], s[12:13], v[60:61] op_sel_hi:[1,0,1]
	v_pk_fma_f32 v[60:61], v[94:95], s[12:13], v[58:59] op_sel_hi:[1,0,1]
	v_cvt_pk_bf16_f32 v58, v62, v63
	v_lshl_add_u64 v[62:63], s[30:31], 0, v[104:105]
	v_cvt_pk_bf16_f32 v59, v64, v65
	v_cvt_pk_bf16_f32 v60, v60, v61
	v_cvt_pk_bf16_f32 v61, v96, v97
	v_lshl_add_u64 v[62:63], v[62:63], 0, v[162:163]
	global_store_dwordx4 v[62:63], v[58:61], off
	s_waitcnt vmcnt(10)
	s_nop 0
	v_lshlrev_b32_e32 v58, 16, v82
	v_and_b32_e32 v59, 0xffff0000, v82
	v_lshlrev_b32_e32 v60, 16, v83
	v_and_b32_e32 v61, 0xffff0000, v83
	v_pk_fma_f32 v[56:57], v[60:61], s[12:13], v[56:57] op_sel_hi:[1,0,1]
	v_pk_fma_f32 v[54:55], v[58:59], s[12:13], v[54:55] op_sel_hi:[1,0,1]
	v_lshlrev_b32_e32 v58, 16, v84
	v_and_b32_e32 v59, 0xffff0000, v84
	v_lshlrev_b32_e32 v60, 16, v85
	v_and_b32_e32 v61, 0xffff0000, v85
	v_pk_fma_f32 v[60:61], v[60:61], s[12:13], v[48:49] op_sel_hi:[1,0,1]
	v_pk_fma_f32 v[48:49], v[58:59], s[12:13], v[46:47] op_sel_hi:[1,0,1]
	v_cvt_pk_bf16_f32 v46, v54, v55
	v_cvt_pk_bf16_f32 v47, v56, v57
	v_cvt_pk_bf16_f32 v48, v48, v49
	v_cvt_pk_bf16_f32 v49, v60, v61
	global_store_dwordx4 v[62:63], v[46:49], off offset:256
	s_waitcnt vmcnt(9)
; DI unsigned pk2(float lo, float hi) { f32x2 v = {lo, hi}; bf16x2_t b = __builtin_convertvector(v, bf16x2_t); return __builtin_bit_cast(unsigned, b); }
; DI f32x4 bf4_lo(u32x4 q) { return (f32x4){__builtin_bit_cast(float, q.x << 16), __builtin_bit_cast(float, q.x & 0xffff0000u), __builtin_bit_cast(float, q.y << 16), __builtin_bit_cast(float, q.y & 0xffff0000u)}; }
; DI f32x4 bf4_hi(u32x4 q) { return (f32x4){__builtin_bit_cast(float, q.z << 16), __builtin_bit_cast(float, q.z & 0xffff0000u), __builtin_bit_cast(float, q.w << 16), __builtin_bit_cast(float, q.w & 0xffff0000u)}; }
; template <class Epi, class Sched, bool ALIGN_EPI = false, bool SP2 = false>
; __device__ __forceinline__ void gemm_phase(PG8_LAS unsigned char* lds, const Gemm g, const Sched& S, const Epi& E) {
;     ...
;         if constexpr (!Epi::AFTER_DRAIN) { E(acc, cur, wr, wc, fr, fq); S.done(cur); }
;         if (!has_next) break;
;     DI void operator()(const f32x4 (&acc)[2][2][4][2], const pg8::Unit& u, int wr, int wc, int fr, int fq) const {
;     ...
; #pragma unroll
;             for (int m = 0; m < 4; ++m)
; #pragma unroll
;                 for (int bj = 0; bj < 2; ++bj) { const f32x4 a = bf4_lo(r[m][bj]) * ALPHA + acc[ai][bj][m][0] * sc, b = bf4_hi(r[m][bj]) * ALPHA + acc[ai][bj][m][1] * sc;
;                     *(u32x4*)(out + (size_t)(row0 + ai * 128 + m * 16) * DM + col0 + bj * 128) = (u32x4){pk2(a[0], a[1]), pk2(a[2], a[3]), pk2(b[0], b[1]), pk2(b[2], b[3])}; }
;         }
	s_nop 0
	v_lshlrev_b32_e32 v46, 16, v74
	v_and_b32_e32 v47, 0xffff0000, v74
	v_lshlrev_b32_e32 v48, 16, v75
	v_and_b32_e32 v49, 0xffff0000, v75
	v_pk_fma_f32 v[48:49], v[48:49], s[12:13], v[52:53] op_sel_hi:[1,0,1]
	v_pk_fma_f32 v[46:47], v[46:47], s[12:13], v[50:51] op_sel_hi:[1,0,1]
	v_lshlrev_b32_e32 v50, 16, v76
	v_and_b32_e32 v51, 0xffff0000, v76
	v_lshlrev_b32_e32 v52, 16, v77
	v_and_b32_e32 v53, 0xffff0000, v77
	v_pk_fma_f32 v[52:53], v[52:53], s[12:13], v[44:45] op_sel_hi:[1,0,1]
	v_pk_fma_f32 v[44:45], v[50:51], s[12:13], v[42:43] op_sel_hi:[1,0,1]
	v_cvt_pk_bf16_f32 v42, v46, v47
	v_lshl_add_u64 v[46:47], s[30:31], 0, v[98:99]
	v_cvt_pk_bf16_f32 v43, v48, v49
	v_cvt_pk_bf16_f32 v44, v44, v45
	v_cvt_pk_bf16_f32 v45, v52, v53
	v_lshl_add_u64 v[46:47], v[46:47], 0, v[162:163]
	global_store_dwordx4 v[46:47], v[42:45], off
	s_waitcnt vmcnt(8)
	s_nop 0
	v_lshlrev_b32_e32 v42, 16, v78
	v_and_b32_e32 v43, 0xffff0000, v78
	v_lshlrev_b32_e32 v44, 16, v79
	v_and_b32_e32 v45, 0xffff0000, v79
	v_pk_fma_f32 v[40:41], v[44:45], s[12:13], v[40:41] op_sel_hi:[1,0,1]
	v_pk_fma_f32 v[38:39], v[42:43], s[12:13], v[38:39] op_sel_hi:[1,0,1]
	v_lshlrev_b32_e32 v42, 16, v80
	v_and_b32_e32 v43, 0xffff0000, v80
	v_lshlrev_b32_e32 v44, 16, v81
	v_and_b32_e32 v45, 0xffff0000, v81
	v_pk_fma_f32 v[44:45], v[44:45], s[12:13], v[32:33] op_sel_hi:[1,0,1]
	v_pk_fma_f32 v[32:33], v[42:43], s[12:13], v[30:31] op_sel_hi:[1,0,1]
	v_cvt_pk_bf16_f32 v30, v38, v39
	v_cvt_pk_bf16_f32 v31, v40, v41
	v_cvt_pk_bf16_f32 v32, v32, v33
	v_cvt_pk_bf16_f32 v33, v44, v45
	global_store_dwordx4 v[46:47], v[30:33], off offset:256
	s_waitcnt vmcnt(8)
	s_nop 0
	v_lshlrev_b32_e32 v30, 16, v70
	v_and_b32_e32 v31, 0xffff0000, v70
	v_lshlrev_b32_e32 v32, 16, v71
	v_and_b32_e32 v33, 0xffff0000, v71
	v_pk_fma_f32 v[32:33], v[32:33], s[12:13], v[36:37] op_sel_hi:[1,0,1]
	v_pk_fma_f32 v[30:31], v[30:31], s[12:13], v[34:35] op_sel_hi:[1,0,1]
	v_lshlrev_b32_e32 v34, 16, v72
	v_and_b32_e32 v35, 0xffff0000, v72
	v_lshlrev_b32_e32 v36, 16, v73
	v_and_b32_e32 v37, 0xffff0000, v73
	v_pk_fma_f32 v[36:37], v[36:37], s[12:13], v[28:29] op_sel_hi:[1,0,1]
	v_pk_fma_f32 v[28:29], v[34:35], s[12:13], v[26:27] op_sel_hi:[1,0,1]
	v_cvt_pk_bf16_f32 v26, v30, v31
	v_lshl_add_u64 v[30:31], s[30:31], 0, v[100:101]
	v_cvt_pk_bf16_f32 v27, v32, v33
	v_cvt_pk_bf16_f32 v28, v28, v29
	v_cvt_pk_bf16_f32 v29, v36, v37
	v_lshl_add_u64 v[30:31], v[30:31], 0, v[162:163]
	global_store_dwordx4 v[30:31], v[26:29], off
	s_waitcnt vmcnt(7)
	s_nop 0
	v_lshlrev_b32_e32 v26, 16, v86
	v_and_b32_e32 v27, 0xffff0000, v86
	v_lshlrev_b32_e32 v28, 16, v87
	v_and_b32_e32 v29, 0xffff0000, v87
	v_pk_fma_f32 v[24:25], v[28:29], s[12:13], v[24:25] op_sel_hi:[1,0,1]
	v_pk_fma_f32 v[22:23], v[26:27], s[12:13], v[22:23] op_sel_hi:[1,0,1]
	v_lshlrev_b32_e32 v26, 16, v88
	v_and_b32_e32 v27, 0xffff0000, v88
	v_lshlrev_b32_e32 v28, 16, v89
	v_and_b32_e32 v29, 0xffff0000, v89
	v_pk_fma_f32 v[28:29], v[28:29], s[12:13], v[16:17] op_sel_hi:[1,0,1]
	v_pk_fma_f32 v[16:17], v[26:27], s[12:13], v[14:15] op_sel_hi:[1,0,1]
	v_cvt_pk_bf16_f32 v14, v22, v23
	v_cvt_pk_bf16_f32 v15, v24, v25
	v_cvt_pk_bf16_f32 v16, v16, v17
	v_cvt_pk_bf16_f32 v17, v28, v29
	global_store_dwordx4 v[30:31], v[14:17], off offset:256
	s_waitcnt vmcnt(7)
	s_nop 0
	v_lshlrev_b32_e32 v14, 16, v90
	v_and_b32_e32 v15, 0xffff0000, v90
	v_lshlrev_b32_e32 v16, 16, v91
	v_and_b32_e32 v17, 0xffff0000, v91
	v_pk_fma_f32 v[16:17], v[16:17], s[12:13], v[20:21] op_sel_hi:[1,0,1]
	v_pk_fma_f32 v[14:15], v[14:15], s[12:13], v[18:19] op_sel_hi:[1,0,1]
	v_lshlrev_b32_e32 v18, 16, v92
	v_and_b32_e32 v19, 0xffff0000, v92
	v_lshlrev_b32_e32 v20, 16, v93
	v_and_b32_e32 v21, 0xffff0000, v93
	v_pk_fma_f32 v[20:21], v[20:21], s[12:13], v[12:13] op_sel_hi:[1,0,1]
	v_pk_fma_f32 v[12:13], v[18:19], s[12:13], v[10:11] op_sel_hi:[1,0,1]
	v_cvt_pk_bf16_f32 v10, v14, v15
	v_lshl_add_u64 v[14:15], s[30:31], 0, v[102:103]
	v_cvt_pk_bf16_f32 v11, v16, v17
	v_cvt_pk_bf16_f32 v12, v12, v13
	v_cvt_pk_bf16_f32 v13, v20, v21
	v_lshl_add_u64 v[14:15], v[14:15], 0, v[162:163]
	global_store_dwordx4 v[14:15], v[10:13], off
	s_waitcnt vmcnt(7)
	s_nop 0
	v_lshlrev_b32_e32 v10, 16, v66
	v_and_b32_e32 v11, 0xffff0000, v66
	v_lshlrev_b32_e32 v12, 16, v67
	v_and_b32_e32 v13, 0xffff0000, v67
	v_pk_fma_f32 v[8:9], v[12:13], s[12:13], v[8:9] op_sel_hi:[1,0,1]
	v_pk_fma_f32 v[6:7], v[10:11], s[12:13], v[6:7] op_sel_hi:[1,0,1]
	v_lshlrev_b32_e32 v10, 16, v68
	v_and_b32_e32 v11, 0xffff0000, v68
	v_lshlrev_b32_e32 v12, 16, v69
	v_and_b32_e32 v13, 0xffff0000, v69
	v_pk_fma_f32 v[12:13], v[12:13], s[12:13], v[4:5] op_sel_hi:[1,0,1]
	v_pk_fma_f32 v[4:5], v[10:11], s[12:13], v[2:3] op_sel_hi:[1,0,1]
	v_cvt_pk_bf16_f32 v2, v6, v7
	v_cvt_pk_bf16_f32 v3, v8, v9
	v_cvt_pk_bf16_f32 v4, v4, v5
	v_cvt_pk_bf16_f32 v5, v12, v13
	global_store_dwordx4 v[14:15], v[2:5], off offset:256
	s_mov_b32 s98, 1
	s_cbranch_vccnz .LBB0_1789
	s_andn2_b64 vcc, exec, s[6:7]
	s_cbranch_vccnz .LBB0_1788
	s_barrier
	s_branch .LBB0_1788

; #define PG8_STAGE(bufoff, gbase, voff) do { _Pragma("unroll") for (int _i = 0; _i < 2; ++_i) \
;         __builtin_amdgcn_global_load_lds((const unsigned*)((const char*)(gbase) + (voff)[_i]), (PG8_LAS unsigned*)(lds + (bufoff) + ldsw + _i * 8192), 16, 0, 0); } while (0)
; #define PG8_WAIT_V(n) asm volatile("s_waitcnt vmcnt(" #n ")" ::: "memory")
; #define PG8_BAR __builtin_amdgcn_s_barrier()
; template <class Epi, class Sched, bool ALIGN_EPI = false, bool SP2 = false>
; __device__ __forceinline__ void gemm_phase(PG8_LAS unsigned char* lds, const Gemm g, const Sched& S, const Epi& E) {
;     ...
;     const int tid = tid_, wid = __builtin_amdgcn_readfirstlane(tid >> 6), lane = tid & 63, wr = wid >> 2, wc = wid & 3, fr = lane & 15, fq = lane >> 4;
;     const int K = g.K, nt = K / BK, LD = g.ld ? g.ld : g.K;
;     unsigned voffA[2], voffB[2];
; #pragma unroll
;     for (int i = 0; i < 2; ++i) { int R, C; stage_rc(tid * 16 + i * 8192, R, C); const int Rb = Epi::PERM ? ((R & ~31) + perm32(R & 31)) : R;
;         voffA[i] = (unsigned)(R * LD + C) * 2u; voffB[i] = (unsigned)(Rb * LD + C) * 2u; }
;     const size_t kstep = (size_t)(BK * 2);
;     const size_t hstep = (size_t)HALF * LD * 2;
;     const size_t tstep = 2 * hstep;
;     const unsigned ldsw = (unsigned)wid * 1024u;
;     const int aoff = lds_byte(wr * 64 + fr, fq * 8), boff = lds_byte(wc * 32 + fr, fq * 8);
;     ...
;         PG8_STAGE(PG8_SB(1, 0), cB + kstep, voffB); PG8_STAGE(PG8_SA(1, 0), cA + kstep, voffA); PG8_STAGE(PG8_SB(1, 1), cB + hstep + kstep, voffB);
;         PG8_WAIT_V(6); PG8_BAR;
.LBB0_1807:
	s_lshl_b32 s6, s6, 5
	s_and_b32 s14, s6, 0x60
	s_mov_b64 s[6:7], 0x80
	s_add_i32 m0, s9, 0x18000
	v_lshl_add_u64 v[8:9], v[8:9], 0, s[6:7]
	s_lshl_b32 s12, s1, 13
	s_lshl_b32 s13, s14, 7
	s_waitcnt vmcnt(2)
	s_barrier
	global_load_lds_dwordx4 v[8:9], off
	v_lshl_add_u64 v[6:7], v[6:7], 0, s[6:7]
	s_add_i32 m0, s9, 0x1a000
	s_add_i32 s43, s9, 0x8000
	s_add_i32 s46, s9, 0xa000
	global_load_lds_dwordx4 v[6:7], off
	v_lshl_add_u64 v[2:3], v[2:3], 0, s[6:7]
	s_mov_b32 m0, s43
	s_add_u32 s10, s30, 0x80080
	global_load_lds_dwordx4 v[2:3], off
	v_lshl_add_u64 v[2:3], v[4:5], 0, s[6:7]
	s_mov_b32 m0, s46
	s_addc_u32 s11, s31, 0
	global_load_lds_dwordx4 v[2:3], off
	s_add_i32 m0, s9, 0x1c000
	v_lshl_add_u64 v[2:3], s[10:11], 0, v[132:133]
	global_load_lds_dwordx4 v[2:3], off
	v_lshl_add_u64 v[2:3], s[10:11], 0, v[130:131]
	s_add_i32 m0, s9, 0x1e000
	s_cmpk_lt_u32 s0, 0x100
	global_load_lds_dwordx4 v[2:3], off
	v_bfe_u32 v2, v11, 4, 2
	v_lshlrev_b32_e32 v5, 4, v2
	v_lshl_or_b32 v140, v2, 2, s14
	v_lshlrev_b32_e32 v2, 14, v16
	v_and_b32_e32 v3, 15, v11
	v_and_b32_e32 v2, 0x7fff8000, v2
	v_lshl_or_b32 v4, s1, 6, v3
	v_lshl_or_b32 v3, v3, 6, v5
	v_lshlrev_b32_e32 v5, 2, v11
	v_lshl_add_u32 v2, v15, 11, v2
	v_and_b32_e32 v5, 32, v5
	v_or_b32_e32 v2, v2, v17
	v_bitop3_b32 v6, v3, s12, v5 bitop3:0xde
	v_bitop3_b32 v138, v3, s13, v5 bitop3:0xde
	s_mov_b64 s[12:13], 0x80080
	v_add_lshl_u32 v2, v2, v18, 1
	v_mov_b32_e32 v3, v133
	v_lshl_add_u64 v[134:135], v[2:3], 0, s[12:13]
	v_lshlrev_b32_e32 v2, 14, v10
	v_and_b32_e32 v2, 0x7fff8000, v2
	v_lshl_add_u32 v2, v12, 11, v2
	s_waitcnt vmcnt(6)
	s_cselect_b64 s[10:11], -1, 0
	v_or_b32_e32 v2, v2, v13
	s_add_i32 s54, 0, 0x10000
	v_add_lshl_u32 v2, v2, v14, 1
	v_add_u32_e32 v141, s54, v138
	s_add_i32 s56, 0, 0x14000
	s_add_i32 s54, s54, s38
	v_add_u32_e32 v139, 0xffffc000, v4
	v_lshl_add_u64 v[136:137], v[2:3], 0, s[12:13]
	v_add_u32_e32 v142, s56, v138
	v_add_u32_e32 v143, 0, v6
	s_mov_b64 s[12:13], 0x100000
	s_mov_b32 s49, 0x100000
	s_mov_b64 s[14:15], 0x120000
	s_mov_b32 s50, 0x120000
	s_mov_b64 s[16:17], 0x140000
	s_mov_b32 s51, 0x140000
	s_mov_b64 s[18:19], 0x160000
	s_add_i32 s52, s9, 0xc000
	s_add_i32 s53, s9, 0xe000
	s_add_i32 s55, s54, 0x2000
	s_add_i32 s56, s56, s38
	s_barrier
	s_mov_b32 s98, 0
	s_branch .LBB0_1810

; #define PG8_STAGE(bufoff, gbase, voff) do { _Pragma("unroll") for (int _i = 0; _i < 2; ++_i) \
;         __builtin_amdgcn_global_load_lds((const unsigned*)((const char*)(gbase) + (voff)[_i]), (PG8_LAS unsigned*)(lds + (bufoff) + ldsw + _i * 8192), 16, 0, 0); } while (0)
; #define PG8_LDA(dst, b, h) do { _Pragma("unroll") for (int m = 0; m < 4; ++m) _Pragma("unroll") for (int k = 0; k < 2; ++k) dst[m][k] = *(const PG8_LAS bf16x8*)(lds + PG8_SA(b, h) + aoff + m * 2048 + k * 1024); } while (0)
; #define PG8_LDB(dst, b, h) do { _Pragma("unroll") for (int n = 0; n < 2; ++n) _Pragma("unroll") for (int k = 0; k < 2; ++k) dst[n][k] = *(const PG8_LAS bf16x8*)(lds + PG8_SB(b, h) + boff + n * 2048 + k * 1024); } while (0)
; #define PG8_WAIT_V(n) asm volatile("s_waitcnt vmcnt(" #n ")" ::: "memory")
; #define PG8_WAIT_L(n) asm volatile("s_waitcnt lgkmcnt(" #n ")" ::: "memory")
; #define PG8_BAR __builtin_amdgcn_s_barrier()
; #define PG8_SCHED __builtin_amdgcn_sched_barrier(0)
; template <class Epi, class Sched, bool ALIGN_EPI = false, bool SP2 = false>
; __device__ __forceinline__ void gemm_phase(PG8_LAS unsigned char* lds, const Gemm g, const Sched& S, const Epi& E) {
;     ...
;         const bool has_next = S.next(ui + 1, nxt);
;         const char* nA = has_next ? (const char*)g.A + (size_t)nxt.pm * tstep + nxt.kb : cA; const char* nB = has_next ? (const char*)g.Bt + (size_t)nxt.pn * tstep + nxt.kb : cB;
;         for (int t = 0; t < nt; t += 2) {
;             const bool last = (t == nt - 2);
;             const char* a1 = cA + (size_t)(t + 1) * kstep;
;             const char* a2 = last ? nA : cA + (size_t)(t + 2) * kstep; const char* b2 = last ? nB : cB + (size_t)(t + 2) * kstep;
;             const char* a3 = a2 + kstep; const char* b3 = b2 + kstep;
;             if (last && has_next) S.a_ready(nxt);
;             if constexpr (SP2) {
;             PG8_LDB(B0, 0, 0); PG8_LDB(B1, 0, 1); PG8_SCHED; PG8_LDA(At, 0, 0); PG8_STAGE(PG8_SA(1, 1), a1 + hstep, voffA);
;             PG8_WAIT_V(8); PG8_WAIT_L(0); PG8_BAR; PG8_MMA(0, 0, At, B0); PG8_MMA(0, 1, At, B1); PG8_BAR; PG8_SCHED;
;     ...
; #pragma unroll
;         for (int a = 0; a < 2; ++a)
; #pragma unroll
;             for (int b = 0; b < 2; ++b)
; #pragma unroll
;                 for (int m = 0; m < 4; ++m)
; #pragma unroll
;                     for (int n = 0; n < 2; ++n) acc[a][b][m][n] = (f32x4){0.f, 0.f, 0.f, 0.f};
.LBB0_1816:
	s_add_u32 s21, s30, 0x100
	v_mov_b32_e32 v2, 0
	s_addc_u32 s23, s31, 0
	s_mov_b32 s58, -2
	s_cmp_lg_u32 s98, 0
	s_cbranch_scc1 .Lpeel_8
	v_mov_b32_e32 v3, v2
	v_mov_b32_e32 v4, v2
	v_mov_b32_e32 v5, v2
	v_mov_b32_e32 v6, v2
	v_mov_b32_e32 v7, v2
	v_mov_b32_e32 v8, v2
	v_mov_b32_e32 v9, v2
	v_mov_b32_e32 v10, v2
	v_mov_b32_e32 v11, v2
	v_mov_b32_e32 v12, v2
	v_mov_b32_e32 v13, v2
	v_mov_b32_e32 v14, v2
	v_mov_b32_e32 v15, v2
	v_mov_b32_e32 v16, v2
	v_mov_b32_e32 v17, v2
	v_mov_b32_e32 v22, v2
	v_mov_b32_e32 v23, v2
	v_mov_b32_e32 v24, v2
	v_mov_b32_e32 v25, v2
	v_mov_b32_e32 v30, v2
	v_mov_b32_e32 v31, v2
	v_mov_b32_e32 v32, v2
	v_mov_b32_e32 v33, v2
	v_mov_b32_e32 v38, v2
	v_mov_b32_e32 v39, v2
	v_mov_b32_e32 v40, v2
	v_mov_b32_e32 v41, v2
	v_mov_b32_e32 v46, v2
	v_mov_b32_e32 v47, v2
	v_mov_b32_e32 v48, v2
	v_mov_b32_e32 v49, v2
	v_mov_b32_e32 v18, v2
	v_mov_b32_e32 v19, v2
	v_mov_b32_e32 v20, v2
	v_mov_b32_e32 v21, v2
	v_mov_b32_e32 v26, v2
	v_mov_b32_e32 v27, v2
	v_mov_b32_e32 v28, v2
	v_mov_b32_e32 v29, v2
	v_mov_b32_e32 v34, v2
	v_mov_b32_e32 v35, v2
	v_mov_b32_e32 v36, v2
	v_mov_b32_e32 v37, v2
	v_mov_b32_e32 v42, v2
	v_mov_b32_e32 v43, v2
	v_mov_b32_e32 v44, v2
	v_mov_b32_e32 v45, v2
	v_mov_b32_e32 v50, v2
	v_mov_b32_e32 v51, v2
	v_mov_b32_e32 v52, v2
	v_mov_b32_e32 v53, v2
	v_mov_b32_e32 v54, v2
	v_mov_b32_e32 v55, v2
	v_mov_b32_e32 v56, v2
	v_mov_b32_e32 v57, v2
	v_mov_b32_e32 v58, v2
	v_mov_b32_e32 v59, v2
	v_mov_b32_e32 v60, v2
	v_mov_b32_e32 v61, v2
	v_mov_b32_e32 v62, v2
	v_mov_b32_e32 v63, v2
	v_mov_b32_e32 v64, v2
	v_mov_b32_e32 v65, v2
	v_mov_b32_e32 v66, v2
	v_mov_b32_e32 v67, v2
	v_mov_b32_e32 v68, v2
	v_mov_b32_e32 v69, v2
	v_mov_b32_e32 v70, v2
	v_mov_b32_e32 v71, v2
	v_mov_b32_e32 v72, v2
	v_mov_b32_e32 v73, v2
	v_mov_b32_e32 v74, v2
	v_mov_b32_e32 v75, v2
	v_mov_b32_e32 v76, v2
	v_mov_b32_e32 v77, v2
	v_mov_b32_e32 v78, v2
	v_mov_b32_e32 v79, v2
	v_mov_b32_e32 v80, v2
	v_mov_b32_e32 v81, v2
	v_mov_b32_e32 v86, v2
	v_mov_b32_e32 v87, v2
	v_mov_b32_e32 v88, v2
	v_mov_b32_e32 v89, v2
	v_mov_b32_e32 v94, v2
	v_mov_b32_e32 v95, v2
	v_mov_b32_e32 v96, v2
	v_mov_b32_e32 v97, v2
	v_mov_b32_e32 v102, v2
	v_mov_b32_e32 v103, v2
	v_mov_b32_e32 v104, v2
	v_mov_b32_e32 v105, v2
	v_mov_b32_e32 v110, v2
	v_mov_b32_e32 v111, v2
	v_mov_b32_e32 v112, v2
	v_mov_b32_e32 v113, v2
	v_mov_b32_e32 v82, v2
	v_mov_b32_e32 v83, v2
	v_mov_b32_e32 v84, v2
	v_mov_b32_e32 v85, v2
	v_mov_b32_e32 v90, v2
	v_mov_b32_e32 v91, v2
	v_mov_b32_e32 v92, v2
	v_mov_b32_e32 v93, v2
	v_mov_b32_e32 v98, v2
	v_mov_b32_e32 v99, v2
	v_mov_b32_e32 v100, v2
	v_mov_b32_e32 v101, v2
	v_mov_b32_e32 v106, v2
	v_mov_b32_e32 v107, v2
	v_mov_b32_e32 v108, v2
	v_mov_b32_e32 v109, v2
	v_mov_b32_e32 v114, v2
	v_mov_b32_e32 v115, v2
	v_mov_b32_e32 v116, v2
	v_mov_b32_e32 v117, v2
	v_mov_b32_e32 v118, v2
	v_mov_b32_e32 v119, v2
	v_mov_b32_e32 v120, v2
	v_mov_b32_e32 v121, v2
	v_mov_b32_e32 v122, v2
	v_mov_b32_e32 v123, v2
	v_mov_b32_e32 v124, v2
	v_mov_b32_e32 v125, v2
	v_mov_b32_e32 v126, v2
	v_mov_b32_e32 v127, v2
	v_mov_b32_e32 v128, v2
	v_mov_b32_e32 v129, v2
.LBB0_1817:
	ds_read_b128 v[144:147], v141
	ds_read_b128 v[148:151], v141 offset:1024
	ds_read_b128 v[152:155], v141 offset:2048
	ds_read_b128 v[156:159], v141 offset:3072
	ds_read_b128 v[160:163], v142
	ds_read_b128 v[164:167], v142 offset:1024
	ds_read_b128 v[168:171], v142 offset:2048
	ds_read_b128 v[172:175], v142 offset:3072
	s_add_u32 s30, s28, 0x100
	s_addc_u32 s31, s29, 0
	s_cmp_eq_u32 s58, 4
	s_cselect_b32 s37, s25, s31
	s_cselect_b32 s36, s24, s30
	s_cselect_b32 s35, s27, s23
	s_cselect_b32 s34, s26, s21
	s_mov_b32 m0, s52
	v_lshl_add_u64 v[208:209], s[28:29], 0, v[134:135]
	ds_read_b128 v[176:179], v143
	ds_read_b128 v[180:183], v143 offset:1024
	ds_read_b128 v[184:187], v143 offset:2048
	ds_read_b128 v[188:191], v143 offset:3072
	ds_read_b128 v[192:195], v143 offset:4096
	ds_read_b128 v[196:199], v143 offset:5120
	ds_read_b128 v[200:203], v143 offset:6144
	ds_read_b128 v[204:207], v143 offset:7168
	global_load_lds_dwordx4 v[208:209], off
	v_lshl_add_u64 v[208:209], s[28:29], 0, v[136:137]
	s_mov_b32 m0, s53
	s_nop 0
	global_load_lds_dwordx4 v[208:209], off
	s_waitcnt vmcnt(8)
	s_waitcnt lgkmcnt(0)
	s_barrier
	s_setprio 1
	s_waitcnt lgkmcnt(0)
	v_mfma_f32_16x16x32_bf16 v[126:129], v[144:147], v[176:179], v[126:129]
	v_mfma_f32_16x16x32_bf16 v[122:125], v[152:155], v[176:179], v[122:125]
	v_mfma_f32_16x16x32_bf16 v[118:121], v[144:147], v[184:187], v[118:121]
	v_mfma_f32_16x16x32_bf16 v[114:117], v[152:155], v[184:187], v[114:117]
	v_mfma_f32_16x16x32_bf16 v[106:109], v[144:147], v[192:195], v[106:109]
	v_mfma_f32_16x16x32_bf16 v[98:101], v[152:155], v[192:195], v[98:101]
	v_mfma_f32_16x16x32_bf16 v[90:93], v[144:147], v[200:203], v[90:93]
	v_mfma_f32_16x16x32_bf16 v[82:85], v[152:155], v[200:203], v[82:85]
	v_mfma_f32_16x16x32_bf16 v[126:129], v[148:151], v[180:183], v[126:129]
	v_mfma_f32_16x16x32_bf16 v[122:125], v[156:159], v[180:183], v[122:125]
	v_mfma_f32_16x16x32_bf16 v[118:121], v[148:151], v[188:191], v[118:121]
	v_mfma_f32_16x16x32_bf16 v[114:117], v[156:159], v[188:191], v[114:117]
	v_mfma_f32_16x16x32_bf16 v[106:109], v[148:151], v[196:199], v[106:109]
	v_mfma_f32_16x16x32_bf16 v[98:101], v[156:159], v[196:199], v[98:101]
	v_mfma_f32_16x16x32_bf16 v[90:93], v[148:151], v[204:207], v[90:93]
	v_mfma_f32_16x16x32_bf16 v[82:85], v[156:159], v[204:207], v[82:85]
	s_setprio 0
	s_setprio 1
	v_mfma_f32_16x16x32_bf16 v[110:113], v[160:163], v[176:179], v[110:113]
	v_mfma_f32_16x16x32_bf16 v[102:105], v[168:171], v[176:179], v[102:105]
	v_mfma_f32_16x16x32_bf16 v[94:97], v[160:163], v[184:187], v[94:97]
	v_mfma_f32_16x16x32_bf16 v[86:89], v[168:171], v[184:187], v[86:89]
	v_mfma_f32_16x16x32_bf16 v[78:81], v[160:163], v[192:195], v[78:81]
	v_mfma_f32_16x16x32_bf16 v[74:77], v[168:171], v[192:195], v[74:77]
	v_mfma_f32_16x16x32_bf16 v[70:73], v[160:163], v[200:203], v[70:73]
	v_mfma_f32_16x16x32_bf16 v[66:69], v[168:171], v[200:203], v[66:69]
	v_mfma_f32_16x16x32_bf16 v[110:113], v[164:167], v[180:183], v[110:113]
	v_mfma_f32_16x16x32_bf16 v[102:105], v[172:175], v[180:183], v[102:105]
	v_mfma_f32_16x16x32_bf16 v[94:97], v[164:167], v[188:191], v[94:97]
	v_mfma_f32_16x16x32_bf16 v[86:89], v[172:175], v[188:191], v[86:89]
	v_mfma_f32_16x16x32_bf16 v[78:81], v[164:167], v[196:199], v[78:81]
	v_mfma_f32_16x16x32_bf16 v[74:77], v[172:175], v[196:199], v[74:77]
	v_mfma_f32_16x16x32_bf16 v[70:73], v[164:167], v[204:207], v[70:73]
	v_mfma_f32_16x16x32_bf16 v[66:69], v[172:175], v[204:207], v[66:69]
	s_setprio 0
	s_barrier
; #define PG8_STAGE(bufoff, gbase, voff) do { _Pragma("unroll") for (int _i = 0; _i < 2; ++_i) \
;         __builtin_amdgcn_global_load_lds((const unsigned*)((const char*)(gbase) + (voff)[_i]), (PG8_LAS unsigned*)(lds + (bufoff) + ldsw + _i * 8192), 16, 0, 0); } while (0)
; #define PG8_LDA(dst, b, h) do { _Pragma("unroll") for (int m = 0; m < 4; ++m) _Pragma("unroll") for (int k = 0; k < 2; ++k) dst[m][k] = *(const PG8_LAS bf16x8*)(lds + PG8_SA(b, h) + aoff + m * 2048 + k * 1024); } while (0)
; #define PG8_LDB(dst, b, h) do { _Pragma("unroll") for (int n = 0; n < 2; ++n) _Pragma("unroll") for (int k = 0; k < 2; ++k) dst[n][k] = *(const PG8_LAS bf16x8*)(lds + PG8_SB(b, h) + boff + n * 2048 + k * 1024); } while (0)
; #define PG8_MMA(ai, bj, At, Bt) do { __builtin_amdgcn_s_setprio(1); _Pragma("unroll") for (int m = 0; m < 4; ++m) _Pragma("unroll") for (int n = 0; n < 2; ++n) _Pragma("unroll") for (int k = 0; k < 2; ++k) \
;         acc[ai][bj][m][n] = __builtin_amdgcn_mfma_f32_16x16x32_bf16(Bt[n][k], At[m][k], acc[ai][bj][m][n], 0, 0, 0); __builtin_amdgcn_s_setprio(0); } while (0)
; #define PG8_WAIT_V(n) asm volatile("s_waitcnt vmcnt(" #n ")" ::: "memory")
; #define PG8_WAIT_L(n) asm volatile("s_waitcnt lgkmcnt(" #n ")" ::: "memory")
; #define PG8_BAR __builtin_amdgcn_s_barrier()
; #define PG8_SCHED __builtin_amdgcn_sched_barrier(0)
; template <class Epi, class Sched, bool ALIGN_EPI = false, bool SP2 = false>
; __device__ __forceinline__ void gemm_phase(PG8_LAS unsigned char* lds, const Gemm g, const Sched& S, const Epi& E) {
;     ...
;             PG8_LDA(At, 0, 1); PG8_STAGE(PG8_SB(0, 0), b2, voffB); PG8_STAGE(PG8_SB(0, 1), b2 + hstep, voffB); PG8_STAGE(PG8_SA(0, 0), a2, voffA);
;             PG8_WAIT_V(8); PG8_WAIT_L(0); PG8_BAR; PG8_MMA(1, 0, At, B0); PG8_MMA(1, 1, At, B1); PG8_BAR; PG8_SCHED;
;             PG8_LDB(B0, 1, 0); PG8_LDB(B1, 1, 1); PG8_SCHED; PG8_LDA(At, 1, 0); PG8_STAGE(PG8_SA(0, 1), a2 + hstep, voffA);
	s_mov_b32 m0, s54
	v_lshl_add_u64 v[208:209], s[34:35], 0, v[132:133]
	s_add_u32 s28, s34, 0x80000
	ds_read_b128 v[176:179], v143 offset:16384
	ds_read_b128 v[180:183], v143 offset:17408
	ds_read_b128 v[184:187], v143 offset:18432
	ds_read_b128 v[188:191], v143 offset:19456
	ds_read_b128 v[192:195], v143 offset:20480
	ds_read_b128 v[196:199], v143 offset:21504
	ds_read_b128 v[200:203], v143 offset:22528
	ds_read_b128 v[204:207], v143 offset:23552
	global_load_lds_dwordx4 v[208:209], off
	v_lshl_add_u64 v[210:211], s[34:35], 0, v[130:131]
	s_mov_b32 m0, s55
	s_addc_u32 s29, s35, 0
	global_load_lds_dwordx4 v[210:211], off
	v_lshl_add_u64 v[212:213], s[28:29], 0, v[132:133]
	s_mov_b32 m0, s56
	v_lshl_add_u64 v[214:215], s[36:37], 0, v[130:131]
	global_load_lds_dwordx4 v[212:213], off
	v_lshl_add_u64 v[212:213], s[28:29], 0, v[130:131]
	s_add_i32 m0, s56, 0x2000
	s_nop 0
	global_load_lds_dwordx4 v[212:213], off
	v_lshl_add_u64 v[212:213], s[36:37], 0, v[132:133]
	s_mov_b32 m0, s9
	s_nop 0
	global_load_lds_dwordx4 v[212:213], off
	s_mov_b32 m0, s39
	s_nop 0
	global_load_lds_dwordx4 v[214:215], off
	s_waitcnt vmcnt(8)
	s_waitcnt lgkmcnt(0)
	s_barrier
	s_setprio 1
	s_waitcnt lgkmcnt(0)
	v_mfma_f32_16x16x32_bf16 v[62:65], v[144:147], v[176:179], v[62:65]
	v_mfma_f32_16x16x32_bf16 v[58:61], v[152:155], v[176:179], v[58:61]
	v_mfma_f32_16x16x32_bf16 v[54:57], v[144:147], v[184:187], v[54:57]
	v_mfma_f32_16x16x32_bf16 v[50:53], v[152:155], v[184:187], v[50:53]
	v_mfma_f32_16x16x32_bf16 v[42:45], v[144:147], v[192:195], v[42:45]
	v_mfma_f32_16x16x32_bf16 v[34:37], v[152:155], v[192:195], v[34:37]
	v_mfma_f32_16x16x32_bf16 v[26:29], v[144:147], v[200:203], v[26:29]
	v_mfma_f32_16x16x32_bf16 v[18:21], v[152:155], v[200:203], v[18:21]
	v_mfma_f32_16x16x32_bf16 v[62:65], v[148:151], v[180:183], v[62:65]
	v_mfma_f32_16x16x32_bf16 v[58:61], v[156:159], v[180:183], v[58:61]
	v_mfma_f32_16x16x32_bf16 v[54:57], v[148:151], v[188:191], v[54:57]
	v_mfma_f32_16x16x32_bf16 v[50:53], v[156:159], v[188:191], v[50:53]
	v_mfma_f32_16x16x32_bf16 v[42:45], v[148:151], v[196:199], v[42:45]
	v_mfma_f32_16x16x32_bf16 v[34:37], v[156:159], v[196:199], v[34:37]
	v_mfma_f32_16x16x32_bf16 v[26:29], v[148:151], v[204:207], v[26:29]
	v_mfma_f32_16x16x32_bf16 v[18:21], v[156:159], v[204:207], v[18:21]
	s_setprio 0
	s_setprio 1
	v_mfma_f32_16x16x32_bf16 v[46:49], v[160:163], v[176:179], v[46:49]
	v_mfma_f32_16x16x32_bf16 v[38:41], v[168:171], v[176:179], v[38:41]
	v_mfma_f32_16x16x32_bf16 v[30:33], v[160:163], v[184:187], v[30:33]
	v_mfma_f32_16x16x32_bf16 v[22:25], v[168:171], v[184:187], v[22:25]
	v_mfma_f32_16x16x32_bf16 v[14:17], v[160:163], v[192:195], v[14:17]
	v_mfma_f32_16x16x32_bf16 v[10:13], v[168:171], v[192:195], v[10:13]
	v_mfma_f32_16x16x32_bf16 v[6:9], v[160:163], v[200:203], v[6:9]
	v_mfma_f32_16x16x32_bf16 v[2:5], v[168:171], v[200:203], v[2:5]
	v_mfma_f32_16x16x32_bf16 v[46:49], v[164:167], v[180:183], v[46:49]
	v_mfma_f32_16x16x32_bf16 v[38:41], v[172:175], v[180:183], v[38:41]
	v_mfma_f32_16x16x32_bf16 v[30:33], v[164:167], v[188:191], v[30:33]
	v_mfma_f32_16x16x32_bf16 v[22:25], v[172:175], v[188:191], v[22:25]
	v_mfma_f32_16x16x32_bf16 v[14:17], v[164:167], v[196:199], v[14:17]
	v_mfma_f32_16x16x32_bf16 v[10:13], v[172:175], v[196:199], v[10:13]
	v_mfma_f32_16x16x32_bf16 v[6:9], v[164:167], v[204:207], v[6:9]
	v_mfma_f32_16x16x32_bf16 v[2:5], v[172:175], v[204:207], v[2:5]
	s_setprio 0
	s_barrier
	s_add_i32 s59, 0, 0x18000
	s_add_i32 s60, 0, 0x1c000
	v_add_u32_e32 v156, s59, v138
	v_add_u32_e32 v172, s60, v138
	ds_read_b128 v[144:147], v156
	ds_read_b128 v[148:151], v156 offset:1024
	ds_read_b128 v[152:155], v156 offset:2048
	ds_read_b128 v[156:159], v156 offset:3072
	ds_read_b128 v[160:163], v172
	ds_read_b128 v[164:167], v172 offset:1024
	ds_read_b128 v[168:171], v172 offset:2048
	ds_read_b128 v[172:175], v172 offset:3072
	s_add_u32 s28, s36, 0x80000
	s_addc_u32 s29, s37, 0
	s_mov_b32 m0, s40
	v_lshl_add_u64 v[216:217], s[28:29], 0, v[132:133]
	ds_read_b128 v[176:179], v143 offset:32768
	ds_read_b128 v[180:183], v143 offset:33792
	ds_read_b128 v[184:187], v143 offset:34816
	ds_read_b128 v[188:191], v143 offset:35840
	ds_read_b128 v[192:195], v143 offset:36864
	ds_read_b128 v[196:199], v143 offset:37888
	ds_read_b128 v[200:203], v143 offset:38912
	ds_read_b128 v[204:207], v143 offset:39936
	global_load_lds_dwordx4 v[216:217], off
	v_lshl_add_u64 v[216:217], s[28:29], 0, v[130:131]
	s_mov_b32 m0, s41
	s_nop 0
	global_load_lds_dwordx4 v[216:217], off
	s_waitcnt vmcnt(8)
	s_waitcnt lgkmcnt(0)
	s_barrier
; #define PG8_STAGE(bufoff, gbase, voff) do { _Pragma("unroll") for (int _i = 0; _i < 2; ++_i) \
;         __builtin_amdgcn_global_load_lds((const unsigned*)((const char*)(gbase) + (voff)[_i]), (PG8_LAS unsigned*)(lds + (bufoff) + ldsw + _i * 8192), 16, 0, 0); } while (0)
; #define PG8_LDA(dst, b, h) do { _Pragma("unroll") for (int m = 0; m < 4; ++m) _Pragma("unroll") for (int k = 0; k < 2; ++k) dst[m][k] = *(const PG8_LAS bf16x8*)(lds + PG8_SA(b, h) + aoff + m * 2048 + k * 1024); } while (0)
; #define PG8_MMA(ai, bj, At, Bt) do { __builtin_amdgcn_s_setprio(1); _Pragma("unroll") for (int m = 0; m < 4; ++m) _Pragma("unroll") for (int n = 0; n < 2; ++n) _Pragma("unroll") for (int k = 0; k < 2; ++k) \
;         acc[ai][bj][m][n] = __builtin_amdgcn_mfma_f32_16x16x32_bf16(Bt[n][k], At[m][k], acc[ai][bj][m][n], 0, 0, 0); __builtin_amdgcn_s_setprio(0); } while (0)
; #define PG8_WAIT_V(n) asm volatile("s_waitcnt vmcnt(" #n ")" ::: "memory")
; #define PG8_WAIT_L(n) asm volatile("s_waitcnt lgkmcnt(" #n ")" ::: "memory")
; #define PG8_BAR __builtin_amdgcn_s_barrier()
; #define PG8_SCHED __builtin_amdgcn_sched_barrier(0)
; template <class Epi, class Sched, bool ALIGN_EPI = false, bool SP2 = false>
; __device__ __forceinline__ void gemm_phase(PG8_LAS unsigned char* lds, const Gemm g, const Sched& S, const Epi& E) {
;     ...
;             PG8_WAIT_V(8); PG8_WAIT_L(0); PG8_BAR; PG8_MMA(0, 0, At, B0); PG8_MMA(0, 1, At, B1); PG8_BAR; PG8_SCHED;
;             PG8_LDA(At, 1, 1); PG8_STAGE(PG8_SB(1, 0), b3, voffB); PG8_STAGE(PG8_SB(1, 1), b3 + hstep, voffB); PG8_STAGE(PG8_SA(1, 0), a3, voffA);
;             PG8_WAIT_V(8); PG8_WAIT_L(0); PG8_BAR; PG8_MMA(1, 0, At, B0); PG8_MMA(1, 1, At, B1); PG8_BAR; PG8_SCHED;
	s_setprio 1
	s_waitcnt lgkmcnt(0)
	v_mfma_f32_16x16x32_bf16 v[126:129], v[144:147], v[176:179], v[126:129]
	v_mfma_f32_16x16x32_bf16 v[122:125], v[152:155], v[176:179], v[122:125]
	v_mfma_f32_16x16x32_bf16 v[118:121], v[144:147], v[184:187], v[118:121]
	v_mfma_f32_16x16x32_bf16 v[114:117], v[152:155], v[184:187], v[114:117]
	v_mfma_f32_16x16x32_bf16 v[106:109], v[144:147], v[192:195], v[106:109]
	v_mfma_f32_16x16x32_bf16 v[98:101], v[152:155], v[192:195], v[98:101]
	v_mfma_f32_16x16x32_bf16 v[90:93], v[144:147], v[200:203], v[90:93]
	v_mfma_f32_16x16x32_bf16 v[82:85], v[152:155], v[200:203], v[82:85]
	v_mfma_f32_16x16x32_bf16 v[126:129], v[148:151], v[180:183], v[126:129]
	v_mfma_f32_16x16x32_bf16 v[122:125], v[156:159], v[180:183], v[122:125]
	v_mfma_f32_16x16x32_bf16 v[118:121], v[148:151], v[188:191], v[118:121]
	v_mfma_f32_16x16x32_bf16 v[114:117], v[156:159], v[188:191], v[114:117]
	v_mfma_f32_16x16x32_bf16 v[106:109], v[148:151], v[196:199], v[106:109]
	v_mfma_f32_16x16x32_bf16 v[98:101], v[156:159], v[196:199], v[98:101]
	v_mfma_f32_16x16x32_bf16 v[90:93], v[148:151], v[204:207], v[90:93]
	v_mfma_f32_16x16x32_bf16 v[82:85], v[156:159], v[204:207], v[82:85]
	s_setprio 0
	s_setprio 1
	v_mfma_f32_16x16x32_bf16 v[110:113], v[160:163], v[176:179], v[110:113]
	v_mfma_f32_16x16x32_bf16 v[102:105], v[168:171], v[176:179], v[102:105]
	v_mfma_f32_16x16x32_bf16 v[94:97], v[160:163], v[184:187], v[94:97]
	v_mfma_f32_16x16x32_bf16 v[86:89], v[168:171], v[184:187], v[86:89]
	v_mfma_f32_16x16x32_bf16 v[78:81], v[160:163], v[192:195], v[78:81]
	v_mfma_f32_16x16x32_bf16 v[74:77], v[168:171], v[192:195], v[74:77]
	v_mfma_f32_16x16x32_bf16 v[70:73], v[160:163], v[200:203], v[70:73]
	v_mfma_f32_16x16x32_bf16 v[66:69], v[168:171], v[200:203], v[66:69]
	v_mfma_f32_16x16x32_bf16 v[110:113], v[164:167], v[180:183], v[110:113]
	v_mfma_f32_16x16x32_bf16 v[102:105], v[172:175], v[180:183], v[102:105]
	v_mfma_f32_16x16x32_bf16 v[94:97], v[164:167], v[188:191], v[94:97]
	v_mfma_f32_16x16x32_bf16 v[86:89], v[172:175], v[188:191], v[86:89]
	v_mfma_f32_16x16x32_bf16 v[78:81], v[164:167], v[196:199], v[78:81]
	v_mfma_f32_16x16x32_bf16 v[74:77], v[172:175], v[196:199], v[74:77]
	v_mfma_f32_16x16x32_bf16 v[70:73], v[164:167], v[204:207], v[70:73]
	v_mfma_f32_16x16x32_bf16 v[66:69], v[172:175], v[204:207], v[66:69]
	s_setprio 0
	s_barrier
	s_add_i32 s28, s59, s38
	v_lshl_add_u64 v[208:209], v[208:209], 0, s[6:7]
	s_mov_b32 m0, s28
	ds_read_b128 v[176:179], v143 offset:49152
	ds_read_b128 v[180:183], v143 offset:50176
	ds_read_b128 v[184:187], v143 offset:51200
	ds_read_b128 v[188:191], v143 offset:52224
	ds_read_b128 v[192:195], v143 offset:53248
	ds_read_b128 v[196:199], v143 offset:54272
	ds_read_b128 v[200:203], v143 offset:55296
	ds_read_b128 v[204:207], v143 offset:56320
	global_load_lds_dwordx4 v[208:209], off
	s_add_i32 m0, s28, 0x2000
	s_add_u32 s28, s34, 0x80080
	v_lshl_add_u64 v[208:209], v[210:211], 0, s[6:7]
	s_addc_u32 s29, s35, 0
	s_add_i32 s34, s60, s38
	global_load_lds_dwordx4 v[208:209], off
	v_lshl_add_u64 v[208:209], s[28:29], 0, v[132:133]
	s_mov_b32 m0, s34
	s_nop 0
	global_load_lds_dwordx4 v[208:209], off
	v_lshl_add_u64 v[208:209], s[28:29], 0, v[130:131]
	s_add_i32 m0, s34, 0x2000
	s_nop 0
	global_load_lds_dwordx4 v[208:209], off
	v_lshl_add_u64 v[208:209], v[212:213], 0, s[6:7]
	s_mov_b32 m0, s43
	s_nop 0
	global_load_lds_dwordx4 v[208:209], off
	v_lshl_add_u64 v[208:209], v[214:215], 0, s[6:7]
	s_mov_b32 m0, s46
	s_nop 0
	global_load_lds_dwordx4 v[208:209], off
	s_waitcnt vmcnt(8)
	s_waitcnt lgkmcnt(0)
	s_barrier
	s_setprio 1
	s_waitcnt lgkmcnt(0)
	v_mfma_f32_16x16x32_bf16 v[62:65], v[144:147], v[176:179], v[62:65]
	v_mfma_f32_16x16x32_bf16 v[58:61], v[152:155], v[176:179], v[58:61]
	v_mfma_f32_16x16x32_bf16 v[54:57], v[144:147], v[184:187], v[54:57]
	v_mfma_f32_16x16x32_bf16 v[50:53], v[152:155], v[184:187], v[50:53]
	v_mfma_f32_16x16x32_bf16 v[42:45], v[144:147], v[192:195], v[42:45]
	v_mfma_f32_16x16x32_bf16 v[34:37], v[152:155], v[192:195], v[34:37]
	v_mfma_f32_16x16x32_bf16 v[26:29], v[144:147], v[200:203], v[26:29]
	v_mfma_f32_16x16x32_bf16 v[18:21], v[152:155], v[200:203], v[18:21]
	v_mfma_f32_16x16x32_bf16 v[62:65], v[148:151], v[180:183], v[62:65]
	v_mfma_f32_16x16x32_bf16 v[58:61], v[156:159], v[180:183], v[58:61]
	v_mfma_f32_16x16x32_bf16 v[54:57], v[148:151], v[188:191], v[54:57]
	v_mfma_f32_16x16x32_bf16 v[50:53], v[156:159], v[188:191], v[50:53]
	v_mfma_f32_16x16x32_bf16 v[42:45], v[148:151], v[196:199], v[42:45]
	v_mfma_f32_16x16x32_bf16 v[34:37], v[156:159], v[196:199], v[34:37]
	v_mfma_f32_16x16x32_bf16 v[26:29], v[148:151], v[204:207], v[26:29]
	v_mfma_f32_16x16x32_bf16 v[18:21], v[156:159], v[204:207], v[18:21]
	s_setprio 0
	s_setprio 1
	v_mfma_f32_16x16x32_bf16 v[46:49], v[160:163], v[176:179], v[46:49]
	v_mfma_f32_16x16x32_bf16 v[38:41], v[168:171], v[176:179], v[38:41]
	v_mfma_f32_16x16x32_bf16 v[30:33], v[160:163], v[184:187], v[30:33]
	v_mfma_f32_16x16x32_bf16 v[22:25], v[168:171], v[184:187], v[22:25]
	v_mfma_f32_16x16x32_bf16 v[14:17], v[160:163], v[192:195], v[14:17]
	v_mfma_f32_16x16x32_bf16 v[10:13], v[168:171], v[192:195], v[10:13]
	v_mfma_f32_16x16x32_bf16 v[6:9], v[160:163], v[200:203], v[6:9]
	v_mfma_f32_16x16x32_bf16 v[2:5], v[168:171], v[200:203], v[2:5]
	v_mfma_f32_16x16x32_bf16 v[46:49], v[164:167], v[180:183], v[46:49]
	v_mfma_f32_16x16x32_bf16 v[38:41], v[172:175], v[180:183], v[38:41]
	v_mfma_f32_16x16x32_bf16 v[30:33], v[164:167], v[188:191], v[30:33]
	v_mfma_f32_16x16x32_bf16 v[22:25], v[172:175], v[188:191], v[22:25]
	v_mfma_f32_16x16x32_bf16 v[14:17], v[164:167], v[196:199], v[14:17]
	v_mfma_f32_16x16x32_bf16 v[10:13], v[172:175], v[196:199], v[10:13]
	v_mfma_f32_16x16x32_bf16 v[6:9], v[164:167], v[204:207], v[6:9]
	v_mfma_f32_16x16x32_bf16 v[2:5], v[172:175], v[204:207], v[2:5]
	s_setprio 0
	s_barrier
	s_add_i32 s58, s58, 2
	s_add_u32 s21, s21, 0x100
	s_addc_u32 s23, s23, 0
	s_cmp_gt_u32 s58, 5
	s_mov_b64 s[28:29], s[30:31]
	s_cbranch_scc0 .LBB0_1817
	s_branch .Lpeel_after_8
; #define PG8_STAGE(bufoff, gbase, voff) do { _Pragma("unroll") for (int _i = 0; _i < 2; ++_i) \
;         __builtin_amdgcn_global_load_lds((const unsigned*)((const char*)(gbase) + (voff)[_i]), (PG8_LAS unsigned*)(lds + (bufoff) + ldsw + _i * 8192), 16, 0, 0); } while (0)
; #define PG8_LDA(dst, b, h) do { _Pragma("unroll") for (int m = 0; m < 4; ++m) _Pragma("unroll") for (int k = 0; k < 2; ++k) dst[m][k] = *(const PG8_LAS bf16x8*)(lds + PG8_SA(b, h) + aoff + m * 2048 + k * 1024); } while (0)
; #define PG8_LDB(dst, b, h) do { _Pragma("unroll") for (int n = 0; n < 2; ++n) _Pragma("unroll") for (int k = 0; k < 2; ++k) dst[n][k] = *(const PG8_LAS bf16x8*)(lds + PG8_SB(b, h) + boff + n * 2048 + k * 1024); } while (0)
; #define PG8_MMA(ai, bj, At, Bt) do { __builtin_amdgcn_s_setprio(1); _Pragma("unroll") for (int m = 0; m < 4; ++m) _Pragma("unroll") for (int n = 0; n < 2; ++n) _Pragma("unroll") for (int k = 0; k < 2; ++k) \
;         acc[ai][bj][m][n] = __builtin_amdgcn_mfma_f32_16x16x32_bf16(Bt[n][k], At[m][k], acc[ai][bj][m][n], 0, 0, 0); __builtin_amdgcn_s_setprio(0); } while (0)
; #define PG8_WAIT_V(n) asm volatile("s_waitcnt vmcnt(" #n ")" ::: "memory")
; #define PG8_WAIT_L(n) asm volatile("s_waitcnt lgkmcnt(" #n ")" ::: "memory")
; #define PG8_BAR __builtin_amdgcn_s_barrier()
; #define PG8_SCHED __builtin_amdgcn_sched_barrier(0)
; template <class Epi, class Sched, bool ALIGN_EPI = false, bool SP2 = false>
; __device__ __forceinline__ void gemm_phase(PG8_LAS unsigned char* lds, const Gemm g, const Sched& S, const Epi& E) {
;     ...
;             PG8_LDB(B0, 0, 0); PG8_LDB(B1, 0, 1); PG8_SCHED; PG8_LDA(At, 0, 0); PG8_STAGE(PG8_SA(1, 1), a1 + hstep, voffA);
;             PG8_WAIT_V(8); PG8_WAIT_L(0); PG8_BAR; PG8_MMA(0, 0, At, B0); PG8_MMA(0, 1, At, B1); PG8_BAR; PG8_SCHED;
;             PG8_LDA(At, 0, 1); PG8_STAGE(PG8_SB(0, 0), b2, voffB); PG8_STAGE(PG8_SB(0, 1), b2 + hstep, voffB); PG8_STAGE(PG8_SA(0, 0), a2, voffA);
;             PG8_WAIT_V(8); PG8_WAIT_L(0); PG8_BAR; PG8_MMA(1, 0, At, B0); PG8_MMA(1, 1, At, B1); PG8_BAR; PG8_SCHED;
.Lpeel_8:
	ds_read_b128 v[144:147], v141
	ds_read_b128 v[148:151], v141 offset:1024
	ds_read_b128 v[152:155], v141 offset:2048
	ds_read_b128 v[156:159], v141 offset:3072
	ds_read_b128 v[160:163], v142
	ds_read_b128 v[164:167], v142 offset:1024
	ds_read_b128 v[168:171], v142 offset:2048
	ds_read_b128 v[172:175], v142 offset:3072
	s_add_u32 s30, s28, 0x100
	s_addc_u32 s31, s29, 0
	s_cmp_eq_u32 s58, 4
	s_cselect_b32 s37, s25, s31
	s_cselect_b32 s36, s24, s30
	s_cselect_b32 s35, s27, s23
	s_cselect_b32 s34, s26, s21
	s_mov_b32 m0, s52
	v_lshl_add_u64 v[208:209], s[28:29], 0, v[134:135]
	ds_read_b128 v[176:179], v143
	ds_read_b128 v[180:183], v143 offset:1024
	ds_read_b128 v[184:187], v143 offset:2048
	ds_read_b128 v[188:191], v143 offset:3072
	ds_read_b128 v[192:195], v143 offset:4096
	ds_read_b128 v[196:199], v143 offset:5120
	ds_read_b128 v[200:203], v143 offset:6144
	ds_read_b128 v[204:207], v143 offset:7168
	global_load_lds_dwordx4 v[208:209], off
	v_lshl_add_u64 v[208:209], s[28:29], 0, v[136:137]
	s_mov_b32 m0, s53
	s_nop 0
	global_load_lds_dwordx4 v[208:209], off
	s_waitcnt vmcnt(40)
	s_waitcnt lgkmcnt(0)
	s_barrier
	s_setprio 1
	s_waitcnt lgkmcnt(0)
	v_mfma_f32_16x16x32_bf16 v[126:129], v[144:147], v[176:179], 0
	v_mfma_f32_16x16x32_bf16 v[122:125], v[152:155], v[176:179], 0
	v_mfma_f32_16x16x32_bf16 v[118:121], v[144:147], v[184:187], 0
	v_mfma_f32_16x16x32_bf16 v[114:117], v[152:155], v[184:187], 0
	v_mfma_f32_16x16x32_bf16 v[106:109], v[144:147], v[192:195], 0
	v_mfma_f32_16x16x32_bf16 v[98:101], v[152:155], v[192:195], 0
	v_mfma_f32_16x16x32_bf16 v[90:93], v[144:147], v[200:203], 0
	v_mfma_f32_16x16x32_bf16 v[82:85], v[152:155], v[200:203], 0
	v_mfma_f32_16x16x32_bf16 v[126:129], v[148:151], v[180:183], v[126:129]
	v_mfma_f32_16x16x32_bf16 v[122:125], v[156:159], v[180:183], v[122:125]
	v_mfma_f32_16x16x32_bf16 v[118:121], v[148:151], v[188:191], v[118:121]
	v_mfma_f32_16x16x32_bf16 v[114:117], v[156:159], v[188:191], v[114:117]
	v_mfma_f32_16x16x32_bf16 v[106:109], v[148:151], v[196:199], v[106:109]
	v_mfma_f32_16x16x32_bf16 v[98:101], v[156:159], v[196:199], v[98:101]
	v_mfma_f32_16x16x32_bf16 v[90:93], v[148:151], v[204:207], v[90:93]
	v_mfma_f32_16x16x32_bf16 v[82:85], v[156:159], v[204:207], v[82:85]
	s_setprio 0
	s_setprio 1
	v_mfma_f32_16x16x32_bf16 v[110:113], v[160:163], v[176:179], 0
	v_mfma_f32_16x16x32_bf16 v[102:105], v[168:171], v[176:179], 0
	v_mfma_f32_16x16x32_bf16 v[94:97], v[160:163], v[184:187], 0
	v_mfma_f32_16x16x32_bf16 v[86:89], v[168:171], v[184:187], 0
	v_mfma_f32_16x16x32_bf16 v[78:81], v[160:163], v[192:195], 0
	v_mfma_f32_16x16x32_bf16 v[74:77], v[168:171], v[192:195], 0
	v_mfma_f32_16x16x32_bf16 v[70:73], v[160:163], v[200:203], 0
	v_mfma_f32_16x16x32_bf16 v[66:69], v[168:171], v[200:203], 0
	v_mfma_f32_16x16x32_bf16 v[110:113], v[164:167], v[180:183], v[110:113]
	v_mfma_f32_16x16x32_bf16 v[102:105], v[172:175], v[180:183], v[102:105]
	v_mfma_f32_16x16x32_bf16 v[94:97], v[164:167], v[188:191], v[94:97]
	v_mfma_f32_16x16x32_bf16 v[86:89], v[172:175], v[188:191], v[86:89]
	v_mfma_f32_16x16x32_bf16 v[78:81], v[164:167], v[196:199], v[78:81]
	v_mfma_f32_16x16x32_bf16 v[74:77], v[172:175], v[196:199], v[74:77]
	v_mfma_f32_16x16x32_bf16 v[70:73], v[164:167], v[204:207], v[70:73]
	v_mfma_f32_16x16x32_bf16 v[66:69], v[172:175], v[204:207], v[66:69]
	s_setprio 0
	s_barrier
	s_mov_b32 m0, s54
	v_lshl_add_u64 v[208:209], s[34:35], 0, v[132:133]
	s_add_u32 s28, s34, 0x80000
	ds_read_b128 v[176:179], v143 offset:16384
	ds_read_b128 v[180:183], v143 offset:17408
	ds_read_b128 v[184:187], v143 offset:18432
	ds_read_b128 v[188:191], v143 offset:19456
	ds_read_b128 v[192:195], v143 offset:20480
	ds_read_b128 v[196:199], v143 offset:21504
	ds_read_b128 v[200:203], v143 offset:22528
	ds_read_b128 v[204:207], v143 offset:23552
	global_load_lds_dwordx4 v[208:209], off
	v_lshl_add_u64 v[210:211], s[34:35], 0, v[130:131]
	s_mov_b32 m0, s55
	s_addc_u32 s29, s35, 0
	global_load_lds_dwordx4 v[210:211], off
	v_lshl_add_u64 v[212:213], s[28:29], 0, v[132:133]
	s_mov_b32 m0, s56
	v_lshl_add_u64 v[214:215], s[36:37], 0, v[130:131]
	global_load_lds_dwordx4 v[212:213], off
	v_lshl_add_u64 v[212:213], s[28:29], 0, v[130:131]
	s_add_i32 m0, s56, 0x2000
	s_nop 0
	global_load_lds_dwordx4 v[212:213], off
	v_lshl_add_u64 v[212:213], s[36:37], 0, v[132:133]
	s_mov_b32 m0, s9
	s_nop 0
	global_load_lds_dwordx4 v[212:213], off
	s_mov_b32 m0, s39
	s_nop 0
	global_load_lds_dwordx4 v[214:215], off
	s_waitcnt vmcnt(40)
	s_waitcnt lgkmcnt(0)
	s_barrier
	s_setprio 1
	s_waitcnt lgkmcnt(0)
	v_mfma_f32_16x16x32_bf16 v[62:65], v[144:147], v[176:179], 0
	v_mfma_f32_16x16x32_bf16 v[58:61], v[152:155], v[176:179], 0
	v_mfma_f32_16x16x32_bf16 v[54:57], v[144:147], v[184:187], 0
	v_mfma_f32_16x16x32_bf16 v[50:53], v[152:155], v[184:187], 0
	v_mfma_f32_16x16x32_bf16 v[42:45], v[144:147], v[192:195], 0
	v_mfma_f32_16x16x32_bf16 v[34:37], v[152:155], v[192:195], 0
	v_mfma_f32_16x16x32_bf16 v[26:29], v[144:147], v[200:203], 0
	v_mfma_f32_16x16x32_bf16 v[18:21], v[152:155], v[200:203], 0
	v_mfma_f32_16x16x32_bf16 v[62:65], v[148:151], v[180:183], v[62:65]
	v_mfma_f32_16x16x32_bf16 v[58:61], v[156:159], v[180:183], v[58:61]
	v_mfma_f32_16x16x32_bf16 v[54:57], v[148:151], v[188:191], v[54:57]
	v_mfma_f32_16x16x32_bf16 v[50:53], v[156:159], v[188:191], v[50:53]
	v_mfma_f32_16x16x32_bf16 v[42:45], v[148:151], v[196:199], v[42:45]
	v_mfma_f32_16x16x32_bf16 v[34:37], v[156:159], v[196:199], v[34:37]
	v_mfma_f32_16x16x32_bf16 v[26:29], v[148:151], v[204:207], v[26:29]
	v_mfma_f32_16x16x32_bf16 v[18:21], v[156:159], v[204:207], v[18:21]
	s_setprio 0
	s_setprio 1
	v_mfma_f32_16x16x32_bf16 v[46:49], v[160:163], v[176:179], 0
	v_mfma_f32_16x16x32_bf16 v[38:41], v[168:171], v[176:179], 0
	v_mfma_f32_16x16x32_bf16 v[30:33], v[160:163], v[184:187], 0
	v_mfma_f32_16x16x32_bf16 v[22:25], v[168:171], v[184:187], 0
	v_mfma_f32_16x16x32_bf16 v[14:17], v[160:163], v[192:195], 0
	v_mfma_f32_16x16x32_bf16 v[10:13], v[168:171], v[192:195], 0
	v_mfma_f32_16x16x32_bf16 v[6:9], v[160:163], v[200:203], 0
	v_mfma_f32_16x16x32_bf16 v[2:5], v[168:171], v[200:203], 0
	v_mfma_f32_16x16x32_bf16 v[46:49], v[164:167], v[180:183], v[46:49]
	v_mfma_f32_16x16x32_bf16 v[38:41], v[172:175], v[180:183], v[38:41]
	v_mfma_f32_16x16x32_bf16 v[30:33], v[164:167], v[188:191], v[30:33]
	v_mfma_f32_16x16x32_bf16 v[22:25], v[172:175], v[188:191], v[22:25]
	v_mfma_f32_16x16x32_bf16 v[14:17], v[164:167], v[196:199], v[14:17]
	v_mfma_f32_16x16x32_bf16 v[10:13], v[172:175], v[196:199], v[10:13]
	v_mfma_f32_16x16x32_bf16 v[6:9], v[164:167], v[204:207], v[6:9]
	v_mfma_f32_16x16x32_bf16 v[2:5], v[172:175], v[204:207], v[2:5]
	s_setprio 0
	s_barrier
; #define PG8_STAGE(bufoff, gbase, voff) do { _Pragma("unroll") for (int _i = 0; _i < 2; ++_i) \
;         __builtin_amdgcn_global_load_lds((const unsigned*)((const char*)(gbase) + (voff)[_i]), (PG8_LAS unsigned*)(lds + (bufoff) + ldsw + _i * 8192), 16, 0, 0); } while (0)
; #define PG8_LDA(dst, b, h) do { _Pragma("unroll") for (int m = 0; m < 4; ++m) _Pragma("unroll") for (int k = 0; k < 2; ++k) dst[m][k] = *(const PG8_LAS bf16x8*)(lds + PG8_SA(b, h) + aoff + m * 2048 + k * 1024); } while (0)
; #define PG8_LDB(dst, b, h) do { _Pragma("unroll") for (int n = 0; n < 2; ++n) _Pragma("unroll") for (int k = 0; k < 2; ++k) dst[n][k] = *(const PG8_LAS bf16x8*)(lds + PG8_SB(b, h) + boff + n * 2048 + k * 1024); } while (0)
; #define PG8_MMA(ai, bj, At, Bt) do { __builtin_amdgcn_s_setprio(1); _Pragma("unroll") for (int m = 0; m < 4; ++m) _Pragma("unroll") for (int n = 0; n < 2; ++n) _Pragma("unroll") for (int k = 0; k < 2; ++k) \
;         acc[ai][bj][m][n] = __builtin_amdgcn_mfma_f32_16x16x32_bf16(Bt[n][k], At[m][k], acc[ai][bj][m][n], 0, 0, 0); __builtin_amdgcn_s_setprio(0); } while (0)
; #define PG8_WAIT_V(n) asm volatile("s_waitcnt vmcnt(" #n ")" ::: "memory")
; #define PG8_WAIT_L(n) asm volatile("s_waitcnt lgkmcnt(" #n ")" ::: "memory")
; #define PG8_BAR __builtin_amdgcn_s_barrier()
; #define PG8_SCHED __builtin_amdgcn_sched_barrier(0)
; template <class Epi, class Sched, bool ALIGN_EPI = false, bool SP2 = false>
; __device__ __forceinline__ void gemm_phase(PG8_LAS unsigned char* lds, const Gemm g, const Sched& S, const Epi& E) {
;     ...
;             PG8_LDB(B0, 1, 0); PG8_LDB(B1, 1, 1); PG8_SCHED; PG8_LDA(At, 1, 0); PG8_STAGE(PG8_SA(0, 1), a2 + hstep, voffA);
;             PG8_WAIT_V(8); PG8_WAIT_L(0); PG8_BAR; PG8_MMA(0, 0, At, B0); PG8_MMA(0, 1, At, B1); PG8_BAR; PG8_SCHED;
	s_add_i32 s59, 0, 0x18000
	s_add_i32 s60, 0, 0x1c000
	v_add_u32_e32 v156, s59, v138
	v_add_u32_e32 v172, s60, v138
	ds_read_b128 v[144:147], v156
	ds_read_b128 v[148:151], v156 offset:1024
	ds_read_b128 v[152:155], v156 offset:2048
	ds_read_b128 v[156:159], v156 offset:3072
	ds_read_b128 v[160:163], v172
	ds_read_b128 v[164:167], v172 offset:1024
	ds_read_b128 v[168:171], v172 offset:2048
	ds_read_b128 v[172:175], v172 offset:3072
	s_add_u32 s28, s36, 0x80000
	s_addc_u32 s29, s37, 0
	s_mov_b32 m0, s40
	v_lshl_add_u64 v[216:217], s[28:29], 0, v[132:133]
	ds_read_b128 v[176:179], v143 offset:32768
	ds_read_b128 v[180:183], v143 offset:33792
	ds_read_b128 v[184:187], v143 offset:34816
	ds_read_b128 v[188:191], v143 offset:35840
	ds_read_b128 v[192:195], v143 offset:36864
	ds_read_b128 v[196:199], v143 offset:37888
	ds_read_b128 v[200:203], v143 offset:38912
	ds_read_b128 v[204:207], v143 offset:39936
	global_load_lds_dwordx4 v[216:217], off
	v_lshl_add_u64 v[216:217], s[28:29], 0, v[130:131]
	s_mov_b32 m0, s41
	s_nop 0
	global_load_lds_dwordx4 v[216:217], off
	s_waitcnt vmcnt(8)
	s_waitcnt lgkmcnt(0)
	s_barrier
	s_setprio 1
	s_waitcnt lgkmcnt(0)
	v_mfma_f32_16x16x32_bf16 v[126:129], v[144:147], v[176:179], v[126:129]
	v_mfma_f32_16x16x32_bf16 v[122:125], v[152:155], v[176:179], v[122:125]
	v_mfma_f32_16x16x32_bf16 v[118:121], v[144:147], v[184:187], v[118:121]
	v_mfma_f32_16x16x32_bf16 v[114:117], v[152:155], v[184:187], v[114:117]
	v_mfma_f32_16x16x32_bf16 v[106:109], v[144:147], v[192:195], v[106:109]
	v_mfma_f32_16x16x32_bf16 v[98:101], v[152:155], v[192:195], v[98:101]
	v_mfma_f32_16x16x32_bf16 v[90:93], v[144:147], v[200:203], v[90:93]
	v_mfma_f32_16x16x32_bf16 v[82:85], v[152:155], v[200:203], v[82:85]
	v_mfma_f32_16x16x32_bf16 v[126:129], v[148:151], v[180:183], v[126:129]
	v_mfma_f32_16x16x32_bf16 v[122:125], v[156:159], v[180:183], v[122:125]
	v_mfma_f32_16x16x32_bf16 v[118:121], v[148:151], v[188:191], v[118:121]
	v_mfma_f32_16x16x32_bf16 v[114:117], v[156:159], v[188:191], v[114:117]
	v_mfma_f32_16x16x32_bf16 v[106:109], v[148:151], v[196:199], v[106:109]
	v_mfma_f32_16x16x32_bf16 v[98:101], v[156:159], v[196:199], v[98:101]
	v_mfma_f32_16x16x32_bf16 v[90:93], v[148:151], v[204:207], v[90:93]
	v_mfma_f32_16x16x32_bf16 v[82:85], v[156:159], v[204:207], v[82:85]
	s_setprio 0
	s_setprio 1
	v_mfma_f32_16x16x32_bf16 v[110:113], v[160:163], v[176:179], v[110:113]
	v_mfma_f32_16x16x32_bf16 v[102:105], v[168:171], v[176:179], v[102:105]
	v_mfma_f32_16x16x32_bf16 v[94:97], v[160:163], v[184:187], v[94:97]
	v_mfma_f32_16x16x32_bf16 v[86:89], v[168:171], v[184:187], v[86:89]
	v_mfma_f32_16x16x32_bf16 v[78:81], v[160:163], v[192:195], v[78:81]
	v_mfma_f32_16x16x32_bf16 v[74:77], v[168:171], v[192:195], v[74:77]
	v_mfma_f32_16x16x32_bf16 v[70:73], v[160:163], v[200:203], v[70:73]
	v_mfma_f32_16x16x32_bf16 v[66:69], v[168:171], v[200:203], v[66:69]
	v_mfma_f32_16x16x32_bf16 v[110:113], v[164:167], v[180:183], v[110:113]
	v_mfma_f32_16x16x32_bf16 v[102:105], v[172:175], v[180:183], v[102:105]
	v_mfma_f32_16x16x32_bf16 v[94:97], v[164:167], v[188:191], v[94:97]
	v_mfma_f32_16x16x32_bf16 v[86:89], v[172:175], v[188:191], v[86:89]
	v_mfma_f32_16x16x32_bf16 v[78:81], v[164:167], v[196:199], v[78:81]
	v_mfma_f32_16x16x32_bf16 v[74:77], v[172:175], v[196:199], v[74:77]
	v_mfma_f32_16x16x32_bf16 v[70:73], v[164:167], v[204:207], v[70:73]
	v_mfma_f32_16x16x32_bf16 v[66:69], v[172:175], v[204:207], v[66:69]
	s_setprio 0
	s_barrier
; #define PG8_STAGE(bufoff, gbase, voff) do { _Pragma("unroll") for (int _i = 0; _i < 2; ++_i) \
;         __builtin_amdgcn_global_load_lds((const unsigned*)((const char*)(gbase) + (voff)[_i]), (PG8_LAS unsigned*)(lds + (bufoff) + ldsw + _i * 8192), 16, 0, 0); } while (0)
; #define PG8_LDA(dst, b, h) do { _Pragma("unroll") for (int m = 0; m < 4; ++m) _Pragma("unroll") for (int k = 0; k < 2; ++k) dst[m][k] = *(const PG8_LAS bf16x8*)(lds + PG8_SA(b, h) + aoff + m * 2048 + k * 1024); } while (0)
; #define PG8_MMA(ai, bj, At, Bt) do { __builtin_amdgcn_s_setprio(1); _Pragma("unroll") for (int m = 0; m < 4; ++m) _Pragma("unroll") for (int n = 0; n < 2; ++n) _Pragma("unroll") for (int k = 0; k < 2; ++k) \
;         acc[ai][bj][m][n] = __builtin_amdgcn_mfma_f32_16x16x32_bf16(Bt[n][k], At[m][k], acc[ai][bj][m][n], 0, 0, 0); __builtin_amdgcn_s_setprio(0); } while (0)
; #define PG8_WAIT_V(n) asm volatile("s_waitcnt vmcnt(" #n ")" ::: "memory")
; #define PG8_WAIT_L(n) asm volatile("s_waitcnt lgkmcnt(" #n ")" ::: "memory")
; #define PG8_BAR __builtin_amdgcn_s_barrier()
; #define PG8_SCHED __builtin_amdgcn_sched_barrier(0)
; template <class Epi, class Sched, bool ALIGN_EPI = false, bool SP2 = false>
; __device__ __forceinline__ void gemm_phase(PG8_LAS unsigned char* lds, const Gemm g, const Sched& S, const Epi& E) {
;     ...
;             PG8_LDA(At, 1, 1); PG8_STAGE(PG8_SB(1, 0), b3, voffB); PG8_STAGE(PG8_SB(1, 1), b3 + hstep, voffB); PG8_STAGE(PG8_SA(1, 0), a3, voffA);
;             PG8_WAIT_V(8); PG8_WAIT_L(0); PG8_BAR; PG8_MMA(1, 0, At, B0); PG8_MMA(1, 1, At, B1); PG8_BAR; PG8_SCHED;
	s_add_i32 s28, s59, s38
	v_lshl_add_u64 v[208:209], v[208:209], 0, s[6:7]
	s_mov_b32 m0, s28
	ds_read_b128 v[176:179], v143 offset:49152
	ds_read_b128 v[180:183], v143 offset:50176
	ds_read_b128 v[184:187], v143 offset:51200
	ds_read_b128 v[188:191], v143 offset:52224
	ds_read_b128 v[192:195], v143 offset:53248
	ds_read_b128 v[196:199], v143 offset:54272
	ds_read_b128 v[200:203], v143 offset:55296
	ds_read_b128 v[204:207], v143 offset:56320
	global_load_lds_dwordx4 v[208:209], off
	s_add_i32 m0, s28, 0x2000
	s_add_u32 s28, s34, 0x80080
	v_lshl_add_u64 v[208:209], v[210:211], 0, s[6:7]
	s_addc_u32 s29, s35, 0
	s_add_i32 s34, s60, s38
	global_load_lds_dwordx4 v[208:209], off
	v_lshl_add_u64 v[208:209], s[28:29], 0, v[132:133]
	s_mov_b32 m0, s34
	s_nop 0
	global_load_lds_dwordx4 v[208:209], off
	v_lshl_add_u64 v[208:209], s[28:29], 0, v[130:131]
	s_add_i32 m0, s34, 0x2000
	s_nop 0
	global_load_lds_dwordx4 v[208:209], off
	v_lshl_add_u64 v[208:209], v[212:213], 0, s[6:7]
	s_mov_b32 m0, s43
	s_nop 0
	global_load_lds_dwordx4 v[208:209], off
	v_lshl_add_u64 v[208:209], v[214:215], 0, s[6:7]
	s_mov_b32 m0, s46
	s_nop 0
	global_load_lds_dwordx4 v[208:209], off
	s_waitcnt vmcnt(8)
	s_waitcnt lgkmcnt(0)
	s_barrier
	s_setprio 1
	s_waitcnt lgkmcnt(0)
	v_mfma_f32_16x16x32_bf16 v[62:65], v[144:147], v[176:179], v[62:65]
	v_mfma_f32_16x16x32_bf16 v[58:61], v[152:155], v[176:179], v[58:61]
	v_mfma_f32_16x16x32_bf16 v[54:57], v[144:147], v[184:187], v[54:57]
	v_mfma_f32_16x16x32_bf16 v[50:53], v[152:155], v[184:187], v[50:53]
	v_mfma_f32_16x16x32_bf16 v[42:45], v[144:147], v[192:195], v[42:45]
	v_mfma_f32_16x16x32_bf16 v[34:37], v[152:155], v[192:195], v[34:37]
	v_mfma_f32_16x16x32_bf16 v[26:29], v[144:147], v[200:203], v[26:29]
	v_mfma_f32_16x16x32_bf16 v[18:21], v[152:155], v[200:203], v[18:21]
	v_mfma_f32_16x16x32_bf16 v[62:65], v[148:151], v[180:183], v[62:65]
	v_mfma_f32_16x16x32_bf16 v[58:61], v[156:159], v[180:183], v[58:61]
	v_mfma_f32_16x16x32_bf16 v[54:57], v[148:151], v[188:191], v[54:57]
	v_mfma_f32_16x16x32_bf16 v[50:53], v[156:159], v[188:191], v[50:53]
	v_mfma_f32_16x16x32_bf16 v[42:45], v[148:151], v[196:199], v[42:45]
	v_mfma_f32_16x16x32_bf16 v[34:37], v[156:159], v[196:199], v[34:37]
	v_mfma_f32_16x16x32_bf16 v[26:29], v[148:151], v[204:207], v[26:29]
	v_mfma_f32_16x16x32_bf16 v[18:21], v[156:159], v[204:207], v[18:21]
	s_setprio 0
	s_setprio 1
	v_mfma_f32_16x16x32_bf16 v[46:49], v[160:163], v[176:179], v[46:49]
	v_mfma_f32_16x16x32_bf16 v[38:41], v[168:171], v[176:179], v[38:41]
	v_mfma_f32_16x16x32_bf16 v[30:33], v[160:163], v[184:187], v[30:33]
	v_mfma_f32_16x16x32_bf16 v[22:25], v[168:171], v[184:187], v[22:25]
	v_mfma_f32_16x16x32_bf16 v[14:17], v[160:163], v[192:195], v[14:17]
	v_mfma_f32_16x16x32_bf16 v[10:13], v[168:171], v[192:195], v[10:13]
	v_mfma_f32_16x16x32_bf16 v[6:9], v[160:163], v[200:203], v[6:9]
	v_mfma_f32_16x16x32_bf16 v[2:5], v[168:171], v[200:203], v[2:5]
	v_mfma_f32_16x16x32_bf16 v[46:49], v[164:167], v[180:183], v[46:49]
	v_mfma_f32_16x16x32_bf16 v[38:41], v[172:175], v[180:183], v[38:41]
	v_mfma_f32_16x16x32_bf16 v[30:33], v[164:167], v[188:191], v[30:33]
	v_mfma_f32_16x16x32_bf16 v[22:25], v[172:175], v[188:191], v[22:25]
	v_mfma_f32_16x16x32_bf16 v[14:17], v[164:167], v[196:199], v[14:17]
	v_mfma_f32_16x16x32_bf16 v[10:13], v[172:175], v[196:199], v[10:13]
	v_mfma_f32_16x16x32_bf16 v[6:9], v[164:167], v[204:207], v[6:9]
	v_mfma_f32_16x16x32_bf16 v[2:5], v[172:175], v[204:207], v[2:5]
	s_setprio 0
	s_barrier
	s_add_i32 s58, s58, 2
	s_add_u32 s21, s21, 0x100
	s_addc_u32 s23, s23, 0
	s_cmp_gt_u32 s58, 5
	s_mov_b64 s[28:29], s[30:31]
	s_branch .LBB0_1817

;     DI void operator()(const f32x4 (&acc)[2][2][4][2], const pg8::Unit& u, int wr, int wc, int fr, int fq) const {
;         const int row0 = (u.pm - MP / 256) * 256 + wr * 64 + fr, col0 = u.pn * 256 + wc * 32 + 4 * fq;
;         float* dst = slab + (size_t)(u.kb / kslice_bytes) * MS * DM;
; #pragma unroll
;         for (int ai = 0; ai < 2; ++ai)
; #pragma unroll
;             for (int m = 0; m < 4; ++m) {
;                 const size_t off = (size_t)(row0 + ai * 128 + m * 16) * DM + col0;
; #pragma unroll
;                 for (int bj = 0; bj < 2; ++bj)
; #pragma unroll
;                     for (int n = 0; n < 2; ++n) *(f32x4*)(dst + off + bj * 128 + n * 16) = acc[ai][bj][m][n];
;             }
;     }
.LBB0_1820:
	s_ashr_i32 s21, s47, 31
	s_lshr_b32 s21, s21, 22
	s_add_i32 s21, s47, s21
	s_ashr_i32 s28, s21, 10
	s_ashr_i32 s29, s28, 31
	s_lshl_b64 s[28:29], s[28:29], 23
	v_readlane_b32 s21, v253, 57
	v_lshl_or_b32 v144, s48, 8, v140
	s_add_u32 s28, s21, s28
	v_readlane_b32 s21, v253, 58
	v_lshl_add_u32 v146, s8, 8, v139
	s_addc_u32 s29, s21, s29
	v_ashrrev_i32_e32 v145, 31, v144
	v_ashrrev_i32_e32 v147, 31, v146
	v_lshl_add_u64 v[144:145], v[144:145], 2, s[28:29]
	v_lshlrev_b64 v[148:149], 13, v[146:147]
	v_lshl_add_u64 v[148:149], v[144:145], 0, v[148:149]
	global_store_dwordx4 v[148:149], v[126:129], off
	global_store_dwordx4 v[148:149], v[122:125], off offset:64
	global_store_dwordx4 v[148:149], v[110:113], off offset:512
	global_store_dwordx4 v[148:149], v[102:105], off offset:576
	s_nop 1
	v_or_b32_e32 v102, 16, v146
	v_ashrrev_i32_e32 v103, 31, v102
	v_lshlrev_b64 v[102:103], 13, v[102:103]
	v_lshl_add_u64 v[102:103], v[144:145], 0, v[102:103]
	global_store_dwordx4 v[102:103], v[118:121], off
	global_store_dwordx4 v[102:103], v[114:117], off offset:64
	global_store_dwordx4 v[102:103], v[94:97], off offset:512
	global_store_dwordx4 v[102:103], v[86:89], off offset:576
	s_nop 1
	v_or_b32_e32 v86, 32, v146
	v_ashrrev_i32_e32 v87, 31, v86
	v_lshlrev_b64 v[86:87], 13, v[86:87]
	v_lshl_add_u64 v[86:87], v[144:145], 0, v[86:87]
	global_store_dwordx4 v[86:87], v[106:109], off
	global_store_dwordx4 v[86:87], v[98:101], off offset:64
	global_store_dwordx4 v[86:87], v[78:81], off offset:512
	global_store_dwordx4 v[86:87], v[74:77], off offset:576
	s_nop 1
	v_or_b32_e32 v74, 48, v146
	v_ashrrev_i32_e32 v75, 31, v74
	v_lshlrev_b64 v[74:75], 13, v[74:75]
	v_lshl_add_u64 v[74:75], v[144:145], 0, v[74:75]
	global_store_dwordx4 v[74:75], v[90:93], off
	global_store_dwordx4 v[74:75], v[82:85], off offset:64
	global_store_dwordx4 v[74:75], v[70:73], off offset:512
	global_store_dwordx4 v[74:75], v[66:69], off offset:576
	s_nop 1
	v_add_co_u32_e32 v68, vcc, s49, v148
	v_lshl_add_u64 v[66:67], v[148:149], 0, s[12:13]
	s_nop 0
	v_addc_co_u32_e32 v69, vcc, 0, v149, vcc
	global_store_dwordx4 v[68:69], v[62:65], off
	global_store_dwordx4 v[66:67], v[58:61], off offset:64
	global_store_dwordx4 v[66:67], v[46:49], off offset:512
	global_store_dwordx4 v[66:67], v[38:41], off offset:576
	s_nop 1
	v_add_co_u32_e32 v40, vcc, s50, v148
	v_lshl_add_u64 v[38:39], v[148:149], 0, s[14:15]
	s_nop 0
	v_addc_co_u32_e32 v41, vcc, 0, v149, vcc
	global_store_dwordx4 v[40:41], v[54:57], off
	global_store_dwordx4 v[38:39], v[50:53], off offset:64
	global_store_dwordx4 v[38:39], v[30:33], off offset:512
	global_store_dwordx4 v[38:39], v[22:25], off offset:576
	s_nop 1
	v_add_co_u32_e32 v24, vcc, s51, v148
	v_lshl_add_u64 v[22:23], v[148:149], 0, s[16:17]
	s_nop 0
	v_addc_co_u32_e32 v25, vcc, 0, v149, vcc
	global_store_dwordx4 v[24:25], v[42:45], off
	global_store_dwordx4 v[22:23], v[34:37], off offset:64
	global_store_dwordx4 v[22:23], v[14:17], off offset:512
	global_store_dwordx4 v[22:23], v[10:13], off offset:576
	s_nop 1
	v_add_co_u32_e32 v12, vcc, 0x160000, v148
	v_lshl_add_u64 v[10:11], v[148:149], 0, s[18:19]
	s_nop 0
	v_addc_co_u32_e32 v13, vcc, 0, v149, vcc
	s_and_b64 vcc, exec, s[0:1]
	s_mov_b64 s[0:1], -1
	global_store_dwordx4 v[12:13], v[26:29], off
	global_store_dwordx4 v[10:11], v[18:21], off offset:64
	global_store_dwordx4 v[10:11], v[6:9], off offset:512
	global_store_dwordx4 v[10:11], v[2:5], off offset:576
	s_mov_b32 s98, 1
	s_cbranch_vccnz .LBB0_1809
	s_andn2_b64 vcc, exec, s[4:5]
	s_cbranch_vccnz .LBB0_1808
	s_barrier
	s_branch .LBB0_1808

; #define PG8_STAGE(bufoff, gbase, voff) do { _Pragma("unroll") for (int _i = 0; _i < 2; ++_i) \
;         __builtin_amdgcn_global_load_lds((const unsigned*)((const char*)(gbase) + (voff)[_i]), (PG8_LAS unsigned*)(lds + (bufoff) + ldsw + _i * 8192), 16, 0, 0); } while (0)
; #define PG8_WAIT_V(n) asm volatile("s_waitcnt vmcnt(" #n ")" ::: "memory")
; #define PG8_BAR __builtin_amdgcn_s_barrier()
; template <class Epi, class Sched, bool ALIGN_EPI = false, bool SP2 = false>
; __device__ __forceinline__ void gemm_phase(PG8_LAS unsigned char* lds, const Gemm g, const Sched& S, const Epi& E) {
;     ...
;     for (int i = 0; i < 2; ++i) { int R, C; stage_rc(tid * 16 + i * 8192, R, C); const int Rb = Epi::PERM ? ((R & ~31) + perm32(R & 31)) : R;
;         voffA[i] = (unsigned)(R * LD + C) * 2u; voffB[i] = (unsigned)(Rb * LD + C) * 2u; }
;     const size_t kstep = (size_t)(BK * 2);
;     const size_t hstep = (size_t)HALF * LD * 2;
;     const size_t tstep = 2 * hstep;
;     const unsigned ldsw = (unsigned)wid * 1024u;
;     const int aoff = lds_byte(wr * 64 + fr, fq * 8), boff = lds_byte(wc * 32 + fr, fq * 8);
;     ...
;         PG8_STAGE(PG8_SB(1, 0), cB + kstep, voffB); PG8_STAGE(PG8_SA(1, 0), cA + kstep, voffA); PG8_STAGE(PG8_SB(1, 1), cB + hstep + kstep, voffB);
;         PG8_WAIT_V(6); PG8_BAR;
.LBB0_2116:
	s_lshl_b32 s1, s1, 5
	s_mov_b64 s[6:7], 0x80
	s_and_b32 s1, s1, 0x60
	s_add_i32 m0, s36, 0x18000
	v_lshl_add_u64 v[8:9], v[8:9], 0, s[6:7]
	s_lshl_b32 s9, s3, 13
	s_lshl_b32 s18, s1, 7
	s_waitcnt vmcnt(2)
	s_barrier
	global_load_lds_dwordx4 v[8:9], off
	v_lshl_add_u64 v[4:5], v[4:5], 0, s[6:7]
	s_add_i32 m0, s36, 0x1a000
	s_add_i32 s41, s36, 0x8000
	s_add_i32 s42, s36, 0xa000
	global_load_lds_dwordx4 v[4:5], off
	v_lshl_add_u64 v[2:3], v[2:3], 0, s[6:7]
	s_mov_b32 m0, s41
	s_add_u32 s12, s28, 0x160080
	global_load_lds_dwordx4 v[2:3], off
	v_lshl_add_u64 v[2:3], v[6:7], 0, s[6:7]
	s_mov_b32 m0, s42
	s_addc_u32 s13, s29, 0
	global_load_lds_dwordx4 v[2:3], off
	s_add_i32 m0, s36, 0x1c000
	v_lshl_add_u64 v[2:3], s[12:13], 0, v[146:147]
	global_load_lds_dwordx4 v[2:3], off
	v_lshl_add_u64 v[2:3], s[12:13], 0, v[150:151]
	s_add_i32 m0, s36, 0x1e000
	s_cmpk_lt_u32 s2, 0x100
	global_load_lds_dwordx4 v[2:3], off
	v_lshrrev_b32_e32 v3, 1, v10
	v_and_b32_e32 v3, 24, v3
	v_and_b32_e32 v2, 15, v10
	v_lshlrev_b32_e32 v4, 1, v3
	v_lshl_or_b32 v1, s3, 6, v2
	v_lshl_or_b32 v2, v2, 6, v4
	v_lshlrev_b32_e32 v4, 2, v10
	v_and_b32_e32 v4, 32, v4
	v_bitop3_b32 v5, v2, s9, v4 bitop3:0xde
	v_bitop3_b32 v143, v2, s18, v4 bitop3:0xde
	v_or_b32_e32 v168, s1, v3
	v_lshrrev_b32_e32 v3, 1, v11
	v_mul_lo_u32 v2, v12, s0
	v_mad_u64_u32 v[2:3], s[2:3], v3, s10, v[2:3]
	v_or_b32_e32 v2, v2, v13
	s_mov_b64 s[12:13], 0x160080
	v_add_lshl_u32 v2, v2, v14, 1
	v_mov_b32_e32 v3, v147
	v_lshl_add_u64 v[152:153], v[2:3], 0, s[12:13]
	v_lshrrev_b32_e32 v3, 1, v15
	v_mul_lo_u32 v2, v16, s0
	v_mad_u64_u32 v[2:3], s[0:1], v3, s10, v[2:3]
	s_waitcnt vmcnt(6)
	v_or_b32_e32 v2, v2, v17
	s_sext_i32_i8 s51, s8
	s_cselect_b64 s[8:9], -1, 0
	v_add_lshl_u32 v2, v2, v18, 1
	v_mov_b32_e32 v3, v147
	s_add_i32 s46, 0, 0x10000
	s_add_i32 s47, 0, 0x14000
	s_ashr_i32 s43, s78, 31
	v_lshl_add_u64 v[154:155], v[2:3], 0, s[12:13]
	v_mov_b64_e32 v[156:157], 0x200
	v_mov_b64_e32 v[158:159], 0x1ff
	v_add_u32_e32 v169, s46, v143
	v_add_u32_e32 v170, s47, v143
	v_add_u32_e32 v171, 0, v5
	s_mov_b32 s10, 0x3f9837f0
	s_mov_b64 s[12:13], 0x80000
	s_mov_b64 s[18:19], 0x90000
	s_mov_b64 s[20:21], 0xa0000
	s_mov_b64 s[22:23], 0xb0000
	s_barrier
	s_mov_b32 s98, 0
	s_branch .LBB0_2119

; #define PG8_STAGE(bufoff, gbase, voff) do { _Pragma("unroll") for (int _i = 0; _i < 2; ++_i) \
;         __builtin_amdgcn_global_load_lds((const unsigned*)((const char*)(gbase) + (voff)[_i]), (PG8_LAS unsigned*)(lds + (bufoff) + ldsw + _i * 8192), 16, 0, 0); } while (0)
; #define PG8_LDA(dst, b, h) do { _Pragma("unroll") for (int m = 0; m < 4; ++m) _Pragma("unroll") for (int k = 0; k < 2; ++k) dst[m][k] = *(const PG8_LAS bf16x8*)(lds + PG8_SA(b, h) + aoff + m * 2048 + k * 1024); } while (0)
; #define PG8_LDB(dst, b, h) do { _Pragma("unroll") for (int n = 0; n < 2; ++n) _Pragma("unroll") for (int k = 0; k < 2; ++k) dst[n][k] = *(const PG8_LAS bf16x8*)(lds + PG8_SB(b, h) + boff + n * 2048 + k * 1024); } while (0)
; #define PG8_WAIT_V(n) asm volatile("s_waitcnt vmcnt(" #n ")" ::: "memory")
; #define PG8_WAIT_L(n) asm volatile("s_waitcnt lgkmcnt(" #n ")" ::: "memory")
; #define PG8_BAR __builtin_amdgcn_s_barrier()
; #define PG8_SCHED __builtin_amdgcn_sched_barrier(0)
; template <class Epi, class Sched, bool ALIGN_EPI = false, bool SP2 = false>
; __device__ __forceinline__ void gemm_phase(PG8_LAS unsigned char* lds, const Gemm g, const Sched& S, const Epi& E) {
;     ...
;         const bool has_next = S.next(ui + 1, nxt);
;         const char* nA = has_next ? (const char*)g.A + (size_t)nxt.pm * tstep + nxt.kb : cA; const char* nB = has_next ? (const char*)g.Bt + (size_t)nxt.pn * tstep + nxt.kb : cB;
;         for (int t = 0; t < nt; t += 2) {
;             const bool last = (t == nt - 2);
;             const char* a1 = cA + (size_t)(t + 1) * kstep;
;             const char* a2 = last ? nA : cA + (size_t)(t + 2) * kstep; const char* b2 = last ? nB : cB + (size_t)(t + 2) * kstep;
;             const char* a3 = a2 + kstep; const char* b3 = b2 + kstep;
;             if (last && has_next) S.a_ready(nxt);
;             if constexpr (SP2) {
;             PG8_LDB(B0, 0, 0); PG8_LDB(B1, 0, 1); PG8_SCHED; PG8_LDA(At, 0, 0); PG8_STAGE(PG8_SA(1, 1), a1 + hstep, voffA);
;             PG8_WAIT_V(8); PG8_WAIT_L(0); PG8_BAR; PG8_MMA(0, 0, At, B0); PG8_MMA(0, 1, At, B1); PG8_BAR; PG8_SCHED;
;     ...
; #pragma unroll
;         for (int a = 0; a < 2; ++a)
; #pragma unroll
;             for (int b = 0; b < 2; ++b)
; #pragma unroll
;                 for (int m = 0; m < 4; ++m)
; #pragma unroll
;                     for (int n = 0; n < 2; ++n) acc[a][b][m][n] = (f32x4){0.f, 0.f, 0.f, 0.f};
.LBB0_2129:
	s_add_u32 s52, s28, 0x100
	v_mov_b32_e32 v2, 0
	s_addc_u32 s53, s29, 0
	s_mov_b32 s54, -2
	s_cmp_lg_u32 s98, 0
	s_cbranch_scc1 .Lpeel_9
	v_mov_b32_e32 v3, v2
	v_mov_b32_e32 v4, v2
	v_mov_b32_e32 v5, v2
	v_mov_b32_e32 v6, v2
	v_mov_b32_e32 v7, v2
	v_mov_b32_e32 v8, v2
	v_mov_b32_e32 v9, v2
	v_mov_b32_e32 v14, v2
	v_mov_b32_e32 v15, v2
	v_mov_b32_e32 v16, v2
	v_mov_b32_e32 v17, v2
	v_mov_b32_e32 v22, v2
	v_mov_b32_e32 v23, v2
	v_mov_b32_e32 v24, v2
	v_mov_b32_e32 v25, v2
	v_mov_b32_e32 v30, v2
	v_mov_b32_e32 v31, v2
	v_mov_b32_e32 v32, v2
	v_mov_b32_e32 v33, v2
	v_mov_b32_e32 v38, v2
	v_mov_b32_e32 v39, v2
	v_mov_b32_e32 v40, v2
	v_mov_b32_e32 v41, v2
	v_mov_b32_e32 v46, v2
	v_mov_b32_e32 v47, v2
	v_mov_b32_e32 v48, v2
	v_mov_b32_e32 v49, v2
	v_mov_b32_e32 v54, v2
	v_mov_b32_e32 v55, v2
	v_mov_b32_e32 v56, v2
	v_mov_b32_e32 v57, v2
	v_mov_b32_e32 v10, v2
	v_mov_b32_e32 v11, v2
	v_mov_b32_e32 v12, v2
	v_mov_b32_e32 v13, v2
	v_mov_b32_e32 v18, v2
	v_mov_b32_e32 v19, v2
	v_mov_b32_e32 v20, v2
	v_mov_b32_e32 v21, v2
	v_mov_b32_e32 v26, v2
	v_mov_b32_e32 v27, v2
	v_mov_b32_e32 v28, v2
	v_mov_b32_e32 v29, v2
	v_mov_b32_e32 v34, v2
	v_mov_b32_e32 v35, v2
	v_mov_b32_e32 v36, v2
	v_mov_b32_e32 v37, v2
	v_mov_b32_e32 v42, v2
	v_mov_b32_e32 v43, v2
	v_mov_b32_e32 v44, v2
	v_mov_b32_e32 v45, v2
	v_mov_b32_e32 v50, v2
	v_mov_b32_e32 v51, v2
	v_mov_b32_e32 v52, v2
	v_mov_b32_e32 v53, v2
	v_mov_b32_e32 v58, v2
	v_mov_b32_e32 v59, v2
	v_mov_b32_e32 v60, v2
	v_mov_b32_e32 v61, v2
	v_mov_b32_e32 v62, v2
	v_mov_b32_e32 v63, v2
	v_mov_b32_e32 v64, v2
	v_mov_b32_e32 v65, v2
	v_mov_b32_e32 v66, v2
	v_mov_b32_e32 v67, v2
	v_mov_b32_e32 v68, v2
	v_mov_b32_e32 v69, v2
	v_mov_b32_e32 v70, v2
	v_mov_b32_e32 v71, v2
	v_mov_b32_e32 v72, v2
	v_mov_b32_e32 v73, v2
	v_mov_b32_e32 v74, v2
	v_mov_b32_e32 v75, v2
	v_mov_b32_e32 v76, v2
	v_mov_b32_e32 v77, v2
	v_mov_b32_e32 v82, v2
	v_mov_b32_e32 v83, v2
	v_mov_b32_e32 v84, v2
	v_mov_b32_e32 v85, v2
	v_mov_b32_e32 v94, v2
	v_mov_b32_e32 v95, v2
	v_mov_b32_e32 v96, v2
	v_mov_b32_e32 v97, v2
	v_mov_b32_e32 v102, v2
	v_mov_b32_e32 v103, v2
	v_mov_b32_e32 v104, v2
	v_mov_b32_e32 v105, v2
	v_mov_b32_e32 v106, v2
	v_mov_b32_e32 v107, v2
	v_mov_b32_e32 v108, v2
	v_mov_b32_e32 v109, v2
	v_mov_b32_e32 v110, v2
	v_mov_b32_e32 v111, v2
	v_mov_b32_e32 v112, v2
	v_mov_b32_e32 v113, v2
	v_mov_b32_e32 v78, v2
	v_mov_b32_e32 v79, v2
	v_mov_b32_e32 v80, v2
	v_mov_b32_e32 v81, v2
	v_mov_b32_e32 v86, v2
	v_mov_b32_e32 v87, v2
	v_mov_b32_e32 v88, v2
	v_mov_b32_e32 v89, v2
	v_mov_b32_e32 v90, v2
	v_mov_b32_e32 v91, v2
	v_mov_b32_e32 v92, v2
	v_mov_b32_e32 v93, v2
	v_mov_b32_e32 v98, v2
	v_mov_b32_e32 v99, v2
	v_mov_b32_e32 v100, v2
	v_mov_b32_e32 v101, v2
	v_mov_b32_e32 v114, v2
	v_mov_b32_e32 v115, v2
	v_mov_b32_e32 v116, v2
	v_mov_b32_e32 v117, v2
	v_mov_b32_e32 v118, v2
	v_mov_b32_e32 v119, v2
	v_mov_b32_e32 v120, v2
	v_mov_b32_e32 v121, v2
	v_mov_b32_e32 v122, v2
	v_mov_b32_e32 v123, v2
	v_mov_b32_e32 v124, v2
	v_mov_b32_e32 v125, v2
	v_mov_b32_e32 v126, v2
	v_mov_b32_e32 v127, v2
	v_mov_b32_e32 v128, v2
	v_mov_b32_e32 v129, v2
.LBB0_2130:
	ds_read_b128 v[130:133], v169
	ds_read_b128 v[134:137], v169 offset:1024
	ds_read_b128 v[138:141], v169 offset:2048
	ds_read_b128 v[160:163], v169 offset:3072
	ds_read_b128 v[164:167], v170
	ds_read_b128 v[172:175], v170 offset:1024
	ds_read_b128 v[176:179], v170 offset:2048
	ds_read_b128 v[180:183], v170 offset:3072
	s_add_u32 s28, s26, 0x100
	s_addc_u32 s29, s27, 0
	s_cmpk_eq_i32 s54, 0x54
	s_cselect_b32 s35, s3, s29
	s_cselect_b32 s34, s2, s28
	s_cselect_b32 s31, s25, s53
	s_cselect_b32 s30, s24, s52
	v_lshl_add_u64 v[216:217], s[26:27], 0, v[152:153]
	s_add_i32 m0, s36, 0xc000
	ds_read_b128 v[184:187], v171
	ds_read_b128 v[188:191], v171 offset:1024
	ds_read_b128 v[192:195], v171 offset:2048
	ds_read_b128 v[196:199], v171 offset:3072
	ds_read_b128 v[200:203], v171 offset:4096
	ds_read_b128 v[204:207], v171 offset:5120
	ds_read_b128 v[208:211], v171 offset:6144
	ds_read_b128 v[212:215], v171 offset:7168
	global_load_lds_dwordx4 v[216:217], off
	v_lshl_add_u64 v[216:217], s[26:27], 0, v[154:155]
	s_add_i32 m0, s36, 0xe000
	s_nop 0
	global_load_lds_dwordx4 v[216:217], off
	s_waitcnt vmcnt(8)
	s_waitcnt lgkmcnt(0)
	s_barrier
	s_setprio 1
	s_waitcnt lgkmcnt(0)
	v_mfma_f32_16x16x32_bf16 v[126:129], v[130:133], v[184:187], v[126:129]
	v_mfma_f32_16x16x32_bf16 v[122:125], v[138:141], v[184:187], v[122:125]
	v_mfma_f32_16x16x32_bf16 v[118:121], v[130:133], v[192:195], v[118:121]
	v_mfma_f32_16x16x32_bf16 v[114:117], v[138:141], v[192:195], v[114:117]
	v_mfma_f32_16x16x32_bf16 v[98:101], v[130:133], v[200:203], v[98:101]
	v_mfma_f32_16x16x32_bf16 v[90:93], v[138:141], v[200:203], v[90:93]
	v_mfma_f32_16x16x32_bf16 v[86:89], v[130:133], v[208:211], v[86:89]
	v_mfma_f32_16x16x32_bf16 v[78:81], v[138:141], v[208:211], v[78:81]
	v_mfma_f32_16x16x32_bf16 v[126:129], v[134:137], v[188:191], v[126:129]
	v_mfma_f32_16x16x32_bf16 v[122:125], v[160:163], v[188:191], v[122:125]
	v_mfma_f32_16x16x32_bf16 v[118:121], v[134:137], v[196:199], v[118:121]
	v_mfma_f32_16x16x32_bf16 v[114:117], v[160:163], v[196:199], v[114:117]
	v_mfma_f32_16x16x32_bf16 v[98:101], v[134:137], v[204:207], v[98:101]
	v_mfma_f32_16x16x32_bf16 v[90:93], v[160:163], v[204:207], v[90:93]
	v_mfma_f32_16x16x32_bf16 v[86:89], v[134:137], v[212:215], v[86:89]
	v_mfma_f32_16x16x32_bf16 v[78:81], v[160:163], v[212:215], v[78:81]
	s_setprio 0
	s_setprio 1
	v_mfma_f32_16x16x32_bf16 v[110:113], v[164:167], v[184:187], v[110:113]
	v_mfma_f32_16x16x32_bf16 v[106:109], v[176:179], v[184:187], v[106:109]
	v_mfma_f32_16x16x32_bf16 v[102:105], v[164:167], v[192:195], v[102:105]
	v_mfma_f32_16x16x32_bf16 v[94:97], v[176:179], v[192:195], v[94:97]
	v_mfma_f32_16x16x32_bf16 v[82:85], v[164:167], v[200:203], v[82:85]
	v_mfma_f32_16x16x32_bf16 v[74:77], v[176:179], v[200:203], v[74:77]
	v_mfma_f32_16x16x32_bf16 v[70:73], v[164:167], v[208:211], v[70:73]
	v_mfma_f32_16x16x32_bf16 v[66:69], v[176:179], v[208:211], v[66:69]
	v_mfma_f32_16x16x32_bf16 v[110:113], v[172:175], v[188:191], v[110:113]
	v_mfma_f32_16x16x32_bf16 v[106:109], v[180:183], v[188:191], v[106:109]
	v_mfma_f32_16x16x32_bf16 v[102:105], v[172:175], v[196:199], v[102:105]
	v_mfma_f32_16x16x32_bf16 v[94:97], v[180:183], v[196:199], v[94:97]
	v_mfma_f32_16x16x32_bf16 v[82:85], v[172:175], v[204:207], v[82:85]
	v_mfma_f32_16x16x32_bf16 v[74:77], v[180:183], v[204:207], v[74:77]
	v_mfma_f32_16x16x32_bf16 v[70:73], v[172:175], v[212:215], v[70:73]
	v_mfma_f32_16x16x32_bf16 v[66:69], v[180:183], v[212:215], v[66:69]
	s_setprio 0
	s_barrier
; #define PG8_STAGE(bufoff, gbase, voff) do { _Pragma("unroll") for (int _i = 0; _i < 2; ++_i) \
;         __builtin_amdgcn_global_load_lds((const unsigned*)((const char*)(gbase) + (voff)[_i]), (PG8_LAS unsigned*)(lds + (bufoff) + ldsw + _i * 8192), 16, 0, 0); } while (0)
; #define PG8_LDA(dst, b, h) do { _Pragma("unroll") for (int m = 0; m < 4; ++m) _Pragma("unroll") for (int k = 0; k < 2; ++k) dst[m][k] = *(const PG8_LAS bf16x8*)(lds + PG8_SA(b, h) + aoff + m * 2048 + k * 1024); } while (0)
; #define PG8_LDB(dst, b, h) do { _Pragma("unroll") for (int n = 0; n < 2; ++n) _Pragma("unroll") for (int k = 0; k < 2; ++k) dst[n][k] = *(const PG8_LAS bf16x8*)(lds + PG8_SB(b, h) + boff + n * 2048 + k * 1024); } while (0)
; #define PG8_MMA(ai, bj, At, Bt) do { __builtin_amdgcn_s_setprio(1); _Pragma("unroll") for (int m = 0; m < 4; ++m) _Pragma("unroll") for (int n = 0; n < 2; ++n) _Pragma("unroll") for (int k = 0; k < 2; ++k) \
;         acc[ai][bj][m][n] = __builtin_amdgcn_mfma_f32_16x16x32_bf16(Bt[n][k], At[m][k], acc[ai][bj][m][n], 0, 0, 0); __builtin_amdgcn_s_setprio(0); } while (0)
; #define PG8_WAIT_V(n) asm volatile("s_waitcnt vmcnt(" #n ")" ::: "memory")
; #define PG8_WAIT_L(n) asm volatile("s_waitcnt lgkmcnt(" #n ")" ::: "memory")
; #define PG8_BAR __builtin_amdgcn_s_barrier()
; #define PG8_SCHED __builtin_amdgcn_sched_barrier(0)
; template <class Epi, class Sched, bool ALIGN_EPI = false, bool SP2 = false>
; __device__ __forceinline__ void gemm_phase(PG8_LAS unsigned char* lds, const Gemm g, const Sched& S, const Epi& E) {
;     ...
;             PG8_LDA(At, 0, 1); PG8_STAGE(PG8_SB(0, 0), b2, voffB); PG8_STAGE(PG8_SB(0, 1), b2 + hstep, voffB); PG8_STAGE(PG8_SA(0, 0), a2, voffA);
;             PG8_WAIT_V(8); PG8_WAIT_L(0); PG8_BAR; PG8_MMA(1, 0, At, B0); PG8_MMA(1, 1, At, B1); PG8_BAR; PG8_SCHED;
;             PG8_LDB(B0, 1, 0); PG8_LDB(B1, 1, 1); PG8_SCHED; PG8_LDA(At, 1, 0); PG8_STAGE(PG8_SA(0, 1), a2 + hstep, voffA);
	s_add_i32 s26, s46, s33
	v_lshl_add_u64 v[216:217], s[30:31], 0, v[146:147]
	s_mov_b32 m0, s26
	ds_read_b128 v[184:187], v171 offset:16384
	ds_read_b128 v[188:191], v171 offset:17408
	ds_read_b128 v[192:195], v171 offset:18432
	ds_read_b128 v[196:199], v171 offset:19456
	ds_read_b128 v[200:203], v171 offset:20480
	ds_read_b128 v[204:207], v171 offset:21504
	ds_read_b128 v[208:211], v171 offset:22528
	ds_read_b128 v[212:215], v171 offset:23552
	global_load_lds_dwordx4 v[216:217], off
	s_add_i32 m0, s26, 0x2000
	s_add_u32 s26, s30, 0x160000
	v_lshl_add_u64 v[220:221], s[30:31], 0, v[150:151]
	s_addc_u32 s27, s31, 0
	s_add_i32 s55, s47, s33
	global_load_lds_dwordx4 v[220:221], off
	v_lshl_add_u64 v[222:223], s[26:27], 0, v[146:147]
	s_mov_b32 m0, s55
	v_lshl_add_u64 v[224:225], s[34:35], 0, v[148:149]
	global_load_lds_dwordx4 v[222:223], off
	v_lshl_add_u64 v[222:223], s[26:27], 0, v[150:151]
	s_add_i32 m0, s55, 0x2000
	s_nop 0
	global_load_lds_dwordx4 v[222:223], off
	v_lshl_add_u64 v[222:223], s[34:35], 0, v[144:145]
	s_mov_b32 m0, s36
	s_nop 0
	global_load_lds_dwordx4 v[222:223], off
	s_mov_b32 m0, s37
	s_nop 0
	global_load_lds_dwordx4 v[224:225], off
	s_waitcnt vmcnt(8)
	s_waitcnt lgkmcnt(0)
	s_barrier
	s_setprio 1
	s_waitcnt lgkmcnt(0)
	v_mfma_f32_16x16x32_bf16 v[62:65], v[130:133], v[184:187], v[62:65]
	v_mfma_f32_16x16x32_bf16 v[58:61], v[138:141], v[184:187], v[58:61]
	v_mfma_f32_16x16x32_bf16 v[50:53], v[130:133], v[192:195], v[50:53]
	v_mfma_f32_16x16x32_bf16 v[42:45], v[138:141], v[192:195], v[42:45]
	v_mfma_f32_16x16x32_bf16 v[34:37], v[130:133], v[200:203], v[34:37]
	v_mfma_f32_16x16x32_bf16 v[26:29], v[138:141], v[200:203], v[26:29]
	v_mfma_f32_16x16x32_bf16 v[18:21], v[130:133], v[208:211], v[18:21]
	v_mfma_f32_16x16x32_bf16 v[10:13], v[138:141], v[208:211], v[10:13]
	v_mfma_f32_16x16x32_bf16 v[62:65], v[134:137], v[188:191], v[62:65]
	v_mfma_f32_16x16x32_bf16 v[58:61], v[160:163], v[188:191], v[58:61]
	v_mfma_f32_16x16x32_bf16 v[50:53], v[134:137], v[196:199], v[50:53]
	v_mfma_f32_16x16x32_bf16 v[42:45], v[160:163], v[196:199], v[42:45]
	v_mfma_f32_16x16x32_bf16 v[34:37], v[134:137], v[204:207], v[34:37]
	v_mfma_f32_16x16x32_bf16 v[26:29], v[160:163], v[204:207], v[26:29]
	v_mfma_f32_16x16x32_bf16 v[18:21], v[134:137], v[212:215], v[18:21]
	v_mfma_f32_16x16x32_bf16 v[10:13], v[160:163], v[212:215], v[10:13]
	s_setprio 0
	s_setprio 1
	v_mfma_f32_16x16x32_bf16 v[54:57], v[164:167], v[184:187], v[54:57]
	v_mfma_f32_16x16x32_bf16 v[46:49], v[176:179], v[184:187], v[46:49]
	v_mfma_f32_16x16x32_bf16 v[38:41], v[164:167], v[192:195], v[38:41]
	v_mfma_f32_16x16x32_bf16 v[30:33], v[176:179], v[192:195], v[30:33]
	v_mfma_f32_16x16x32_bf16 v[22:25], v[164:167], v[200:203], v[22:25]
	v_mfma_f32_16x16x32_bf16 v[14:17], v[176:179], v[200:203], v[14:17]
	v_mfma_f32_16x16x32_bf16 v[6:9], v[164:167], v[208:211], v[6:9]
	v_mfma_f32_16x16x32_bf16 v[2:5], v[176:179], v[208:211], v[2:5]
	v_mfma_f32_16x16x32_bf16 v[54:57], v[172:175], v[188:191], v[54:57]
	v_mfma_f32_16x16x32_bf16 v[46:49], v[180:183], v[188:191], v[46:49]
	v_mfma_f32_16x16x32_bf16 v[38:41], v[172:175], v[196:199], v[38:41]
	v_mfma_f32_16x16x32_bf16 v[30:33], v[180:183], v[196:199], v[30:33]
	v_mfma_f32_16x16x32_bf16 v[22:25], v[172:175], v[204:207], v[22:25]
	v_mfma_f32_16x16x32_bf16 v[14:17], v[180:183], v[204:207], v[14:17]
	v_mfma_f32_16x16x32_bf16 v[6:9], v[172:175], v[212:215], v[6:9]
	v_mfma_f32_16x16x32_bf16 v[2:5], v[180:183], v[212:215], v[2:5]
	s_setprio 0
	s_barrier
	s_add_i32 s55, 0, 0x18000
	s_add_i32 s56, 0, 0x1c000
	v_add_u32_e32 v160, s55, v143
	v_add_u32_e32 v180, s56, v143
	ds_read_b128 v[130:133], v160
	ds_read_b128 v[134:137], v160 offset:1024
	ds_read_b128 v[138:141], v160 offset:2048
	ds_read_b128 v[160:163], v160 offset:3072
	ds_read_b128 v[164:167], v180
	ds_read_b128 v[172:175], v180 offset:1024
	ds_read_b128 v[176:179], v180 offset:2048
	ds_read_b128 v[180:183], v180 offset:3072
	s_add_u32 s26, s34, 0x160000
	s_addc_u32 s27, s35, 0
	s_mov_b32 m0, s38
	v_lshl_add_u64 v[226:227], s[26:27], 0, v[144:145]
	ds_read_b128 v[184:187], v171 offset:32768
	ds_read_b128 v[188:191], v171 offset:33792
	ds_read_b128 v[192:195], v171 offset:34816
	ds_read_b128 v[196:199], v171 offset:35840
	ds_read_b128 v[200:203], v171 offset:36864
	ds_read_b128 v[204:207], v171 offset:37888
	ds_read_b128 v[208:211], v171 offset:38912
	ds_read_b128 v[212:215], v171 offset:39936
	global_load_lds_dwordx4 v[226:227], off
	v_lshl_add_u64 v[226:227], s[26:27], 0, v[148:149]
	s_mov_b32 m0, s39
	s_nop 0
	global_load_lds_dwordx4 v[226:227], off
	s_waitcnt vmcnt(8)
	s_waitcnt lgkmcnt(0)
	s_barrier
; #define PG8_STAGE(bufoff, gbase, voff) do { _Pragma("unroll") for (int _i = 0; _i < 2; ++_i) \
;         __builtin_amdgcn_global_load_lds((const unsigned*)((const char*)(gbase) + (voff)[_i]), (PG8_LAS unsigned*)(lds + (bufoff) + ldsw + _i * 8192), 16, 0, 0); } while (0)
; #define PG8_LDA(dst, b, h) do { _Pragma("unroll") for (int m = 0; m < 4; ++m) _Pragma("unroll") for (int k = 0; k < 2; ++k) dst[m][k] = *(const PG8_LAS bf16x8*)(lds + PG8_SA(b, h) + aoff + m * 2048 + k * 1024); } while (0)
; #define PG8_MMA(ai, bj, At, Bt) do { __builtin_amdgcn_s_setprio(1); _Pragma("unroll") for (int m = 0; m < 4; ++m) _Pragma("unroll") for (int n = 0; n < 2; ++n) _Pragma("unroll") for (int k = 0; k < 2; ++k) \
;         acc[ai][bj][m][n] = __builtin_amdgcn_mfma_f32_16x16x32_bf16(Bt[n][k], At[m][k], acc[ai][bj][m][n], 0, 0, 0); __builtin_amdgcn_s_setprio(0); } while (0)
; #define PG8_WAIT_V(n) asm volatile("s_waitcnt vmcnt(" #n ")" ::: "memory")
; #define PG8_WAIT_L(n) asm volatile("s_waitcnt lgkmcnt(" #n ")" ::: "memory")
; #define PG8_BAR __builtin_amdgcn_s_barrier()
; #define PG8_SCHED __builtin_amdgcn_sched_barrier(0)
; template <class Epi, class Sched, bool ALIGN_EPI = false, bool SP2 = false>
; __device__ __forceinline__ void gemm_phase(PG8_LAS unsigned char* lds, const Gemm g, const Sched& S, const Epi& E) {
;     ...
;             PG8_WAIT_V(8); PG8_WAIT_L(0); PG8_BAR; PG8_MMA(0, 0, At, B0); PG8_MMA(0, 1, At, B1); PG8_BAR; PG8_SCHED;
;             PG8_LDA(At, 1, 1); PG8_STAGE(PG8_SB(1, 0), b3, voffB); PG8_STAGE(PG8_SB(1, 1), b3 + hstep, voffB); PG8_STAGE(PG8_SA(1, 0), a3, voffA);
;             PG8_WAIT_V(8); PG8_WAIT_L(0); PG8_BAR; PG8_MMA(1, 0, At, B0); PG8_MMA(1, 1, At, B1); PG8_BAR; PG8_SCHED;
	s_setprio 1
	s_waitcnt lgkmcnt(0)
	v_mfma_f32_16x16x32_bf16 v[126:129], v[130:133], v[184:187], v[126:129]
	v_mfma_f32_16x16x32_bf16 v[122:125], v[138:141], v[184:187], v[122:125]
	v_mfma_f32_16x16x32_bf16 v[118:121], v[130:133], v[192:195], v[118:121]
	v_mfma_f32_16x16x32_bf16 v[114:117], v[138:141], v[192:195], v[114:117]
	v_mfma_f32_16x16x32_bf16 v[98:101], v[130:133], v[200:203], v[98:101]
	v_mfma_f32_16x16x32_bf16 v[90:93], v[138:141], v[200:203], v[90:93]
	v_mfma_f32_16x16x32_bf16 v[86:89], v[130:133], v[208:211], v[86:89]
	v_mfma_f32_16x16x32_bf16 v[78:81], v[138:141], v[208:211], v[78:81]
	v_mfma_f32_16x16x32_bf16 v[126:129], v[134:137], v[188:191], v[126:129]
	v_mfma_f32_16x16x32_bf16 v[122:125], v[160:163], v[188:191], v[122:125]
	v_mfma_f32_16x16x32_bf16 v[118:121], v[134:137], v[196:199], v[118:121]
	v_mfma_f32_16x16x32_bf16 v[114:117], v[160:163], v[196:199], v[114:117]
	v_mfma_f32_16x16x32_bf16 v[98:101], v[134:137], v[204:207], v[98:101]
	v_mfma_f32_16x16x32_bf16 v[90:93], v[160:163], v[204:207], v[90:93]
	v_mfma_f32_16x16x32_bf16 v[86:89], v[134:137], v[212:215], v[86:89]
	v_mfma_f32_16x16x32_bf16 v[78:81], v[160:163], v[212:215], v[78:81]
	s_setprio 0
	s_setprio 1
	v_mfma_f32_16x16x32_bf16 v[110:113], v[164:167], v[184:187], v[110:113]
	v_mfma_f32_16x16x32_bf16 v[106:109], v[176:179], v[184:187], v[106:109]
	v_mfma_f32_16x16x32_bf16 v[102:105], v[164:167], v[192:195], v[102:105]
	v_mfma_f32_16x16x32_bf16 v[94:97], v[176:179], v[192:195], v[94:97]
	v_mfma_f32_16x16x32_bf16 v[82:85], v[164:167], v[200:203], v[82:85]
	v_mfma_f32_16x16x32_bf16 v[74:77], v[176:179], v[200:203], v[74:77]
	v_mfma_f32_16x16x32_bf16 v[70:73], v[164:167], v[208:211], v[70:73]
	v_mfma_f32_16x16x32_bf16 v[66:69], v[176:179], v[208:211], v[66:69]
	v_mfma_f32_16x16x32_bf16 v[110:113], v[172:175], v[188:191], v[110:113]
	v_mfma_f32_16x16x32_bf16 v[106:109], v[180:183], v[188:191], v[106:109]
	v_mfma_f32_16x16x32_bf16 v[102:105], v[172:175], v[196:199], v[102:105]
	v_mfma_f32_16x16x32_bf16 v[94:97], v[180:183], v[196:199], v[94:97]
	v_mfma_f32_16x16x32_bf16 v[82:85], v[172:175], v[204:207], v[82:85]
	v_mfma_f32_16x16x32_bf16 v[74:77], v[180:183], v[204:207], v[74:77]
	v_mfma_f32_16x16x32_bf16 v[70:73], v[172:175], v[212:215], v[70:73]
	v_mfma_f32_16x16x32_bf16 v[66:69], v[180:183], v[212:215], v[66:69]
	s_setprio 0
	s_barrier
	s_add_i32 s26, s55, s33
	v_lshl_add_u64 v[216:217], v[216:217], 0, s[6:7]
	s_mov_b32 m0, s26
	ds_read_b128 v[184:187], v171 offset:49152
	ds_read_b128 v[188:191], v171 offset:50176
	ds_read_b128 v[192:195], v171 offset:51200
	ds_read_b128 v[196:199], v171 offset:52224
	ds_read_b128 v[200:203], v171 offset:53248
	ds_read_b128 v[204:207], v171 offset:54272
	ds_read_b128 v[208:211], v171 offset:55296
	ds_read_b128 v[212:215], v171 offset:56320
	global_load_lds_dwordx4 v[216:217], off
	s_add_i32 m0, s26, 0x2000
	s_add_u32 s26, s30, 0x160080
	v_lshl_add_u64 v[216:217], v[220:221], 0, s[6:7]
	s_addc_u32 s27, s31, 0
	s_add_i32 s30, s56, s33
	global_load_lds_dwordx4 v[216:217], off
	v_lshl_add_u64 v[216:217], s[26:27], 0, v[146:147]
	s_mov_b32 m0, s30
	s_nop 0
	global_load_lds_dwordx4 v[216:217], off
	v_lshl_add_u64 v[216:217], s[26:27], 0, v[150:151]
	s_add_i32 m0, s30, 0x2000
	s_nop 0
	global_load_lds_dwordx4 v[216:217], off
	v_lshl_add_u64 v[216:217], v[222:223], 0, s[6:7]
	s_mov_b32 m0, s41
	s_nop 0
	global_load_lds_dwordx4 v[216:217], off
	v_lshl_add_u64 v[216:217], v[224:225], 0, s[6:7]
	s_mov_b32 m0, s42
	s_nop 0
	global_load_lds_dwordx4 v[216:217], off
	s_waitcnt vmcnt(8)
	s_waitcnt lgkmcnt(0)
	s_barrier
	s_setprio 1
	s_waitcnt lgkmcnt(0)
	v_mfma_f32_16x16x32_bf16 v[62:65], v[130:133], v[184:187], v[62:65]
	v_mfma_f32_16x16x32_bf16 v[58:61], v[138:141], v[184:187], v[58:61]
	v_mfma_f32_16x16x32_bf16 v[50:53], v[130:133], v[192:195], v[50:53]
	v_mfma_f32_16x16x32_bf16 v[42:45], v[138:141], v[192:195], v[42:45]
	v_mfma_f32_16x16x32_bf16 v[34:37], v[130:133], v[200:203], v[34:37]
	v_mfma_f32_16x16x32_bf16 v[26:29], v[138:141], v[200:203], v[26:29]
	v_mfma_f32_16x16x32_bf16 v[18:21], v[130:133], v[208:211], v[18:21]
	v_mfma_f32_16x16x32_bf16 v[10:13], v[138:141], v[208:211], v[10:13]
	v_mfma_f32_16x16x32_bf16 v[62:65], v[134:137], v[188:191], v[62:65]
	v_mfma_f32_16x16x32_bf16 v[58:61], v[160:163], v[188:191], v[58:61]
	v_mfma_f32_16x16x32_bf16 v[50:53], v[134:137], v[196:199], v[50:53]
	v_mfma_f32_16x16x32_bf16 v[42:45], v[160:163], v[196:199], v[42:45]
	v_mfma_f32_16x16x32_bf16 v[34:37], v[134:137], v[204:207], v[34:37]
	v_mfma_f32_16x16x32_bf16 v[26:29], v[160:163], v[204:207], v[26:29]
	v_mfma_f32_16x16x32_bf16 v[18:21], v[134:137], v[212:215], v[18:21]
	v_mfma_f32_16x16x32_bf16 v[10:13], v[160:163], v[212:215], v[10:13]
	s_setprio 0
	s_setprio 1
	v_mfma_f32_16x16x32_bf16 v[54:57], v[164:167], v[184:187], v[54:57]
	v_mfma_f32_16x16x32_bf16 v[46:49], v[176:179], v[184:187], v[46:49]
	v_mfma_f32_16x16x32_bf16 v[38:41], v[164:167], v[192:195], v[38:41]
	v_mfma_f32_16x16x32_bf16 v[30:33], v[176:179], v[192:195], v[30:33]
	v_mfma_f32_16x16x32_bf16 v[22:25], v[164:167], v[200:203], v[22:25]
	v_mfma_f32_16x16x32_bf16 v[14:17], v[176:179], v[200:203], v[14:17]
	v_mfma_f32_16x16x32_bf16 v[6:9], v[164:167], v[208:211], v[6:9]
	v_mfma_f32_16x16x32_bf16 v[2:5], v[176:179], v[208:211], v[2:5]
	v_mfma_f32_16x16x32_bf16 v[54:57], v[172:175], v[188:191], v[54:57]
	v_mfma_f32_16x16x32_bf16 v[46:49], v[180:183], v[188:191], v[46:49]
	v_mfma_f32_16x16x32_bf16 v[38:41], v[172:175], v[196:199], v[38:41]
	v_mfma_f32_16x16x32_bf16 v[30:33], v[180:183], v[196:199], v[30:33]
	v_mfma_f32_16x16x32_bf16 v[22:25], v[172:175], v[204:207], v[22:25]
	v_mfma_f32_16x16x32_bf16 v[14:17], v[180:183], v[204:207], v[14:17]
	v_mfma_f32_16x16x32_bf16 v[6:9], v[172:175], v[212:215], v[6:9]
	v_mfma_f32_16x16x32_bf16 v[2:5], v[180:183], v[212:215], v[2:5]
	s_setprio 0
	s_barrier
	s_add_i32 s54, s54, 2
	s_add_u32 s52, s52, 0x100
	s_addc_u32 s53, s53, 0
	s_cmpk_gt_u32 s54, 0x55
	s_mov_b64 s[26:27], s[28:29]
	s_cbranch_scc0 .LBB0_2130
	s_branch .Lpeel_after_9
; #define PG8_STAGE(bufoff, gbase, voff) do { _Pragma("unroll") for (int _i = 0; _i < 2; ++_i) \
;         __builtin_amdgcn_global_load_lds((const unsigned*)((const char*)(gbase) + (voff)[_i]), (PG8_LAS unsigned*)(lds + (bufoff) + ldsw + _i * 8192), 16, 0, 0); } while (0)
; #define PG8_LDA(dst, b, h) do { _Pragma("unroll") for (int m = 0; m < 4; ++m) _Pragma("unroll") for (int k = 0; k < 2; ++k) dst[m][k] = *(const PG8_LAS bf16x8*)(lds + PG8_SA(b, h) + aoff + m * 2048 + k * 1024); } while (0)
; #define PG8_LDB(dst, b, h) do { _Pragma("unroll") for (int n = 0; n < 2; ++n) _Pragma("unroll") for (int k = 0; k < 2; ++k) dst[n][k] = *(const PG8_LAS bf16x8*)(lds + PG8_SB(b, h) + boff + n * 2048 + k * 1024); } while (0)
; #define PG8_MMA(ai, bj, At, Bt) do { __builtin_amdgcn_s_setprio(1); _Pragma("unroll") for (int m = 0; m < 4; ++m) _Pragma("unroll") for (int n = 0; n < 2; ++n) _Pragma("unroll") for (int k = 0; k < 2; ++k) \
;         acc[ai][bj][m][n] = __builtin_amdgcn_mfma_f32_16x16x32_bf16(Bt[n][k], At[m][k], acc[ai][bj][m][n], 0, 0, 0); __builtin_amdgcn_s_setprio(0); } while (0)
; #define PG8_WAIT_V(n) asm volatile("s_waitcnt vmcnt(" #n ")" ::: "memory")
; #define PG8_WAIT_L(n) asm volatile("s_waitcnt lgkmcnt(" #n ")" ::: "memory")
; #define PG8_BAR __builtin_amdgcn_s_barrier()
; #define PG8_SCHED __builtin_amdgcn_sched_barrier(0)
; template <class Epi, class Sched, bool ALIGN_EPI = false, bool SP2 = false>
; __device__ __forceinline__ void gemm_phase(PG8_LAS unsigned char* lds, const Gemm g, const Sched& S, const Epi& E) {
;     ...
;             PG8_LDB(B0, 0, 0); PG8_LDB(B1, 0, 1); PG8_SCHED; PG8_LDA(At, 0, 0); PG8_STAGE(PG8_SA(1, 1), a1 + hstep, voffA);
;             PG8_WAIT_V(8); PG8_WAIT_L(0); PG8_BAR; PG8_MMA(0, 0, At, B0); PG8_MMA(0, 1, At, B1); PG8_BAR; PG8_SCHED;
;             PG8_LDA(At, 0, 1); PG8_STAGE(PG8_SB(0, 0), b2, voffB); PG8_STAGE(PG8_SB(0, 1), b2 + hstep, voffB); PG8_STAGE(PG8_SA(0, 0), a2, voffA);
.Lpeel_9:
	ds_read_b128 v[130:133], v169
	ds_read_b128 v[134:137], v169 offset:1024
	ds_read_b128 v[138:141], v169 offset:2048
	ds_read_b128 v[160:163], v169 offset:3072
	ds_read_b128 v[164:167], v170
	ds_read_b128 v[172:175], v170 offset:1024
	ds_read_b128 v[176:179], v170 offset:2048
	ds_read_b128 v[180:183], v170 offset:3072
	s_add_u32 s28, s26, 0x100
	s_addc_u32 s29, s27, 0
	s_cmpk_eq_i32 s54, 0x54
	s_cselect_b32 s35, s3, s29
	s_cselect_b32 s34, s2, s28
	s_cselect_b32 s31, s25, s53
	s_cselect_b32 s30, s24, s52
	v_lshl_add_u64 v[216:217], s[26:27], 0, v[152:153]
	s_add_i32 m0, s36, 0xc000
	ds_read_b128 v[184:187], v171
	ds_read_b128 v[188:191], v171 offset:1024
	ds_read_b128 v[192:195], v171 offset:2048
	ds_read_b128 v[196:199], v171 offset:3072
	ds_read_b128 v[200:203], v171 offset:4096
	ds_read_b128 v[204:207], v171 offset:5120
	ds_read_b128 v[208:211], v171 offset:6144
	ds_read_b128 v[212:215], v171 offset:7168
	global_load_lds_dwordx4 v[216:217], off
	v_lshl_add_u64 v[216:217], s[26:27], 0, v[154:155]
	s_add_i32 m0, s36, 0xe000
	s_nop 0
	global_load_lds_dwordx4 v[216:217], off
	s_waitcnt vmcnt(40)
	s_waitcnt lgkmcnt(0)
	s_barrier
	s_setprio 1
	s_waitcnt lgkmcnt(0)
	v_mfma_f32_16x16x32_bf16 v[126:129], v[130:133], v[184:187], 0
	v_mfma_f32_16x16x32_bf16 v[122:125], v[138:141], v[184:187], 0
	v_mfma_f32_16x16x32_bf16 v[118:121], v[130:133], v[192:195], 0
	v_mfma_f32_16x16x32_bf16 v[114:117], v[138:141], v[192:195], 0
	v_mfma_f32_16x16x32_bf16 v[98:101], v[130:133], v[200:203], 0
	v_mfma_f32_16x16x32_bf16 v[90:93], v[138:141], v[200:203], 0
	v_mfma_f32_16x16x32_bf16 v[86:89], v[130:133], v[208:211], 0
	v_mfma_f32_16x16x32_bf16 v[78:81], v[138:141], v[208:211], 0
	v_mfma_f32_16x16x32_bf16 v[126:129], v[134:137], v[188:191], v[126:129]
	v_mfma_f32_16x16x32_bf16 v[122:125], v[160:163], v[188:191], v[122:125]
	v_mfma_f32_16x16x32_bf16 v[118:121], v[134:137], v[196:199], v[118:121]
	v_mfma_f32_16x16x32_bf16 v[114:117], v[160:163], v[196:199], v[114:117]
	v_mfma_f32_16x16x32_bf16 v[98:101], v[134:137], v[204:207], v[98:101]
	v_mfma_f32_16x16x32_bf16 v[90:93], v[160:163], v[204:207], v[90:93]
	v_mfma_f32_16x16x32_bf16 v[86:89], v[134:137], v[212:215], v[86:89]
	v_mfma_f32_16x16x32_bf16 v[78:81], v[160:163], v[212:215], v[78:81]
	s_setprio 0
	s_setprio 1
	v_mfma_f32_16x16x32_bf16 v[110:113], v[164:167], v[184:187], 0
	v_mfma_f32_16x16x32_bf16 v[106:109], v[176:179], v[184:187], 0
	v_mfma_f32_16x16x32_bf16 v[102:105], v[164:167], v[192:195], 0
	v_mfma_f32_16x16x32_bf16 v[94:97], v[176:179], v[192:195], 0
	v_mfma_f32_16x16x32_bf16 v[82:85], v[164:167], v[200:203], 0
	v_mfma_f32_16x16x32_bf16 v[74:77], v[176:179], v[200:203], 0
	v_mfma_f32_16x16x32_bf16 v[70:73], v[164:167], v[208:211], 0
	v_mfma_f32_16x16x32_bf16 v[66:69], v[176:179], v[208:211], 0
	v_mfma_f32_16x16x32_bf16 v[110:113], v[172:175], v[188:191], v[110:113]
	v_mfma_f32_16x16x32_bf16 v[106:109], v[180:183], v[188:191], v[106:109]
	v_mfma_f32_16x16x32_bf16 v[102:105], v[172:175], v[196:199], v[102:105]
	v_mfma_f32_16x16x32_bf16 v[94:97], v[180:183], v[196:199], v[94:97]
	v_mfma_f32_16x16x32_bf16 v[82:85], v[172:175], v[204:207], v[82:85]
	v_mfma_f32_16x16x32_bf16 v[74:77], v[180:183], v[204:207], v[74:77]
	v_mfma_f32_16x16x32_bf16 v[70:73], v[172:175], v[212:215], v[70:73]
	v_mfma_f32_16x16x32_bf16 v[66:69], v[180:183], v[212:215], v[66:69]
	s_setprio 0
	s_barrier
	s_add_i32 s26, s46, s33
	v_lshl_add_u64 v[216:217], s[30:31], 0, v[146:147]
	s_mov_b32 m0, s26
	ds_read_b128 v[184:187], v171 offset:16384
	ds_read_b128 v[188:191], v171 offset:17408
	ds_read_b128 v[192:195], v171 offset:18432
	ds_read_b128 v[196:199], v171 offset:19456
	ds_read_b128 v[200:203], v171 offset:20480
	ds_read_b128 v[204:207], v171 offset:21504
	ds_read_b128 v[208:211], v171 offset:22528
	ds_read_b128 v[212:215], v171 offset:23552
	global_load_lds_dwordx4 v[216:217], off
	s_add_i32 m0, s26, 0x2000
	s_add_u32 s26, s30, 0x160000
	v_lshl_add_u64 v[220:221], s[30:31], 0, v[150:151]
	s_addc_u32 s27, s31, 0
	s_add_i32 s55, s47, s33
	global_load_lds_dwordx4 v[220:221], off
	v_lshl_add_u64 v[222:223], s[26:27], 0, v[146:147]
	s_mov_b32 m0, s55
	v_lshl_add_u64 v[224:225], s[34:35], 0, v[148:149]
	global_load_lds_dwordx4 v[222:223], off
	v_lshl_add_u64 v[222:223], s[26:27], 0, v[150:151]
	s_add_i32 m0, s55, 0x2000
	s_nop 0
	global_load_lds_dwordx4 v[222:223], off
	v_lshl_add_u64 v[222:223], s[34:35], 0, v[144:145]
	s_mov_b32 m0, s36
	s_nop 0
	global_load_lds_dwordx4 v[222:223], off
	s_mov_b32 m0, s37
	s_nop 0
	global_load_lds_dwordx4 v[224:225], off
	s_waitcnt vmcnt(40)
	s_waitcnt lgkmcnt(0)
	s_barrier
; #define PG8_STAGE(bufoff, gbase, voff) do { _Pragma("unroll") for (int _i = 0; _i < 2; ++_i) \
;         __builtin_amdgcn_global_load_lds((const unsigned*)((const char*)(gbase) + (voff)[_i]), (PG8_LAS unsigned*)(lds + (bufoff) + ldsw + _i * 8192), 16, 0, 0); } while (0)
; #define PG8_LDA(dst, b, h) do { _Pragma("unroll") for (int m = 0; m < 4; ++m) _Pragma("unroll") for (int k = 0; k < 2; ++k) dst[m][k] = *(const PG8_LAS bf16x8*)(lds + PG8_SA(b, h) + aoff + m * 2048 + k * 1024); } while (0)
; #define PG8_LDB(dst, b, h) do { _Pragma("unroll") for (int n = 0; n < 2; ++n) _Pragma("unroll") for (int k = 0; k < 2; ++k) dst[n][k] = *(const PG8_LAS bf16x8*)(lds + PG8_SB(b, h) + boff + n * 2048 + k * 1024); } while (0)
; #define PG8_MMA(ai, bj, At, Bt) do { __builtin_amdgcn_s_setprio(1); _Pragma("unroll") for (int m = 0; m < 4; ++m) _Pragma("unroll") for (int n = 0; n < 2; ++n) _Pragma("unroll") for (int k = 0; k < 2; ++k) \
;         acc[ai][bj][m][n] = __builtin_amdgcn_mfma_f32_16x16x32_bf16(Bt[n][k], At[m][k], acc[ai][bj][m][n], 0, 0, 0); __builtin_amdgcn_s_setprio(0); } while (0)
; #define PG8_WAIT_V(n) asm volatile("s_waitcnt vmcnt(" #n ")" ::: "memory")
; #define PG8_WAIT_L(n) asm volatile("s_waitcnt lgkmcnt(" #n ")" ::: "memory")
; #define PG8_BAR __builtin_amdgcn_s_barrier()
; #define PG8_SCHED __builtin_amdgcn_sched_barrier(0)
; template <class Epi, class Sched, bool ALIGN_EPI = false, bool SP2 = false>
; __device__ __forceinline__ void gemm_phase(PG8_LAS unsigned char* lds, const Gemm g, const Sched& S, const Epi& E) {
;     ...
;             PG8_WAIT_V(8); PG8_WAIT_L(0); PG8_BAR; PG8_MMA(1, 0, At, B0); PG8_MMA(1, 1, At, B1); PG8_BAR; PG8_SCHED;
;             PG8_LDB(B0, 1, 0); PG8_LDB(B1, 1, 1); PG8_SCHED; PG8_LDA(At, 1, 0); PG8_STAGE(PG8_SA(0, 1), a2 + hstep, voffA);
;             PG8_WAIT_V(8); PG8_WAIT_L(0); PG8_BAR; PG8_MMA(0, 0, At, B0); PG8_MMA(0, 1, At, B1); PG8_BAR; PG8_SCHED;
	s_setprio 1
	s_waitcnt lgkmcnt(0)
	v_mfma_f32_16x16x32_bf16 v[62:65], v[130:133], v[184:187], 0
	v_mfma_f32_16x16x32_bf16 v[58:61], v[138:141], v[184:187], 0
	v_mfma_f32_16x16x32_bf16 v[50:53], v[130:133], v[192:195], 0
	v_mfma_f32_16x16x32_bf16 v[42:45], v[138:141], v[192:195], 0
	v_mfma_f32_16x16x32_bf16 v[34:37], v[130:133], v[200:203], 0
	v_mfma_f32_16x16x32_bf16 v[26:29], v[138:141], v[200:203], 0
	v_mfma_f32_16x16x32_bf16 v[18:21], v[130:133], v[208:211], 0
	v_mfma_f32_16x16x32_bf16 v[10:13], v[138:141], v[208:211], 0
	v_mfma_f32_16x16x32_bf16 v[62:65], v[134:137], v[188:191], v[62:65]
	v_mfma_f32_16x16x32_bf16 v[58:61], v[160:163], v[188:191], v[58:61]
	v_mfma_f32_16x16x32_bf16 v[50:53], v[134:137], v[196:199], v[50:53]
	v_mfma_f32_16x16x32_bf16 v[42:45], v[160:163], v[196:199], v[42:45]
	v_mfma_f32_16x16x32_bf16 v[34:37], v[134:137], v[204:207], v[34:37]
	v_mfma_f32_16x16x32_bf16 v[26:29], v[160:163], v[204:207], v[26:29]
	v_mfma_f32_16x16x32_bf16 v[18:21], v[134:137], v[212:215], v[18:21]
	v_mfma_f32_16x16x32_bf16 v[10:13], v[160:163], v[212:215], v[10:13]
	s_setprio 0
	s_setprio 1
	v_mfma_f32_16x16x32_bf16 v[54:57], v[164:167], v[184:187], 0
	v_mfma_f32_16x16x32_bf16 v[46:49], v[176:179], v[184:187], 0
	v_mfma_f32_16x16x32_bf16 v[38:41], v[164:167], v[192:195], 0
	v_mfma_f32_16x16x32_bf16 v[30:33], v[176:179], v[192:195], 0
	v_mfma_f32_16x16x32_bf16 v[22:25], v[164:167], v[200:203], 0
	v_mfma_f32_16x16x32_bf16 v[14:17], v[176:179], v[200:203], 0
	v_mfma_f32_16x16x32_bf16 v[6:9], v[164:167], v[208:211], 0
	v_mfma_f32_16x16x32_bf16 v[2:5], v[176:179], v[208:211], 0
	v_mfma_f32_16x16x32_bf16 v[54:57], v[172:175], v[188:191], v[54:57]
	v_mfma_f32_16x16x32_bf16 v[46:49], v[180:183], v[188:191], v[46:49]
	v_mfma_f32_16x16x32_bf16 v[38:41], v[172:175], v[196:199], v[38:41]
	v_mfma_f32_16x16x32_bf16 v[30:33], v[180:183], v[196:199], v[30:33]
	v_mfma_f32_16x16x32_bf16 v[22:25], v[172:175], v[204:207], v[22:25]
	v_mfma_f32_16x16x32_bf16 v[14:17], v[180:183], v[204:207], v[14:17]
	v_mfma_f32_16x16x32_bf16 v[6:9], v[172:175], v[212:215], v[6:9]
	v_mfma_f32_16x16x32_bf16 v[2:5], v[180:183], v[212:215], v[2:5]
	s_setprio 0
	s_barrier
	s_add_i32 s55, 0, 0x18000
	s_add_i32 s56, 0, 0x1c000
	v_add_u32_e32 v160, s55, v143
	v_add_u32_e32 v180, s56, v143
	ds_read_b128 v[130:133], v160
	ds_read_b128 v[134:137], v160 offset:1024
	ds_read_b128 v[138:141], v160 offset:2048
	ds_read_b128 v[160:163], v160 offset:3072
	ds_read_b128 v[164:167], v180
	ds_read_b128 v[172:175], v180 offset:1024
	ds_read_b128 v[176:179], v180 offset:2048
	ds_read_b128 v[180:183], v180 offset:3072
	s_add_u32 s26, s34, 0x160000
	s_addc_u32 s27, s35, 0
	s_mov_b32 m0, s38
	v_lshl_add_u64 v[226:227], s[26:27], 0, v[144:145]
	ds_read_b128 v[184:187], v171 offset:32768
	ds_read_b128 v[188:191], v171 offset:33792
	ds_read_b128 v[192:195], v171 offset:34816
	ds_read_b128 v[196:199], v171 offset:35840
	ds_read_b128 v[200:203], v171 offset:36864
	ds_read_b128 v[204:207], v171 offset:37888
	ds_read_b128 v[208:211], v171 offset:38912
	ds_read_b128 v[212:215], v171 offset:39936
	global_load_lds_dwordx4 v[226:227], off
	v_lshl_add_u64 v[226:227], s[26:27], 0, v[148:149]
	s_mov_b32 m0, s39
	s_nop 0
	global_load_lds_dwordx4 v[226:227], off
	s_waitcnt vmcnt(8)
	s_waitcnt lgkmcnt(0)
	s_barrier
	s_setprio 1
	s_waitcnt lgkmcnt(0)
	v_mfma_f32_16x16x32_bf16 v[126:129], v[130:133], v[184:187], v[126:129]
	v_mfma_f32_16x16x32_bf16 v[122:125], v[138:141], v[184:187], v[122:125]
	v_mfma_f32_16x16x32_bf16 v[118:121], v[130:133], v[192:195], v[118:121]
	v_mfma_f32_16x16x32_bf16 v[114:117], v[138:141], v[192:195], v[114:117]
	v_mfma_f32_16x16x32_bf16 v[98:101], v[130:133], v[200:203], v[98:101]
	v_mfma_f32_16x16x32_bf16 v[90:93], v[138:141], v[200:203], v[90:93]
	v_mfma_f32_16x16x32_bf16 v[86:89], v[130:133], v[208:211], v[86:89]
	v_mfma_f32_16x16x32_bf16 v[78:81], v[138:141], v[208:211], v[78:81]
	v_mfma_f32_16x16x32_bf16 v[126:129], v[134:137], v[188:191], v[126:129]
	v_mfma_f32_16x16x32_bf16 v[122:125], v[160:163], v[188:191], v[122:125]
	v_mfma_f32_16x16x32_bf16 v[118:121], v[134:137], v[196:199], v[118:121]
	v_mfma_f32_16x16x32_bf16 v[114:117], v[160:163], v[196:199], v[114:117]
	v_mfma_f32_16x16x32_bf16 v[98:101], v[134:137], v[204:207], v[98:101]
	v_mfma_f32_16x16x32_bf16 v[90:93], v[160:163], v[204:207], v[90:93]
	v_mfma_f32_16x16x32_bf16 v[86:89], v[134:137], v[212:215], v[86:89]
	v_mfma_f32_16x16x32_bf16 v[78:81], v[160:163], v[212:215], v[78:81]
	s_setprio 0
	s_setprio 1
	v_mfma_f32_16x16x32_bf16 v[110:113], v[164:167], v[184:187], v[110:113]
	v_mfma_f32_16x16x32_bf16 v[106:109], v[176:179], v[184:187], v[106:109]
	v_mfma_f32_16x16x32_bf16 v[102:105], v[164:167], v[192:195], v[102:105]
	v_mfma_f32_16x16x32_bf16 v[94:97], v[176:179], v[192:195], v[94:97]
	v_mfma_f32_16x16x32_bf16 v[82:85], v[164:167], v[200:203], v[82:85]
	v_mfma_f32_16x16x32_bf16 v[74:77], v[176:179], v[200:203], v[74:77]
	v_mfma_f32_16x16x32_bf16 v[70:73], v[164:167], v[208:211], v[70:73]
	v_mfma_f32_16x16x32_bf16 v[66:69], v[176:179], v[208:211], v[66:69]
	v_mfma_f32_16x16x32_bf16 v[110:113], v[172:175], v[188:191], v[110:113]
	v_mfma_f32_16x16x32_bf16 v[106:109], v[180:183], v[188:191], v[106:109]
	v_mfma_f32_16x16x32_bf16 v[102:105], v[172:175], v[196:199], v[102:105]
	v_mfma_f32_16x16x32_bf16 v[94:97], v[180:183], v[196:199], v[94:97]
	v_mfma_f32_16x16x32_bf16 v[82:85], v[172:175], v[204:207], v[82:85]
	v_mfma_f32_16x16x32_bf16 v[74:77], v[180:183], v[204:207], v[74:77]
	v_mfma_f32_16x16x32_bf16 v[70:73], v[172:175], v[212:215], v[70:73]
	v_mfma_f32_16x16x32_bf16 v[66:69], v[180:183], v[212:215], v[66:69]
	s_setprio 0
	s_barrier
; #define PG8_STAGE(bufoff, gbase, voff) do { _Pragma("unroll") for (int _i = 0; _i < 2; ++_i) \
;         __builtin_amdgcn_global_load_lds((const unsigned*)((const char*)(gbase) + (voff)[_i]), (PG8_LAS unsigned*)(lds + (bufoff) + ldsw + _i * 8192), 16, 0, 0); } while (0)
; #define PG8_LDA(dst, b, h) do { _Pragma("unroll") for (int m = 0; m < 4; ++m) _Pragma("unroll") for (int k = 0; k < 2; ++k) dst[m][k] = *(const PG8_LAS bf16x8*)(lds + PG8_SA(b, h) + aoff + m * 2048 + k * 1024); } while (0)
; #define PG8_MMA(ai, bj, At, Bt) do { __builtin_amdgcn_s_setprio(1); _Pragma("unroll") for (int m = 0; m < 4; ++m) _Pragma("unroll") for (int n = 0; n < 2; ++n) _Pragma("unroll") for (int k = 0; k < 2; ++k) \
;         acc[ai][bj][m][n] = __builtin_amdgcn_mfma_f32_16x16x32_bf16(Bt[n][k], At[m][k], acc[ai][bj][m][n], 0, 0, 0); __builtin_amdgcn_s_setprio(0); } while (0)
; #define PG8_WAIT_V(n) asm volatile("s_waitcnt vmcnt(" #n ")" ::: "memory")
; #define PG8_WAIT_L(n) asm volatile("s_waitcnt lgkmcnt(" #n ")" ::: "memory")
; #define PG8_BAR __builtin_amdgcn_s_barrier()
; #define PG8_SCHED __builtin_amdgcn_sched_barrier(0)
; template <class Epi, class Sched, bool ALIGN_EPI = false, bool SP2 = false>
; __device__ __forceinline__ void gemm_phase(PG8_LAS unsigned char* lds, const Gemm g, const Sched& S, const Epi& E) {
;     ...
;             PG8_LDA(At, 1, 1); PG8_STAGE(PG8_SB(1, 0), b3, voffB); PG8_STAGE(PG8_SB(1, 1), b3 + hstep, voffB); PG8_STAGE(PG8_SA(1, 0), a3, voffA);
;             PG8_WAIT_V(8); PG8_WAIT_L(0); PG8_BAR; PG8_MMA(1, 0, At, B0); PG8_MMA(1, 1, At, B1); PG8_BAR; PG8_SCHED;
	s_add_i32 s26, s55, s33
	v_lshl_add_u64 v[216:217], v[216:217], 0, s[6:7]
	s_mov_b32 m0, s26
	ds_read_b128 v[184:187], v171 offset:49152
	ds_read_b128 v[188:191], v171 offset:50176
	ds_read_b128 v[192:195], v171 offset:51200
	ds_read_b128 v[196:199], v171 offset:52224
	ds_read_b128 v[200:203], v171 offset:53248
	ds_read_b128 v[204:207], v171 offset:54272
	ds_read_b128 v[208:211], v171 offset:55296
	ds_read_b128 v[212:215], v171 offset:56320
	global_load_lds_dwordx4 v[216:217], off
	s_add_i32 m0, s26, 0x2000
	s_add_u32 s26, s30, 0x160080
	v_lshl_add_u64 v[216:217], v[220:221], 0, s[6:7]
	s_addc_u32 s27, s31, 0
	s_add_i32 s30, s56, s33
	global_load_lds_dwordx4 v[216:217], off
	v_lshl_add_u64 v[216:217], s[26:27], 0, v[146:147]
	s_mov_b32 m0, s30
	s_nop 0
	global_load_lds_dwordx4 v[216:217], off
	v_lshl_add_u64 v[216:217], s[26:27], 0, v[150:151]
	s_add_i32 m0, s30, 0x2000
	s_nop 0
	global_load_lds_dwordx4 v[216:217], off
	v_lshl_add_u64 v[216:217], v[222:223], 0, s[6:7]
	s_mov_b32 m0, s41
	s_nop 0
	global_load_lds_dwordx4 v[216:217], off
	v_lshl_add_u64 v[216:217], v[224:225], 0, s[6:7]
	s_mov_b32 m0, s42
	s_nop 0
	global_load_lds_dwordx4 v[216:217], off
	s_waitcnt vmcnt(8)
	s_waitcnt lgkmcnt(0)
	s_barrier
	s_setprio 1
	s_waitcnt lgkmcnt(0)
	v_mfma_f32_16x16x32_bf16 v[62:65], v[130:133], v[184:187], v[62:65]
	v_mfma_f32_16x16x32_bf16 v[58:61], v[138:141], v[184:187], v[58:61]
	v_mfma_f32_16x16x32_bf16 v[50:53], v[130:133], v[192:195], v[50:53]
	v_mfma_f32_16x16x32_bf16 v[42:45], v[138:141], v[192:195], v[42:45]
	v_mfma_f32_16x16x32_bf16 v[34:37], v[130:133], v[200:203], v[34:37]
	v_mfma_f32_16x16x32_bf16 v[26:29], v[138:141], v[200:203], v[26:29]
	v_mfma_f32_16x16x32_bf16 v[18:21], v[130:133], v[208:211], v[18:21]
	v_mfma_f32_16x16x32_bf16 v[10:13], v[138:141], v[208:211], v[10:13]
	v_mfma_f32_16x16x32_bf16 v[62:65], v[134:137], v[188:191], v[62:65]
	v_mfma_f32_16x16x32_bf16 v[58:61], v[160:163], v[188:191], v[58:61]
	v_mfma_f32_16x16x32_bf16 v[50:53], v[134:137], v[196:199], v[50:53]
	v_mfma_f32_16x16x32_bf16 v[42:45], v[160:163], v[196:199], v[42:45]
	v_mfma_f32_16x16x32_bf16 v[34:37], v[134:137], v[204:207], v[34:37]
	v_mfma_f32_16x16x32_bf16 v[26:29], v[160:163], v[204:207], v[26:29]
	v_mfma_f32_16x16x32_bf16 v[18:21], v[134:137], v[212:215], v[18:21]
	v_mfma_f32_16x16x32_bf16 v[10:13], v[160:163], v[212:215], v[10:13]
	s_setprio 0
	s_setprio 1
	v_mfma_f32_16x16x32_bf16 v[54:57], v[164:167], v[184:187], v[54:57]
	v_mfma_f32_16x16x32_bf16 v[46:49], v[176:179], v[184:187], v[46:49]
	v_mfma_f32_16x16x32_bf16 v[38:41], v[164:167], v[192:195], v[38:41]
	v_mfma_f32_16x16x32_bf16 v[30:33], v[176:179], v[192:195], v[30:33]
	v_mfma_f32_16x16x32_bf16 v[22:25], v[164:167], v[200:203], v[22:25]
	v_mfma_f32_16x16x32_bf16 v[14:17], v[176:179], v[200:203], v[14:17]
	v_mfma_f32_16x16x32_bf16 v[6:9], v[164:167], v[208:211], v[6:9]
	v_mfma_f32_16x16x32_bf16 v[2:5], v[176:179], v[208:211], v[2:5]
	v_mfma_f32_16x16x32_bf16 v[54:57], v[172:175], v[188:191], v[54:57]
	v_mfma_f32_16x16x32_bf16 v[46:49], v[180:183], v[188:191], v[46:49]
	v_mfma_f32_16x16x32_bf16 v[38:41], v[172:175], v[196:199], v[38:41]
	v_mfma_f32_16x16x32_bf16 v[30:33], v[180:183], v[196:199], v[30:33]
	v_mfma_f32_16x16x32_bf16 v[22:25], v[172:175], v[204:207], v[22:25]
	v_mfma_f32_16x16x32_bf16 v[14:17], v[180:183], v[204:207], v[14:17]
	v_mfma_f32_16x16x32_bf16 v[6:9], v[172:175], v[212:215], v[6:9]
	v_mfma_f32_16x16x32_bf16 v[2:5], v[180:183], v[212:215], v[2:5]
	s_setprio 0
	s_barrier
	s_add_i32 s54, s54, 2
	s_add_u32 s52, s52, 0x100
	s_addc_u32 s53, s53, 0
	s_cmpk_gt_u32 s54, 0x55
	s_mov_b64 s[26:27], s[28:29]
	s_branch .LBB0_2130

; DI unsigned pk2(float lo, float hi) { f32x2 v = {lo, hi}; bf16x2_t b = __builtin_convertvector(v, bf16x2_t); return __builtin_bit_cast(unsigned, b); }
; DI f32x4 bf4_lo(u32x4 q) { return (f32x4){__builtin_bit_cast(float, q.x << 16), __builtin_bit_cast(float, q.x & 0xffff0000u), __builtin_bit_cast(float, q.y << 16), __builtin_bit_cast(float, q.y & 0xffff0000u)}; }
; DI f32x4 bf4_hi(u32x4 q) { return (f32x4){__builtin_bit_cast(float, q.z << 16), __builtin_bit_cast(float, q.z & 0xffff0000u), __builtin_bit_cast(float, q.w << 16), __builtin_bit_cast(float, q.w & 0xffff0000u)}; }
;     DI void operator()(const f32x4 (&acc)[2][2][4][2], const pg8::Unit& u, int wr, int wc, int fr, int fq) const {
;         const int row0 = u.pm * 256 + wr * 64 + fr, col0 = u.pn * 256 + wc * 32 + 8 * fq;
; #pragma unroll
;         for (int ai = 0; ai < 2; ++ai) {
;             u32x4 r[4][2];
; #pragma unroll
;             for (int m = 0; m < 4; ++m)
; #pragma unroll
;                 for (int bj = 0; bj < 2; ++bj) r[m][bj] = *(const u32x4*)(res + (size_t)(row0 + ai * 128 + m * 16) * DM + col0 + bj * 128);
;             asm volatile("" ::: "memory");
; #pragma unroll
;             for (int m = 0; m < 4; ++m)
; #pragma unroll
;                 for (int bj = 0; bj < 2; ++bj) { const f32x4 a = bf4_lo(r[m][bj]) * ALPHA + acc[ai][bj][m][0] * sc, b = bf4_hi(r[m][bj]) * ALPHA + acc[ai][bj][m][1] * sc;
;                     *(u32x4*)(out + (size_t)(row0 + ai * 128 + m * 16) * DM + col0 + bj * 128) = (u32x4){pk2(a[0], a[1]), pk2(a[2], a[3]), pk2(b[0], b[1]), pk2(b[2], b[3])}; }
;         }
.LBB0_2133:
	v_lshl_or_b32 v132, s51, 8, v168
	v_lshl_add_u32 v130, s50, 8, v1
	v_ashrrev_i32_e32 v133, 31, v132
	v_readlane_b32 s26, v253, 41
	v_lshlrev_b64 v[160:161], 1, v[132:133]
	v_readlane_b32 s27, v253, 42
	v_ashrrev_i32_e32 v131, 31, v130
	v_lshlrev_b64 v[164:165], 12, v[130:131]
	v_lshl_add_u64 v[162:163], s[26:27], 0, v[160:161]
	v_lshl_add_u64 v[132:133], v[162:163], 0, v[164:165]
	global_load_dwordx4 v[172:175], v[132:133], off
	global_load_dwordx4 v[176:179], v[132:133], off offset:256
	v_or_b32_e32 v132, 16, v130
	v_ashrrev_i32_e32 v133, 31, v132
	v_lshlrev_b64 v[192:193], 12, v[132:133]
	v_lshl_add_u64 v[132:133], v[162:163], 0, v[192:193]
	global_load_dwordx4 v[180:183], v[132:133], off
	global_load_dwordx4 v[184:187], v[132:133], off offset:256
	v_or_b32_e32 v134, 32, v130
	v_or_b32_e32 v130, 48, v130
	v_ashrrev_i32_e32 v135, 31, v134
	v_readlane_b32 s26, v253, 55
	v_ashrrev_i32_e32 v131, 31, v130
	v_lshlrev_b64 v[194:195], 12, v[134:135]
	v_readlane_b32 s27, v253, 56
	v_lshlrev_b64 v[166:167], 12, v[130:131]
	v_lshl_add_u64 v[132:133], v[162:163], 0, v[194:195]
	v_lshl_add_u64 v[130:131], s[26:27], 0, v[164:165]
	v_lshl_add_u64 v[196:197], v[162:163], 0, v[166:167]
	v_lshl_add_u64 v[198:199], v[130:131], 0, v[160:161]
	global_load_dwordx4 v[188:191], v[132:133], off
	global_load_dwordx4 v[138:141], v[132:133], off offset:256
	global_load_dwordx4 v[134:137], v[196:197], off
	s_nop 0
	global_load_dwordx4 v[130:133], v[196:197], off offset:256
	s_and_b64 vcc, exec, s[0:1]
	s_mov_b64 s[0:1], -1
	s_waitcnt vmcnt(0)
	v_lshlrev_b32_e32 v196, 16, v172
	v_and_b32_e32 v197, 0xffff0000, v172
	v_lshlrev_b32_e32 v172, 16, v173
	v_and_b32_e32 v173, 0xffff0000, v173
	v_lshlrev_b32_e32 v200, 16, v174
	v_and_b32_e32 v201, 0xffff0000, v174
	v_lshlrev_b32_e32 v174, 16, v175
	v_and_b32_e32 v175, 0xffff0000, v175
	v_lshlrev_b32_e32 v202, 16, v176
	v_and_b32_e32 v203, 0xffff0000, v176
	v_lshlrev_b32_e32 v176, 16, v177
	v_and_b32_e32 v177, 0xffff0000, v177
	v_lshlrev_b32_e32 v204, 16, v178
	v_and_b32_e32 v205, 0xffff0000, v178
	v_lshlrev_b32_e32 v178, 16, v179
	v_and_b32_e32 v179, 0xffff0000, v179
	v_pk_mul_f32 v[196:197], v[196:197], s[10:11] op_sel_hi:[1,0]
	v_pk_mul_f32 v[172:173], v[172:173], s[10:11] op_sel_hi:[1,0]
	v_pk_mul_f32 v[200:201], v[200:201], s[10:11] op_sel_hi:[1,0]
	v_pk_mul_f32 v[174:175], v[174:175], s[10:11] op_sel_hi:[1,0]
	v_pk_mul_f32 v[202:203], v[202:203], s[10:11] op_sel_hi:[1,0]
	v_pk_mul_f32 v[176:177], v[176:177], s[10:11] op_sel_hi:[1,0]
	v_pk_mul_f32 v[204:205], v[204:205], s[10:11] op_sel_hi:[1,0]
	v_pk_mul_f32 v[178:179], v[178:179], s[10:11] op_sel_hi:[1,0]
	v_pk_fma_f32 v[128:129], v[128:129], 0.5, v[172:173] op_sel_hi:[1,0,1]
	v_pk_fma_f32 v[126:127], v[126:127], 0.5, v[196:197] op_sel_hi:[1,0,1]
	v_pk_fma_f32 v[124:125], v[124:125], 0.5, v[174:175] op_sel_hi:[1,0,1]
	v_pk_fma_f32 v[122:123], v[122:123], 0.5, v[200:201] op_sel_hi:[1,0,1]
	v_pk_fma_f32 v[112:113], v[112:113], 0.5, v[176:177] op_sel_hi:[1,0,1]
	v_pk_fma_f32 v[110:111], v[110:111], 0.5, v[202:203] op_sel_hi:[1,0,1]
	v_pk_fma_f32 v[172:173], v[108:109], 0.5, v[178:179] op_sel_hi:[1,0,1]
	v_pk_fma_f32 v[174:175], v[106:107], 0.5, v[204:205] op_sel_hi:[1,0,1]
	v_cvt_pk_bf16_f32 v106, v126, v127
	v_cvt_pk_bf16_f32 v107, v128, v129
	v_cvt_pk_bf16_f32 v108, v122, v123
	v_cvt_pk_bf16_f32 v109, v124, v125
	v_cvt_pk_bf16_f32 v110, v110, v111
	v_cvt_pk_bf16_f32 v111, v112, v113
	v_cvt_pk_bf16_f32 v112, v174, v175
	v_cvt_pk_bf16_f32 v113, v172, v173
	global_store_dwordx4 v[198:199], v[106:109], off
	global_store_dwordx4 v[198:199], v[110:113], off offset:256
	v_lshlrev_b32_e32 v206, 16, v180
	v_lshlrev_b32_e32 v108, 16, v184
	v_and_b32_e32 v109, 0xffff0000, v184
	v_lshlrev_b32_e32 v110, 16, v185
	v_and_b32_e32 v111, 0xffff0000, v185
	v_pk_mul_f32 v[108:109], v[108:109], s[10:11] op_sel_hi:[1,0]
	v_pk_mul_f32 v[110:111], v[110:111], s[10:11] op_sel_hi:[1,0]
	v_pk_fma_f32 v[102:103], v[102:103], 0.5, v[108:109] op_sel_hi:[1,0,1]
	v_pk_fma_f32 v[104:105], v[104:105], 0.5, v[110:111] op_sel_hi:[1,0,1]
	v_lshlrev_b32_e32 v108, 16, v186
	v_and_b32_e32 v109, 0xffff0000, v186
	v_lshlrev_b32_e32 v110, 16, v187
	v_and_b32_e32 v111, 0xffff0000, v187
	v_pk_mul_f32 v[108:109], v[108:109], s[10:11] op_sel_hi:[1,0]
	v_pk_mul_f32 v[110:111], v[110:111], s[10:11] op_sel_hi:[1,0]
	v_lshl_add_u64 v[106:107], s[26:27], 0, v[192:193]
	v_pk_fma_f32 v[110:111], v[96:97], 0.5, v[110:111] op_sel_hi:[1,0,1]
	v_pk_fma_f32 v[96:97], v[94:95], 0.5, v[108:109] op_sel_hi:[1,0,1]
	v_lshl_add_u64 v[106:107], v[106:107], 0, v[160:161]
	v_cvt_pk_bf16_f32 v94, v102, v103
	v_cvt_pk_bf16_f32 v95, v104, v105
	v_cvt_pk_bf16_f32 v96, v96, v97
	v_cvt_pk_bf16_f32 v97, v110, v111
	global_store_dwordx4 v[106:107], v[94:97], off offset:256
	v_lshl_add_u64 v[102:103], v[164:165], 0, s[12:13]
	v_lshl_add_u64 v[104:105], v[164:165], 0, s[18:19]
	v_lshlrev_b32_e32 v94, 16, v188
	v_and_b32_e32 v95, 0xffff0000, v188
	v_lshlrev_b32_e32 v96, 16, v189
	v_and_b32_e32 v97, 0xffff0000, v189
	v_pk_mul_f32 v[94:95], v[94:95], s[10:11] op_sel_hi:[1,0]
	v_pk_mul_f32 v[96:97], v[96:97], s[10:11] op_sel_hi:[1,0]
	v_pk_fma_f32 v[94:95], v[98:99], 0.5, v[94:95] op_sel_hi:[1,0,1]
	v_pk_fma_f32 v[96:97], v[100:101], 0.5, v[96:97] op_sel_hi:[1,0,1]
	v_lshlrev_b32_e32 v98, 16, v190
	v_and_b32_e32 v99, 0xffff0000, v190
	v_lshlrev_b32_e32 v100, 16, v191
	v_and_b32_e32 v101, 0xffff0000, v191
	v_pk_mul_f32 v[98:99], v[98:99], s[10:11] op_sel_hi:[1,0]
	v_pk_mul_f32 v[100:101], v[100:101], s[10:11] op_sel_hi:[1,0]
	v_and_b32_e32 v207, 0xffff0000, v180
	v_pk_fma_f32 v[100:101], v[92:93], 0.5, v[100:101] op_sel_hi:[1,0,1]
; DI unsigned pk2(float lo, float hi) { f32x2 v = {lo, hi}; bf16x2_t b = __builtin_convertvector(v, bf16x2_t); return __builtin_bit_cast(unsigned, b); }
; DI f32x4 bf4_lo(u32x4 q) { return (f32x4){__builtin_bit_cast(float, q.x << 16), __builtin_bit_cast(float, q.x & 0xffff0000u), __builtin_bit_cast(float, q.y << 16), __builtin_bit_cast(float, q.y & 0xffff0000u)}; }
; DI f32x4 bf4_hi(u32x4 q) { return (f32x4){__builtin_bit_cast(float, q.z << 16), __builtin_bit_cast(float, q.z & 0xffff0000u), __builtin_bit_cast(float, q.w << 16), __builtin_bit_cast(float, q.w & 0xffff0000u)}; }
;     DI void operator()(const f32x4 (&acc)[2][2][4][2], const pg8::Unit& u, int wr, int wc, int fr, int fq) const {
;         const int row0 = u.pm * 256 + wr * 64 + fr, col0 = u.pn * 256 + wc * 32 + 8 * fq;
; #pragma unroll
;         for (int ai = 0; ai < 2; ++ai) {
;             u32x4 r[4][2];
; #pragma unroll
;             for (int m = 0; m < 4; ++m)
; #pragma unroll
;                 for (int bj = 0; bj < 2; ++bj) r[m][bj] = *(const u32x4*)(res + (size_t)(row0 + ai * 128 + m * 16) * DM + col0 + bj * 128);
;             asm volatile("" ::: "memory");
; #pragma unroll
;             for (int m = 0; m < 4; ++m)
; #pragma unroll
;                 for (int bj = 0; bj < 2; ++bj) { const f32x4 a = bf4_lo(r[m][bj]) * ALPHA + acc[ai][bj][m][0] * sc, b = bf4_hi(r[m][bj]) * ALPHA + acc[ai][bj][m][1] * sc;
;                     *(u32x4*)(out + (size_t)(row0 + ai * 128 + m * 16) * DM + col0 + bj * 128) = (u32x4){pk2(a[0], a[1]), pk2(a[2], a[3]), pk2(b[0], b[1]), pk2(b[2], b[3])}; }
;         }
;     }
	v_pk_fma_f32 v[92:93], v[90:91], 0.5, v[98:99] op_sel_hi:[1,0,1]
	v_cvt_pk_bf16_f32 v90, v94, v95
	v_lshl_add_u64 v[94:95], s[26:27], 0, v[194:195]
	v_cvt_pk_bf16_f32 v91, v96, v97
	v_cvt_pk_bf16_f32 v92, v92, v93
	v_cvt_pk_bf16_f32 v93, v100, v101
	v_lshl_add_u64 v[94:95], v[94:95], 0, v[160:161]
	v_lshl_add_u64 v[96:97], v[162:163], 0, v[102:103]
	global_store_dwordx4 v[94:95], v[90:93], off
	global_load_dwordx4 v[90:93], v[96:97], off
	v_lshlrev_b32_e32 v98, 16, v138
	v_and_b32_e32 v99, 0xffff0000, v138
	v_lshlrev_b32_e32 v100, 16, v139
	v_and_b32_e32 v101, 0xffff0000, v139
	v_pk_mul_f32 v[98:99], v[98:99], s[10:11] op_sel_hi:[1,0]
	v_pk_mul_f32 v[100:101], v[100:101], s[10:11] op_sel_hi:[1,0]
	v_pk_fma_f32 v[82:83], v[82:83], 0.5, v[98:99] op_sel_hi:[1,0,1]
	v_pk_fma_f32 v[84:85], v[84:85], 0.5, v[100:101] op_sel_hi:[1,0,1]
	v_lshlrev_b32_e32 v98, 16, v140
	v_and_b32_e32 v99, 0xffff0000, v140
	v_lshlrev_b32_e32 v100, 16, v141
	v_and_b32_e32 v101, 0xffff0000, v141
	v_pk_mul_f32 v[98:99], v[98:99], s[10:11] op_sel_hi:[1,0]
	v_pk_mul_f32 v[100:101], v[100:101], s[10:11] op_sel_hi:[1,0]
	v_lshlrev_b32_e32 v180, 16, v181
	v_pk_fma_f32 v[100:101], v[76:77], 0.5, v[100:101] op_sel_hi:[1,0,1]
	v_pk_fma_f32 v[76:77], v[74:75], 0.5, v[98:99] op_sel_hi:[1,0,1]
	v_cvt_pk_bf16_f32 v74, v82, v83
	v_cvt_pk_bf16_f32 v75, v84, v85
	v_cvt_pk_bf16_f32 v76, v76, v77
	v_cvt_pk_bf16_f32 v77, v100, v101
	global_store_dwordx4 v[94:95], v[74:77], off offset:256
	global_load_dwordx4 v[74:77], v[96:97], off offset:256
	v_lshlrev_b32_e32 v82, 16, v134
	v_and_b32_e32 v83, 0xffff0000, v134
	v_lshlrev_b32_e32 v84, 16, v135
	v_and_b32_e32 v85, 0xffff0000, v135
	v_pk_mul_f32 v[82:83], v[82:83], s[10:11] op_sel_hi:[1,0]
	v_pk_mul_f32 v[84:85], v[84:85], s[10:11] op_sel_hi:[1,0]
	v_pk_fma_f32 v[82:83], v[86:87], 0.5, v[82:83] op_sel_hi:[1,0,1]
	v_pk_fma_f32 v[84:85], v[88:89], 0.5, v[84:85] op_sel_hi:[1,0,1]
	v_lshlrev_b32_e32 v86, 16, v136
	v_and_b32_e32 v87, 0xffff0000, v136
	v_lshlrev_b32_e32 v88, 16, v137
	v_and_b32_e32 v89, 0xffff0000, v137
	v_pk_mul_f32 v[86:87], v[86:87], s[10:11] op_sel_hi:[1,0]
	v_pk_mul_f32 v[88:89], v[88:89], s[10:11] op_sel_hi:[1,0]
	v_and_b32_e32 v181, 0xffff0000, v181
	v_pk_fma_f32 v[88:89], v[80:81], 0.5, v[88:89] op_sel_hi:[1,0,1]
	v_pk_fma_f32 v[80:81], v[78:79], 0.5, v[86:87] op_sel_hi:[1,0,1]
	v_lshl_add_u64 v[86:87], v[162:163], 0, v[104:105]
	v_cvt_pk_bf16_f32 v78, v82, v83
	v_cvt_pk_bf16_f32 v79, v84, v85
	v_cvt_pk_bf16_f32 v80, v80, v81
	global_load_dwordx4 v[82:85], v[86:87], off
	v_cvt_pk_bf16_f32 v81, v88, v89
	v_lshl_add_u64 v[88:89], s[26:27], 0, v[166:167]
	v_lshl_add_u64 v[88:89], v[88:89], 0, v[160:161]
	global_store_dwordx4 v[88:89], v[78:81], off
	v_lshlrev_b32_e32 v208, 16, v182
	v_and_b32_e32 v209, 0xffff0000, v182
	v_lshlrev_b32_e32 v78, 16, v130
	v_and_b32_e32 v79, 0xffff0000, v130
	v_lshlrev_b32_e32 v80, 16, v131
	v_and_b32_e32 v81, 0xffff0000, v131
	v_pk_mul_f32 v[78:79], v[78:79], s[10:11] op_sel_hi:[1,0]
	v_pk_mul_f32 v[80:81], v[80:81], s[10:11] op_sel_hi:[1,0]
	v_pk_fma_f32 v[70:71], v[70:71], 0.5, v[78:79] op_sel_hi:[1,0,1]
	v_pk_fma_f32 v[72:73], v[72:73], 0.5, v[80:81] op_sel_hi:[1,0,1]
	v_lshlrev_b32_e32 v78, 16, v132
	v_and_b32_e32 v79, 0xffff0000, v132
	v_lshlrev_b32_e32 v80, 16, v133
	v_and_b32_e32 v81, 0xffff0000, v133
	v_pk_mul_f32 v[78:79], v[78:79], s[10:11] op_sel_hi:[1,0]
	v_pk_mul_f32 v[80:81], v[80:81], s[10:11] op_sel_hi:[1,0]
	v_lshlrev_b32_e32 v182, 16, v183
	v_pk_fma_f32 v[94:95], v[68:69], 0.5, v[80:81] op_sel_hi:[1,0,1]
	v_pk_fma_f32 v[68:69], v[66:67], 0.5, v[78:79] op_sel_hi:[1,0,1]
	global_load_dwordx4 v[78:81], v[86:87], off offset:256
	v_and_b32_e32 v183, 0xffff0000, v183
	v_pk_mul_f32 v[206:207], v[206:207], s[10:11] op_sel_hi:[1,0]
	v_pk_mul_f32 v[180:181], v[180:181], s[10:11] op_sel_hi:[1,0]
	v_pk_mul_f32 v[208:209], v[208:209], s[10:11] op_sel_hi:[1,0]
	v_pk_mul_f32 v[182:183], v[182:183], s[10:11] op_sel_hi:[1,0]
	v_pk_fma_f32 v[120:121], v[120:121], 0.5, v[180:181] op_sel_hi:[1,0,1]
	v_pk_fma_f32 v[118:119], v[118:119], 0.5, v[206:207] op_sel_hi:[1,0,1]
	v_pk_fma_f32 v[176:177], v[116:117], 0.5, v[182:183] op_sel_hi:[1,0,1]
	v_pk_fma_f32 v[116:117], v[114:115], 0.5, v[208:209] op_sel_hi:[1,0,1]
	v_cvt_pk_bf16_f32 v114, v118, v119
	v_cvt_pk_bf16_f32 v115, v120, v121
	v_cvt_pk_bf16_f32 v116, v116, v117
	v_cvt_pk_bf16_f32 v117, v176, v177
	v_cvt_pk_bf16_f32 v66, v70, v71
	v_cvt_pk_bf16_f32 v67, v72, v73
	v_cvt_pk_bf16_f32 v68, v68, v69
	v_cvt_pk_bf16_f32 v69, v94, v95
	v_lshl_add_u64 v[72:73], v[164:165], 0, s[20:21]
	global_store_dwordx4 v[106:107], v[114:117], off
	global_store_dwordx4 v[88:89], v[66:69], off offset:256
	v_lshl_add_u64 v[70:71], v[164:165], 0, s[22:23]
	s_waitcnt vmcnt(7)
	v_lshlrev_b32_e32 v106, 16, v90
	v_lshl_add_u64 v[66:67], v[162:163], 0, v[72:73]
	global_load_dwordx4 v[86:89], v[66:67], off
	global_load_dwordx4 v[94:97], v[66:67], off offset:256
	v_lshl_add_u64 v[66:67], v[162:163], 0, v[70:71]
	global_load_dwordx4 v[98:101], v[66:67], off
	s_nop 0
	global_load_dwordx4 v[66:69], v[66:67], off offset:256
	v_and_b32_e32 v107, 0xffff0000, v90
	v_lshlrev_b32_e32 v90, 16, v91
	v_and_b32_e32 v91, 0xffff0000, v91
	v_pk_mul_f32 v[90:91], v[90:91], s[10:11] op_sel_hi:[1,0]
	v_pk_mul_f32 v[106:107], v[106:107], s[10:11] op_sel_hi:[1,0]
	v_pk_fma_f32 v[64:65], v[64:65], 0.5, v[90:91] op_sel_hi:[1,0,1]
	v_lshlrev_b32_e32 v90, 16, v92
	v_and_b32_e32 v91, 0xffff0000, v92
	v_lshlrev_b32_e32 v92, 16, v93
	v_and_b32_e32 v93, 0xffff0000, v93
	v_pk_fma_f32 v[62:63], v[62:63], 0.5, v[106:107] op_sel_hi:[1,0,1]
	v_pk_mul_f32 v[90:91], v[90:91], s[10:11] op_sel_hi:[1,0]
	v_pk_mul_f32 v[92:93], v[92:93], s[10:11] op_sel_hi:[1,0]
	s_nop 0
	v_pk_fma_f32 v[92:93], v[60:61], 0.5, v[92:93] op_sel_hi:[1,0,1]
	v_pk_fma_f32 v[60:61], v[58:59], 0.5, v[90:91] op_sel_hi:[1,0,1]
	v_cvt_pk_bf16_f32 v58, v62, v63
	v_lshl_add_u64 v[62:63], s[26:27], 0, v[102:103]
	v_cvt_pk_bf16_f32 v59, v64, v65
	v_cvt_pk_bf16_f32 v60, v60, v61
	v_cvt_pk_bf16_f32 v61, v92, v93
	v_lshl_add_u64 v[62:63], v[62:63], 0, v[160:161]
	global_store_dwordx4 v[62:63], v[58:61], off
	s_waitcnt vmcnt(10)
; DI unsigned pk2(float lo, float hi) { f32x2 v = {lo, hi}; bf16x2_t b = __builtin_convertvector(v, bf16x2_t); return __builtin_bit_cast(unsigned, b); }
; DI f32x4 bf4_lo(u32x4 q) { return (f32x4){__builtin_bit_cast(float, q.x << 16), __builtin_bit_cast(float, q.x & 0xffff0000u), __builtin_bit_cast(float, q.y << 16), __builtin_bit_cast(float, q.y & 0xffff0000u)}; }
; DI f32x4 bf4_hi(u32x4 q) { return (f32x4){__builtin_bit_cast(float, q.z << 16), __builtin_bit_cast(float, q.z & 0xffff0000u), __builtin_bit_cast(float, q.w << 16), __builtin_bit_cast(float, q.w & 0xffff0000u)}; }
;     DI void operator()(const f32x4 (&acc)[2][2][4][2], const pg8::Unit& u, int wr, int wc, int fr, int fq) const {
;         const int row0 = u.pm * 256 + wr * 64 + fr, col0 = u.pn * 256 + wc * 32 + 8 * fq;
; #pragma unroll
;         for (int ai = 0; ai < 2; ++ai) {
;             u32x4 r[4][2];
; #pragma unroll
;             for (int m = 0; m < 4; ++m)
; #pragma unroll
;                 for (int bj = 0; bj < 2; ++bj) r[m][bj] = *(const u32x4*)(res + (size_t)(row0 + ai * 128 + m * 16) * DM + col0 + bj * 128);
;             asm volatile("" ::: "memory");
; #pragma unroll
;             for (int m = 0; m < 4; ++m)
; #pragma unroll
;                 for (int bj = 0; bj < 2; ++bj) { const f32x4 a = bf4_lo(r[m][bj]) * ALPHA + acc[ai][bj][m][0] * sc, b = bf4_hi(r[m][bj]) * ALPHA + acc[ai][bj][m][1] * sc;
;                     *(u32x4*)(out + (size_t)(row0 + ai * 128 + m * 16) * DM + col0 + bj * 128) = (u32x4){pk2(a[0], a[1]), pk2(a[2], a[3]), pk2(b[0], b[1]), pk2(b[2], b[3])}; }
;         }
;     }
	s_nop 0
	v_lshlrev_b32_e32 v58, 16, v74
	v_and_b32_e32 v59, 0xffff0000, v74
	v_lshlrev_b32_e32 v60, 16, v75
	v_and_b32_e32 v61, 0xffff0000, v75
	v_pk_mul_f32 v[58:59], v[58:59], s[10:11] op_sel_hi:[1,0]
	v_pk_mul_f32 v[60:61], v[60:61], s[10:11] op_sel_hi:[1,0]
	v_pk_fma_f32 v[54:55], v[54:55], 0.5, v[58:59] op_sel_hi:[1,0,1]
	v_pk_fma_f32 v[56:57], v[56:57], 0.5, v[60:61] op_sel_hi:[1,0,1]
	v_lshlrev_b32_e32 v58, 16, v76
	v_and_b32_e32 v59, 0xffff0000, v76
	v_lshlrev_b32_e32 v60, 16, v77
	v_and_b32_e32 v61, 0xffff0000, v77
	v_pk_mul_f32 v[58:59], v[58:59], s[10:11] op_sel_hi:[1,0]
	v_pk_mul_f32 v[60:61], v[60:61], s[10:11] op_sel_hi:[1,0]
	s_nop 0
	v_pk_fma_f32 v[60:61], v[48:49], 0.5, v[60:61] op_sel_hi:[1,0,1]
	v_pk_fma_f32 v[48:49], v[46:47], 0.5, v[58:59] op_sel_hi:[1,0,1]
	v_cvt_pk_bf16_f32 v46, v54, v55
	v_cvt_pk_bf16_f32 v47, v56, v57
	v_cvt_pk_bf16_f32 v48, v48, v49
	v_cvt_pk_bf16_f32 v49, v60, v61
	global_store_dwordx4 v[62:63], v[46:49], off offset:256
	s_waitcnt vmcnt(10)
	s_nop 0
	v_lshlrev_b32_e32 v46, 16, v82
	v_and_b32_e32 v47, 0xffff0000, v82
	v_lshlrev_b32_e32 v48, 16, v83
	v_and_b32_e32 v49, 0xffff0000, v83
	v_pk_mul_f32 v[46:47], v[46:47], s[10:11] op_sel_hi:[1,0]
	v_pk_mul_f32 v[48:49], v[48:49], s[10:11] op_sel_hi:[1,0]
	v_pk_fma_f32 v[46:47], v[50:51], 0.5, v[46:47] op_sel_hi:[1,0,1]
	v_pk_fma_f32 v[48:49], v[52:53], 0.5, v[48:49] op_sel_hi:[1,0,1]
	v_lshlrev_b32_e32 v50, 16, v84
	v_and_b32_e32 v51, 0xffff0000, v84
	v_lshlrev_b32_e32 v52, 16, v85
	v_and_b32_e32 v53, 0xffff0000, v85
	v_pk_mul_f32 v[50:51], v[50:51], s[10:11] op_sel_hi:[1,0]
	v_pk_mul_f32 v[52:53], v[52:53], s[10:11] op_sel_hi:[1,0]
	s_nop 0
	v_pk_fma_f32 v[52:53], v[44:45], 0.5, v[52:53] op_sel_hi:[1,0,1]
	v_pk_fma_f32 v[44:45], v[42:43], 0.5, v[50:51] op_sel_hi:[1,0,1]
	v_cvt_pk_bf16_f32 v42, v46, v47
	v_lshl_add_u64 v[46:47], s[26:27], 0, v[104:105]
	v_cvt_pk_bf16_f32 v43, v48, v49
	v_cvt_pk_bf16_f32 v44, v44, v45
	v_cvt_pk_bf16_f32 v45, v52, v53
	v_lshl_add_u64 v[46:47], v[46:47], 0, v[160:161]
	global_store_dwordx4 v[46:47], v[42:45], off
	s_waitcnt vmcnt(9)
	s_nop 0
	v_lshlrev_b32_e32 v42, 16, v78
	v_and_b32_e32 v43, 0xffff0000, v78
	v_lshlrev_b32_e32 v44, 16, v79
	v_and_b32_e32 v45, 0xffff0000, v79
	v_pk_mul_f32 v[42:43], v[42:43], s[10:11] op_sel_hi:[1,0]
	v_pk_mul_f32 v[44:45], v[44:45], s[10:11] op_sel_hi:[1,0]
	v_pk_fma_f32 v[38:39], v[38:39], 0.5, v[42:43] op_sel_hi:[1,0,1]
	v_pk_fma_f32 v[40:41], v[40:41], 0.5, v[44:45] op_sel_hi:[1,0,1]
	v_lshlrev_b32_e32 v42, 16, v80
	v_and_b32_e32 v43, 0xffff0000, v80
	v_lshlrev_b32_e32 v44, 16, v81
	v_and_b32_e32 v45, 0xffff0000, v81
	v_pk_mul_f32 v[42:43], v[42:43], s[10:11] op_sel_hi:[1,0]
	v_pk_mul_f32 v[44:45], v[44:45], s[10:11] op_sel_hi:[1,0]
	s_nop 0
	v_pk_fma_f32 v[44:45], v[32:33], 0.5, v[44:45] op_sel_hi:[1,0,1]
	v_pk_fma_f32 v[32:33], v[30:31], 0.5, v[42:43] op_sel_hi:[1,0,1]
	v_cvt_pk_bf16_f32 v30, v38, v39
	v_cvt_pk_bf16_f32 v31, v40, v41
	v_cvt_pk_bf16_f32 v32, v32, v33
	v_cvt_pk_bf16_f32 v33, v44, v45
	global_store_dwordx4 v[46:47], v[30:33], off offset:256
	s_waitcnt vmcnt(7)
	s_nop 0
	v_lshlrev_b32_e32 v30, 16, v86
	v_and_b32_e32 v31, 0xffff0000, v86
	v_lshlrev_b32_e32 v32, 16, v87
	v_and_b32_e32 v33, 0xffff0000, v87
	v_pk_mul_f32 v[30:31], v[30:31], s[10:11] op_sel_hi:[1,0]
	v_pk_mul_f32 v[32:33], v[32:33], s[10:11] op_sel_hi:[1,0]
	v_pk_fma_f32 v[30:31], v[34:35], 0.5, v[30:31] op_sel_hi:[1,0,1]
	v_pk_fma_f32 v[32:33], v[36:37], 0.5, v[32:33] op_sel_hi:[1,0,1]
	v_lshlrev_b32_e32 v34, 16, v88
	v_and_b32_e32 v35, 0xffff0000, v88
	v_lshlrev_b32_e32 v36, 16, v89
	v_and_b32_e32 v37, 0xffff0000, v89
	v_pk_mul_f32 v[34:35], v[34:35], s[10:11] op_sel_hi:[1,0]
	v_pk_mul_f32 v[36:37], v[36:37], s[10:11] op_sel_hi:[1,0]
	s_nop 0
	v_pk_fma_f32 v[36:37], v[28:29], 0.5, v[36:37] op_sel_hi:[1,0,1]
	v_pk_fma_f32 v[28:29], v[26:27], 0.5, v[34:35] op_sel_hi:[1,0,1]
	v_cvt_pk_bf16_f32 v26, v30, v31
	v_lshl_add_u64 v[30:31], s[26:27], 0, v[72:73]
	v_cvt_pk_bf16_f32 v27, v32, v33
	v_cvt_pk_bf16_f32 v28, v28, v29
	v_cvt_pk_bf16_f32 v29, v36, v37
	v_lshl_add_u64 v[30:31], v[30:31], 0, v[160:161]
	global_store_dwordx4 v[30:31], v[26:29], off
	s_waitcnt vmcnt(7)
; #define PG8_BAR __builtin_amdgcn_s_barrier()
; DI unsigned pk2(float lo, float hi) { f32x2 v = {lo, hi}; bf16x2_t b = __builtin_convertvector(v, bf16x2_t); return __builtin_bit_cast(unsigned, b); }
; DI f32x4 bf4_lo(u32x4 q) { return (f32x4){__builtin_bit_cast(float, q.x << 16), __builtin_bit_cast(float, q.x & 0xffff0000u), __builtin_bit_cast(float, q.y << 16), __builtin_bit_cast(float, q.y & 0xffff0000u)}; }
; DI f32x4 bf4_hi(u32x4 q) { return (f32x4){__builtin_bit_cast(float, q.z << 16), __builtin_bit_cast(float, q.z & 0xffff0000u), __builtin_bit_cast(float, q.w << 16), __builtin_bit_cast(float, q.w & 0xffff0000u)}; }
; template <class Epi, class Sched, bool ALIGN_EPI = false, bool SP2 = false>
; __device__ __forceinline__ void gemm_phase(PG8_LAS unsigned char* lds, const Gemm g, const Sched& S, const Epi& E) {
;     ...
;         if constexpr (ALIGN_EPI) { if (wr == 0) PG8_BAR; }
;         if constexpr (!Epi::AFTER_DRAIN) { E(acc, cur, wr, wc, fr, fq); S.done(cur); }
;         if (!has_next) break;
; #pragma unroll
;         for (int a = 0; a < 2; ++a)
; #pragma unroll
;             for (int b = 0; b < 2; ++b)
; #pragma unroll
;                 for (int m = 0; m < 4; ++m)
; #pragma unroll
;                     for (int n = 0; n < 2; ++n) acc[a][b][m][n] = (f32x4){0.f, 0.f, 0.f, 0.f};
;         cur = nxt; cA = nA; cB = nB; ++ui;
;         if constexpr (ALIGN_EPI) { if (wr == 1) PG8_BAR; }
;     DI void operator()(const f32x4 (&acc)[2][2][4][2], const pg8::Unit& u, int wr, int wc, int fr, int fq) const {
;     ...
;             for (int m = 0; m < 4; ++m)
; #pragma unroll
;                 for (int bj = 0; bj < 2; ++bj) { const f32x4 a = bf4_lo(r[m][bj]) * ALPHA + acc[ai][bj][m][0] * sc, b = bf4_hi(r[m][bj]) * ALPHA + acc[ai][bj][m][1] * sc;
;                     *(u32x4*)(out + (size_t)(row0 + ai * 128 + m * 16) * DM + col0 + bj * 128) = (u32x4){pk2(a[0], a[1]), pk2(a[2], a[3]), pk2(b[0], b[1]), pk2(b[2], b[3])}; }
;         }
;     }
	s_nop 0
	v_lshlrev_b32_e32 v26, 16, v94
	v_and_b32_e32 v27, 0xffff0000, v94
	v_lshlrev_b32_e32 v28, 16, v95
	v_and_b32_e32 v29, 0xffff0000, v95
	v_pk_mul_f32 v[26:27], v[26:27], s[10:11] op_sel_hi:[1,0]
	v_pk_mul_f32 v[28:29], v[28:29], s[10:11] op_sel_hi:[1,0]
	v_pk_fma_f32 v[22:23], v[22:23], 0.5, v[26:27] op_sel_hi:[1,0,1]
	v_pk_fma_f32 v[24:25], v[24:25], 0.5, v[28:29] op_sel_hi:[1,0,1]
	v_lshlrev_b32_e32 v26, 16, v96
	v_and_b32_e32 v27, 0xffff0000, v96
	v_lshlrev_b32_e32 v28, 16, v97
	v_and_b32_e32 v29, 0xffff0000, v97
	v_pk_mul_f32 v[26:27], v[26:27], s[10:11] op_sel_hi:[1,0]
	v_pk_mul_f32 v[28:29], v[28:29], s[10:11] op_sel_hi:[1,0]
	s_nop 0
	v_pk_fma_f32 v[28:29], v[16:17], 0.5, v[28:29] op_sel_hi:[1,0,1]
	v_pk_fma_f32 v[16:17], v[14:15], 0.5, v[26:27] op_sel_hi:[1,0,1]
	v_cvt_pk_bf16_f32 v14, v22, v23
	v_cvt_pk_bf16_f32 v15, v24, v25
	v_cvt_pk_bf16_f32 v16, v16, v17
	v_cvt_pk_bf16_f32 v17, v28, v29
	global_store_dwordx4 v[30:31], v[14:17], off offset:256
	s_waitcnt vmcnt(7)
	s_nop 0
	v_lshlrev_b32_e32 v14, 16, v98
	v_and_b32_e32 v15, 0xffff0000, v98
	v_lshlrev_b32_e32 v16, 16, v99
	v_and_b32_e32 v17, 0xffff0000, v99
	v_pk_mul_f32 v[14:15], v[14:15], s[10:11] op_sel_hi:[1,0]
	v_pk_mul_f32 v[16:17], v[16:17], s[10:11] op_sel_hi:[1,0]
	v_pk_fma_f32 v[14:15], v[18:19], 0.5, v[14:15] op_sel_hi:[1,0,1]
	v_pk_fma_f32 v[16:17], v[20:21], 0.5, v[16:17] op_sel_hi:[1,0,1]
	v_lshlrev_b32_e32 v18, 16, v100
	v_and_b32_e32 v19, 0xffff0000, v100
	v_lshlrev_b32_e32 v20, 16, v101
	v_and_b32_e32 v21, 0xffff0000, v101
	v_pk_mul_f32 v[18:19], v[18:19], s[10:11] op_sel_hi:[1,0]
	v_pk_mul_f32 v[20:21], v[20:21], s[10:11] op_sel_hi:[1,0]
	s_nop 0
	v_pk_fma_f32 v[20:21], v[12:13], 0.5, v[20:21] op_sel_hi:[1,0,1]
	v_pk_fma_f32 v[12:13], v[10:11], 0.5, v[18:19] op_sel_hi:[1,0,1]
	v_cvt_pk_bf16_f32 v10, v14, v15
	v_lshl_add_u64 v[14:15], s[26:27], 0, v[70:71]
	v_cvt_pk_bf16_f32 v11, v16, v17
	v_cvt_pk_bf16_f32 v12, v12, v13
	v_cvt_pk_bf16_f32 v13, v20, v21
	v_lshl_add_u64 v[14:15], v[14:15], 0, v[160:161]
	global_store_dwordx4 v[14:15], v[10:13], off
	s_waitcnt vmcnt(7)
	s_nop 0
	v_lshlrev_b32_e32 v10, 16, v66
	v_and_b32_e32 v11, 0xffff0000, v66
	v_lshlrev_b32_e32 v12, 16, v67
	v_and_b32_e32 v13, 0xffff0000, v67
	v_pk_mul_f32 v[10:11], v[10:11], s[10:11] op_sel_hi:[1,0]
	v_pk_mul_f32 v[12:13], v[12:13], s[10:11] op_sel_hi:[1,0]
	v_pk_fma_f32 v[6:7], v[6:7], 0.5, v[10:11] op_sel_hi:[1,0,1]
	v_pk_fma_f32 v[8:9], v[8:9], 0.5, v[12:13] op_sel_hi:[1,0,1]
	v_lshlrev_b32_e32 v10, 16, v68
	v_and_b32_e32 v11, 0xffff0000, v68
	v_lshlrev_b32_e32 v12, 16, v69
	v_and_b32_e32 v13, 0xffff0000, v69
	v_pk_mul_f32 v[10:11], v[10:11], s[10:11] op_sel_hi:[1,0]
	v_pk_mul_f32 v[12:13], v[12:13], s[10:11] op_sel_hi:[1,0]
	s_nop 0
	v_pk_fma_f32 v[12:13], v[4:5], 0.5, v[12:13] op_sel_hi:[1,0,1]
	v_pk_fma_f32 v[4:5], v[2:3], 0.5, v[10:11] op_sel_hi:[1,0,1]
	v_cvt_pk_bf16_f32 v2, v6, v7
	v_cvt_pk_bf16_f32 v3, v8, v9
	v_cvt_pk_bf16_f32 v4, v4, v5
	v_cvt_pk_bf16_f32 v5, v12, v13
	global_store_dwordx4 v[14:15], v[2:5], off offset:256
	s_mov_b32 s98, 1
	s_cbranch_vccnz .LBB0_2118
	s_andn2_b64 vcc, exec, s[4:5]
	s_cbranch_vccnz .LBB0_2117
	s_barrier
	s_branch .LBB0_2117

; #define PG8_STAGE(bufoff, gbase, voff) do { _Pragma("unroll") for (int _i = 0; _i < 2; ++_i) \
;         __builtin_amdgcn_global_load_lds((const unsigned*)((const char*)(gbase) + (voff)[_i]), (PG8_LAS unsigned*)(lds + (bufoff) + ldsw + _i * 8192), 16, 0, 0); } while (0)
; #define PG8_WAIT_V(n) asm volatile("s_waitcnt vmcnt(" #n ")" ::: "memory")
; #define PG8_BAR __builtin_amdgcn_s_barrier()
; template <class Epi, class Sched, bool ALIGN_EPI = false, bool SP2 = false>
; __device__ __forceinline__ void gemm_phase(PG8_LAS unsigned char* lds, const Gemm g, const Sched& S, const Epi& E) {
;     ...
;     for (int i = 0; i < 2; ++i) { int R, C; stage_rc(tid * 16 + i * 8192, R, C); const int Rb = Epi::PERM ? ((R & ~31) + perm32(R & 31)) : R;
;         voffA[i] = (unsigned)(R * LD + C) * 2u; voffB[i] = (unsigned)(Rb * LD + C) * 2u; }
;     const size_t kstep = (size_t)(BK * 2);
;     const size_t hstep = (size_t)HALF * LD * 2;
;     const size_t tstep = 2 * hstep;
;     const unsigned ldsw = (unsigned)wid * 1024u;
;     const int aoff = lds_byte(wr * 64 + fr, fq * 8), boff = lds_byte(wc * 32 + fr, fq * 8);
;     ...
;         PG8_STAGE(PG8_SB(1, 0), cB + kstep, voffB); PG8_STAGE(PG8_SA(1, 0), cA + kstep, voffA); PG8_STAGE(PG8_SB(1, 1), cB + hstep + kstep, voffB);
;         PG8_WAIT_V(6); PG8_BAR;
.LBB0_2140:
	s_lshl_b32 s6, s6, 5
	s_and_b32 s11, s6, 0x60
	s_mov_b64 s[6:7], 0x80
	s_add_i32 m0, s34, 0x18000
	v_lshl_add_u64 v[8:9], v[8:9], 0, s[6:7]
	s_lshl_b32 s9, s8, 13
	s_lshl_b32 s18, s11, 7
	s_waitcnt vmcnt(2)
	s_barrier
	global_load_lds_dwordx4 v[8:9], off
	v_lshl_add_u64 v[6:7], v[6:7], 0, s[6:7]
	s_add_i32 m0, s34, 0x1a000
	s_add_i32 s39, s34, 0x8000
	s_add_i32 s41, s34, 0xa000
	global_load_lds_dwordx4 v[6:7], off
	v_lshl_add_u64 v[2:3], v[2:3], 0, s[6:7]
	s_mov_b32 m0, s39
	s_add_u32 s12, s26, 0x160080
	global_load_lds_dwordx4 v[2:3], off
	v_lshl_add_u64 v[2:3], v[4:5], 0, s[6:7]
	s_mov_b32 m0, s41
	s_addc_u32 s13, s27, 0
	global_load_lds_dwordx4 v[2:3], off
	s_add_i32 m0, s34, 0x1c000
	v_lshl_add_u64 v[2:3], s[12:13], 0, v[132:133]
	global_load_lds_dwordx4 v[2:3], off
	v_lshl_add_u64 v[2:3], s[12:13], 0, v[130:131]
	s_add_i32 m0, s34, 0x1e000
	s_mov_b64 s[12:13], 0x160080
	global_load_lds_dwordx4 v[2:3], off
	v_bfe_u32 v2, v1, 4, 2
	v_and_b32_e32 v3, 15, v1
	v_lshlrev_b32_e32 v5, 4, v2
	v_lshlrev_b32_e32 v1, 2, v1
	v_lshl_or_b32 v4, s8, 6, v3
	v_lshl_or_b32 v3, v3, 6, v5
	v_and_b32_e32 v1, 32, v1
	v_bitop3_b32 v5, v3, s9, v1 bitop3:0xde
	v_bitop3_b32 v6, v3, s18, v1 bitop3:0xde
	v_lshl_or_b32 v138, v2, 2, s11
	v_lshrrev_b32_e32 v3, 1, v15
	v_mul_lo_u32 v2, v14, s1
	v_mad_u64_u32 v[2:3], s[18:19], v3, s10, v[2:3]
	v_or_b32_e32 v2, v2, v16
	v_add_lshl_u32 v2, v2, v17, 1
	v_mov_b32_e32 v3, v133
	v_lshl_add_u64 v[134:135], v[2:3], 0, s[12:13]
	v_lshrrev_b32_e32 v3, 1, v10
	v_mul_lo_u32 v2, v11, s1
	s_cmpk_lt_u32 s0, 0x100
	v_mad_u64_u32 v[2:3], s[0:1], v3, s10, v[2:3]
	s_waitcnt vmcnt(6)
	s_cselect_b64 s[8:9], -1, 0
	v_or_b32_e32 v2, v2, v12
	s_add_i32 s51, 0, 0x10000
	s_add_i32 s53, 0, 0x14000
	v_add_lshl_u32 v2, v2, v13, 1
	v_mov_b32_e32 v3, v133
	v_add_u32_e32 v139, s51, v6
	v_add_u32_e32 v140, s53, v6
	s_add_i32 s51, s51, s33
	s_add_i32 s53, s53, s33
	s_add_i32 s55, 0, 0x18000
	s_add_i32 s56, 0, 0x1c000
	v_add_u32_e32 v1, 0xffffc000, v4
	v_lshl_add_u64 v[136:137], v[2:3], 0, s[12:13]
	v_add_u32_e32 v141, 0, v5
	s_mov_b64 s[10:11], 0x100000
	s_mov_b32 s46, 0x100000
	s_mov_b64 s[12:13], 0x120000
	s_mov_b32 s47, 0x120000
	s_mov_b64 s[18:19], 0x140000
	s_mov_b32 s48, 0x140000
	s_add_i32 s49, s34, 0xc000
	s_add_i32 s50, s34, 0xe000
	s_add_i32 s52, s51, 0x2000
	s_add_i32 s54, s53, 0x2000
	v_add_u32_e32 v143, s55, v6
	v_add_u32_e32 v144, s56, v6
	s_barrier
	s_mov_b32 s98, 0
	s_branch .LBB0_2143

; #define PG8_STAGE(bufoff, gbase, voff) do { _Pragma("unroll") for (int _i = 0; _i < 2; ++_i) \
;         __builtin_amdgcn_global_load_lds((const unsigned*)((const char*)(gbase) + (voff)[_i]), (PG8_LAS unsigned*)(lds + (bufoff) + ldsw + _i * 8192), 16, 0, 0); } while (0)
; #define PG8_LDA(dst, b, h) do { _Pragma("unroll") for (int m = 0; m < 4; ++m) _Pragma("unroll") for (int k = 0; k < 2; ++k) dst[m][k] = *(const PG8_LAS bf16x8*)(lds + PG8_SA(b, h) + aoff + m * 2048 + k * 1024); } while (0)
; #define PG8_LDB(dst, b, h) do { _Pragma("unroll") for (int n = 0; n < 2; ++n) _Pragma("unroll") for (int k = 0; k < 2; ++k) dst[n][k] = *(const PG8_LAS bf16x8*)(lds + PG8_SB(b, h) + boff + n * 2048 + k * 1024); } while (0)
; #define PG8_MMA(ai, bj, At, Bt) do { __builtin_amdgcn_s_setprio(1); _Pragma("unroll") for (int m = 0; m < 4; ++m) _Pragma("unroll") for (int n = 0; n < 2; ++n) _Pragma("unroll") for (int k = 0; k < 2; ++k) \
;         acc[ai][bj][m][n] = __builtin_amdgcn_mfma_f32_16x16x32_bf16(Bt[n][k], At[m][k], acc[ai][bj][m][n], 0, 0, 0); __builtin_amdgcn_s_setprio(0); } while (0)
; #define PG8_WAIT_V(n) asm volatile("s_waitcnt vmcnt(" #n ")" ::: "memory")
; #define PG8_BAR __builtin_amdgcn_s_barrier()
; template <class Epi, class Sched, bool ALIGN_EPI = false, bool SP2 = false>
; __device__ __forceinline__ void gemm_phase(PG8_LAS unsigned char* lds, const Gemm g, const Sched& S, const Epi& E) {
;     ...
;         for (int t = 0; t < nt; t += 2) {
;             const bool last = (t == nt - 2);
;             const char* a1 = cA + (size_t)(t + 1) * kstep;
;             const char* a2 = last ? nA : cA + (size_t)(t + 2) * kstep; const char* b2 = last ? nB : cB + (size_t)(t + 2) * kstep;
;             const char* a3 = a2 + kstep; const char* b3 = b2 + kstep;
;             if (last && has_next) S.a_ready(nxt);
;             if constexpr (SP2) {
;             PG8_LDB(B0, 0, 0); PG8_LDB(B1, 0, 1); PG8_SCHED; PG8_LDA(At, 0, 0); PG8_STAGE(PG8_SA(1, 1), a1 + hstep, voffA);
;             PG8_WAIT_V(8); PG8_WAIT_L(0); PG8_BAR; PG8_MMA(0, 0, At, B0); PG8_MMA(0, 1, At, B1); PG8_BAR; PG8_SCHED;
;     ...
; #pragma unroll
;         for (int a = 0; a < 2; ++a)
; #pragma unroll
;             for (int b = 0; b < 2; ++b)
; #pragma unroll
;                 for (int m = 0; m < 4; ++m)
; #pragma unroll
;                     for (int n = 0; n < 2; ++n) acc[a][b][m][n] = (f32x4){0.f, 0.f, 0.f, 0.f};
.LBB0_2149:
	s_add_u32 s60, s26, 0x100
	v_mov_b32_e32 v2, 0
	s_addc_u32 s61, s27, 0
	s_mov_b32 s62, -2
	s_cmp_lg_u32 s98, 0
	s_cbranch_scc1 .Lpeel_10
	v_mov_b32_e32 v3, v2
	v_mov_b32_e32 v4, v2
	v_mov_b32_e32 v5, v2
	v_mov_b32_e32 v6, v2
	v_mov_b32_e32 v7, v2
	v_mov_b32_e32 v8, v2
	v_mov_b32_e32 v9, v2
	v_mov_b32_e32 v10, v2
	v_mov_b32_e32 v11, v2
	v_mov_b32_e32 v12, v2
	v_mov_b32_e32 v13, v2
	v_mov_b32_e32 v14, v2
	v_mov_b32_e32 v15, v2
	v_mov_b32_e32 v16, v2
	v_mov_b32_e32 v17, v2
	v_mov_b32_e32 v22, v2
	v_mov_b32_e32 v23, v2
	v_mov_b32_e32 v24, v2
	v_mov_b32_e32 v25, v2
	v_mov_b32_e32 v30, v2
	v_mov_b32_e32 v31, v2
	v_mov_b32_e32 v32, v2
	v_mov_b32_e32 v33, v2
	v_mov_b32_e32 v38, v2
	v_mov_b32_e32 v39, v2
	v_mov_b32_e32 v40, v2
	v_mov_b32_e32 v41, v2
	v_mov_b32_e32 v46, v2
	v_mov_b32_e32 v47, v2
	v_mov_b32_e32 v48, v2
	v_mov_b32_e32 v49, v2
	v_mov_b32_e32 v18, v2
	v_mov_b32_e32 v19, v2
	v_mov_b32_e32 v20, v2
	v_mov_b32_e32 v21, v2
	v_mov_b32_e32 v26, v2
	v_mov_b32_e32 v27, v2
	v_mov_b32_e32 v28, v2
	v_mov_b32_e32 v29, v2
	v_mov_b32_e32 v34, v2
	v_mov_b32_e32 v35, v2
	v_mov_b32_e32 v36, v2
	v_mov_b32_e32 v37, v2
	v_mov_b32_e32 v42, v2
	v_mov_b32_e32 v43, v2
	v_mov_b32_e32 v44, v2
	v_mov_b32_e32 v45, v2
	v_mov_b32_e32 v50, v2
	v_mov_b32_e32 v51, v2
	v_mov_b32_e32 v52, v2
	v_mov_b32_e32 v53, v2
	v_mov_b32_e32 v54, v2
	v_mov_b32_e32 v55, v2
	v_mov_b32_e32 v56, v2
	v_mov_b32_e32 v57, v2
	v_mov_b32_e32 v58, v2
	v_mov_b32_e32 v59, v2
	v_mov_b32_e32 v60, v2
	v_mov_b32_e32 v61, v2
	v_mov_b32_e32 v62, v2
	v_mov_b32_e32 v63, v2
	v_mov_b32_e32 v64, v2
	v_mov_b32_e32 v65, v2
	v_mov_b32_e32 v66, v2
	v_mov_b32_e32 v67, v2
	v_mov_b32_e32 v68, v2
	v_mov_b32_e32 v69, v2
	v_mov_b32_e32 v70, v2
	v_mov_b32_e32 v71, v2
	v_mov_b32_e32 v72, v2
	v_mov_b32_e32 v73, v2
	v_mov_b32_e32 v74, v2
	v_mov_b32_e32 v75, v2
	v_mov_b32_e32 v76, v2
	v_mov_b32_e32 v77, v2
	v_mov_b32_e32 v78, v2
	v_mov_b32_e32 v79, v2
	v_mov_b32_e32 v80, v2
	v_mov_b32_e32 v81, v2
	v_mov_b32_e32 v86, v2
	v_mov_b32_e32 v87, v2
	v_mov_b32_e32 v88, v2
	v_mov_b32_e32 v89, v2
	v_mov_b32_e32 v94, v2
	v_mov_b32_e32 v95, v2
	v_mov_b32_e32 v96, v2
	v_mov_b32_e32 v97, v2
	v_mov_b32_e32 v102, v2
	v_mov_b32_e32 v103, v2
	v_mov_b32_e32 v104, v2
	v_mov_b32_e32 v105, v2
	v_mov_b32_e32 v110, v2
	v_mov_b32_e32 v111, v2
	v_mov_b32_e32 v112, v2
	v_mov_b32_e32 v113, v2
	v_mov_b32_e32 v82, v2
	v_mov_b32_e32 v83, v2
	v_mov_b32_e32 v84, v2
	v_mov_b32_e32 v85, v2
	v_mov_b32_e32 v90, v2
	v_mov_b32_e32 v91, v2
	v_mov_b32_e32 v92, v2
	v_mov_b32_e32 v93, v2
	v_mov_b32_e32 v98, v2
	v_mov_b32_e32 v99, v2
	v_mov_b32_e32 v100, v2
	v_mov_b32_e32 v101, v2
	v_mov_b32_e32 v106, v2
	v_mov_b32_e32 v107, v2
	v_mov_b32_e32 v108, v2
	v_mov_b32_e32 v109, v2
	v_mov_b32_e32 v114, v2
	v_mov_b32_e32 v115, v2
	v_mov_b32_e32 v116, v2
	v_mov_b32_e32 v117, v2
	v_mov_b32_e32 v118, v2
	v_mov_b32_e32 v119, v2
	v_mov_b32_e32 v120, v2
	v_mov_b32_e32 v121, v2
	v_mov_b32_e32 v122, v2
	v_mov_b32_e32 v123, v2
	v_mov_b32_e32 v124, v2
	v_mov_b32_e32 v125, v2
	v_mov_b32_e32 v126, v2
	v_mov_b32_e32 v127, v2
	v_mov_b32_e32 v128, v2
	v_mov_b32_e32 v129, v2
.LBB0_2150:
	ds_read_b128 v[146:149], v139
	ds_read_b128 v[150:153], v139 offset:1024
	ds_read_b128 v[154:157], v139 offset:2048
	ds_read_b128 v[158:161], v139 offset:3072
	ds_read_b128 v[162:165], v140
	ds_read_b128 v[166:169], v140 offset:1024
	ds_read_b128 v[170:173], v140 offset:2048
	ds_read_b128 v[174:177], v140 offset:3072
	s_add_u32 s26, s24, 0x100
	s_addc_u32 s27, s25, 0
	s_cmp_eq_u32 s62, 18
	s_cselect_b32 s31, s21, s27
	s_cselect_b32 s30, s20, s26
	s_cselect_b32 s29, s23, s61
	s_cselect_b32 s28, s22, s60
	s_mov_b32 m0, s49
	v_lshl_add_u64 v[210:211], s[24:25], 0, v[134:135]
	ds_read_b128 v[178:181], v141
	ds_read_b128 v[182:185], v141 offset:1024
	ds_read_b128 v[186:189], v141 offset:2048
	ds_read_b128 v[190:193], v141 offset:3072
	ds_read_b128 v[194:197], v141 offset:4096
	ds_read_b128 v[198:201], v141 offset:5120
	ds_read_b128 v[202:205], v141 offset:6144
	ds_read_b128 v[206:209], v141 offset:7168
	global_load_lds_dwordx4 v[210:211], off
	v_lshl_add_u64 v[210:211], s[24:25], 0, v[136:137]
	s_mov_b32 m0, s50
	s_nop 0
	global_load_lds_dwordx4 v[210:211], off
	s_waitcnt vmcnt(8)
	s_waitcnt lgkmcnt(0)
	s_barrier
	s_setprio 1
	s_waitcnt lgkmcnt(0)
	v_mfma_f32_16x16x32_bf16 v[126:129], v[146:149], v[178:181], v[126:129]
	v_mfma_f32_16x16x32_bf16 v[122:125], v[154:157], v[178:181], v[122:125]
	v_mfma_f32_16x16x32_bf16 v[118:121], v[146:149], v[186:189], v[118:121]
	v_mfma_f32_16x16x32_bf16 v[114:117], v[154:157], v[186:189], v[114:117]
	v_mfma_f32_16x16x32_bf16 v[106:109], v[146:149], v[194:197], v[106:109]
	v_mfma_f32_16x16x32_bf16 v[98:101], v[154:157], v[194:197], v[98:101]
	v_mfma_f32_16x16x32_bf16 v[90:93], v[146:149], v[202:205], v[90:93]
	v_mfma_f32_16x16x32_bf16 v[82:85], v[154:157], v[202:205], v[82:85]
	v_mfma_f32_16x16x32_bf16 v[126:129], v[150:153], v[182:185], v[126:129]
	v_mfma_f32_16x16x32_bf16 v[122:125], v[158:161], v[182:185], v[122:125]
	v_mfma_f32_16x16x32_bf16 v[118:121], v[150:153], v[190:193], v[118:121]
	v_mfma_f32_16x16x32_bf16 v[114:117], v[158:161], v[190:193], v[114:117]
	v_mfma_f32_16x16x32_bf16 v[106:109], v[150:153], v[198:201], v[106:109]
	v_mfma_f32_16x16x32_bf16 v[98:101], v[158:161], v[198:201], v[98:101]
	v_mfma_f32_16x16x32_bf16 v[90:93], v[150:153], v[206:209], v[90:93]
	v_mfma_f32_16x16x32_bf16 v[82:85], v[158:161], v[206:209], v[82:85]
	s_setprio 0
	s_setprio 1
	v_mfma_f32_16x16x32_bf16 v[110:113], v[162:165], v[178:181], v[110:113]
	v_mfma_f32_16x16x32_bf16 v[102:105], v[170:173], v[178:181], v[102:105]
	v_mfma_f32_16x16x32_bf16 v[94:97], v[162:165], v[186:189], v[94:97]
	v_mfma_f32_16x16x32_bf16 v[86:89], v[170:173], v[186:189], v[86:89]
	v_mfma_f32_16x16x32_bf16 v[78:81], v[162:165], v[194:197], v[78:81]
	v_mfma_f32_16x16x32_bf16 v[74:77], v[170:173], v[194:197], v[74:77]
	v_mfma_f32_16x16x32_bf16 v[70:73], v[162:165], v[202:205], v[70:73]
	v_mfma_f32_16x16x32_bf16 v[66:69], v[170:173], v[202:205], v[66:69]
	v_mfma_f32_16x16x32_bf16 v[110:113], v[166:169], v[182:185], v[110:113]
	v_mfma_f32_16x16x32_bf16 v[102:105], v[174:177], v[182:185], v[102:105]
	v_mfma_f32_16x16x32_bf16 v[94:97], v[166:169], v[190:193], v[94:97]
	v_mfma_f32_16x16x32_bf16 v[86:89], v[174:177], v[190:193], v[86:89]
	v_mfma_f32_16x16x32_bf16 v[78:81], v[166:169], v[198:201], v[78:81]
	v_mfma_f32_16x16x32_bf16 v[74:77], v[174:177], v[198:201], v[74:77]
	v_mfma_f32_16x16x32_bf16 v[70:73], v[166:169], v[206:209], v[70:73]
	v_mfma_f32_16x16x32_bf16 v[66:69], v[174:177], v[206:209], v[66:69]
	s_setprio 0
	s_barrier
; #define PG8_STAGE(bufoff, gbase, voff) do { _Pragma("unroll") for (int _i = 0; _i < 2; ++_i) \
;         __builtin_amdgcn_global_load_lds((const unsigned*)((const char*)(gbase) + (voff)[_i]), (PG8_LAS unsigned*)(lds + (bufoff) + ldsw + _i * 8192), 16, 0, 0); } while (0)
; #define PG8_LDA(dst, b, h) do { _Pragma("unroll") for (int m = 0; m < 4; ++m) _Pragma("unroll") for (int k = 0; k < 2; ++k) dst[m][k] = *(const PG8_LAS bf16x8*)(lds + PG8_SA(b, h) + aoff + m * 2048 + k * 1024); } while (0)
; #define PG8_LDB(dst, b, h) do { _Pragma("unroll") for (int n = 0; n < 2; ++n) _Pragma("unroll") for (int k = 0; k < 2; ++k) dst[n][k] = *(const PG8_LAS bf16x8*)(lds + PG8_SB(b, h) + boff + n * 2048 + k * 1024); } while (0)
; #define PG8_MMA(ai, bj, At, Bt) do { __builtin_amdgcn_s_setprio(1); _Pragma("unroll") for (int m = 0; m < 4; ++m) _Pragma("unroll") for (int n = 0; n < 2; ++n) _Pragma("unroll") for (int k = 0; k < 2; ++k) \
;         acc[ai][bj][m][n] = __builtin_amdgcn_mfma_f32_16x16x32_bf16(Bt[n][k], At[m][k], acc[ai][bj][m][n], 0, 0, 0); __builtin_amdgcn_s_setprio(0); } while (0)
; #define PG8_WAIT_V(n) asm volatile("s_waitcnt vmcnt(" #n ")" ::: "memory")
; #define PG8_WAIT_L(n) asm volatile("s_waitcnt lgkmcnt(" #n ")" ::: "memory")
; #define PG8_BAR __builtin_amdgcn_s_barrier()
; #define PG8_SCHED __builtin_amdgcn_sched_barrier(0)
; template <class Epi, class Sched, bool ALIGN_EPI = false, bool SP2 = false>
; __device__ __forceinline__ void gemm_phase(PG8_LAS unsigned char* lds, const Gemm g, const Sched& S, const Epi& E) {
;     ...
;             PG8_LDA(At, 0, 1); PG8_STAGE(PG8_SB(0, 0), b2, voffB); PG8_STAGE(PG8_SB(0, 1), b2 + hstep, voffB); PG8_STAGE(PG8_SA(0, 0), a2, voffA);
;             PG8_WAIT_V(8); PG8_WAIT_L(0); PG8_BAR; PG8_MMA(1, 0, At, B0); PG8_MMA(1, 1, At, B1); PG8_BAR; PG8_SCHED;
;             PG8_LDB(B0, 1, 0); PG8_LDB(B1, 1, 1); PG8_SCHED; PG8_LDA(At, 1, 0); PG8_STAGE(PG8_SA(0, 1), a2 + hstep, voffA);
;             PG8_WAIT_V(8); PG8_WAIT_L(0); PG8_BAR; PG8_MMA(0, 0, At, B0); PG8_MMA(0, 1, At, B1); PG8_BAR; PG8_SCHED;
	s_mov_b32 m0, s51
	v_lshl_add_u64 v[210:211], s[28:29], 0, v[132:133]
	s_add_u32 s24, s28, 0x160000
	ds_read_b128 v[178:181], v141 offset:16384
	ds_read_b128 v[182:185], v141 offset:17408
	ds_read_b128 v[186:189], v141 offset:18432
	ds_read_b128 v[190:193], v141 offset:19456
	ds_read_b128 v[194:197], v141 offset:20480
	ds_read_b128 v[198:201], v141 offset:21504
	ds_read_b128 v[202:205], v141 offset:22528
	ds_read_b128 v[206:209], v141 offset:23552
	global_load_lds_dwordx4 v[210:211], off
	v_lshl_add_u64 v[212:213], s[28:29], 0, v[130:131]
	s_mov_b32 m0, s52
	s_addc_u32 s25, s29, 0
	global_load_lds_dwordx4 v[212:213], off
	v_lshl_add_u64 v[214:215], s[24:25], 0, v[132:133]
	s_mov_b32 m0, s53
	v_lshl_add_u64 v[216:217], s[30:31], 0, v[130:131]
	global_load_lds_dwordx4 v[214:215], off
	v_lshl_add_u64 v[214:215], s[24:25], 0, v[130:131]
	s_mov_b32 m0, s54
	s_nop 0
	global_load_lds_dwordx4 v[214:215], off
	v_lshl_add_u64 v[214:215], s[30:31], 0, v[132:133]
	s_mov_b32 m0, s34
	s_nop 0
	global_load_lds_dwordx4 v[214:215], off
	s_mov_b32 m0, s35
	s_nop 0
	global_load_lds_dwordx4 v[216:217], off
	s_waitcnt vmcnt(8)
	s_waitcnt lgkmcnt(0)
	s_barrier
	s_setprio 1
	s_waitcnt lgkmcnt(0)
	v_mfma_f32_16x16x32_bf16 v[62:65], v[146:149], v[178:181], v[62:65]
	v_mfma_f32_16x16x32_bf16 v[58:61], v[154:157], v[178:181], v[58:61]
	v_mfma_f32_16x16x32_bf16 v[54:57], v[146:149], v[186:189], v[54:57]
	v_mfma_f32_16x16x32_bf16 v[50:53], v[154:157], v[186:189], v[50:53]
	v_mfma_f32_16x16x32_bf16 v[42:45], v[146:149], v[194:197], v[42:45]
	v_mfma_f32_16x16x32_bf16 v[34:37], v[154:157], v[194:197], v[34:37]
	v_mfma_f32_16x16x32_bf16 v[26:29], v[146:149], v[202:205], v[26:29]
	v_mfma_f32_16x16x32_bf16 v[18:21], v[154:157], v[202:205], v[18:21]
	v_mfma_f32_16x16x32_bf16 v[62:65], v[150:153], v[182:185], v[62:65]
	v_mfma_f32_16x16x32_bf16 v[58:61], v[158:161], v[182:185], v[58:61]
	v_mfma_f32_16x16x32_bf16 v[54:57], v[150:153], v[190:193], v[54:57]
	v_mfma_f32_16x16x32_bf16 v[50:53], v[158:161], v[190:193], v[50:53]
	v_mfma_f32_16x16x32_bf16 v[42:45], v[150:153], v[198:201], v[42:45]
	v_mfma_f32_16x16x32_bf16 v[34:37], v[158:161], v[198:201], v[34:37]
	v_mfma_f32_16x16x32_bf16 v[26:29], v[150:153], v[206:209], v[26:29]
	v_mfma_f32_16x16x32_bf16 v[18:21], v[158:161], v[206:209], v[18:21]
	s_setprio 0
	s_setprio 1
	v_mfma_f32_16x16x32_bf16 v[46:49], v[162:165], v[178:181], v[46:49]
	v_mfma_f32_16x16x32_bf16 v[38:41], v[170:173], v[178:181], v[38:41]
	v_mfma_f32_16x16x32_bf16 v[30:33], v[162:165], v[186:189], v[30:33]
	v_mfma_f32_16x16x32_bf16 v[22:25], v[170:173], v[186:189], v[22:25]
	v_mfma_f32_16x16x32_bf16 v[14:17], v[162:165], v[194:197], v[14:17]
	v_mfma_f32_16x16x32_bf16 v[10:13], v[170:173], v[194:197], v[10:13]
	v_mfma_f32_16x16x32_bf16 v[6:9], v[162:165], v[202:205], v[6:9]
	v_mfma_f32_16x16x32_bf16 v[2:5], v[170:173], v[202:205], v[2:5]
	v_mfma_f32_16x16x32_bf16 v[46:49], v[166:169], v[182:185], v[46:49]
	v_mfma_f32_16x16x32_bf16 v[38:41], v[174:177], v[182:185], v[38:41]
	v_mfma_f32_16x16x32_bf16 v[30:33], v[166:169], v[190:193], v[30:33]
	v_mfma_f32_16x16x32_bf16 v[22:25], v[174:177], v[190:193], v[22:25]
	v_mfma_f32_16x16x32_bf16 v[14:17], v[166:169], v[198:201], v[14:17]
	v_mfma_f32_16x16x32_bf16 v[10:13], v[174:177], v[198:201], v[10:13]
	v_mfma_f32_16x16x32_bf16 v[6:9], v[166:169], v[206:209], v[6:9]
	v_mfma_f32_16x16x32_bf16 v[2:5], v[174:177], v[206:209], v[2:5]
	s_setprio 0
	s_barrier
	ds_read_b128 v[146:149], v143
	ds_read_b128 v[150:153], v143 offset:1024
	ds_read_b128 v[154:157], v143 offset:2048
	ds_read_b128 v[158:161], v143 offset:3072
	ds_read_b128 v[162:165], v144
	ds_read_b128 v[166:169], v144 offset:1024
	ds_read_b128 v[170:173], v144 offset:2048
	ds_read_b128 v[174:177], v144 offset:3072
	s_add_u32 s24, s30, 0x160000
	s_addc_u32 s25, s31, 0
	s_mov_b32 m0, s36
	v_lshl_add_u64 v[220:221], s[24:25], 0, v[132:133]
	ds_read_b128 v[178:181], v141 offset:32768
	ds_read_b128 v[182:185], v141 offset:33792
	ds_read_b128 v[186:189], v141 offset:34816
	ds_read_b128 v[190:193], v141 offset:35840
	ds_read_b128 v[194:197], v141 offset:36864
	ds_read_b128 v[198:201], v141 offset:37888
	ds_read_b128 v[202:205], v141 offset:38912
	ds_read_b128 v[206:209], v141 offset:39936
	global_load_lds_dwordx4 v[220:221], off
	v_lshl_add_u64 v[220:221], s[24:25], 0, v[130:131]
	s_mov_b32 m0, s37
	s_nop 0
	global_load_lds_dwordx4 v[220:221], off
	s_waitcnt vmcnt(8)
	s_waitcnt lgkmcnt(0)
	s_barrier
	s_setprio 1
	s_waitcnt lgkmcnt(0)
	v_mfma_f32_16x16x32_bf16 v[126:129], v[146:149], v[178:181], v[126:129]
	v_mfma_f32_16x16x32_bf16 v[122:125], v[154:157], v[178:181], v[122:125]
	v_mfma_f32_16x16x32_bf16 v[118:121], v[146:149], v[186:189], v[118:121]
	v_mfma_f32_16x16x32_bf16 v[114:117], v[154:157], v[186:189], v[114:117]
	v_mfma_f32_16x16x32_bf16 v[106:109], v[146:149], v[194:197], v[106:109]
	v_mfma_f32_16x16x32_bf16 v[98:101], v[154:157], v[194:197], v[98:101]
	v_mfma_f32_16x16x32_bf16 v[90:93], v[146:149], v[202:205], v[90:93]
	v_mfma_f32_16x16x32_bf16 v[82:85], v[154:157], v[202:205], v[82:85]
	v_mfma_f32_16x16x32_bf16 v[126:129], v[150:153], v[182:185], v[126:129]
	v_mfma_f32_16x16x32_bf16 v[122:125], v[158:161], v[182:185], v[122:125]
	v_mfma_f32_16x16x32_bf16 v[118:121], v[150:153], v[190:193], v[118:121]
	v_mfma_f32_16x16x32_bf16 v[114:117], v[158:161], v[190:193], v[114:117]
	v_mfma_f32_16x16x32_bf16 v[106:109], v[150:153], v[198:201], v[106:109]
	v_mfma_f32_16x16x32_bf16 v[98:101], v[158:161], v[198:201], v[98:101]
	v_mfma_f32_16x16x32_bf16 v[90:93], v[150:153], v[206:209], v[90:93]
	v_mfma_f32_16x16x32_bf16 v[82:85], v[158:161], v[206:209], v[82:85]
	s_setprio 0
	s_setprio 1
	v_mfma_f32_16x16x32_bf16 v[110:113], v[162:165], v[178:181], v[110:113]
	v_mfma_f32_16x16x32_bf16 v[102:105], v[170:173], v[178:181], v[102:105]
	v_mfma_f32_16x16x32_bf16 v[94:97], v[162:165], v[186:189], v[94:97]
	v_mfma_f32_16x16x32_bf16 v[86:89], v[170:173], v[186:189], v[86:89]
	v_mfma_f32_16x16x32_bf16 v[78:81], v[162:165], v[194:197], v[78:81]
	v_mfma_f32_16x16x32_bf16 v[74:77], v[170:173], v[194:197], v[74:77]
	v_mfma_f32_16x16x32_bf16 v[70:73], v[162:165], v[202:205], v[70:73]
	v_mfma_f32_16x16x32_bf16 v[66:69], v[170:173], v[202:205], v[66:69]
	v_mfma_f32_16x16x32_bf16 v[110:113], v[166:169], v[182:185], v[110:113]
	v_mfma_f32_16x16x32_bf16 v[102:105], v[174:177], v[182:185], v[102:105]
	v_mfma_f32_16x16x32_bf16 v[94:97], v[166:169], v[190:193], v[94:97]
	v_mfma_f32_16x16x32_bf16 v[86:89], v[174:177], v[190:193], v[86:89]
	v_mfma_f32_16x16x32_bf16 v[78:81], v[166:169], v[198:201], v[78:81]
	v_mfma_f32_16x16x32_bf16 v[74:77], v[174:177], v[198:201], v[74:77]
	v_mfma_f32_16x16x32_bf16 v[70:73], v[166:169], v[206:209], v[70:73]
	v_mfma_f32_16x16x32_bf16 v[66:69], v[174:177], v[206:209], v[66:69]
	s_setprio 0
	s_barrier
; #define PG8_STAGE(bufoff, gbase, voff) do { _Pragma("unroll") for (int _i = 0; _i < 2; ++_i) \
;         __builtin_amdgcn_global_load_lds((const unsigned*)((const char*)(gbase) + (voff)[_i]), (PG8_LAS unsigned*)(lds + (bufoff) + ldsw + _i * 8192), 16, 0, 0); } while (0)
; #define PG8_LDA(dst, b, h) do { _Pragma("unroll") for (int m = 0; m < 4; ++m) _Pragma("unroll") for (int k = 0; k < 2; ++k) dst[m][k] = *(const PG8_LAS bf16x8*)(lds + PG8_SA(b, h) + aoff + m * 2048 + k * 1024); } while (0)
; #define PG8_LDB(dst, b, h) do { _Pragma("unroll") for (int n = 0; n < 2; ++n) _Pragma("unroll") for (int k = 0; k < 2; ++k) dst[n][k] = *(const PG8_LAS bf16x8*)(lds + PG8_SB(b, h) + boff + n * 2048 + k * 1024); } while (0)
; #define PG8_MMA(ai, bj, At, Bt) do { __builtin_amdgcn_s_setprio(1); _Pragma("unroll") for (int m = 0; m < 4; ++m) _Pragma("unroll") for (int n = 0; n < 2; ++n) _Pragma("unroll") for (int k = 0; k < 2; ++k) \
;         acc[ai][bj][m][n] = __builtin_amdgcn_mfma_f32_16x16x32_bf16(Bt[n][k], At[m][k], acc[ai][bj][m][n], 0, 0, 0); __builtin_amdgcn_s_setprio(0); } while (0)
; #define PG8_WAIT_V(n) asm volatile("s_waitcnt vmcnt(" #n ")" ::: "memory")
; #define PG8_BAR __builtin_amdgcn_s_barrier()
; template <class Epi, class Sched, bool ALIGN_EPI = false, bool SP2 = false>
; __device__ __forceinline__ void gemm_phase(PG8_LAS unsigned char* lds, const Gemm g, const Sched& S, const Epi& E) {
;     ...
;         for (int t = 0; t < nt; t += 2) {
;             const bool last = (t == nt - 2);
;             const char* a1 = cA + (size_t)(t + 1) * kstep;
;             const char* a2 = last ? nA : cA + (size_t)(t + 2) * kstep; const char* b2 = last ? nB : cB + (size_t)(t + 2) * kstep;
;             const char* a3 = a2 + kstep; const char* b3 = b2 + kstep;
;             if (last && has_next) S.a_ready(nxt);
;             if constexpr (SP2) {
;             PG8_LDB(B0, 0, 0); PG8_LDB(B1, 0, 1); PG8_SCHED; PG8_LDA(At, 0, 0); PG8_STAGE(PG8_SA(1, 1), a1 + hstep, voffA);
;             PG8_WAIT_V(8); PG8_WAIT_L(0); PG8_BAR; PG8_MMA(0, 0, At, B0); PG8_MMA(0, 1, At, B1); PG8_BAR; PG8_SCHED;
;     ...
;             PG8_LDA(At, 1, 1); PG8_STAGE(PG8_SB(1, 0), b3, voffB); PG8_STAGE(PG8_SB(1, 1), b3 + hstep, voffB); PG8_STAGE(PG8_SA(1, 0), a3, voffA);
;             PG8_WAIT_V(8); PG8_WAIT_L(0); PG8_BAR; PG8_MMA(1, 0, At, B0); PG8_MMA(1, 1, At, B1); PG8_BAR; PG8_SCHED;
	s_add_i32 s24, s55, s33
	v_lshl_add_u64 v[210:211], v[210:211], 0, s[6:7]
	s_mov_b32 m0, s24
	ds_read_b128 v[178:181], v141 offset:49152
	ds_read_b128 v[182:185], v141 offset:50176
	ds_read_b128 v[186:189], v141 offset:51200
	ds_read_b128 v[190:193], v141 offset:52224
	ds_read_b128 v[194:197], v141 offset:53248
	ds_read_b128 v[198:201], v141 offset:54272
	ds_read_b128 v[202:205], v141 offset:55296
	ds_read_b128 v[206:209], v141 offset:56320
	global_load_lds_dwordx4 v[210:211], off
	s_add_i32 m0, s24, 0x2000
	s_add_u32 s24, s28, 0x160080
	v_lshl_add_u64 v[210:211], v[212:213], 0, s[6:7]
	s_addc_u32 s25, s29, 0
	s_add_i32 s28, s56, s33
	global_load_lds_dwordx4 v[210:211], off
	v_lshl_add_u64 v[210:211], s[24:25], 0, v[132:133]
	s_mov_b32 m0, s28
	s_nop 0
	global_load_lds_dwordx4 v[210:211], off
	v_lshl_add_u64 v[210:211], s[24:25], 0, v[130:131]
	s_add_i32 m0, s28, 0x2000
	s_nop 0
	global_load_lds_dwordx4 v[210:211], off
	v_lshl_add_u64 v[210:211], v[214:215], 0, s[6:7]
	s_mov_b32 m0, s39
	s_nop 0
	global_load_lds_dwordx4 v[210:211], off
	v_lshl_add_u64 v[210:211], v[216:217], 0, s[6:7]
	s_mov_b32 m0, s41
	s_nop 0
	global_load_lds_dwordx4 v[210:211], off
	s_waitcnt vmcnt(8)
	s_waitcnt lgkmcnt(0)
	s_barrier
	s_setprio 1
	s_waitcnt lgkmcnt(0)
	v_mfma_f32_16x16x32_bf16 v[62:65], v[146:149], v[178:181], v[62:65]
	v_mfma_f32_16x16x32_bf16 v[58:61], v[154:157], v[178:181], v[58:61]
	v_mfma_f32_16x16x32_bf16 v[54:57], v[146:149], v[186:189], v[54:57]
	v_mfma_f32_16x16x32_bf16 v[50:53], v[154:157], v[186:189], v[50:53]
	v_mfma_f32_16x16x32_bf16 v[42:45], v[146:149], v[194:197], v[42:45]
	v_mfma_f32_16x16x32_bf16 v[34:37], v[154:157], v[194:197], v[34:37]
	v_mfma_f32_16x16x32_bf16 v[26:29], v[146:149], v[202:205], v[26:29]
	v_mfma_f32_16x16x32_bf16 v[18:21], v[154:157], v[202:205], v[18:21]
	v_mfma_f32_16x16x32_bf16 v[62:65], v[150:153], v[182:185], v[62:65]
	v_mfma_f32_16x16x32_bf16 v[58:61], v[158:161], v[182:185], v[58:61]
	v_mfma_f32_16x16x32_bf16 v[54:57], v[150:153], v[190:193], v[54:57]
	v_mfma_f32_16x16x32_bf16 v[50:53], v[158:161], v[190:193], v[50:53]
	v_mfma_f32_16x16x32_bf16 v[42:45], v[150:153], v[198:201], v[42:45]
	v_mfma_f32_16x16x32_bf16 v[34:37], v[158:161], v[198:201], v[34:37]
	v_mfma_f32_16x16x32_bf16 v[26:29], v[150:153], v[206:209], v[26:29]
	v_mfma_f32_16x16x32_bf16 v[18:21], v[158:161], v[206:209], v[18:21]
	s_setprio 0
	s_setprio 1
	v_mfma_f32_16x16x32_bf16 v[46:49], v[162:165], v[178:181], v[46:49]
	v_mfma_f32_16x16x32_bf16 v[38:41], v[170:173], v[178:181], v[38:41]
	v_mfma_f32_16x16x32_bf16 v[30:33], v[162:165], v[186:189], v[30:33]
	v_mfma_f32_16x16x32_bf16 v[22:25], v[170:173], v[186:189], v[22:25]
	v_mfma_f32_16x16x32_bf16 v[14:17], v[162:165], v[194:197], v[14:17]
	v_mfma_f32_16x16x32_bf16 v[10:13], v[170:173], v[194:197], v[10:13]
	v_mfma_f32_16x16x32_bf16 v[6:9], v[162:165], v[202:205], v[6:9]
	v_mfma_f32_16x16x32_bf16 v[2:5], v[170:173], v[202:205], v[2:5]
	v_mfma_f32_16x16x32_bf16 v[46:49], v[166:169], v[182:185], v[46:49]
	v_mfma_f32_16x16x32_bf16 v[38:41], v[174:177], v[182:185], v[38:41]
	v_mfma_f32_16x16x32_bf16 v[30:33], v[166:169], v[190:193], v[30:33]
	v_mfma_f32_16x16x32_bf16 v[22:25], v[174:177], v[190:193], v[22:25]
	v_mfma_f32_16x16x32_bf16 v[14:17], v[166:169], v[198:201], v[14:17]
	v_mfma_f32_16x16x32_bf16 v[10:13], v[174:177], v[198:201], v[10:13]
	v_mfma_f32_16x16x32_bf16 v[6:9], v[166:169], v[206:209], v[6:9]
	v_mfma_f32_16x16x32_bf16 v[2:5], v[174:177], v[206:209], v[2:5]
	s_setprio 0
	s_barrier
	s_add_i32 s62, s62, 2
	s_add_u32 s60, s60, 0x100
	s_addc_u32 s61, s61, 0
	s_cmp_gt_u32 s62, 19
	s_mov_b64 s[24:25], s[26:27]
	s_cbranch_scc0 .LBB0_2150
	s_branch .Lpeel_after_10
.Lpeel_10:
	ds_read_b128 v[146:149], v139
	ds_read_b128 v[150:153], v139 offset:1024
	ds_read_b128 v[154:157], v139 offset:2048
	ds_read_b128 v[158:161], v139 offset:3072
	ds_read_b128 v[162:165], v140
	ds_read_b128 v[166:169], v140 offset:1024
	ds_read_b128 v[170:173], v140 offset:2048
	ds_read_b128 v[174:177], v140 offset:3072
	s_add_u32 s26, s24, 0x100
	s_addc_u32 s27, s25, 0
	s_cmp_eq_u32 s62, 18
	s_cselect_b32 s31, s21, s27
	s_cselect_b32 s30, s20, s26
	s_cselect_b32 s29, s23, s61
	s_cselect_b32 s28, s22, s60
	s_mov_b32 m0, s49
	v_lshl_add_u64 v[210:211], s[24:25], 0, v[134:135]
	ds_read_b128 v[178:181], v141
	ds_read_b128 v[182:185], v141 offset:1024
	ds_read_b128 v[186:189], v141 offset:2048
	ds_read_b128 v[190:193], v141 offset:3072
	ds_read_b128 v[194:197], v141 offset:4096
	ds_read_b128 v[198:201], v141 offset:5120
	ds_read_b128 v[202:205], v141 offset:6144
	ds_read_b128 v[206:209], v141 offset:7168
	global_load_lds_dwordx4 v[210:211], off
	v_lshl_add_u64 v[210:211], s[24:25], 0, v[136:137]
	s_mov_b32 m0, s50
	s_nop 0
	global_load_lds_dwordx4 v[210:211], off
	s_waitcnt vmcnt(40)
	s_waitcnt lgkmcnt(0)
	s_barrier
; #define PG8_STAGE(bufoff, gbase, voff) do { _Pragma("unroll") for (int _i = 0; _i < 2; ++_i) \
;         __builtin_amdgcn_global_load_lds((const unsigned*)((const char*)(gbase) + (voff)[_i]), (PG8_LAS unsigned*)(lds + (bufoff) + ldsw + _i * 8192), 16, 0, 0); } while (0)
; #define PG8_LDA(dst, b, h) do { _Pragma("unroll") for (int m = 0; m < 4; ++m) _Pragma("unroll") for (int k = 0; k < 2; ++k) dst[m][k] = *(const PG8_LAS bf16x8*)(lds + PG8_SA(b, h) + aoff + m * 2048 + k * 1024); } while (0)
; #define PG8_LDB(dst, b, h) do { _Pragma("unroll") for (int n = 0; n < 2; ++n) _Pragma("unroll") for (int k = 0; k < 2; ++k) dst[n][k] = *(const PG8_LAS bf16x8*)(lds + PG8_SB(b, h) + boff + n * 2048 + k * 1024); } while (0)
; #define PG8_MMA(ai, bj, At, Bt) do { __builtin_amdgcn_s_setprio(1); _Pragma("unroll") for (int m = 0; m < 4; ++m) _Pragma("unroll") for (int n = 0; n < 2; ++n) _Pragma("unroll") for (int k = 0; k < 2; ++k) \
;         acc[ai][bj][m][n] = __builtin_amdgcn_mfma_f32_16x16x32_bf16(Bt[n][k], At[m][k], acc[ai][bj][m][n], 0, 0, 0); __builtin_amdgcn_s_setprio(0); } while (0)
; #define PG8_WAIT_V(n) asm volatile("s_waitcnt vmcnt(" #n ")" ::: "memory")
; #define PG8_WAIT_L(n) asm volatile("s_waitcnt lgkmcnt(" #n ")" ::: "memory")
; #define PG8_BAR __builtin_amdgcn_s_barrier()
; #define PG8_SCHED __builtin_amdgcn_sched_barrier(0)
; template <class Epi, class Sched, bool ALIGN_EPI = false, bool SP2 = false>
; __device__ __forceinline__ void gemm_phase(PG8_LAS unsigned char* lds, const Gemm g, const Sched& S, const Epi& E) {
;     ...
;             PG8_LDB(B0, 0, 0); PG8_LDB(B1, 0, 1); PG8_SCHED; PG8_LDA(At, 0, 0); PG8_STAGE(PG8_SA(1, 1), a1 + hstep, voffA);
;             PG8_WAIT_V(8); PG8_WAIT_L(0); PG8_BAR; PG8_MMA(0, 0, At, B0); PG8_MMA(0, 1, At, B1); PG8_BAR; PG8_SCHED;
;             PG8_LDA(At, 0, 1); PG8_STAGE(PG8_SB(0, 0), b2, voffB); PG8_STAGE(PG8_SB(0, 1), b2 + hstep, voffB); PG8_STAGE(PG8_SA(0, 0), a2, voffA);
;             PG8_WAIT_V(8); PG8_WAIT_L(0); PG8_BAR; PG8_MMA(1, 0, At, B0); PG8_MMA(1, 1, At, B1); PG8_BAR; PG8_SCHED;
	s_setprio 1
	s_waitcnt lgkmcnt(0)
	v_mfma_f32_16x16x32_bf16 v[126:129], v[146:149], v[178:181], 0
	v_mfma_f32_16x16x32_bf16 v[122:125], v[154:157], v[178:181], 0
	v_mfma_f32_16x16x32_bf16 v[118:121], v[146:149], v[186:189], 0
	v_mfma_f32_16x16x32_bf16 v[114:117], v[154:157], v[186:189], 0
	v_mfma_f32_16x16x32_bf16 v[106:109], v[146:149], v[194:197], 0
	v_mfma_f32_16x16x32_bf16 v[98:101], v[154:157], v[194:197], 0
	v_mfma_f32_16x16x32_bf16 v[90:93], v[146:149], v[202:205], 0
	v_mfma_f32_16x16x32_bf16 v[82:85], v[154:157], v[202:205], 0
	v_mfma_f32_16x16x32_bf16 v[126:129], v[150:153], v[182:185], v[126:129]
	v_mfma_f32_16x16x32_bf16 v[122:125], v[158:161], v[182:185], v[122:125]
	v_mfma_f32_16x16x32_bf16 v[118:121], v[150:153], v[190:193], v[118:121]
	v_mfma_f32_16x16x32_bf16 v[114:117], v[158:161], v[190:193], v[114:117]
	v_mfma_f32_16x16x32_bf16 v[106:109], v[150:153], v[198:201], v[106:109]
	v_mfma_f32_16x16x32_bf16 v[98:101], v[158:161], v[198:201], v[98:101]
	v_mfma_f32_16x16x32_bf16 v[90:93], v[150:153], v[206:209], v[90:93]
	v_mfma_f32_16x16x32_bf16 v[82:85], v[158:161], v[206:209], v[82:85]
	s_setprio 0
	s_setprio 1
	v_mfma_f32_16x16x32_bf16 v[110:113], v[162:165], v[178:181], 0
	v_mfma_f32_16x16x32_bf16 v[102:105], v[170:173], v[178:181], 0
	v_mfma_f32_16x16x32_bf16 v[94:97], v[162:165], v[186:189], 0
	v_mfma_f32_16x16x32_bf16 v[86:89], v[170:173], v[186:189], 0
	v_mfma_f32_16x16x32_bf16 v[78:81], v[162:165], v[194:197], 0
	v_mfma_f32_16x16x32_bf16 v[74:77], v[170:173], v[194:197], 0
	v_mfma_f32_16x16x32_bf16 v[70:73], v[162:165], v[202:205], 0
	v_mfma_f32_16x16x32_bf16 v[66:69], v[170:173], v[202:205], 0
	v_mfma_f32_16x16x32_bf16 v[110:113], v[166:169], v[182:185], v[110:113]
	v_mfma_f32_16x16x32_bf16 v[102:105], v[174:177], v[182:185], v[102:105]
	v_mfma_f32_16x16x32_bf16 v[94:97], v[166:169], v[190:193], v[94:97]
	v_mfma_f32_16x16x32_bf16 v[86:89], v[174:177], v[190:193], v[86:89]
	v_mfma_f32_16x16x32_bf16 v[78:81], v[166:169], v[198:201], v[78:81]
	v_mfma_f32_16x16x32_bf16 v[74:77], v[174:177], v[198:201], v[74:77]
	v_mfma_f32_16x16x32_bf16 v[70:73], v[166:169], v[206:209], v[70:73]
	v_mfma_f32_16x16x32_bf16 v[66:69], v[174:177], v[206:209], v[66:69]
	s_setprio 0
	s_barrier
	s_mov_b32 m0, s51
	v_lshl_add_u64 v[210:211], s[28:29], 0, v[132:133]
	s_add_u32 s24, s28, 0x160000
	ds_read_b128 v[178:181], v141 offset:16384
	ds_read_b128 v[182:185], v141 offset:17408
	ds_read_b128 v[186:189], v141 offset:18432
	ds_read_b128 v[190:193], v141 offset:19456
	ds_read_b128 v[194:197], v141 offset:20480
	ds_read_b128 v[198:201], v141 offset:21504
	ds_read_b128 v[202:205], v141 offset:22528
	ds_read_b128 v[206:209], v141 offset:23552
	global_load_lds_dwordx4 v[210:211], off
	v_lshl_add_u64 v[212:213], s[28:29], 0, v[130:131]
	s_mov_b32 m0, s52
	s_addc_u32 s25, s29, 0
	global_load_lds_dwordx4 v[212:213], off
	v_lshl_add_u64 v[214:215], s[24:25], 0, v[132:133]
	s_mov_b32 m0, s53
	v_lshl_add_u64 v[216:217], s[30:31], 0, v[130:131]
	global_load_lds_dwordx4 v[214:215], off
	v_lshl_add_u64 v[214:215], s[24:25], 0, v[130:131]
	s_mov_b32 m0, s54
	s_nop 0
	global_load_lds_dwordx4 v[214:215], off
	v_lshl_add_u64 v[214:215], s[30:31], 0, v[132:133]
	s_mov_b32 m0, s34
	s_nop 0
	global_load_lds_dwordx4 v[214:215], off
	s_mov_b32 m0, s35
	s_nop 0
	global_load_lds_dwordx4 v[216:217], off
	s_waitcnt vmcnt(40)
	s_waitcnt lgkmcnt(0)
	s_barrier
	s_setprio 1
	s_waitcnt lgkmcnt(0)
	v_mfma_f32_16x16x32_bf16 v[62:65], v[146:149], v[178:181], 0
	v_mfma_f32_16x16x32_bf16 v[58:61], v[154:157], v[178:181], 0
	v_mfma_f32_16x16x32_bf16 v[54:57], v[146:149], v[186:189], 0
	v_mfma_f32_16x16x32_bf16 v[50:53], v[154:157], v[186:189], 0
	v_mfma_f32_16x16x32_bf16 v[42:45], v[146:149], v[194:197], 0
	v_mfma_f32_16x16x32_bf16 v[34:37], v[154:157], v[194:197], 0
	v_mfma_f32_16x16x32_bf16 v[26:29], v[146:149], v[202:205], 0
	v_mfma_f32_16x16x32_bf16 v[18:21], v[154:157], v[202:205], 0
	v_mfma_f32_16x16x32_bf16 v[62:65], v[150:153], v[182:185], v[62:65]
	v_mfma_f32_16x16x32_bf16 v[58:61], v[158:161], v[182:185], v[58:61]
	v_mfma_f32_16x16x32_bf16 v[54:57], v[150:153], v[190:193], v[54:57]
	v_mfma_f32_16x16x32_bf16 v[50:53], v[158:161], v[190:193], v[50:53]
	v_mfma_f32_16x16x32_bf16 v[42:45], v[150:153], v[198:201], v[42:45]
	v_mfma_f32_16x16x32_bf16 v[34:37], v[158:161], v[198:201], v[34:37]
	v_mfma_f32_16x16x32_bf16 v[26:29], v[150:153], v[206:209], v[26:29]
	v_mfma_f32_16x16x32_bf16 v[18:21], v[158:161], v[206:209], v[18:21]
	s_setprio 0
	s_setprio 1
	v_mfma_f32_16x16x32_bf16 v[46:49], v[162:165], v[178:181], 0
	v_mfma_f32_16x16x32_bf16 v[38:41], v[170:173], v[178:181], 0
	v_mfma_f32_16x16x32_bf16 v[30:33], v[162:165], v[186:189], 0
	v_mfma_f32_16x16x32_bf16 v[22:25], v[170:173], v[186:189], 0
	v_mfma_f32_16x16x32_bf16 v[14:17], v[162:165], v[194:197], 0
	v_mfma_f32_16x16x32_bf16 v[10:13], v[170:173], v[194:197], 0
	v_mfma_f32_16x16x32_bf16 v[6:9], v[162:165], v[202:205], 0
	v_mfma_f32_16x16x32_bf16 v[2:5], v[170:173], v[202:205], 0
	v_mfma_f32_16x16x32_bf16 v[46:49], v[166:169], v[182:185], v[46:49]
	v_mfma_f32_16x16x32_bf16 v[38:41], v[174:177], v[182:185], v[38:41]
	v_mfma_f32_16x16x32_bf16 v[30:33], v[166:169], v[190:193], v[30:33]
	v_mfma_f32_16x16x32_bf16 v[22:25], v[174:177], v[190:193], v[22:25]
	v_mfma_f32_16x16x32_bf16 v[14:17], v[166:169], v[198:201], v[14:17]
	v_mfma_f32_16x16x32_bf16 v[10:13], v[174:177], v[198:201], v[10:13]
	v_mfma_f32_16x16x32_bf16 v[6:9], v[166:169], v[206:209], v[6:9]
	v_mfma_f32_16x16x32_bf16 v[2:5], v[174:177], v[206:209], v[2:5]
	s_setprio 0
	s_barrier
; #define PG8_STAGE(bufoff, gbase, voff) do { _Pragma("unroll") for (int _i = 0; _i < 2; ++_i) \
;         __builtin_amdgcn_global_load_lds((const unsigned*)((const char*)(gbase) + (voff)[_i]), (PG8_LAS unsigned*)(lds + (bufoff) + ldsw + _i * 8192), 16, 0, 0); } while (0)
; #define PG8_LDA(dst, b, h) do { _Pragma("unroll") for (int m = 0; m < 4; ++m) _Pragma("unroll") for (int k = 0; k < 2; ++k) dst[m][k] = *(const PG8_LAS bf16x8*)(lds + PG8_SA(b, h) + aoff + m * 2048 + k * 1024); } while (0)
; #define PG8_LDB(dst, b, h) do { _Pragma("unroll") for (int n = 0; n < 2; ++n) _Pragma("unroll") for (int k = 0; k < 2; ++k) dst[n][k] = *(const PG8_LAS bf16x8*)(lds + PG8_SB(b, h) + boff + n * 2048 + k * 1024); } while (0)
; #define PG8_MMA(ai, bj, At, Bt) do { __builtin_amdgcn_s_setprio(1); _Pragma("unroll") for (int m = 0; m < 4; ++m) _Pragma("unroll") for (int n = 0; n < 2; ++n) _Pragma("unroll") for (int k = 0; k < 2; ++k) \
;         acc[ai][bj][m][n] = __builtin_amdgcn_mfma_f32_16x16x32_bf16(Bt[n][k], At[m][k], acc[ai][bj][m][n], 0, 0, 0); __builtin_amdgcn_s_setprio(0); } while (0)
; #define PG8_WAIT_V(n) asm volatile("s_waitcnt vmcnt(" #n ")" ::: "memory")
; #define PG8_WAIT_L(n) asm volatile("s_waitcnt lgkmcnt(" #n ")" ::: "memory")
; #define PG8_BAR __builtin_amdgcn_s_barrier()
; #define PG8_SCHED __builtin_amdgcn_sched_barrier(0)
; template <class Epi, class Sched, bool ALIGN_EPI = false, bool SP2 = false>
; __device__ __forceinline__ void gemm_phase(PG8_LAS unsigned char* lds, const Gemm g, const Sched& S, const Epi& E) {
;     ...
;             PG8_LDB(B0, 1, 0); PG8_LDB(B1, 1, 1); PG8_SCHED; PG8_LDA(At, 1, 0); PG8_STAGE(PG8_SA(0, 1), a2 + hstep, voffA);
;             PG8_WAIT_V(8); PG8_WAIT_L(0); PG8_BAR; PG8_MMA(0, 0, At, B0); PG8_MMA(0, 1, At, B1); PG8_BAR; PG8_SCHED;
;             PG8_LDA(At, 1, 1); PG8_STAGE(PG8_SB(1, 0), b3, voffB); PG8_STAGE(PG8_SB(1, 1), b3 + hstep, voffB); PG8_STAGE(PG8_SA(1, 0), a3, voffA);
;             PG8_WAIT_V(8); PG8_WAIT_L(0); PG8_BAR; PG8_MMA(1, 0, At, B0); PG8_MMA(1, 1, At, B1); PG8_BAR; PG8_SCHED;
	ds_read_b128 v[146:149], v143
	ds_read_b128 v[150:153], v143 offset:1024
	ds_read_b128 v[154:157], v143 offset:2048
	ds_read_b128 v[158:161], v143 offset:3072
	ds_read_b128 v[162:165], v144
	ds_read_b128 v[166:169], v144 offset:1024
	ds_read_b128 v[170:173], v144 offset:2048
	ds_read_b128 v[174:177], v144 offset:3072
	s_add_u32 s24, s30, 0x160000
	s_addc_u32 s25, s31, 0
	s_mov_b32 m0, s36
	v_lshl_add_u64 v[220:221], s[24:25], 0, v[132:133]
	ds_read_b128 v[178:181], v141 offset:32768
	ds_read_b128 v[182:185], v141 offset:33792
	ds_read_b128 v[186:189], v141 offset:34816
	ds_read_b128 v[190:193], v141 offset:35840
	ds_read_b128 v[194:197], v141 offset:36864
	ds_read_b128 v[198:201], v141 offset:37888
	ds_read_b128 v[202:205], v141 offset:38912
	ds_read_b128 v[206:209], v141 offset:39936
	global_load_lds_dwordx4 v[220:221], off
	v_lshl_add_u64 v[220:221], s[24:25], 0, v[130:131]
	s_mov_b32 m0, s37
	s_nop 0
	global_load_lds_dwordx4 v[220:221], off
	s_waitcnt vmcnt(8)
	s_waitcnt lgkmcnt(0)
	s_barrier
	s_setprio 1
	s_waitcnt lgkmcnt(0)
	v_mfma_f32_16x16x32_bf16 v[126:129], v[146:149], v[178:181], v[126:129]
	v_mfma_f32_16x16x32_bf16 v[122:125], v[154:157], v[178:181], v[122:125]
	v_mfma_f32_16x16x32_bf16 v[118:121], v[146:149], v[186:189], v[118:121]
	v_mfma_f32_16x16x32_bf16 v[114:117], v[154:157], v[186:189], v[114:117]
	v_mfma_f32_16x16x32_bf16 v[106:109], v[146:149], v[194:197], v[106:109]
	v_mfma_f32_16x16x32_bf16 v[98:101], v[154:157], v[194:197], v[98:101]
	v_mfma_f32_16x16x32_bf16 v[90:93], v[146:149], v[202:205], v[90:93]
	v_mfma_f32_16x16x32_bf16 v[82:85], v[154:157], v[202:205], v[82:85]
	v_mfma_f32_16x16x32_bf16 v[126:129], v[150:153], v[182:185], v[126:129]
	v_mfma_f32_16x16x32_bf16 v[122:125], v[158:161], v[182:185], v[122:125]
	v_mfma_f32_16x16x32_bf16 v[118:121], v[150:153], v[190:193], v[118:121]
	v_mfma_f32_16x16x32_bf16 v[114:117], v[158:161], v[190:193], v[114:117]
	v_mfma_f32_16x16x32_bf16 v[106:109], v[150:153], v[198:201], v[106:109]
	v_mfma_f32_16x16x32_bf16 v[98:101], v[158:161], v[198:201], v[98:101]
	v_mfma_f32_16x16x32_bf16 v[90:93], v[150:153], v[206:209], v[90:93]
	v_mfma_f32_16x16x32_bf16 v[82:85], v[158:161], v[206:209], v[82:85]
	s_setprio 0
	s_setprio 1
	v_mfma_f32_16x16x32_bf16 v[110:113], v[162:165], v[178:181], v[110:113]
	v_mfma_f32_16x16x32_bf16 v[102:105], v[170:173], v[178:181], v[102:105]
	v_mfma_f32_16x16x32_bf16 v[94:97], v[162:165], v[186:189], v[94:97]
	v_mfma_f32_16x16x32_bf16 v[86:89], v[170:173], v[186:189], v[86:89]
	v_mfma_f32_16x16x32_bf16 v[78:81], v[162:165], v[194:197], v[78:81]
	v_mfma_f32_16x16x32_bf16 v[74:77], v[170:173], v[194:197], v[74:77]
	v_mfma_f32_16x16x32_bf16 v[70:73], v[162:165], v[202:205], v[70:73]
	v_mfma_f32_16x16x32_bf16 v[66:69], v[170:173], v[202:205], v[66:69]
	v_mfma_f32_16x16x32_bf16 v[110:113], v[166:169], v[182:185], v[110:113]
	v_mfma_f32_16x16x32_bf16 v[102:105], v[174:177], v[182:185], v[102:105]
	v_mfma_f32_16x16x32_bf16 v[94:97], v[166:169], v[190:193], v[94:97]
	v_mfma_f32_16x16x32_bf16 v[86:89], v[174:177], v[190:193], v[86:89]
	v_mfma_f32_16x16x32_bf16 v[78:81], v[166:169], v[198:201], v[78:81]
	v_mfma_f32_16x16x32_bf16 v[74:77], v[174:177], v[198:201], v[74:77]
	v_mfma_f32_16x16x32_bf16 v[70:73], v[166:169], v[206:209], v[70:73]
	v_mfma_f32_16x16x32_bf16 v[66:69], v[174:177], v[206:209], v[66:69]
	s_setprio 0
	s_barrier
	s_add_i32 s24, s55, s33
	v_lshl_add_u64 v[210:211], v[210:211], 0, s[6:7]
	s_mov_b32 m0, s24
	ds_read_b128 v[178:181], v141 offset:49152
	ds_read_b128 v[182:185], v141 offset:50176
	ds_read_b128 v[186:189], v141 offset:51200
	ds_read_b128 v[190:193], v141 offset:52224
	ds_read_b128 v[194:197], v141 offset:53248
	ds_read_b128 v[198:201], v141 offset:54272
	ds_read_b128 v[202:205], v141 offset:55296
	ds_read_b128 v[206:209], v141 offset:56320
	global_load_lds_dwordx4 v[210:211], off
	s_add_i32 m0, s24, 0x2000
	s_add_u32 s24, s28, 0x160080
	v_lshl_add_u64 v[210:211], v[212:213], 0, s[6:7]
	s_addc_u32 s25, s29, 0
	s_add_i32 s28, s56, s33
	global_load_lds_dwordx4 v[210:211], off
	v_lshl_add_u64 v[210:211], s[24:25], 0, v[132:133]
	s_mov_b32 m0, s28
	s_nop 0
	global_load_lds_dwordx4 v[210:211], off
	v_lshl_add_u64 v[210:211], s[24:25], 0, v[130:131]
	s_add_i32 m0, s28, 0x2000
	s_nop 0
	global_load_lds_dwordx4 v[210:211], off
	v_lshl_add_u64 v[210:211], v[214:215], 0, s[6:7]
	s_mov_b32 m0, s39
	s_nop 0
	global_load_lds_dwordx4 v[210:211], off
	v_lshl_add_u64 v[210:211], v[216:217], 0, s[6:7]
	s_mov_b32 m0, s41
	s_nop 0
	global_load_lds_dwordx4 v[210:211], off
	s_waitcnt vmcnt(8)
	s_waitcnt lgkmcnt(0)
	s_barrier
	s_setprio 1
	s_waitcnt lgkmcnt(0)
	v_mfma_f32_16x16x32_bf16 v[62:65], v[146:149], v[178:181], v[62:65]
	v_mfma_f32_16x16x32_bf16 v[58:61], v[154:157], v[178:181], v[58:61]
	v_mfma_f32_16x16x32_bf16 v[54:57], v[146:149], v[186:189], v[54:57]
	v_mfma_f32_16x16x32_bf16 v[50:53], v[154:157], v[186:189], v[50:53]
	v_mfma_f32_16x16x32_bf16 v[42:45], v[146:149], v[194:197], v[42:45]
	v_mfma_f32_16x16x32_bf16 v[34:37], v[154:157], v[194:197], v[34:37]
	v_mfma_f32_16x16x32_bf16 v[26:29], v[146:149], v[202:205], v[26:29]
	v_mfma_f32_16x16x32_bf16 v[18:21], v[154:157], v[202:205], v[18:21]
	v_mfma_f32_16x16x32_bf16 v[62:65], v[150:153], v[182:185], v[62:65]
	v_mfma_f32_16x16x32_bf16 v[58:61], v[158:161], v[182:185], v[58:61]
	v_mfma_f32_16x16x32_bf16 v[54:57], v[150:153], v[190:193], v[54:57]
	v_mfma_f32_16x16x32_bf16 v[50:53], v[158:161], v[190:193], v[50:53]
	v_mfma_f32_16x16x32_bf16 v[42:45], v[150:153], v[198:201], v[42:45]
	v_mfma_f32_16x16x32_bf16 v[34:37], v[158:161], v[198:201], v[34:37]
	v_mfma_f32_16x16x32_bf16 v[26:29], v[150:153], v[206:209], v[26:29]
	v_mfma_f32_16x16x32_bf16 v[18:21], v[158:161], v[206:209], v[18:21]
	s_setprio 0
	s_setprio 1
	v_mfma_f32_16x16x32_bf16 v[46:49], v[162:165], v[178:181], v[46:49]
	v_mfma_f32_16x16x32_bf16 v[38:41], v[170:173], v[178:181], v[38:41]
	v_mfma_f32_16x16x32_bf16 v[30:33], v[162:165], v[186:189], v[30:33]
	v_mfma_f32_16x16x32_bf16 v[22:25], v[170:173], v[186:189], v[22:25]
	v_mfma_f32_16x16x32_bf16 v[14:17], v[162:165], v[194:197], v[14:17]
	v_mfma_f32_16x16x32_bf16 v[10:13], v[170:173], v[194:197], v[10:13]
	v_mfma_f32_16x16x32_bf16 v[6:9], v[162:165], v[202:205], v[6:9]
	v_mfma_f32_16x16x32_bf16 v[2:5], v[170:173], v[202:205], v[2:5]
	v_mfma_f32_16x16x32_bf16 v[46:49], v[166:169], v[182:185], v[46:49]
	v_mfma_f32_16x16x32_bf16 v[38:41], v[174:177], v[182:185], v[38:41]
	v_mfma_f32_16x16x32_bf16 v[30:33], v[166:169], v[190:193], v[30:33]
	v_mfma_f32_16x16x32_bf16 v[22:25], v[174:177], v[190:193], v[22:25]
	v_mfma_f32_16x16x32_bf16 v[14:17], v[166:169], v[198:201], v[14:17]
	v_mfma_f32_16x16x32_bf16 v[10:13], v[174:177], v[198:201], v[10:13]
	v_mfma_f32_16x16x32_bf16 v[6:9], v[166:169], v[206:209], v[6:9]
	v_mfma_f32_16x16x32_bf16 v[2:5], v[174:177], v[206:209], v[2:5]
	s_setprio 0
	s_barrier
	s_add_i32 s62, s62, 2
	s_add_u32 s60, s60, 0x100
	s_addc_u32 s61, s61, 0
	s_cmp_gt_u32 s62, 19
	s_mov_b64 s[24:25], s[26:27]
	s_branch .LBB0_2150

;     DI void operator()(const f32x4 (&acc)[2][2][4][2], const pg8::Unit& u, int wr, int wc, int fr, int fq) const {
;         const int row0 = (u.pm - MP / 256) * 256 + wr * 64 + fr, col0 = u.pn * 256 + wc * 32 + 4 * fq;
;         float* dst = slab + (size_t)(u.kb / kslice_bytes) * MS * DM;
; #pragma unroll
;         for (int ai = 0; ai < 2; ++ai)
; #pragma unroll
;             for (int m = 0; m < 4; ++m) {
;                 const size_t off = (size_t)(row0 + ai * 128 + m * 16) * DM + col0;
; #pragma unroll
;                 for (int bj = 0; bj < 2; ++bj)
; #pragma unroll
;                     for (int n = 0; n < 2; ++n) *(f32x4*)(dst + off + bj * 128 + n * 16) = acc[ai][bj][m][n];
;             }
;     }
.LBB0_2153:
	s_mul_hi_i32 s24, s42, 0x2e8ba2e9
	s_lshr_b32 s25, s24, 31
	s_ashr_i32 s24, s24, 9
	s_add_i32 s24, s24, s25
	s_ashr_i32 s25, s24, 31
	s_lshl_b64 s[24:25], s[24:25], 23
	v_readlane_b32 s26, v253, 57
	v_lshl_or_b32 v146, s43, 8, v138
	s_add_u32 s24, s26, s24
	v_readlane_b32 s26, v253, 58
	v_lshl_add_u32 v148, s40, 8, v1
	s_addc_u32 s25, s26, s25
	v_ashrrev_i32_e32 v147, 31, v146
	v_ashrrev_i32_e32 v149, 31, v148
	v_lshl_add_u64 v[146:147], v[146:147], 2, s[24:25]
	v_lshlrev_b64 v[150:151], 13, v[148:149]
	v_lshl_add_u64 v[150:151], v[146:147], 0, v[150:151]
	global_store_dwordx4 v[150:151], v[126:129], off
	global_store_dwordx4 v[150:151], v[122:125], off offset:64
	global_store_dwordx4 v[150:151], v[110:113], off offset:512
	global_store_dwordx4 v[150:151], v[102:105], off offset:576
	s_nop 1
	v_or_b32_e32 v102, 16, v148
	v_ashrrev_i32_e32 v103, 31, v102
	v_lshlrev_b64 v[102:103], 13, v[102:103]
	v_lshl_add_u64 v[102:103], v[146:147], 0, v[102:103]
	global_store_dwordx4 v[102:103], v[118:121], off
	global_store_dwordx4 v[102:103], v[114:117], off offset:64
	global_store_dwordx4 v[102:103], v[94:97], off offset:512
	global_store_dwordx4 v[102:103], v[86:89], off offset:576
	s_nop 1
	v_or_b32_e32 v86, 32, v148
	v_ashrrev_i32_e32 v87, 31, v86
	v_lshlrev_b64 v[86:87], 13, v[86:87]
	v_lshl_add_u64 v[86:87], v[146:147], 0, v[86:87]
	global_store_dwordx4 v[86:87], v[106:109], off
	global_store_dwordx4 v[86:87], v[98:101], off offset:64
	global_store_dwordx4 v[86:87], v[78:81], off offset:512
	global_store_dwordx4 v[86:87], v[74:77], off offset:576
	s_nop 1
	v_or_b32_e32 v74, 48, v148
	v_ashrrev_i32_e32 v75, 31, v74
	v_lshlrev_b64 v[74:75], 13, v[74:75]
	v_lshl_add_u64 v[74:75], v[146:147], 0, v[74:75]
	global_store_dwordx4 v[74:75], v[90:93], off
	global_store_dwordx4 v[74:75], v[82:85], off offset:64
	global_store_dwordx4 v[74:75], v[70:73], off offset:512
	global_store_dwordx4 v[74:75], v[66:69], off offset:576
	s_nop 1
	v_add_co_u32_e32 v68, vcc, s46, v150
	v_lshl_add_u64 v[66:67], v[150:151], 0, s[10:11]
	s_nop 0
	v_addc_co_u32_e32 v69, vcc, 0, v151, vcc
	global_store_dwordx4 v[68:69], v[62:65], off
	global_store_dwordx4 v[66:67], v[58:61], off offset:64
	global_store_dwordx4 v[66:67], v[46:49], off offset:512
	global_store_dwordx4 v[66:67], v[38:41], off offset:576
	s_nop 1
	v_add_co_u32_e32 v40, vcc, s47, v150
	v_lshl_add_u64 v[38:39], v[150:151], 0, s[12:13]
	s_nop 0
	v_addc_co_u32_e32 v41, vcc, 0, v151, vcc
	global_store_dwordx4 v[40:41], v[54:57], off
	global_store_dwordx4 v[38:39], v[50:53], off offset:64
	global_store_dwordx4 v[38:39], v[30:33], off offset:512
	global_store_dwordx4 v[38:39], v[22:25], off offset:576
	s_nop 1
	v_add_co_u32_e32 v24, vcc, s48, v150
	v_lshl_add_u64 v[22:23], v[150:151], 0, s[18:19]
	s_nop 0
	v_addc_co_u32_e32 v25, vcc, 0, v151, vcc
	global_store_dwordx4 v[24:25], v[42:45], off
	global_store_dwordx4 v[22:23], v[34:37], off offset:64
	global_store_dwordx4 v[22:23], v[14:17], off offset:512
	global_store_dwordx4 v[22:23], v[10:13], off offset:576
	s_nop 1
	v_add_co_u32_e32 v12, vcc, 0x160000, v150
	v_lshl_add_u64 v[10:11], v[150:151], 0, s[2:3]
	s_nop 0
	v_addc_co_u32_e32 v13, vcc, 0, v151, vcc
	s_and_b64 vcc, exec, s[0:1]
	s_mov_b64 s[0:1], -1
	global_store_dwordx4 v[12:13], v[26:29], off
	global_store_dwordx4 v[10:11], v[18:21], off offset:64
	global_store_dwordx4 v[10:11], v[6:9], off offset:512
	global_store_dwordx4 v[10:11], v[2:5], off offset:576
	s_mov_b32 s98, 1
	s_cbranch_vccnz .LBB0_2142
	s_andn2_b64 vcc, exec, s[4:5]
	s_cbranch_vccnz .LBB0_2141
	s_barrier
	s_branch .LBB0_2141
